# phase-output 16-byte stores (GEMM epilogues P1/P3/P4/P5 and attention outputs) made write-through (sc1) so the grid-barrier L2 write-back has little left to flush
# baseline (speedup 1.0000x reference)
; #define PG8_LAS __attribute__((address_space(3)))
; __device__ __forceinline__ unsigned cvt_pk_bf16(float lo, float hi) { unsigned r; asm volatile("v_cvt_pk_bf16_f32 %0, %1, %2" : "=v"(r) : "v"(lo), "v"(hi)); return r; }
; __device__ __forceinline__ size_t tm_block(int pm, int ct, int nct) { return ((size_t)pm * nct + ct) * 32768; }
; __device__ __forceinline__ u32x4 pack8(const f32x4& v0, const f32x4& v1) { u32x4 w; w.x = cvt_pk_bf16(v0[0], v0[1]); w.y = cvt_pk_bf16(v0[2], v0[3]); w.z = cvt_pk_bf16(v1[0], v1[1]); w.w = cvt_pk_bf16(v1[2], v1[3]); return w; }
;     template <bool NT> __device__ __forceinline__ void flush(int ai, int m) const {
;         const u32x4 r0 = *(const PG8_LAS u32x4*)rp, r1 = *(const PG8_LAS u32x4*)(rp + 8 * PG8_SCR_STRIDE);
;         u32x4* p = (u32x4*)(ob + ai * 16384 + m * 2048);
;         if (NT) { __builtin_nontemporal_store(r0, p); __builtin_nontemporal_store(r1, p + 64); } else { *p = r0; *(p + 64) = r1; } }
;     __device__ __forceinline__ void operator()(const f32x4 (&acc)[2][2][4][2], const Unit& u, int wr, int wc, int fr, int fq) const {
;         const PieceOut po(scr, O, tm_block(u.pm, u.pn * 4 + wc, nct), wr, wc, fr, fq);
;         const float qs = (u.pn < 2 || u.pn == 3 || u.pn == 4) ? 0.125f * 1.4426950408889634f : 1.0f;
; #pragma unroll
;         for (int ai = 0; ai < 2; ++ai)
; #pragma unroll
;             for (int m = 0; m < 4; ++m) { po.put(0, pack8(acc[ai][0][m][0] * qs, acc[ai][0][m][1] * qs)); po.put(1, pack8(acc[ai][1][m][0] * qs, acc[ai][1][m][1] * qs)); po.flush<true>(ai, m); }
;     }
.LBB0_153:
	s_lshl_b32 s15, s70, 2
	s_or_b32 s15, s15, s53
	s_mul_hi_i32 s17, s22, 0x44
	s_mulk_i32 s22, 0x44
	s_ashr_i32 s25, s15, 31
	s_add_u32 s24, s22, s15
	s_addc_u32 s25, s17, s25
	s_lshl_b64 s[24:25], s[24:25], 15
	s_cmp_lt_i32 s70, 2
	s_cselect_b64 s[26:27], -1, 0
	s_add_i32 s15, s70, -3
	s_cmp_lt_u32 s15, 2
	s_cselect_b64 s[28:29], -1, 0
	s_or_b64 vcc, s[26:27], s[28:29]
	v_cndmask_b32_e32 v148, 1.0, v155, vcc
	v_pk_mul_f32 v[128:129], v[148:149], v[128:129] op_sel_hi:[0,1]
	v_pk_mul_f32 v[126:127], v[148:149], v[126:127] op_sel_hi:[0,1]
	v_pk_mul_f32 v[156:157], v[148:149], v[124:125] op_sel_hi:[0,1]
	v_pk_mul_f32 v[124:125], v[148:149], v[122:123] op_sel_hi:[0,1]
	v_cvt_pk_bf16_f32 v122, v126, v127
	v_cvt_pk_bf16_f32 v123, v128, v129
	v_cvt_pk_bf16_f32 v124, v124, v125
	v_cvt_pk_bf16_f32 v125, v156, v157
	ds_write_b128 v153, v[122:125]
	v_pk_mul_f32 v[122:123], v[148:149], v[112:113] op_sel_hi:[0,1]
	v_pk_mul_f32 v[112:113], v[148:149], v[110:111] op_sel_hi:[0,1]
	v_pk_mul_f32 v[120:121], v[148:149], v[120:121] op_sel_hi:[0,1]
	v_pk_mul_f32 v[118:119], v[148:149], v[118:119] op_sel_hi:[0,1]
	v_cvt_pk_bf16_f32 v110, v118, v119
	v_cvt_pk_bf16_f32 v111, v120, v121
	v_cvt_pk_bf16_f32 v112, v112, v113
	v_cvt_pk_bf16_f32 v113, v122, v123
	ds_write_b128 v153, v[110:113] offset:64
	ds_read_b128 v[110:113], v154
	ds_read_b128 v[118:121], v154 offset:1152
	v_lshl_add_u64 v[122:123], v[138:139], 0, s[24:25]
	s_waitcnt lgkmcnt(0)
	global_store_dwordx4 v[122:123], v[110:113], off sc1
	global_store_dwordx4 v[122:123], v[118:121], off offset:1024 sc1
	s_nop 0
	v_pk_mul_f32 v[110:111], v[148:149], v[116:117] op_sel_hi:[0,1]
	v_pk_mul_f32 v[112:113], v[148:149], v[114:115] op_sel_hi:[0,1]
	v_pk_mul_f32 v[114:115], v[148:149], v[108:109] op_sel_hi:[0,1]
	v_pk_mul_f32 v[108:109], v[148:149], v[106:107] op_sel_hi:[0,1]
	v_cvt_pk_bf16_f32 v106, v112, v113
	v_cvt_pk_bf16_f32 v107, v110, v111
	v_cvt_pk_bf16_f32 v108, v108, v109
	v_cvt_pk_bf16_f32 v109, v114, v115
	ds_write_b128 v153, v[106:109]
	v_pk_mul_f32 v[106:107], v[148:149], v[96:97] op_sel_hi:[0,1]
	v_pk_mul_f32 v[96:97], v[148:149], v[94:95] op_sel_hi:[0,1]
	v_pk_mul_f32 v[104:105], v[148:149], v[104:105] op_sel_hi:[0,1]
	v_pk_mul_f32 v[102:103], v[148:149], v[102:103] op_sel_hi:[0,1]
	v_cvt_pk_bf16_f32 v94, v102, v103
	v_cvt_pk_bf16_f32 v95, v104, v105
	v_cvt_pk_bf16_f32 v96, v96, v97
	v_cvt_pk_bf16_f32 v97, v106, v107
	ds_write_b128 v153, v[94:97] offset:64
	ds_read_b128 v[94:97], v154
	ds_read_b128 v[102:105], v154 offset:1152
	s_waitcnt lgkmcnt(0)
	global_store_dwordx4 v[122:123], v[94:97], off offset:2048 sc1
	global_store_dwordx4 v[122:123], v[102:105], off offset:3072 sc1
	s_nop 0
	v_pk_mul_f32 v[94:95], v[148:149], v[100:101] op_sel_hi:[0,1]
	v_pk_mul_f32 v[96:97], v[148:149], v[98:99] op_sel_hi:[0,1]
	v_pk_mul_f32 v[98:99], v[148:149], v[92:93] op_sel_hi:[0,1]
	v_pk_mul_f32 v[92:93], v[148:149], v[90:91] op_sel_hi:[0,1]
	v_cvt_pk_bf16_f32 v90, v96, v97
	v_cvt_pk_bf16_f32 v91, v94, v95
	v_cvt_pk_bf16_f32 v92, v92, v93
	v_cvt_pk_bf16_f32 v93, v98, v99
	ds_write_b128 v153, v[90:93]
	v_pk_mul_f32 v[90:91], v[148:149], v[84:85] op_sel_hi:[0,1]
	v_pk_mul_f32 v[84:85], v[148:149], v[82:83] op_sel_hi:[0,1]
	v_pk_mul_f32 v[88:89], v[148:149], v[88:89] op_sel_hi:[0,1]
	v_pk_mul_f32 v[86:87], v[148:149], v[86:87] op_sel_hi:[0,1]
	v_cvt_pk_bf16_f32 v82, v86, v87
	v_cvt_pk_bf16_f32 v83, v88, v89
	v_cvt_pk_bf16_f32 v84, v84, v85
	v_cvt_pk_bf16_f32 v85, v90, v91
	ds_write_b128 v153, v[82:85] offset:64
	ds_read_b128 v[82:85], v154
	ds_read_b128 v[86:89], v154 offset:1152
	v_add_co_u32_e32 v90, vcc, s58, v122
	v_pk_mul_f32 v[80:81], v[148:149], v[80:81] op_sel_hi:[0,1]
	s_nop 0
	v_addc_co_u32_e32 v91, vcc, 0, v123, vcc
	s_waitcnt lgkmcnt(0)
	global_store_dwordx4 v[90:91], v[82:85], off sc1
	global_store_dwordx4 v[90:91], v[86:89], off offset:1024 sc1
	v_pk_mul_f32 v[78:79], v[148:149], v[78:79] op_sel_hi:[0,1]
	v_pk_mul_f32 v[82:83], v[148:149], v[76:77] op_sel_hi:[0,1]
	v_pk_mul_f32 v[76:77], v[148:149], v[74:75] op_sel_hi:[0,1]
	v_cvt_pk_bf16_f32 v74, v78, v79
	v_cvt_pk_bf16_f32 v75, v80, v81
	v_cvt_pk_bf16_f32 v76, v76, v77
	v_cvt_pk_bf16_f32 v77, v82, v83
	ds_write_b128 v153, v[74:77]
	v_pk_mul_f32 v[74:75], v[148:149], v[68:69] op_sel_hi:[0,1]
	v_pk_mul_f32 v[68:69], v[148:149], v[66:67] op_sel_hi:[0,1]
	v_pk_mul_f32 v[72:73], v[148:149], v[72:73] op_sel_hi:[0,1]
	v_pk_mul_f32 v[70:71], v[148:149], v[70:71] op_sel_hi:[0,1]
	v_cvt_pk_bf16_f32 v66, v70, v71
	v_cvt_pk_bf16_f32 v67, v72, v73
	v_cvt_pk_bf16_f32 v68, v68, v69
	v_cvt_pk_bf16_f32 v69, v74, v75
	ds_write_b128 v153, v[66:69] offset:64
	ds_read_b128 v[66:69], v154
	ds_read_b128 v[70:73], v154 offset:1152
	s_waitcnt lgkmcnt(0)
; #define PG8_LAS __attribute__((address_space(3)))
; __device__ __forceinline__ unsigned cvt_pk_bf16(float lo, float hi) { unsigned r; asm volatile("v_cvt_pk_bf16_f32 %0, %1, %2" : "=v"(r) : "v"(lo), "v"(hi)); return r; }
; __device__ __forceinline__ size_t tm_block(int pm, int ct, int nct) { return ((size_t)pm * nct + ct) * 32768; }
; __device__ __forceinline__ u32x4 pack8(const f32x4& v0, const f32x4& v1) { u32x4 w; w.x = cvt_pk_bf16(v0[0], v0[1]); w.y = cvt_pk_bf16(v0[2], v0[3]); w.z = cvt_pk_bf16(v1[0], v1[1]); w.w = cvt_pk_bf16(v1[2], v1[3]); return w; }
;     template <bool NT> __device__ __forceinline__ void flush(int ai, int m) const {
;         const u32x4 r0 = *(const PG8_LAS u32x4*)rp, r1 = *(const PG8_LAS u32x4*)(rp + 8 * PG8_SCR_STRIDE);
;         u32x4* p = (u32x4*)(ob + ai * 16384 + m * 2048);
;         if (NT) { __builtin_nontemporal_store(r0, p); __builtin_nontemporal_store(r1, p + 64); } else { *p = r0; *(p + 64) = r1; } }
;     __device__ __forceinline__ void operator()(const f32x4 (&acc)[2][2][4][2], const Unit& u, int wr, int wc, int fr, int fq) const {
;         const PieceOut po(scr, O, tm_block(u.pm, u.pn * 4 + wc, nct), wr, wc, fr, fq);
;         const float qs = (u.pn < 2 || u.pn == 3 || u.pn == 4) ? 0.125f * 1.4426950408889634f : 1.0f;
; #pragma unroll
;         for (int ai = 0; ai < 2; ++ai)
; #pragma unroll
;             for (int m = 0; m < 4; ++m) { po.put(0, pack8(acc[ai][0][m][0] * qs, acc[ai][0][m][1] * qs)); po.put(1, pack8(acc[ai][1][m][0] * qs, acc[ai][1][m][1] * qs)); po.flush<true>(ai, m); }
;     }
	global_store_dwordx4 v[90:91], v[66:69], off offset:2048 sc1
	global_store_dwordx4 v[90:91], v[70:73], off offset:3072 sc1
	v_pk_mul_f32 v[64:65], v[148:149], v[64:65] op_sel_hi:[0,1]
	v_pk_mul_f32 v[62:63], v[148:149], v[62:63] op_sel_hi:[0,1]
	v_pk_mul_f32 v[66:67], v[148:149], v[60:61] op_sel_hi:[0,1]
	v_pk_mul_f32 v[60:61], v[148:149], v[58:59] op_sel_hi:[0,1]
	v_cvt_pk_bf16_f32 v58, v62, v63
	v_cvt_pk_bf16_f32 v59, v64, v65
	v_cvt_pk_bf16_f32 v60, v60, v61
	v_cvt_pk_bf16_f32 v61, v66, v67
	ds_write_b128 v153, v[58:61]
	v_pk_mul_f32 v[58:59], v[148:149], v[52:53] op_sel_hi:[0,1]
	v_pk_mul_f32 v[52:53], v[148:149], v[50:51] op_sel_hi:[0,1]
	v_pk_mul_f32 v[56:57], v[148:149], v[56:57] op_sel_hi:[0,1]
	v_pk_mul_f32 v[54:55], v[148:149], v[54:55] op_sel_hi:[0,1]
	v_cvt_pk_bf16_f32 v50, v54, v55
	v_cvt_pk_bf16_f32 v51, v56, v57
	v_cvt_pk_bf16_f32 v52, v52, v53
	v_cvt_pk_bf16_f32 v53, v58, v59
	ds_write_b128 v153, v[50:53] offset:64
	ds_read_b128 v[50:53], v154
	ds_read_b128 v[54:57], v154 offset:1152
	v_add_co_u32_e32 v58, vcc, s52, v122
	v_pk_mul_f32 v[48:49], v[148:149], v[48:49] op_sel_hi:[0,1]
	s_nop 0
	v_addc_co_u32_e32 v59, vcc, 0, v123, vcc
	v_add_co_u32_e32 v60, vcc, s59, v122
	v_pk_mul_f32 v[46:47], v[148:149], v[46:47] op_sel_hi:[0,1]
	s_nop 0
	v_addc_co_u32_e32 v61, vcc, 0, v123, vcc
	s_waitcnt lgkmcnt(0)
	global_store_dwordx4 v[60:61], v[50:53], off offset:-4096 sc1
	global_store_dwordx4 v[58:59], v[54:57], off offset:1024 sc1
	v_pk_mul_f32 v[40:41], v[148:149], v[40:41] op_sel_hi:[0,1]
	v_pk_mul_f32 v[50:51], v[148:149], v[44:45] op_sel_hi:[0,1]
	v_pk_mul_f32 v[44:45], v[148:149], v[42:43] op_sel_hi:[0,1]
	v_cvt_pk_bf16_f32 v42, v46, v47
	v_cvt_pk_bf16_f32 v43, v48, v49
	v_cvt_pk_bf16_f32 v44, v44, v45
	v_cvt_pk_bf16_f32 v45, v50, v51
	ds_write_b128 v153, v[42:45]
	v_pk_mul_f32 v[42:43], v[148:149], v[32:33] op_sel_hi:[0,1]
	v_pk_mul_f32 v[32:33], v[148:149], v[30:31] op_sel_hi:[0,1]
	v_pk_mul_f32 v[38:39], v[148:149], v[38:39] op_sel_hi:[0,1]
	v_cvt_pk_bf16_f32 v30, v38, v39
	v_cvt_pk_bf16_f32 v31, v40, v41
	v_cvt_pk_bf16_f32 v32, v32, v33
	v_cvt_pk_bf16_f32 v33, v42, v43
	ds_write_b128 v153, v[30:33] offset:64
	ds_read_b128 v[30:33], v154
	ds_read_b128 v[38:41], v154 offset:1152
	s_waitcnt lgkmcnt(0)
	global_store_dwordx4 v[58:59], v[30:33], off offset:2048 sc1
	global_store_dwordx4 v[58:59], v[38:41], off offset:3072 sc1
	s_nop 0
	v_pk_mul_f32 v[30:31], v[148:149], v[36:37] op_sel_hi:[0,1]
	v_pk_mul_f32 v[32:33], v[148:149], v[34:35] op_sel_hi:[0,1]
	v_pk_mul_f32 v[34:35], v[148:149], v[28:29] op_sel_hi:[0,1]
	v_pk_mul_f32 v[28:29], v[148:149], v[26:27] op_sel_hi:[0,1]
	v_cvt_pk_bf16_f32 v26, v32, v33
	v_cvt_pk_bf16_f32 v27, v30, v31
	v_cvt_pk_bf16_f32 v28, v28, v29
	v_cvt_pk_bf16_f32 v29, v34, v35
	ds_write_b128 v153, v[26:29]
	v_pk_mul_f32 v[26:27], v[148:149], v[16:17] op_sel_hi:[0,1]
	v_pk_mul_f32 v[16:17], v[148:149], v[14:15] op_sel_hi:[0,1]
	v_pk_mul_f32 v[24:25], v[148:149], v[24:25] op_sel_hi:[0,1]
	v_pk_mul_f32 v[22:23], v[148:149], v[22:23] op_sel_hi:[0,1]
	v_cvt_pk_bf16_f32 v14, v22, v23
	v_cvt_pk_bf16_f32 v15, v24, v25
	v_cvt_pk_bf16_f32 v16, v16, v17
	v_cvt_pk_bf16_f32 v17, v26, v27
	ds_write_b128 v153, v[14:17] offset:64
	ds_read_b128 v[14:17], v154
	ds_read_b128 v[22:25], v154 offset:1152
	s_waitcnt lgkmcnt(0)
	global_store_dwordx4 v[60:61], v[14:17], off sc1
	global_store_dwordx4 v[60:61], v[22:25], off offset:1024 sc1
	s_nop 0
	v_pk_mul_f32 v[14:15], v[148:149], v[20:21] op_sel_hi:[0,1]
	v_pk_mul_f32 v[16:17], v[148:149], v[18:19] op_sel_hi:[0,1]
	v_pk_mul_f32 v[18:19], v[148:149], v[12:13] op_sel_hi:[0,1]
	v_pk_mul_f32 v[12:13], v[148:149], v[10:11] op_sel_hi:[0,1]
	v_cvt_pk_bf16_f32 v10, v16, v17
	v_cvt_pk_bf16_f32 v11, v14, v15
	v_cvt_pk_bf16_f32 v12, v12, v13
	v_cvt_pk_bf16_f32 v13, v18, v19
	ds_write_b128 v153, v[10:13]
	v_pk_mul_f32 v[10:11], v[148:149], v[4:5] op_sel_hi:[0,1]
	v_pk_mul_f32 v[4:5], v[148:149], v[2:3] op_sel_hi:[0,1]
	v_pk_mul_f32 v[8:9], v[148:149], v[8:9] op_sel_hi:[0,1]
	v_pk_mul_f32 v[6:7], v[148:149], v[6:7] op_sel_hi:[0,1]
	v_cvt_pk_bf16_f32 v2, v6, v7
	v_cvt_pk_bf16_f32 v3, v8, v9
	v_cvt_pk_bf16_f32 v4, v4, v5
	v_cvt_pk_bf16_f32 v5, v10, v11
	ds_write_b128 v153, v[2:5] offset:64
	ds_read_b128 v[2:5], v154
	ds_read_b128 v[6:9], v154 offset:1152
	s_andn2_b64 vcc, exec, s[4:5]
	s_mov_b64 s[4:5], -1
	s_waitcnt lgkmcnt(0)
	global_store_dwordx4 v[60:61], v[2:5], off offset:2048 sc1
	global_store_dwordx4 v[60:61], v[6:9], off offset:3072 sc1
	s_cbranch_vccnz .LBB0_146
	s_andn2_b64 vcc, exec, s[10:11]
	s_cbranch_vccnz .LBB0_145
	s_barrier
	s_branch .LBB0_145

; template <bool MASK> __device__ __forceinline__ void a_scores(f32x4& S0, f32x4& S1, float basef, float c1, float slope2, int krow0, int kstart) {
; #pragma unroll
;     for (int r = 0; r < 4; ++r) {
;         const float d0 = fabsf(basef - (float)r), d1 = fabsf(basef - (float)(16 + r));
;         const float v0 = S0[r] - slope2 * d0, v1 = S1[r] - slope2 * d1;
;         if (MASK) { const int p0 = kstart + krow0 + r, p1 = p0 + 16;
;             S0[r] = (d0 <= 128.f && p0 >= 0 && p0 < SEQ) ? v0 : -INFINITY; S1[r] = (d1 <= 128.f && p1 >= 0 && p1 < SEQ) ? v1 : -INFINITY; }
;         else { S0[r] = v0; S1[r] = v1; }
;     }
; }
; __device__ __forceinline__ void attn_a_prefetch(const bf16* Z, int unit, v4u (&kr)[7], v4u (&vr)[7]) {
;     const int tid = threadIdx.x; const int ib = unit & 63, kvh = (unit >> 6) & 1, b = unit >> 7;
;     const size_t tok0 = (size_t)b * SEQ; const int kstart = (ib - 1) * 128;
; #pragma unroll
;     for (int k = 0; k < 7; ++k) { const int it = tid + k * NTHREADS; const int row = it >> 3, ch = it & 7, pos = kstart + row;
;         kr[k] = (v4u){0u, 0u, 0u, 0u}; vr[k] = (v4u){0u, 0u, 0u, 0u};
;         if (it < A_ROWS * 8 && row < 384 && pos >= 0 && pos < SEQ) { const int t = (int)tok0 + pos; kr[k] = *(const v4u*)((const unsigned char*)Z + tmo(t, Z_KA / 64 + kvh, ZLD / 64) + ch * 16); vr[k] = *(const v4u*)((const unsigned char*)Z + tmo(t, Z_VA / 64 + kvh, ZLD / 64) + ch * 16); } }
; }
; __device__ __forceinline__ void attn_a_commit(LAS unsigned char* lds, const v4u (&kr)[7], const v4u (&vr)[7]) {
;     const int tid = threadIdx.x; LAS unsigned char* Kl = lds + A_KOFF; LAS unsigned char* Vl = lds + A_VOFF;
; #pragma unroll
;     for (int k = 0; k < 7; ++k) { const int it = tid + k * NTHREADS; const int row = it >> 3, ch = it & 7;
;         if (it < A_ROWS * 8) { *(LAS v4u*)(Kl + swz(row, ch)) = kr[k]; *(LAS v4u*)(Vl + swz(row, ch)) = vr[k]; } }
; }
; __device__ __forceinline__ void attn_a_unit(LAS unsigned char* lds, const bf16* Z, bf16* Y, const float* sink, int unit) {
;     const int tid = threadIdx.x, lane = tid & 63, wid = tid >> 6, lq = lane & 15, g = lane >> 4;
;     const int ib = unit & 63, kvh = (unit >> 6) & 1, b = unit >> 7;
;     const size_t tok0 = (size_t)b * SEQ; const int kstart = (ib - 1) * 128;
;     LAS unsigned char* Kl = lds + A_KOFF; LAS unsigned char* Vl = lds + A_VOFF;
;     const int hq = kvh * 4 + (wid >> 1);
.LBB0_257:
	s_waitcnt vmcnt(14)
	v_and_b32_e32 v219, 15, v218
	v_bfe_u32 v244, v218, 4, 2
	v_add_u32_e32 v245, s85, v219
	v_lshlrev_b32_e32 v245, 7, v245
	v_bitop3_b32 v120, v219, v244, 7 bitop3:0x6c
	v_lshl_add_u32 v122, v120, 4, v245
	v_xor_b32_e32 v120, 4, v120
	v_lshl_add_u32 v123, v120, 4, v245
	v_lshlrev_b32_e32 v245, 2, v244
	v_sub_u32_e32 v120, v219, v245
	v_cmp_ge_i32_e64 s[16:17], 0, v120
	v_cmp_le_i32_e64 s[28:29], 0, v120
	v_cmp_ge_i32_e64 s[18:19], 1, v120
	v_cmp_le_i32_e64 s[52:53], 1, v120
	v_cmp_ge_i32_e64 s[22:23], 2, v120
	v_cmp_le_i32_e64 s[54:55], 2, v120
	v_cmp_ge_i32_e64 s[24:25], 3, v120
	v_cmp_le_i32_e64 s[88:89], 3, v120
	v_cmp_eq_u32_e64 s[74:75], 0, v244
	v_cvt_f32_i32_e32 v129, v120
	v_lshrrev_b32_e32 v120, 2, v219
	v_add_u32_e32 v245, v245, v120
	v_bfe_u32 v120, v219, 1, 1
	v_and_b32_e32 v219, 1, v219
	v_lshlrev_b32_e32 v219, 3, v219
	v_add_u32_e32 v244, s85, v245
	v_lshl_add_u32 v219, v244, 7, v219
	v_add_u32_e32 v219, 0xc800, v219
	v_or_b32_e32 v245, 0, v120
	v_bitop3_b32 v245, v244, v245, 7 bitop3:0x6c
	v_lshl_add_u32 v124, v245, 4, v219
	v_or_b32_e32 v245, 2, v120
	v_bitop3_b32 v245, v244, v245, 7 bitop3:0x6c
	v_lshl_add_u32 v125, v245, 4, v219
	v_or_b32_e32 v245, 4, v120
	v_bitop3_b32 v245, v244, v245, 7 bitop3:0x6c
	v_lshl_add_u32 v126, v245, 4, v219
	v_or_b32_e32 v245, 6, v120
	v_bitop3_b32 v245, v244, v245, 7 bitop3:0x6c
	v_lshl_add_u32 v127, v245, 4, v219
	v_mov_b32_e32 v131, s84
	v_xor_b32_e32 v130, 0x80000000, v131
	v_mov_b32_e32 v219, s76
	v_mul_f32_e32 v145, 0x3fb8aa3b, v219
	v_mul_f32_e32 v132, v130, v129
	v_mul_f32_e32 v133, v131, v129
	s_cmp_eq_u32 s77, 0
	s_cbranch_scc1 .La_edge_lo
	s_cmp_eq_u32 s77, 63
	s_cbranch_scc1 .La_edge_hi
	v_fmamk_f32 v50, v130, 0x43000000, v132
	v_fmamk_f32 v51, v130, 0x42fe0000, v132
	v_fmamk_f32 v52, v130, 0x42fc0000, v132
	v_fmamk_f32 v53, v130, 0x42fa0000, v132
	v_fmamk_f32 v54, v130, 0x42e00000, v132
	v_fmamk_f32 v55, v130, 0x42de0000, v132
	v_fmamk_f32 v56, v130, 0x42dc0000, v132
	v_fmamk_f32 v57, v130, 0x42da0000, v132
	v_fmamk_f32 v58, v130, 0x42c00000, v132
	v_fmamk_f32 v59, v130, 0x42be0000, v132
	v_fmamk_f32 v60, v130, 0x42bc0000, v132
	v_fmamk_f32 v61, v130, 0x42ba0000, v132
	v_fmamk_f32 v62, v130, 0x42a00000, v132
	v_fmamk_f32 v63, v130, 0x429e0000, v132
	v_fmamk_f32 v64, v130, 0x429c0000, v132
	v_fmamk_f32 v65, v130, 0x429a0000, v132
	v_fmamk_f32 v66, v130, 0x42800000, v132
	v_fmamk_f32 v67, v130, 0x427c0000, v132
	v_fmamk_f32 v68, v130, 0x42780000, v132
	v_fmamk_f32 v69, v130, 0x42740000, v132
	v_fmamk_f32 v70, v130, 0x42400000, v132
	v_fmamk_f32 v71, v130, 0x423c0000, v132
	v_fmamk_f32 v72, v130, 0x42380000, v132
	v_fmamk_f32 v73, v130, 0x42340000, v132
	v_fmamk_f32 v74, v130, 0x42000000, v132
	v_fmamk_f32 v75, v130, 0x41f80000, v132
	v_fmamk_f32 v76, v130, 0x41f00000, v132
	v_fmamk_f32 v77, v130, 0x41e80000, v132
	v_fmamk_f32 v78, v130, 0x41800000, v132
	v_fmamk_f32 v79, v130, 0x41700000, v132
	v_fmamk_f32 v80, v130, 0x41600000, v132
	v_fmamk_f32 v81, v130, 0x41500000, v132
	v_add_f32_e32 v219, 0, v129
	v_mul_f32_e64 v82, v130, |v219|
	v_add_f32_e32 v244, 0xbf800000, v129
	v_mul_f32_e64 v83, v130, |v244|
	v_add_f32_e32 v219, 0xc0000000, v129
	v_mul_f32_e64 v84, v130, |v219|
	v_add_f32_e32 v244, 0xc0400000, v129
	v_mul_f32_e64 v85, v130, |v244|
	v_fmamk_f32 v86, v131, 0xc1800000, v133
	v_fmamk_f32 v87, v131, 0xc1880000, v133
	v_fmamk_f32 v88, v131, 0xc1900000, v133
	v_fmamk_f32 v89, v131, 0xc1980000, v133
	v_fmamk_f32 v90, v131, 0xc2000000, v133
	v_fmamk_f32 v91, v131, 0xc2040000, v133
	v_fmamk_f32 v92, v131, 0xc2080000, v133
	v_fmamk_f32 v93, v131, 0xc20c0000, v133
	v_fmamk_f32 v94, v131, 0xc2400000, v133
	v_fmamk_f32 v95, v131, 0xc2440000, v133
	v_fmamk_f32 v96, v131, 0xc2480000, v133
	v_fmamk_f32 v97, v131, 0xc24c0000, v133
	v_fmamk_f32 v98, v131, 0xc2800000, v133
	v_fmamk_f32 v99, v131, 0xc2820000, v133
	v_fmamk_f32 v100, v131, 0xc2840000, v133
	v_fmamk_f32 v101, v131, 0xc2860000, v133
	v_fmamk_f32 v102, v131, 0xc2a00000, v133
	v_fmamk_f32 v103, v131, 0xc2a20000, v133
	v_fmamk_f32 v104, v131, 0xc2a40000, v133
	v_fmamk_f32 v105, v131, 0xc2a60000, v133
	v_fmamk_f32 v106, v131, 0xc2c00000, v133
	v_fmamk_f32 v107, v131, 0xc2c20000, v133
	v_fmamk_f32 v108, v131, 0xc2c40000, v133
	v_fmamk_f32 v109, v131, 0xc2c60000, v133
	v_fmamk_f32 v110, v131, 0xc2e00000, v133
	v_fmamk_f32 v111, v131, 0xc2e20000, v133
	v_fmamk_f32 v112, v131, 0xc2e40000, v133
	v_fmamk_f32 v113, v131, 0xc2e60000, v133
	v_fmamk_f32 v114, v131, 0xc3000000, v133
	v_fmamk_f32 v115, v131, 0xc3010000, v133
	v_fmamk_f32 v116, v131, 0xc3020000, v133
	v_fmamk_f32 v117, v131, 0xc3030000, v133
	v_mov_b32_e32 v245, 0xff800000
	v_cndmask_b32_e64 v50, v245, v50, s[16:17]
	v_cndmask_b32_e64 v51, v245, v51, s[18:19]
	v_cndmask_b32_e64 v52, v245, v52, s[22:23]
	v_cndmask_b32_e64 v53, v245, v53, s[24:25]
	v_cndmask_b32_e64 v114, v245, v114, s[28:29]
	v_cndmask_b32_e64 v115, v245, v115, s[52:53]
	v_cndmask_b32_e64 v116, v245, v116, s[54:55]
	v_cndmask_b32_e64 v117, v245, v117, s[88:89]
	ds_read_b128 v[186:189], v122 offset:0
	ds_read_b128 v[190:193], v123 offset:0
	ds_read_b128 v[194:197], v122 offset:2048
	ds_read_b128 v[198:201], v123 offset:2048
	ds_read_b128 v[202:205], v122 offset:4096
	ds_read_b128 v[206:209], v123 offset:4096
	s_waitcnt lgkmcnt(5)
	v_mfma_f32_16x16x32_bf16 v[50:53], v[186:189], v[146:149], v[50:53]
	s_waitcnt lgkmcnt(4)
	v_mfma_f32_16x16x32_bf16 v[50:53], v[190:193], v[150:153], v[50:53]
	ds_read_b128 v[186:189], v122 offset:6144
	ds_read_b128 v[190:193], v123 offset:6144
	s_waitcnt lgkmcnt(5)
	v_mfma_f32_16x16x32_bf16 v[54:57], v[194:197], v[146:149], v[54:57]
	s_waitcnt lgkmcnt(4)
; #define LAS __attribute__((address_space(3)))
; #define MFMA16(a, b, c) __builtin_amdgcn_mfma_f32_16x16x32_bf16((a), (b), (c), 0, 0, 0)
; __device__ __forceinline__ void qk_at(const LAS unsigned char* kp0, const LAS unsigned char* kp1, int off, bf16x8 qf0, bf16x8 qf1, f32x4& S0, f32x4& S1) {
;     const bf16x8 k00 = *(const LAS bf16x8*)(kp0 + off), k01 = *(const LAS bf16x8*)(kp1 + off);
;     const bf16x8 k10 = *(const LAS bf16x8*)(kp0 + off + 2048), k11 = *(const LAS bf16x8*)(kp1 + off + 2048);
;     const f32x4 z = {0.f, 0.f, 0.f, 0.f};
;     S0 = MFMA16(k00, qf0, z); S0 = MFMA16(k01, qf1, S0);
;     S1 = MFMA16(k10, qf0, z); S1 = MFMA16(k11, qf1, S1);
; }
; __device__ __forceinline__ void softmax_step(f32x4& s0, f32x4& s1, float& m, float& l, f32x4 (&O)[4]) {
;     float t = fmaxf(fmaxf(fmaxf(s0[0], s0[1]), fmaxf(s0[2], s0[3])), fmaxf(fmaxf(s1[0], s1[1]), fmaxf(s1[2], s1[3])));
;     t = xrow16_max(t);
	v_mfma_f32_16x16x32_bf16 v[54:57], v[198:201], v[150:153], v[54:57]
	ds_read_b128 v[194:197], v122 offset:8192
	ds_read_b128 v[198:201], v123 offset:8192
	s_waitcnt lgkmcnt(5)
	v_mfma_f32_16x16x32_bf16 v[58:61], v[202:205], v[146:149], v[58:61]
	s_waitcnt lgkmcnt(4)
	v_mfma_f32_16x16x32_bf16 v[58:61], v[206:209], v[150:153], v[58:61]
	ds_read_b128 v[202:205], v122 offset:10240
	ds_read_b128 v[206:209], v123 offset:10240
	s_waitcnt lgkmcnt(5)
	v_mfma_f32_16x16x32_bf16 v[62:65], v[186:189], v[146:149], v[62:65]
	s_waitcnt lgkmcnt(4)
	v_mfma_f32_16x16x32_bf16 v[62:65], v[190:193], v[150:153], v[62:65]
	ds_read_b128 v[186:189], v122 offset:12288
	ds_read_b128 v[190:193], v123 offset:12288
	s_waitcnt lgkmcnt(5)
	v_mfma_f32_16x16x32_bf16 v[66:69], v[194:197], v[146:149], v[66:69]
	s_waitcnt lgkmcnt(4)
	v_mfma_f32_16x16x32_bf16 v[66:69], v[198:201], v[150:153], v[66:69]
	ds_read_b128 v[194:197], v122 offset:14336
	ds_read_b128 v[198:201], v123 offset:14336
	s_waitcnt lgkmcnt(5)
	v_mfma_f32_16x16x32_bf16 v[70:73], v[202:205], v[146:149], v[70:73]
	s_waitcnt lgkmcnt(4)
	v_mfma_f32_16x16x32_bf16 v[70:73], v[206:209], v[150:153], v[70:73]
	ds_read_b128 v[202:205], v122 offset:16384
	ds_read_b128 v[206:209], v123 offset:16384
	s_waitcnt lgkmcnt(5)
	v_mfma_f32_16x16x32_bf16 v[74:77], v[186:189], v[146:149], v[74:77]
	s_waitcnt lgkmcnt(4)
	v_mfma_f32_16x16x32_bf16 v[74:77], v[190:193], v[150:153], v[74:77]
	ds_read_b128 v[186:189], v122 offset:18432
	ds_read_b128 v[190:193], v123 offset:18432
	s_waitcnt lgkmcnt(5)
	v_mfma_f32_16x16x32_bf16 v[78:81], v[194:197], v[146:149], v[78:81]
	s_waitcnt lgkmcnt(4)
	v_mfma_f32_16x16x32_bf16 v[78:81], v[198:201], v[150:153], v[78:81]
	ds_read_b128 v[194:197], v122 offset:20480
	ds_read_b128 v[198:201], v123 offset:20480
	s_waitcnt lgkmcnt(5)
	v_mfma_f32_16x16x32_bf16 v[82:85], v[202:205], v[146:149], v[82:85]
	s_waitcnt lgkmcnt(4)
	v_mfma_f32_16x16x32_bf16 v[82:85], v[206:209], v[150:153], v[82:85]
	ds_read_b128 v[202:205], v122 offset:22528
	ds_read_b128 v[206:209], v123 offset:22528
	s_waitcnt lgkmcnt(5)
	v_mfma_f32_16x16x32_bf16 v[86:89], v[186:189], v[146:149], v[86:89]
	s_waitcnt lgkmcnt(4)
	v_mfma_f32_16x16x32_bf16 v[86:89], v[190:193], v[150:153], v[86:89]
	ds_read_b128 v[186:189], v122 offset:24576
	ds_read_b128 v[190:193], v123 offset:24576
	s_waitcnt lgkmcnt(5)
	v_mfma_f32_16x16x32_bf16 v[90:93], v[194:197], v[146:149], v[90:93]
	s_waitcnt lgkmcnt(4)
	v_mfma_f32_16x16x32_bf16 v[90:93], v[198:201], v[150:153], v[90:93]
	ds_read_b128 v[194:197], v122 offset:26624
	ds_read_b128 v[198:201], v123 offset:26624
	s_waitcnt lgkmcnt(5)
	v_mfma_f32_16x16x32_bf16 v[94:97], v[202:205], v[146:149], v[94:97]
	s_waitcnt lgkmcnt(4)
	v_mfma_f32_16x16x32_bf16 v[94:97], v[206:209], v[150:153], v[94:97]
	ds_read_b128 v[202:205], v122 offset:28672
	ds_read_b128 v[206:209], v123 offset:28672
	s_waitcnt lgkmcnt(5)
	v_mfma_f32_16x16x32_bf16 v[98:101], v[186:189], v[146:149], v[98:101]
	s_waitcnt lgkmcnt(4)
	v_mfma_f32_16x16x32_bf16 v[98:101], v[190:193], v[150:153], v[98:101]
	ds_read_b128 v[186:189], v122 offset:30720
	ds_read_b128 v[190:193], v123 offset:30720
	s_waitcnt lgkmcnt(5)
	v_mfma_f32_16x16x32_bf16 v[102:105], v[194:197], v[146:149], v[102:105]
	s_waitcnt lgkmcnt(4)
	v_mfma_f32_16x16x32_bf16 v[102:105], v[198:201], v[150:153], v[102:105]
	ds_read_b128 v[194:197], v122 offset:32768
	ds_read_b128 v[198:201], v123 offset:32768
	s_waitcnt lgkmcnt(5)
	v_mfma_f32_16x16x32_bf16 v[106:109], v[202:205], v[146:149], v[106:109]
	s_waitcnt lgkmcnt(4)
	v_mfma_f32_16x16x32_bf16 v[106:109], v[206:209], v[150:153], v[106:109]
	s_waitcnt lgkmcnt(3)
	v_mfma_f32_16x16x32_bf16 v[110:113], v[186:189], v[146:149], v[110:113]
	s_waitcnt lgkmcnt(2)
	v_mfma_f32_16x16x32_bf16 v[110:113], v[190:193], v[150:153], v[110:113]
	s_waitcnt lgkmcnt(1)
	v_mfma_f32_16x16x32_bf16 v[114:117], v[194:197], v[146:149], v[114:117]
	s_waitcnt lgkmcnt(0)
	v_mfma_f32_16x16x32_bf16 v[114:117], v[198:201], v[150:153], v[114:117]
	v_max3_f32 v219, v50, v51, v52
	v_max3_f32 v244, v54, v55, v56
	v_max3_f32 v245, v58, v59, v60
	v_max3_f32 v120, v62, v63, v64
	v_max3_f32 v219, v219, v53, v66
	v_max3_f32 v244, v244, v57, v70
	v_max3_f32 v245, v245, v61, v74
	v_max3_f32 v120, v120, v65, v78
	v_max3_f32 v219, v219, v67, v68
	v_max3_f32 v244, v244, v71, v72
	v_max3_f32 v245, v245, v75, v76
	v_max3_f32 v120, v120, v79, v80
	ds_read_b64_tr_b16 v[186:187], v124 offset:0
	ds_read_b64_tr_b16 v[188:189], v124 offset:2048
	ds_read_b64_tr_b16 v[190:191], v125 offset:0
	ds_read_b64_tr_b16 v[192:193], v125 offset:2048
	ds_read_b64_tr_b16 v[194:195], v126 offset:0
	ds_read_b64_tr_b16 v[196:197], v126 offset:2048
	ds_read_b64_tr_b16 v[198:199], v127 offset:0
	ds_read_b64_tr_b16 v[200:201], v127 offset:2048
	v_max3_f32 v219, v219, v69, v82
	v_max3_f32 v244, v244, v73, v86
	v_max3_f32 v245, v245, v77, v90
	v_max3_f32 v120, v120, v81, v94
	v_max3_f32 v219, v219, v83, v84
	v_max3_f32 v244, v244, v87, v88
	v_max3_f32 v245, v245, v91, v92
	v_max3_f32 v120, v120, v95, v96
	v_max3_f32 v219, v219, v85, v98
	v_max3_f32 v244, v244, v89, v102
	v_max3_f32 v245, v245, v93, v106
	v_max3_f32 v120, v120, v97, v110
	v_max3_f32 v219, v219, v99, v100
	v_max3_f32 v244, v244, v103, v104
	v_max3_f32 v245, v245, v107, v108
	v_max3_f32 v120, v120, v111, v112
	v_max3_f32 v219, v219, v101, v114
	v_max3_f32 v219, v219, v115, v116
	v_max_f32_e32 v219, v219, v117
	v_max_f32_e32 v244, v244, v105
	v_max_f32_e32 v245, v245, v109
	v_max_f32_e32 v120, v120, v113
	v_max3_f32 v178, v219, v244, v245
	v_max_f32_e32 v178, v178, v120
	v_mov_b32_e32 v219, v178
	s_nop 1
	v_permlane16_swap_b32_e32 v178, v219
	v_max_f32_e32 v178, v178, v219
	v_mov_b32_e32 v219, v178
	s_nop 1
	v_permlane32_swap_b32_e32 v178, v219
	v_max3_f32 v178, v178, v219, v145
	s_waitcnt lgkmcnt(7)
; __device__ __forceinline__ void softmax_step(f32x4& s0, f32x4& s1, float& m, float& l, f32x4 (&O)[4]) {
;     float t = fmaxf(fmaxf(fmaxf(s0[0], s0[1]), fmaxf(s0[2], s0[3])), fmaxf(fmaxf(s1[0], s1[1]), fmaxf(s1[2], s1[3])));
;     t = xrow16_max(t);
;     const float mn = fmaxf(m, t), alpha = __builtin_amdgcn_exp2f(m - mn);
;     m = mn;
; #pragma unroll
;     for (int k = 0; k < 4; ++k) { s0[k] = __builtin_amdgcn_exp2f(s0[k] - mn); s1[k] = __builtin_amdgcn_exp2f(s1[k] - mn); }
;     l = l * alpha + ((s0[0] + s0[1]) + (s0[2] + s0[3])) + ((s1[0] + s1[1]) + (s1[2] + s1[3]));
	ds_read_b64_tr_b16 v[202:203], v124 offset:4096
	ds_read_b64_tr_b16 v[204:205], v124 offset:6144
	ds_read_b64_tr_b16 v[206:207], v125 offset:4096
	ds_read_b64_tr_b16 v[208:209], v125 offset:6144
	ds_read_b64_tr_b16 v[228:229], v126 offset:4096
	ds_read_b64_tr_b16 v[230:231], v126 offset:6144
	ds_read_b64_tr_b16 v[232:233], v127 offset:4096
	ds_read_b64_tr_b16 v[234:235], v127 offset:6144
	v_mov_b32_e32 v244, v178
	v_pk_add_f32 v[50:51], v[50:51], v[244:245] op_sel_hi:[1,0] neg_lo:[0,1] neg_hi:[0,1]
	v_pk_add_f32 v[52:53], v[52:53], v[244:245] op_sel_hi:[1,0] neg_lo:[0,1] neg_hi:[0,1]
	v_pk_add_f32 v[54:55], v[54:55], v[244:245] op_sel_hi:[1,0] neg_lo:[0,1] neg_hi:[0,1]
	v_pk_add_f32 v[56:57], v[56:57], v[244:245] op_sel_hi:[1,0] neg_lo:[0,1] neg_hi:[0,1]
	v_pk_add_f32 v[58:59], v[58:59], v[244:245] op_sel_hi:[1,0] neg_lo:[0,1] neg_hi:[0,1]
	v_pk_add_f32 v[60:61], v[60:61], v[244:245] op_sel_hi:[1,0] neg_lo:[0,1] neg_hi:[0,1]
	v_pk_add_f32 v[62:63], v[62:63], v[244:245] op_sel_hi:[1,0] neg_lo:[0,1] neg_hi:[0,1]
	v_pk_add_f32 v[64:65], v[64:65], v[244:245] op_sel_hi:[1,0] neg_lo:[0,1] neg_hi:[0,1]
	v_pk_add_f32 v[66:67], v[66:67], v[244:245] op_sel_hi:[1,0] neg_lo:[0,1] neg_hi:[0,1]
	v_pk_add_f32 v[68:69], v[68:69], v[244:245] op_sel_hi:[1,0] neg_lo:[0,1] neg_hi:[0,1]
	v_pk_add_f32 v[70:71], v[70:71], v[244:245] op_sel_hi:[1,0] neg_lo:[0,1] neg_hi:[0,1]
	v_pk_add_f32 v[72:73], v[72:73], v[244:245] op_sel_hi:[1,0] neg_lo:[0,1] neg_hi:[0,1]
	v_pk_add_f32 v[74:75], v[74:75], v[244:245] op_sel_hi:[1,0] neg_lo:[0,1] neg_hi:[0,1]
	v_pk_add_f32 v[76:77], v[76:77], v[244:245] op_sel_hi:[1,0] neg_lo:[0,1] neg_hi:[0,1]
	v_pk_add_f32 v[78:79], v[78:79], v[244:245] op_sel_hi:[1,0] neg_lo:[0,1] neg_hi:[0,1]
	v_pk_add_f32 v[80:81], v[80:81], v[244:245] op_sel_hi:[1,0] neg_lo:[0,1] neg_hi:[0,1]
	v_pk_add_f32 v[82:83], v[82:83], v[244:245] op_sel_hi:[1,0] neg_lo:[0,1] neg_hi:[0,1]
	v_pk_add_f32 v[84:85], v[84:85], v[244:245] op_sel_hi:[1,0] neg_lo:[0,1] neg_hi:[0,1]
	v_pk_add_f32 v[86:87], v[86:87], v[244:245] op_sel_hi:[1,0] neg_lo:[0,1] neg_hi:[0,1]
	v_pk_add_f32 v[88:89], v[88:89], v[244:245] op_sel_hi:[1,0] neg_lo:[0,1] neg_hi:[0,1]
	v_pk_add_f32 v[90:91], v[90:91], v[244:245] op_sel_hi:[1,0] neg_lo:[0,1] neg_hi:[0,1]
	v_pk_add_f32 v[92:93], v[92:93], v[244:245] op_sel_hi:[1,0] neg_lo:[0,1] neg_hi:[0,1]
	v_pk_add_f32 v[94:95], v[94:95], v[244:245] op_sel_hi:[1,0] neg_lo:[0,1] neg_hi:[0,1]
	v_pk_add_f32 v[96:97], v[96:97], v[244:245] op_sel_hi:[1,0] neg_lo:[0,1] neg_hi:[0,1]
	v_pk_add_f32 v[98:99], v[98:99], v[244:245] op_sel_hi:[1,0] neg_lo:[0,1] neg_hi:[0,1]
	v_pk_add_f32 v[100:101], v[100:101], v[244:245] op_sel_hi:[1,0] neg_lo:[0,1] neg_hi:[0,1]
	v_pk_add_f32 v[102:103], v[102:103], v[244:245] op_sel_hi:[1,0] neg_lo:[0,1] neg_hi:[0,1]
	v_pk_add_f32 v[104:105], v[104:105], v[244:245] op_sel_hi:[1,0] neg_lo:[0,1] neg_hi:[0,1]
	v_pk_add_f32 v[106:107], v[106:107], v[244:245] op_sel_hi:[1,0] neg_lo:[0,1] neg_hi:[0,1]
	v_pk_add_f32 v[108:109], v[108:109], v[244:245] op_sel_hi:[1,0] neg_lo:[0,1] neg_hi:[0,1]
	v_pk_add_f32 v[110:111], v[110:111], v[244:245] op_sel_hi:[1,0] neg_lo:[0,1] neg_hi:[0,1]
	v_pk_add_f32 v[112:113], v[112:113], v[244:245] op_sel_hi:[1,0] neg_lo:[0,1] neg_hi:[0,1]
	v_pk_add_f32 v[114:115], v[114:115], v[244:245] op_sel_hi:[1,0] neg_lo:[0,1] neg_hi:[0,1]
	v_pk_add_f32 v[116:117], v[116:117], v[244:245] op_sel_hi:[1,0] neg_lo:[0,1] neg_hi:[0,1]
	v_sub_f32_e32 v219, v145, v178
	v_exp_f32_e32 v50, v50
	v_exp_f32_e32 v51, v51
	v_exp_f32_e32 v52, v52
	v_exp_f32_e32 v53, v53
	v_exp_f32_e32 v54, v54
	v_exp_f32_e32 v55, v55
	v_exp_f32_e32 v56, v56
	v_exp_f32_e32 v57, v57
	v_exp_f32_e32 v58, v58
	v_exp_f32_e32 v59, v59
	v_exp_f32_e32 v60, v60
	v_exp_f32_e32 v61, v61
	v_exp_f32_e32 v62, v62
	v_exp_f32_e32 v63, v63
	v_exp_f32_e32 v64, v64
	v_exp_f32_e32 v65, v65
	v_exp_f32_e32 v66, v66
	v_exp_f32_e32 v67, v67
	v_exp_f32_e32 v68, v68
	v_exp_f32_e32 v69, v69
	v_exp_f32_e32 v70, v70
	v_exp_f32_e32 v71, v71
	v_exp_f32_e32 v72, v72
	v_exp_f32_e32 v73, v73
	v_exp_f32_e32 v74, v74
	v_exp_f32_e32 v75, v75
	v_exp_f32_e32 v76, v76
	v_exp_f32_e32 v77, v77
	v_exp_f32_e32 v78, v78
	v_exp_f32_e32 v79, v79
	v_exp_f32_e32 v80, v80
	v_exp_f32_e32 v81, v81
	v_exp_f32_e32 v82, v82
	v_exp_f32_e32 v83, v83
	v_exp_f32_e32 v84, v84
	v_exp_f32_e32 v85, v85
	v_exp_f32_e32 v86, v86
	v_exp_f32_e32 v87, v87
	v_exp_f32_e32 v88, v88
	v_exp_f32_e32 v89, v89
	v_exp_f32_e32 v90, v90
	v_exp_f32_e32 v91, v91
	v_exp_f32_e32 v92, v92
	v_exp_f32_e32 v93, v93
	v_exp_f32_e32 v94, v94
	v_exp_f32_e32 v95, v95
	v_exp_f32_e32 v96, v96
	v_exp_f32_e32 v97, v97
	v_exp_f32_e32 v98, v98
	v_exp_f32_e32 v99, v99
	v_exp_f32_e32 v100, v100
	v_exp_f32_e32 v101, v101
	v_exp_f32_e32 v102, v102
	v_exp_f32_e32 v103, v103
	v_exp_f32_e32 v104, v104
	v_exp_f32_e32 v105, v105
	v_exp_f32_e32 v106, v106
	v_exp_f32_e32 v107, v107
	v_exp_f32_e32 v108, v108
	v_exp_f32_e32 v109, v109
	v_exp_f32_e32 v110, v110
	v_exp_f32_e32 v111, v111
	v_exp_f32_e32 v112, v112
	v_exp_f32_e32 v113, v113
	v_exp_f32_e32 v114, v114
	v_exp_f32_e32 v115, v115
	v_exp_f32_e32 v116, v116
	v_exp_f32_e32 v117, v117
	v_exp_f32_e32 v219, v219
	v_pk_add_f32 v[236:237], v[50:51], v[52:53]
	v_pk_add_f32 v[238:239], v[54:55], v[56:57]
	v_pk_add_f32 v[240:241], v[58:59], v[60:61]
	v_pk_add_f32 v[242:243], v[62:63], v[64:65]
	v_pk_add_f32 v[236:237], v[236:237], v[66:67]
	v_pk_add_f32 v[238:239], v[238:239], v[70:71]
	v_pk_add_f32 v[240:241], v[240:241], v[74:75]
	v_pk_add_f32 v[242:243], v[242:243], v[78:79]
	v_pk_add_f32 v[236:237], v[236:237], v[68:69]
	v_pk_add_f32 v[238:239], v[238:239], v[72:73]
	v_pk_add_f32 v[240:241], v[240:241], v[76:77]
	v_pk_add_f32 v[242:243], v[242:243], v[80:81]
	v_pk_add_f32 v[236:237], v[236:237], v[82:83]
	v_pk_add_f32 v[238:239], v[238:239], v[86:87]
	v_pk_add_f32 v[240:241], v[240:241], v[90:91]
	v_pk_add_f32 v[242:243], v[242:243], v[94:95]
	v_pk_add_f32 v[236:237], v[236:237], v[84:85]
	v_pk_add_f32 v[238:239], v[238:239], v[88:89]
	v_pk_add_f32 v[240:241], v[240:241], v[92:93]
	v_pk_add_f32 v[242:243], v[242:243], v[96:97]
	v_pk_add_f32 v[236:237], v[236:237], v[98:99]
	v_pk_add_f32 v[238:239], v[238:239], v[102:103]
	v_pk_add_f32 v[240:241], v[240:241], v[106:107]
	v_pk_add_f32 v[242:243], v[242:243], v[110:111]
	v_pk_add_f32 v[236:237], v[236:237], v[100:101]
	v_pk_add_f32 v[238:239], v[238:239], v[104:105]
	v_pk_add_f32 v[240:241], v[240:241], v[108:109]
	v_pk_add_f32 v[242:243], v[242:243], v[112:113]
	v_pk_add_f32 v[236:237], v[236:237], v[114:115]
	v_pk_add_f32 v[236:237], v[236:237], v[116:117]
	v_pk_add_f32 v[236:237], v[236:237], v[238:239]
	v_pk_add_f32 v[240:241], v[240:241], v[242:243]
	v_cndmask_b32_e64 v219, 0, v219, s[74:75]
	v_pk_add_f32 v[236:237], v[236:237], v[240:241]
	v_add_f32_e32 v185, v236, v237
	v_add_f32_e32 v185, v185, v219
	v_cvt_pk_bf16_f32 v236, v50, v51
	v_cvt_pk_bf16_f32 v237, v52, v53
	v_cvt_pk_bf16_f32 v238, v54, v55
	v_cvt_pk_bf16_f32 v239, v56, v57
	s_nop 1
	s_waitcnt lgkmcnt(14)
; #define LAS __attribute__((address_space(3)))
; __device__ __forceinline__ unsigned pk2(float lo, float hi) { return pg8::cvt_pk_bf16(lo, hi); }
; __device__ __forceinline__ s16x4 vtr(const LAS unsigned char* p) { return __builtin_bit_cast(s16x4, __builtin_amdgcn_ds_read_tr16_b64_v4i16((LAS s16x4*)p)); }
; #define MFMA16(a, b, c) __builtin_amdgcn_mfma_f32_16x16x32_bf16((a), (b), (c), 0, 0, 0)
; __device__ __forceinline__ void pv_at(const LAS unsigned char* const (&vp)[4], int off, const f32x4& P0, const f32x4& P1, f32x4 (&O)[4]) {
;     v4u pw; pw.x = pk2(P0[0], P0[1]); pw.y = pk2(P0[2], P0[3]); pw.z = pk2(P1[0], P1[1]); pw.w = pk2(P1[2], P1[3]);
;     const bf16x8 pb = __builtin_bit_cast(bf16x8, pw);
; #pragma unroll
;     for (int db = 0; db < 4; ++db) {
;         const s16x4 lo = vtr(vp[db] + off), hi = vtr(vp[db] + off + 2048);
;         const bf16x8 vt = (bf16x8){lo[0], lo[1], lo[2], lo[3], hi[0], hi[1], hi[2], hi[3]};
;         O[db] = MFMA16(vt, pb, O[db]);
;     }
; }
	v_mfma_f32_16x16x32_bf16 v[210:213], v[186:189], v[236:239], 0
	s_waitcnt lgkmcnt(12)
	v_mfma_f32_16x16x32_bf16 v[214:217], v[190:193], v[236:239], 0
	s_waitcnt lgkmcnt(10)
	v_mfma_f32_16x16x32_bf16 v[220:223], v[194:197], v[236:239], 0
	s_waitcnt lgkmcnt(8)
	v_mfma_f32_16x16x32_bf16 v[224:227], v[198:201], v[236:239], 0
	v_cvt_pk_bf16_f32 v240, v58, v59
	v_cvt_pk_bf16_f32 v241, v60, v61
	v_cvt_pk_bf16_f32 v242, v62, v63
	v_cvt_pk_bf16_f32 v243, v64, v65
	s_waitcnt lgkmcnt(7)
	ds_read_b64_tr_b16 v[186:187], v124 offset:8192
	ds_read_b64_tr_b16 v[188:189], v124 offset:10240
	ds_read_b64_tr_b16 v[190:191], v125 offset:8192
	ds_read_b64_tr_b16 v[192:193], v125 offset:10240
	ds_read_b64_tr_b16 v[194:195], v126 offset:8192
	ds_read_b64_tr_b16 v[196:197], v126 offset:10240
	ds_read_b64_tr_b16 v[198:199], v127 offset:8192
	ds_read_b64_tr_b16 v[200:201], v127 offset:10240
	s_waitcnt lgkmcnt(14)
	v_mfma_f32_16x16x32_bf16 v[210:213], v[202:205], v[240:243], v[210:213]
	s_waitcnt lgkmcnt(12)
	v_mfma_f32_16x16x32_bf16 v[214:217], v[206:209], v[240:243], v[214:217]
	s_waitcnt lgkmcnt(10)
	v_mfma_f32_16x16x32_bf16 v[220:223], v[228:231], v[240:243], v[220:223]
	s_waitcnt lgkmcnt(8)
	v_mfma_f32_16x16x32_bf16 v[224:227], v[232:235], v[240:243], v[224:227]
	v_cvt_pk_bf16_f32 v236, v66, v67
	v_cvt_pk_bf16_f32 v237, v68, v69
	v_cvt_pk_bf16_f32 v238, v70, v71
	v_cvt_pk_bf16_f32 v239, v72, v73
	s_waitcnt lgkmcnt(7)
	ds_read_b64_tr_b16 v[202:203], v124 offset:12288
	ds_read_b64_tr_b16 v[204:205], v124 offset:14336
	ds_read_b64_tr_b16 v[206:207], v125 offset:12288
	ds_read_b64_tr_b16 v[208:209], v125 offset:14336
	ds_read_b64_tr_b16 v[228:229], v126 offset:12288
	ds_read_b64_tr_b16 v[230:231], v126 offset:14336
	ds_read_b64_tr_b16 v[232:233], v127 offset:12288
	ds_read_b64_tr_b16 v[234:235], v127 offset:14336
	s_waitcnt lgkmcnt(14)
	v_mfma_f32_16x16x32_bf16 v[210:213], v[186:189], v[236:239], v[210:213]
	s_waitcnt lgkmcnt(12)
	v_mfma_f32_16x16x32_bf16 v[214:217], v[190:193], v[236:239], v[214:217]
	s_waitcnt lgkmcnt(10)
	v_mfma_f32_16x16x32_bf16 v[220:223], v[194:197], v[236:239], v[220:223]
	s_waitcnt lgkmcnt(8)
	v_mfma_f32_16x16x32_bf16 v[224:227], v[198:201], v[236:239], v[224:227]
	v_cvt_pk_bf16_f32 v240, v74, v75
	v_cvt_pk_bf16_f32 v241, v76, v77
	v_cvt_pk_bf16_f32 v242, v78, v79
	v_cvt_pk_bf16_f32 v243, v80, v81
	s_waitcnt lgkmcnt(7)
	ds_read_b64_tr_b16 v[186:187], v124 offset:16384
	ds_read_b64_tr_b16 v[188:189], v124 offset:18432
	ds_read_b64_tr_b16 v[190:191], v125 offset:16384
	ds_read_b64_tr_b16 v[192:193], v125 offset:18432
	ds_read_b64_tr_b16 v[194:195], v126 offset:16384
	ds_read_b64_tr_b16 v[196:197], v126 offset:18432
	ds_read_b64_tr_b16 v[198:199], v127 offset:16384
	ds_read_b64_tr_b16 v[200:201], v127 offset:18432
	s_waitcnt lgkmcnt(14)
	v_mfma_f32_16x16x32_bf16 v[210:213], v[202:205], v[240:243], v[210:213]
	s_waitcnt lgkmcnt(12)
	v_mfma_f32_16x16x32_bf16 v[214:217], v[206:209], v[240:243], v[214:217]
	s_waitcnt lgkmcnt(10)
	v_mfma_f32_16x16x32_bf16 v[220:223], v[228:231], v[240:243], v[220:223]
	s_waitcnt lgkmcnt(8)
	v_mfma_f32_16x16x32_bf16 v[224:227], v[232:235], v[240:243], v[224:227]
	v_cvt_pk_bf16_f32 v236, v82, v83
	v_cvt_pk_bf16_f32 v237, v84, v85
	v_cvt_pk_bf16_f32 v238, v86, v87
	v_cvt_pk_bf16_f32 v239, v88, v89
	s_waitcnt lgkmcnt(7)
	ds_read_b64_tr_b16 v[202:203], v124 offset:20480
	ds_read_b64_tr_b16 v[204:205], v124 offset:22528
	ds_read_b64_tr_b16 v[206:207], v125 offset:20480
	ds_read_b64_tr_b16 v[208:209], v125 offset:22528
	ds_read_b64_tr_b16 v[228:229], v126 offset:20480
	ds_read_b64_tr_b16 v[230:231], v126 offset:22528
	ds_read_b64_tr_b16 v[232:233], v127 offset:20480
	ds_read_b64_tr_b16 v[234:235], v127 offset:22528
	s_waitcnt lgkmcnt(14)
	v_mfma_f32_16x16x32_bf16 v[210:213], v[186:189], v[236:239], v[210:213]
	s_waitcnt lgkmcnt(12)
	v_mfma_f32_16x16x32_bf16 v[214:217], v[190:193], v[236:239], v[214:217]
	s_waitcnt lgkmcnt(10)
	v_mfma_f32_16x16x32_bf16 v[220:223], v[194:197], v[236:239], v[220:223]
	s_waitcnt lgkmcnt(8)
	v_mfma_f32_16x16x32_bf16 v[224:227], v[198:201], v[236:239], v[224:227]
	v_cvt_pk_bf16_f32 v240, v90, v91
	v_cvt_pk_bf16_f32 v241, v92, v93
	v_cvt_pk_bf16_f32 v242, v94, v95
	v_cvt_pk_bf16_f32 v243, v96, v97
	s_waitcnt lgkmcnt(7)
	ds_read_b64_tr_b16 v[186:187], v124 offset:24576
	ds_read_b64_tr_b16 v[188:189], v124 offset:26624
	ds_read_b64_tr_b16 v[190:191], v125 offset:24576
	ds_read_b64_tr_b16 v[192:193], v125 offset:26624
	ds_read_b64_tr_b16 v[194:195], v126 offset:24576
	ds_read_b64_tr_b16 v[196:197], v126 offset:26624
	ds_read_b64_tr_b16 v[198:199], v127 offset:24576
	ds_read_b64_tr_b16 v[200:201], v127 offset:26624
	s_waitcnt lgkmcnt(14)
	v_mfma_f32_16x16x32_bf16 v[210:213], v[202:205], v[240:243], v[210:213]
	s_waitcnt lgkmcnt(12)
	v_mfma_f32_16x16x32_bf16 v[214:217], v[206:209], v[240:243], v[214:217]
	s_waitcnt lgkmcnt(10)
	v_mfma_f32_16x16x32_bf16 v[220:223], v[228:231], v[240:243], v[220:223]
	s_waitcnt lgkmcnt(8)
	v_mfma_f32_16x16x32_bf16 v[224:227], v[232:235], v[240:243], v[224:227]
	v_cvt_pk_bf16_f32 v236, v98, v99
	v_cvt_pk_bf16_f32 v237, v100, v101
	v_cvt_pk_bf16_f32 v238, v102, v103
	v_cvt_pk_bf16_f32 v239, v104, v105
	s_waitcnt lgkmcnt(7)
	ds_read_b64_tr_b16 v[202:203], v124 offset:28672
	ds_read_b64_tr_b16 v[204:205], v124 offset:30720
	ds_read_b64_tr_b16 v[206:207], v125 offset:28672
	ds_read_b64_tr_b16 v[208:209], v125 offset:30720
	ds_read_b64_tr_b16 v[228:229], v126 offset:28672
	ds_read_b64_tr_b16 v[230:231], v126 offset:30720
	ds_read_b64_tr_b16 v[232:233], v127 offset:28672
	ds_read_b64_tr_b16 v[234:235], v127 offset:30720
	s_waitcnt lgkmcnt(14)
; __device__ __forceinline__ unsigned pk2(float lo, float hi) { return pg8::cvt_pk_bf16(lo, hi); }
; __device__ __forceinline__ void store_o(bf16* yrow, int g, float l, const f32x4 (&O)[4]) {
;     const float inv = 1.0f / xrow16_sum(l);
;     unsigned wx[4], wy[4];
; #pragma unroll
;     for (int db = 0; db < 4; ++db) { wx[db] = pk2(O[db][0] * inv, O[db][1] * inv); wy[db] = pk2(O[db][2] * inv, O[db][3] * inv); }
; #pragma unroll
;     for (int p = 0; p < 2; ++p) {
;         auto rx = __builtin_amdgcn_permlane16_swap(wx[2 * p], wx[2 * p + 1], false, false); wx[2 * p] = rx[0]; wx[2 * p + 1] = rx[1];
;         auto ry = __builtin_amdgcn_permlane16_swap(wy[2 * p], wy[2 * p + 1], false, false); wy[2 * p] = ry[0]; wy[2 * p + 1] = ry[1]; }
; #pragma unroll
;     for (int p = 0; p < 2; ++p) {
;         auto rx = __builtin_amdgcn_permlane32_swap(wx[p], wx[p + 2], false, false); wx[p] = rx[0]; wx[p + 2] = rx[1];
;         auto ry = __builtin_amdgcn_permlane32_swap(wy[p], wy[p + 2], false, false); wy[p] = ry[0]; wy[p + 2] = ry[1]; }
;     v4u lo = {wx[0], wy[0], wx[1], wy[1]}, hi = {wx[2], wy[2], wx[3], wy[3]};
;     *(v4u*)(yrow + 16 * g) = lo; *(v4u*)(yrow + 16 * g + 8) = hi;
; }
; template <bool MASK> __device__ __forceinline__ void a_scores(f32x4& S0, f32x4& S1, float basef, float c1, float slope2, int krow0, int kstart) {
; #pragma unroll
;     for (int r = 0; r < 4; ++r) {
;         const float d0 = fabsf(basef - (float)r), d1 = fabsf(basef - (float)(16 + r));
;         const float v0 = S0[r] - slope2 * d0, v1 = S1[r] - slope2 * d1;
;         if (MASK) { const int p0 = kstart + krow0 + r, p1 = p0 + 16;
;             S0[r] = (d0 <= 128.f && p0 >= 0 && p0 < SEQ) ? v0 : -INFINITY; S1[r] = (d1 <= 128.f && p1 >= 0 && p1 < SEQ) ? v1 : -INFINITY; }
;         else { S0[r] = v0; S1[r] = v1; }
;     }
; }
	v_mfma_f32_16x16x32_bf16 v[210:213], v[186:189], v[236:239], v[210:213]
	s_waitcnt lgkmcnt(12)
	v_mfma_f32_16x16x32_bf16 v[214:217], v[190:193], v[236:239], v[214:217]
	s_waitcnt lgkmcnt(10)
	v_mfma_f32_16x16x32_bf16 v[220:223], v[194:197], v[236:239], v[220:223]
	s_waitcnt lgkmcnt(8)
	v_mfma_f32_16x16x32_bf16 v[224:227], v[198:201], v[236:239], v[224:227]
	v_cvt_pk_bf16_f32 v240, v106, v107
	v_cvt_pk_bf16_f32 v241, v108, v109
	v_cvt_pk_bf16_f32 v242, v110, v111
	v_cvt_pk_bf16_f32 v243, v112, v113
	s_waitcnt lgkmcnt(7)
	ds_read_b64_tr_b16 v[186:187], v124 offset:32768
	ds_read_b64_tr_b16 v[188:189], v124 offset:34816
	ds_read_b64_tr_b16 v[190:191], v125 offset:32768
	ds_read_b64_tr_b16 v[192:193], v125 offset:34816
	ds_read_b64_tr_b16 v[194:195], v126 offset:32768
	ds_read_b64_tr_b16 v[196:197], v126 offset:34816
	ds_read_b64_tr_b16 v[198:199], v127 offset:32768
	ds_read_b64_tr_b16 v[200:201], v127 offset:34816
	s_waitcnt lgkmcnt(14)
	v_mfma_f32_16x16x32_bf16 v[210:213], v[202:205], v[240:243], v[210:213]
	s_waitcnt lgkmcnt(12)
	v_mfma_f32_16x16x32_bf16 v[214:217], v[206:209], v[240:243], v[214:217]
	s_waitcnt lgkmcnt(10)
	v_mfma_f32_16x16x32_bf16 v[220:223], v[228:231], v[240:243], v[220:223]
	s_waitcnt lgkmcnt(8)
	v_mfma_f32_16x16x32_bf16 v[224:227], v[232:235], v[240:243], v[224:227]
	v_cvt_pk_bf16_f32 v236, v114, v115
	v_cvt_pk_bf16_f32 v237, v116, v117
	v_mov_b32_e32 v238, 0
	v_mov_b32_e32 v239, 0
	s_nop 1
	s_waitcnt lgkmcnt(6)
	v_mfma_f32_16x16x32_bf16 v[210:213], v[186:189], v[236:239], v[210:213]
	s_waitcnt lgkmcnt(4)
	v_mfma_f32_16x16x32_bf16 v[214:217], v[190:193], v[236:239], v[214:217]
	s_waitcnt lgkmcnt(2)
	v_mfma_f32_16x16x32_bf16 v[220:223], v[194:197], v[236:239], v[220:223]
	s_waitcnt lgkmcnt(0)
	v_mfma_f32_16x16x32_bf16 v[224:227], v[198:201], v[236:239], v[224:227]
	v_mov_b32_e32 v219, v185
	s_nop 1
	v_permlane16_swap_b32_e32 v185, v219
	v_add_f32_e32 v185, v185, v219
	v_mov_b32_e32 v219, v185
	s_nop 1
	v_permlane32_swap_b32_e32 v185, v219
	v_add_f32_e32 v185, v185, v219
	v_div_scale_f32 v236, s[78:79], v185, v185, 1.0
	v_div_scale_f32 v237, vcc, 1.0, v185, 1.0
	v_rcp_f32_e32 v238, v236
	s_nop 0
	v_fma_f32 v239, -v236, v238, 1.0
	v_fmac_f32_e32 v238, v239, v238
	v_mul_f32_e32 v240, v237, v238
	v_fma_f32 v241, -v236, v240, v237
	v_fmac_f32_e32 v240, v241, v238
	v_fma_f32 v237, -v236, v240, v237
	v_div_fmas_f32 v237, v237, v238, v240
	v_div_fixup_f32 v244, v237, v185, 1.0
	v_mul_f32_e32 v240, v210, v244
	v_mul_f32_e32 v241, v211, v244
	v_mul_f32_e32 v242, v212, v244
	v_mul_f32_e32 v243, v213, v244
	v_cvt_pk_bf16_f32 v186, v240, v241
	v_cvt_pk_bf16_f32 v187, v242, v243
	v_mul_f32_e32 v240, v214, v244
	v_mul_f32_e32 v241, v215, v244
	v_mul_f32_e32 v242, v216, v244
	v_mul_f32_e32 v243, v217, v244
	v_cvt_pk_bf16_f32 v188, v240, v241
	v_cvt_pk_bf16_f32 v189, v242, v243
	v_mul_f32_e32 v240, v220, v244
	v_mul_f32_e32 v241, v221, v244
	v_mul_f32_e32 v242, v222, v244
	v_mul_f32_e32 v243, v223, v244
	v_cvt_pk_bf16_f32 v190, v240, v241
	v_cvt_pk_bf16_f32 v191, v242, v243
	v_mul_f32_e32 v240, v224, v244
	v_mul_f32_e32 v241, v225, v244
	v_mul_f32_e32 v242, v226, v244
	v_mul_f32_e32 v243, v227, v244
	v_cvt_pk_bf16_f32 v192, v240, v241
	v_cvt_pk_bf16_f32 v193, v242, v243
	s_nop 1
	v_permlane16_swap_b32_e32 v186, v188
	v_permlane16_swap_b32_e32 v187, v189
	v_permlane16_swap_b32_e32 v190, v192
	v_permlane16_swap_b32_e32 v191, v193
	s_nop 0
	v_permlane32_swap_b32_e32 v186, v190
	v_permlane32_swap_b32_e32 v187, v191
	v_permlane32_swap_b32_e32 v188, v192
	v_permlane32_swap_b32_e32 v189, v193
	global_store_dwordx4 v128, v[186:189], s[82:83] offset:0 sc1
	global_store_dwordx4 v128, v[190:193], s[82:83] offset:16 sc1
	s_nop 1
	v_fmamk_f32 v50, v130, 0x43000000, v132
	v_fmamk_f32 v51, v130, 0x42fe0000, v132
	v_fmamk_f32 v52, v130, 0x42fc0000, v132
	v_fmamk_f32 v53, v130, 0x42fa0000, v132
	v_fmamk_f32 v54, v130, 0x42e00000, v132
	v_fmamk_f32 v55, v130, 0x42de0000, v132
	v_fmamk_f32 v56, v130, 0x42dc0000, v132
	v_fmamk_f32 v57, v130, 0x42da0000, v132
	v_fmamk_f32 v58, v130, 0x42c00000, v132
	v_fmamk_f32 v59, v130, 0x42be0000, v132
	v_fmamk_f32 v60, v130, 0x42bc0000, v132
	v_fmamk_f32 v61, v130, 0x42ba0000, v132
	v_fmamk_f32 v62, v130, 0x42a00000, v132
	v_fmamk_f32 v63, v130, 0x429e0000, v132
	v_fmamk_f32 v64, v130, 0x429c0000, v132
	v_fmamk_f32 v65, v130, 0x429a0000, v132
	v_fmamk_f32 v66, v130, 0x42800000, v132
	v_fmamk_f32 v67, v130, 0x427c0000, v132
	v_fmamk_f32 v68, v130, 0x42780000, v132
	v_fmamk_f32 v69, v130, 0x42740000, v132
	v_fmamk_f32 v70, v130, 0x42400000, v132
	v_fmamk_f32 v71, v130, 0x423c0000, v132
	v_fmamk_f32 v72, v130, 0x42380000, v132
	v_fmamk_f32 v73, v130, 0x42340000, v132
	v_fmamk_f32 v74, v130, 0x42000000, v132
	v_fmamk_f32 v75, v130, 0x41f80000, v132
	v_fmamk_f32 v76, v130, 0x41f00000, v132
	v_fmamk_f32 v77, v130, 0x41e80000, v132
	v_fmamk_f32 v78, v130, 0x41800000, v132
	v_fmamk_f32 v79, v130, 0x41700000, v132
	v_fmamk_f32 v80, v130, 0x41600000, v132
	v_fmamk_f32 v81, v130, 0x41500000, v132
	v_add_f32_e32 v219, 0, v129
	v_mul_f32_e64 v82, v130, |v219|
	v_add_f32_e32 v244, 0xbf800000, v129
	v_mul_f32_e64 v83, v130, |v244|
	v_add_f32_e32 v219, 0xc0000000, v129
	v_mul_f32_e64 v84, v130, |v219|
	v_add_f32_e32 v244, 0xc0400000, v129
	v_mul_f32_e64 v85, v130, |v244|
	v_fmamk_f32 v86, v131, 0xc1800000, v133
	v_fmamk_f32 v87, v131, 0xc1880000, v133
	v_fmamk_f32 v88, v131, 0xc1900000, v133
	v_fmamk_f32 v89, v131, 0xc1980000, v133
	v_fmamk_f32 v90, v131, 0xc2000000, v133
	v_fmamk_f32 v91, v131, 0xc2040000, v133
	v_fmamk_f32 v92, v131, 0xc2080000, v133
	v_fmamk_f32 v93, v131, 0xc20c0000, v133
	v_fmamk_f32 v94, v131, 0xc2400000, v133
; #define LAS __attribute__((address_space(3)))
; #define MFMA16(a, b, c) __builtin_amdgcn_mfma_f32_16x16x32_bf16((a), (b), (c), 0, 0, 0)
; __device__ __forceinline__ void qk_at(const LAS unsigned char* kp0, const LAS unsigned char* kp1, int off, bf16x8 qf0, bf16x8 qf1, f32x4& S0, f32x4& S1) {
;     const bf16x8 k00 = *(const LAS bf16x8*)(kp0 + off), k01 = *(const LAS bf16x8*)(kp1 + off);
;     const bf16x8 k10 = *(const LAS bf16x8*)(kp0 + off + 2048), k11 = *(const LAS bf16x8*)(kp1 + off + 2048);
;     const f32x4 z = {0.f, 0.f, 0.f, 0.f};
;     S0 = MFMA16(k00, qf0, z); S0 = MFMA16(k01, qf1, S0);
;     S1 = MFMA16(k10, qf0, z); S1 = MFMA16(k11, qf1, S1);
; }
; template <bool MASK> __device__ __forceinline__ void a_scores(f32x4& S0, f32x4& S1, float basef, float c1, float slope2, int krow0, int kstart) {
; #pragma unroll
;     for (int r = 0; r < 4; ++r) {
;         const float d0 = fabsf(basef - (float)r), d1 = fabsf(basef - (float)(16 + r));
;         const float v0 = S0[r] - slope2 * d0, v1 = S1[r] - slope2 * d1;
;         if (MASK) { const int p0 = kstart + krow0 + r, p1 = p0 + 16;
;             S0[r] = (d0 <= 128.f && p0 >= 0 && p0 < SEQ) ? v0 : -INFINITY; S1[r] = (d1 <= 128.f && p1 >= 0 && p1 < SEQ) ? v1 : -INFINITY; }
;         else { S0[r] = v0; S1[r] = v1; }
;     }
; }
	v_fmamk_f32 v95, v131, 0xc2440000, v133
	v_fmamk_f32 v96, v131, 0xc2480000, v133
	v_fmamk_f32 v97, v131, 0xc24c0000, v133
	v_fmamk_f32 v98, v131, 0xc2800000, v133
	v_fmamk_f32 v99, v131, 0xc2820000, v133
	v_fmamk_f32 v100, v131, 0xc2840000, v133
	v_fmamk_f32 v101, v131, 0xc2860000, v133
	v_fmamk_f32 v102, v131, 0xc2a00000, v133
	v_fmamk_f32 v103, v131, 0xc2a20000, v133
	v_fmamk_f32 v104, v131, 0xc2a40000, v133
	v_fmamk_f32 v105, v131, 0xc2a60000, v133
	v_fmamk_f32 v106, v131, 0xc2c00000, v133
	v_fmamk_f32 v107, v131, 0xc2c20000, v133
	v_fmamk_f32 v108, v131, 0xc2c40000, v133
	v_fmamk_f32 v109, v131, 0xc2c60000, v133
	v_fmamk_f32 v110, v131, 0xc2e00000, v133
	v_fmamk_f32 v111, v131, 0xc2e20000, v133
	v_fmamk_f32 v112, v131, 0xc2e40000, v133
	v_fmamk_f32 v113, v131, 0xc2e60000, v133
	v_fmamk_f32 v114, v131, 0xc3000000, v133
	v_fmamk_f32 v115, v131, 0xc3010000, v133
	v_fmamk_f32 v116, v131, 0xc3020000, v133
	v_fmamk_f32 v117, v131, 0xc3030000, v133
	v_mov_b32_e32 v245, 0xff800000
	v_cndmask_b32_e64 v50, v245, v50, s[16:17]
	v_cndmask_b32_e64 v51, v245, v51, s[18:19]
	v_cndmask_b32_e64 v52, v245, v52, s[22:23]
	v_cndmask_b32_e64 v53, v245, v53, s[24:25]
	v_cndmask_b32_e64 v114, v245, v114, s[28:29]
	v_cndmask_b32_e64 v115, v245, v115, s[52:53]
	v_cndmask_b32_e64 v116, v245, v116, s[54:55]
	v_cndmask_b32_e64 v117, v245, v117, s[88:89]
	ds_read_b128 v[186:189], v122 offset:2048
	ds_read_b128 v[190:193], v123 offset:2048
	ds_read_b128 v[194:197], v122 offset:4096
	ds_read_b128 v[198:201], v123 offset:4096
	ds_read_b128 v[202:205], v122 offset:6144
	ds_read_b128 v[206:209], v123 offset:6144
	s_waitcnt lgkmcnt(5)
	v_mfma_f32_16x16x32_bf16 v[50:53], v[186:189], v[154:157], v[50:53]
	s_waitcnt lgkmcnt(4)
	v_mfma_f32_16x16x32_bf16 v[50:53], v[190:193], v[158:161], v[50:53]
	ds_read_b128 v[186:189], v122 offset:8192
	ds_read_b128 v[190:193], v123 offset:8192
	s_waitcnt lgkmcnt(5)
	v_mfma_f32_16x16x32_bf16 v[54:57], v[194:197], v[154:157], v[54:57]
	s_waitcnt lgkmcnt(4)
	v_mfma_f32_16x16x32_bf16 v[54:57], v[198:201], v[158:161], v[54:57]
	ds_read_b128 v[194:197], v122 offset:10240
	ds_read_b128 v[198:201], v123 offset:10240
	s_waitcnt lgkmcnt(5)
	v_mfma_f32_16x16x32_bf16 v[58:61], v[202:205], v[154:157], v[58:61]
	s_waitcnt lgkmcnt(4)
	v_mfma_f32_16x16x32_bf16 v[58:61], v[206:209], v[158:161], v[58:61]
	ds_read_b128 v[202:205], v122 offset:12288
	ds_read_b128 v[206:209], v123 offset:12288
	s_waitcnt lgkmcnt(5)
	v_mfma_f32_16x16x32_bf16 v[62:65], v[186:189], v[154:157], v[62:65]
	s_waitcnt lgkmcnt(4)
	v_mfma_f32_16x16x32_bf16 v[62:65], v[190:193], v[158:161], v[62:65]
	ds_read_b128 v[186:189], v122 offset:14336
	ds_read_b128 v[190:193], v123 offset:14336
	s_waitcnt lgkmcnt(5)
	v_mfma_f32_16x16x32_bf16 v[66:69], v[194:197], v[154:157], v[66:69]
	s_waitcnt lgkmcnt(4)
	v_mfma_f32_16x16x32_bf16 v[66:69], v[198:201], v[158:161], v[66:69]
	ds_read_b128 v[194:197], v122 offset:16384
	ds_read_b128 v[198:201], v123 offset:16384
	s_waitcnt lgkmcnt(5)
	v_mfma_f32_16x16x32_bf16 v[70:73], v[202:205], v[154:157], v[70:73]
	s_waitcnt lgkmcnt(4)
	v_mfma_f32_16x16x32_bf16 v[70:73], v[206:209], v[158:161], v[70:73]
	ds_read_b128 v[202:205], v122 offset:18432
	ds_read_b128 v[206:209], v123 offset:18432
	s_waitcnt lgkmcnt(5)
	v_mfma_f32_16x16x32_bf16 v[74:77], v[186:189], v[154:157], v[74:77]
	s_waitcnt lgkmcnt(4)
	v_mfma_f32_16x16x32_bf16 v[74:77], v[190:193], v[158:161], v[74:77]
	ds_read_b128 v[186:189], v122 offset:20480
	ds_read_b128 v[190:193], v123 offset:20480
	s_waitcnt lgkmcnt(5)
	v_mfma_f32_16x16x32_bf16 v[78:81], v[194:197], v[154:157], v[78:81]
	s_waitcnt lgkmcnt(4)
	v_mfma_f32_16x16x32_bf16 v[78:81], v[198:201], v[158:161], v[78:81]
	ds_read_b128 v[194:197], v122 offset:22528
	ds_read_b128 v[198:201], v123 offset:22528
	s_waitcnt lgkmcnt(5)
	v_mfma_f32_16x16x32_bf16 v[82:85], v[202:205], v[154:157], v[82:85]
	s_waitcnt lgkmcnt(4)
	v_mfma_f32_16x16x32_bf16 v[82:85], v[206:209], v[158:161], v[82:85]
	ds_read_b128 v[202:205], v122 offset:24576
	ds_read_b128 v[206:209], v123 offset:24576
	s_waitcnt lgkmcnt(5)
	v_mfma_f32_16x16x32_bf16 v[86:89], v[186:189], v[154:157], v[86:89]
	s_waitcnt lgkmcnt(4)
	v_mfma_f32_16x16x32_bf16 v[86:89], v[190:193], v[158:161], v[86:89]
	ds_read_b128 v[186:189], v122 offset:26624
	ds_read_b128 v[190:193], v123 offset:26624
	s_waitcnt lgkmcnt(5)
	v_mfma_f32_16x16x32_bf16 v[90:93], v[194:197], v[154:157], v[90:93]
	s_waitcnt lgkmcnt(4)
	v_mfma_f32_16x16x32_bf16 v[90:93], v[198:201], v[158:161], v[90:93]
	ds_read_b128 v[194:197], v122 offset:28672
	ds_read_b128 v[198:201], v123 offset:28672
	s_waitcnt lgkmcnt(5)
	v_mfma_f32_16x16x32_bf16 v[94:97], v[202:205], v[154:157], v[94:97]
	s_waitcnt lgkmcnt(4)
	v_mfma_f32_16x16x32_bf16 v[94:97], v[206:209], v[158:161], v[94:97]
	ds_read_b128 v[202:205], v122 offset:30720
	ds_read_b128 v[206:209], v123 offset:30720
	s_waitcnt lgkmcnt(5)
	v_mfma_f32_16x16x32_bf16 v[98:101], v[186:189], v[154:157], v[98:101]
	s_waitcnt lgkmcnt(4)
	v_mfma_f32_16x16x32_bf16 v[98:101], v[190:193], v[158:161], v[98:101]
	ds_read_b128 v[186:189], v122 offset:32768
	ds_read_b128 v[190:193], v123 offset:32768
	s_waitcnt lgkmcnt(5)
	v_mfma_f32_16x16x32_bf16 v[102:105], v[194:197], v[154:157], v[102:105]
	s_waitcnt lgkmcnt(4)
	v_mfma_f32_16x16x32_bf16 v[102:105], v[198:201], v[158:161], v[102:105]
	ds_read_b128 v[194:197], v122 offset:34816
	ds_read_b128 v[198:201], v123 offset:34816
	s_waitcnt lgkmcnt(5)
	v_mfma_f32_16x16x32_bf16 v[106:109], v[202:205], v[154:157], v[106:109]
	s_waitcnt lgkmcnt(4)
	v_mfma_f32_16x16x32_bf16 v[106:109], v[206:209], v[158:161], v[106:109]
	s_waitcnt lgkmcnt(3)
; #define LAS __attribute__((address_space(3)))
; #define MFMA16(a, b, c) __builtin_amdgcn_mfma_f32_16x16x32_bf16((a), (b), (c), 0, 0, 0)
; __device__ __forceinline__ void qk_at(const LAS unsigned char* kp0, const LAS unsigned char* kp1, int off, bf16x8 qf0, bf16x8 qf1, f32x4& S0, f32x4& S1) {
;     const bf16x8 k00 = *(const LAS bf16x8*)(kp0 + off), k01 = *(const LAS bf16x8*)(kp1 + off);
;     const bf16x8 k10 = *(const LAS bf16x8*)(kp0 + off + 2048), k11 = *(const LAS bf16x8*)(kp1 + off + 2048);
;     const f32x4 z = {0.f, 0.f, 0.f, 0.f};
;     S0 = MFMA16(k00, qf0, z); S0 = MFMA16(k01, qf1, S0);
;     S1 = MFMA16(k10, qf0, z); S1 = MFMA16(k11, qf1, S1);
; }
; __device__ __forceinline__ void softmax_step(f32x4& s0, f32x4& s1, float& m, float& l, f32x4 (&O)[4]) {
;     float t = fmaxf(fmaxf(fmaxf(s0[0], s0[1]), fmaxf(s0[2], s0[3])), fmaxf(fmaxf(s1[0], s1[1]), fmaxf(s1[2], s1[3])));
;     t = xrow16_max(t);
;     const float mn = fmaxf(m, t), alpha = __builtin_amdgcn_exp2f(m - mn);
;     m = mn;
; #pragma unroll
;     for (int k = 0; k < 4; ++k) { s0[k] = __builtin_amdgcn_exp2f(s0[k] - mn); s1[k] = __builtin_amdgcn_exp2f(s1[k] - mn); }
	v_mfma_f32_16x16x32_bf16 v[110:113], v[186:189], v[154:157], v[110:113]
	s_waitcnt lgkmcnt(2)
	v_mfma_f32_16x16x32_bf16 v[110:113], v[190:193], v[158:161], v[110:113]
	s_waitcnt lgkmcnt(1)
	v_mfma_f32_16x16x32_bf16 v[114:117], v[194:197], v[154:157], v[114:117]
	s_waitcnt lgkmcnt(0)
	v_mfma_f32_16x16x32_bf16 v[114:117], v[198:201], v[158:161], v[114:117]
	v_max3_f32 v219, v50, v51, v52
	v_max3_f32 v244, v54, v55, v56
	v_max3_f32 v245, v58, v59, v60
	v_max3_f32 v120, v62, v63, v64
	v_max3_f32 v219, v219, v53, v66
	v_max3_f32 v244, v244, v57, v70
	v_max3_f32 v245, v245, v61, v74
	v_max3_f32 v120, v120, v65, v78
	v_max3_f32 v219, v219, v67, v68
	v_max3_f32 v244, v244, v71, v72
	v_max3_f32 v245, v245, v75, v76
	v_max3_f32 v120, v120, v79, v80
	ds_read_b64_tr_b16 v[186:187], v124 offset:2048
	ds_read_b64_tr_b16 v[188:189], v124 offset:4096
	ds_read_b64_tr_b16 v[190:191], v125 offset:2048
	ds_read_b64_tr_b16 v[192:193], v125 offset:4096
	ds_read_b64_tr_b16 v[194:195], v126 offset:2048
	ds_read_b64_tr_b16 v[196:197], v126 offset:4096
	ds_read_b64_tr_b16 v[198:199], v127 offset:2048
	ds_read_b64_tr_b16 v[200:201], v127 offset:4096
	v_max3_f32 v219, v219, v69, v82
	v_max3_f32 v244, v244, v73, v86
	v_max3_f32 v245, v245, v77, v90
	v_max3_f32 v120, v120, v81, v94
	v_max3_f32 v219, v219, v83, v84
	v_max3_f32 v244, v244, v87, v88
	v_max3_f32 v245, v245, v91, v92
	v_max3_f32 v120, v120, v95, v96
	v_max3_f32 v219, v219, v85, v98
	v_max3_f32 v244, v244, v89, v102
	v_max3_f32 v245, v245, v93, v106
	v_max3_f32 v120, v120, v97, v110
	v_max3_f32 v219, v219, v99, v100
	v_max3_f32 v244, v244, v103, v104
	v_max3_f32 v245, v245, v107, v108
	v_max3_f32 v120, v120, v111, v112
	v_max3_f32 v219, v219, v101, v114
	v_max3_f32 v219, v219, v115, v116
	v_max_f32_e32 v219, v219, v117
	v_max_f32_e32 v244, v244, v105
	v_max_f32_e32 v245, v245, v109
	v_max_f32_e32 v120, v120, v113
	v_max3_f32 v178, v219, v244, v245
	v_max_f32_e32 v178, v178, v120
	v_mov_b32_e32 v219, v178
	s_nop 1
	v_permlane16_swap_b32_e32 v178, v219
	v_max_f32_e32 v178, v178, v219
	v_mov_b32_e32 v219, v178
	s_nop 1
	v_permlane32_swap_b32_e32 v178, v219
	v_max3_f32 v178, v178, v219, v145
	s_waitcnt lgkmcnt(7)
	ds_read_b64_tr_b16 v[202:203], v124 offset:6144
	ds_read_b64_tr_b16 v[204:205], v124 offset:8192
	ds_read_b64_tr_b16 v[206:207], v125 offset:6144
	ds_read_b64_tr_b16 v[208:209], v125 offset:8192
	ds_read_b64_tr_b16 v[228:229], v126 offset:6144
	ds_read_b64_tr_b16 v[230:231], v126 offset:8192
	ds_read_b64_tr_b16 v[232:233], v127 offset:6144
	ds_read_b64_tr_b16 v[234:235], v127 offset:8192
	v_mov_b32_e32 v244, v178
	v_pk_add_f32 v[50:51], v[50:51], v[244:245] op_sel_hi:[1,0] neg_lo:[0,1] neg_hi:[0,1]
	v_pk_add_f32 v[52:53], v[52:53], v[244:245] op_sel_hi:[1,0] neg_lo:[0,1] neg_hi:[0,1]
	v_pk_add_f32 v[54:55], v[54:55], v[244:245] op_sel_hi:[1,0] neg_lo:[0,1] neg_hi:[0,1]
	v_pk_add_f32 v[56:57], v[56:57], v[244:245] op_sel_hi:[1,0] neg_lo:[0,1] neg_hi:[0,1]
	v_pk_add_f32 v[58:59], v[58:59], v[244:245] op_sel_hi:[1,0] neg_lo:[0,1] neg_hi:[0,1]
	v_pk_add_f32 v[60:61], v[60:61], v[244:245] op_sel_hi:[1,0] neg_lo:[0,1] neg_hi:[0,1]
	v_pk_add_f32 v[62:63], v[62:63], v[244:245] op_sel_hi:[1,0] neg_lo:[0,1] neg_hi:[0,1]
	v_pk_add_f32 v[64:65], v[64:65], v[244:245] op_sel_hi:[1,0] neg_lo:[0,1] neg_hi:[0,1]
	v_pk_add_f32 v[66:67], v[66:67], v[244:245] op_sel_hi:[1,0] neg_lo:[0,1] neg_hi:[0,1]
	v_pk_add_f32 v[68:69], v[68:69], v[244:245] op_sel_hi:[1,0] neg_lo:[0,1] neg_hi:[0,1]
	v_pk_add_f32 v[70:71], v[70:71], v[244:245] op_sel_hi:[1,0] neg_lo:[0,1] neg_hi:[0,1]
	v_pk_add_f32 v[72:73], v[72:73], v[244:245] op_sel_hi:[1,0] neg_lo:[0,1] neg_hi:[0,1]
	v_pk_add_f32 v[74:75], v[74:75], v[244:245] op_sel_hi:[1,0] neg_lo:[0,1] neg_hi:[0,1]
	v_pk_add_f32 v[76:77], v[76:77], v[244:245] op_sel_hi:[1,0] neg_lo:[0,1] neg_hi:[0,1]
	v_pk_add_f32 v[78:79], v[78:79], v[244:245] op_sel_hi:[1,0] neg_lo:[0,1] neg_hi:[0,1]
	v_pk_add_f32 v[80:81], v[80:81], v[244:245] op_sel_hi:[1,0] neg_lo:[0,1] neg_hi:[0,1]
	v_pk_add_f32 v[82:83], v[82:83], v[244:245] op_sel_hi:[1,0] neg_lo:[0,1] neg_hi:[0,1]
	v_pk_add_f32 v[84:85], v[84:85], v[244:245] op_sel_hi:[1,0] neg_lo:[0,1] neg_hi:[0,1]
	v_pk_add_f32 v[86:87], v[86:87], v[244:245] op_sel_hi:[1,0] neg_lo:[0,1] neg_hi:[0,1]
	v_pk_add_f32 v[88:89], v[88:89], v[244:245] op_sel_hi:[1,0] neg_lo:[0,1] neg_hi:[0,1]
	v_pk_add_f32 v[90:91], v[90:91], v[244:245] op_sel_hi:[1,0] neg_lo:[0,1] neg_hi:[0,1]
	v_pk_add_f32 v[92:93], v[92:93], v[244:245] op_sel_hi:[1,0] neg_lo:[0,1] neg_hi:[0,1]
	v_pk_add_f32 v[94:95], v[94:95], v[244:245] op_sel_hi:[1,0] neg_lo:[0,1] neg_hi:[0,1]
	v_pk_add_f32 v[96:97], v[96:97], v[244:245] op_sel_hi:[1,0] neg_lo:[0,1] neg_hi:[0,1]
	v_pk_add_f32 v[98:99], v[98:99], v[244:245] op_sel_hi:[1,0] neg_lo:[0,1] neg_hi:[0,1]
	v_pk_add_f32 v[100:101], v[100:101], v[244:245] op_sel_hi:[1,0] neg_lo:[0,1] neg_hi:[0,1]
	v_pk_add_f32 v[102:103], v[102:103], v[244:245] op_sel_hi:[1,0] neg_lo:[0,1] neg_hi:[0,1]
	v_pk_add_f32 v[104:105], v[104:105], v[244:245] op_sel_hi:[1,0] neg_lo:[0,1] neg_hi:[0,1]
	v_pk_add_f32 v[106:107], v[106:107], v[244:245] op_sel_hi:[1,0] neg_lo:[0,1] neg_hi:[0,1]
	v_pk_add_f32 v[108:109], v[108:109], v[244:245] op_sel_hi:[1,0] neg_lo:[0,1] neg_hi:[0,1]
	v_pk_add_f32 v[110:111], v[110:111], v[244:245] op_sel_hi:[1,0] neg_lo:[0,1] neg_hi:[0,1]
	v_pk_add_f32 v[112:113], v[112:113], v[244:245] op_sel_hi:[1,0] neg_lo:[0,1] neg_hi:[0,1]
	v_pk_add_f32 v[114:115], v[114:115], v[244:245] op_sel_hi:[1,0] neg_lo:[0,1] neg_hi:[0,1]
	v_pk_add_f32 v[116:117], v[116:117], v[244:245] op_sel_hi:[1,0] neg_lo:[0,1] neg_hi:[0,1]
	v_sub_f32_e32 v219, v145, v178
	v_exp_f32_e32 v50, v50
; #define LAS __attribute__((address_space(3)))
; __device__ __forceinline__ unsigned pk2(float lo, float hi) { return pg8::cvt_pk_bf16(lo, hi); }
; __device__ __forceinline__ s16x4 vtr(const LAS unsigned char* p) { return __builtin_bit_cast(s16x4, __builtin_amdgcn_ds_read_tr16_b64_v4i16((LAS s16x4*)p)); }
; #define MFMA16(a, b, c) __builtin_amdgcn_mfma_f32_16x16x32_bf16((a), (b), (c), 0, 0, 0)
; __device__ __forceinline__ void pv_at(const LAS unsigned char* const (&vp)[4], int off, const f32x4& P0, const f32x4& P1, f32x4 (&O)[4]) {
;     v4u pw; pw.x = pk2(P0[0], P0[1]); pw.y = pk2(P0[2], P0[3]); pw.z = pk2(P1[0], P1[1]); pw.w = pk2(P1[2], P1[3]);
;     const bf16x8 pb = __builtin_bit_cast(bf16x8, pw);
; #pragma unroll
;     for (int db = 0; db < 4; ++db) {
;         const s16x4 lo = vtr(vp[db] + off), hi = vtr(vp[db] + off + 2048);
;         const bf16x8 vt = (bf16x8){lo[0], lo[1], lo[2], lo[3], hi[0], hi[1], hi[2], hi[3]};
;         O[db] = MFMA16(vt, pb, O[db]);
;     }
; }
; __device__ __forceinline__ void softmax_step(f32x4& s0, f32x4& s1, float& m, float& l, f32x4 (&O)[4]) {
;     float t = fmaxf(fmaxf(fmaxf(s0[0], s0[1]), fmaxf(s0[2], s0[3])), fmaxf(fmaxf(s1[0], s1[1]), fmaxf(s1[2], s1[3])));
;     t = xrow16_max(t);
;     const float mn = fmaxf(m, t), alpha = __builtin_amdgcn_exp2f(m - mn);
;     m = mn;
; #pragma unroll
;     for (int k = 0; k < 4; ++k) { s0[k] = __builtin_amdgcn_exp2f(s0[k] - mn); s1[k] = __builtin_amdgcn_exp2f(s1[k] - mn); }
;     l = l * alpha + ((s0[0] + s0[1]) + (s0[2] + s0[3])) + ((s1[0] + s1[1]) + (s1[2] + s1[3]));
	v_exp_f32_e32 v51, v51
	v_exp_f32_e32 v52, v52
	v_exp_f32_e32 v53, v53
	v_exp_f32_e32 v54, v54
	v_exp_f32_e32 v55, v55
	v_exp_f32_e32 v56, v56
	v_exp_f32_e32 v57, v57
	v_exp_f32_e32 v58, v58
	v_exp_f32_e32 v59, v59
	v_exp_f32_e32 v60, v60
	v_exp_f32_e32 v61, v61
	v_exp_f32_e32 v62, v62
	v_exp_f32_e32 v63, v63
	v_exp_f32_e32 v64, v64
	v_exp_f32_e32 v65, v65
	v_exp_f32_e32 v66, v66
	v_exp_f32_e32 v67, v67
	v_exp_f32_e32 v68, v68
	v_exp_f32_e32 v69, v69
	v_exp_f32_e32 v70, v70
	v_exp_f32_e32 v71, v71
	v_exp_f32_e32 v72, v72
	v_exp_f32_e32 v73, v73
	v_exp_f32_e32 v74, v74
	v_exp_f32_e32 v75, v75
	v_exp_f32_e32 v76, v76
	v_exp_f32_e32 v77, v77
	v_exp_f32_e32 v78, v78
	v_exp_f32_e32 v79, v79
	v_exp_f32_e32 v80, v80
	v_exp_f32_e32 v81, v81
	v_exp_f32_e32 v82, v82
	v_exp_f32_e32 v83, v83
	v_exp_f32_e32 v84, v84
	v_exp_f32_e32 v85, v85
	v_exp_f32_e32 v86, v86
	v_exp_f32_e32 v87, v87
	v_exp_f32_e32 v88, v88
	v_exp_f32_e32 v89, v89
	v_exp_f32_e32 v90, v90
	v_exp_f32_e32 v91, v91
	v_exp_f32_e32 v92, v92
	v_exp_f32_e32 v93, v93
	v_exp_f32_e32 v94, v94
	v_exp_f32_e32 v95, v95
	v_exp_f32_e32 v96, v96
	v_exp_f32_e32 v97, v97
	v_exp_f32_e32 v98, v98
	v_exp_f32_e32 v99, v99
	v_exp_f32_e32 v100, v100
	v_exp_f32_e32 v101, v101
	v_exp_f32_e32 v102, v102
	v_exp_f32_e32 v103, v103
	v_exp_f32_e32 v104, v104
	v_exp_f32_e32 v105, v105
	v_exp_f32_e32 v106, v106
	v_exp_f32_e32 v107, v107
	v_exp_f32_e32 v108, v108
	v_exp_f32_e32 v109, v109
	v_exp_f32_e32 v110, v110
	v_exp_f32_e32 v111, v111
	v_exp_f32_e32 v112, v112
	v_exp_f32_e32 v113, v113
	v_exp_f32_e32 v114, v114
	v_exp_f32_e32 v115, v115
	v_exp_f32_e32 v116, v116
	v_exp_f32_e32 v117, v117
	v_exp_f32_e32 v219, v219
	v_pk_add_f32 v[236:237], v[50:51], v[52:53]
	v_pk_add_f32 v[238:239], v[54:55], v[56:57]
	v_pk_add_f32 v[240:241], v[58:59], v[60:61]
	v_pk_add_f32 v[242:243], v[62:63], v[64:65]
	v_pk_add_f32 v[236:237], v[236:237], v[66:67]
	v_pk_add_f32 v[238:239], v[238:239], v[70:71]
	v_pk_add_f32 v[240:241], v[240:241], v[74:75]
	v_pk_add_f32 v[242:243], v[242:243], v[78:79]
	v_pk_add_f32 v[236:237], v[236:237], v[68:69]
	v_pk_add_f32 v[238:239], v[238:239], v[72:73]
	v_pk_add_f32 v[240:241], v[240:241], v[76:77]
	v_pk_add_f32 v[242:243], v[242:243], v[80:81]
	v_pk_add_f32 v[236:237], v[236:237], v[82:83]
	v_pk_add_f32 v[238:239], v[238:239], v[86:87]
	v_pk_add_f32 v[240:241], v[240:241], v[90:91]
	v_pk_add_f32 v[242:243], v[242:243], v[94:95]
	v_pk_add_f32 v[236:237], v[236:237], v[84:85]
	v_pk_add_f32 v[238:239], v[238:239], v[88:89]
	v_pk_add_f32 v[240:241], v[240:241], v[92:93]
	v_pk_add_f32 v[242:243], v[242:243], v[96:97]
	v_pk_add_f32 v[236:237], v[236:237], v[98:99]
	v_pk_add_f32 v[238:239], v[238:239], v[102:103]
	v_pk_add_f32 v[240:241], v[240:241], v[106:107]
	v_pk_add_f32 v[242:243], v[242:243], v[110:111]
	v_pk_add_f32 v[236:237], v[236:237], v[100:101]
	v_pk_add_f32 v[238:239], v[238:239], v[104:105]
	v_pk_add_f32 v[240:241], v[240:241], v[108:109]
	v_pk_add_f32 v[242:243], v[242:243], v[112:113]
	v_pk_add_f32 v[236:237], v[236:237], v[114:115]
	v_pk_add_f32 v[236:237], v[236:237], v[116:117]
	v_pk_add_f32 v[236:237], v[236:237], v[238:239]
	v_pk_add_f32 v[240:241], v[240:241], v[242:243]
	v_cndmask_b32_e64 v219, 0, v219, s[74:75]
	v_pk_add_f32 v[236:237], v[236:237], v[240:241]
	v_add_f32_e32 v185, v236, v237
	v_add_f32_e32 v185, v185, v219
	v_cvt_pk_bf16_f32 v236, v50, v51
	v_cvt_pk_bf16_f32 v237, v52, v53
	v_cvt_pk_bf16_f32 v238, v54, v55
	v_cvt_pk_bf16_f32 v239, v56, v57
	s_nop 1
	s_waitcnt lgkmcnt(14)
	v_mfma_f32_16x16x32_bf16 v[210:213], v[186:189], v[236:239], 0
	s_waitcnt lgkmcnt(12)
	v_mfma_f32_16x16x32_bf16 v[214:217], v[190:193], v[236:239], 0
	s_waitcnt lgkmcnt(10)
	v_mfma_f32_16x16x32_bf16 v[220:223], v[194:197], v[236:239], 0
	s_waitcnt lgkmcnt(8)
	v_mfma_f32_16x16x32_bf16 v[224:227], v[198:201], v[236:239], 0
	v_cvt_pk_bf16_f32 v240, v58, v59
	v_cvt_pk_bf16_f32 v241, v60, v61
	v_cvt_pk_bf16_f32 v242, v62, v63
	v_cvt_pk_bf16_f32 v243, v64, v65
	s_waitcnt lgkmcnt(7)
	ds_read_b64_tr_b16 v[186:187], v124 offset:10240
	ds_read_b64_tr_b16 v[188:189], v124 offset:12288
	ds_read_b64_tr_b16 v[190:191], v125 offset:10240
	ds_read_b64_tr_b16 v[192:193], v125 offset:12288
	ds_read_b64_tr_b16 v[194:195], v126 offset:10240
	ds_read_b64_tr_b16 v[196:197], v126 offset:12288
	ds_read_b64_tr_b16 v[198:199], v127 offset:10240
	ds_read_b64_tr_b16 v[200:201], v127 offset:12288
	s_waitcnt lgkmcnt(14)
	v_mfma_f32_16x16x32_bf16 v[210:213], v[202:205], v[240:243], v[210:213]
	s_waitcnt lgkmcnt(12)
	v_mfma_f32_16x16x32_bf16 v[214:217], v[206:209], v[240:243], v[214:217]
	s_waitcnt lgkmcnt(10)
	v_mfma_f32_16x16x32_bf16 v[220:223], v[228:231], v[240:243], v[220:223]
	s_waitcnt lgkmcnt(8)
	v_mfma_f32_16x16x32_bf16 v[224:227], v[232:235], v[240:243], v[224:227]
	v_cvt_pk_bf16_f32 v236, v66, v67
	v_cvt_pk_bf16_f32 v237, v68, v69
	v_cvt_pk_bf16_f32 v238, v70, v71
	v_cvt_pk_bf16_f32 v239, v72, v73
	s_waitcnt lgkmcnt(7)
	ds_read_b64_tr_b16 v[202:203], v124 offset:14336
	ds_read_b64_tr_b16 v[204:205], v124 offset:16384
	ds_read_b64_tr_b16 v[206:207], v125 offset:14336
	ds_read_b64_tr_b16 v[208:209], v125 offset:16384
	ds_read_b64_tr_b16 v[228:229], v126 offset:14336
	ds_read_b64_tr_b16 v[230:231], v126 offset:16384
	ds_read_b64_tr_b16 v[232:233], v127 offset:14336
	ds_read_b64_tr_b16 v[234:235], v127 offset:16384
	s_waitcnt lgkmcnt(14)
	v_mfma_f32_16x16x32_bf16 v[210:213], v[186:189], v[236:239], v[210:213]
	s_waitcnt lgkmcnt(12)
	v_mfma_f32_16x16x32_bf16 v[214:217], v[190:193], v[236:239], v[214:217]
	s_waitcnt lgkmcnt(10)
	v_mfma_f32_16x16x32_bf16 v[220:223], v[194:197], v[236:239], v[220:223]
	s_waitcnt lgkmcnt(8)
; #define LAS __attribute__((address_space(3)))
; __device__ __forceinline__ unsigned pk2(float lo, float hi) { return pg8::cvt_pk_bf16(lo, hi); }
; __device__ __forceinline__ s16x4 vtr(const LAS unsigned char* p) { return __builtin_bit_cast(s16x4, __builtin_amdgcn_ds_read_tr16_b64_v4i16((LAS s16x4*)p)); }
; #define MFMA16(a, b, c) __builtin_amdgcn_mfma_f32_16x16x32_bf16((a), (b), (c), 0, 0, 0)
; __device__ __forceinline__ void pv_at(const LAS unsigned char* const (&vp)[4], int off, const f32x4& P0, const f32x4& P1, f32x4 (&O)[4]) {
;     v4u pw; pw.x = pk2(P0[0], P0[1]); pw.y = pk2(P0[2], P0[3]); pw.z = pk2(P1[0], P1[1]); pw.w = pk2(P1[2], P1[3]);
;     const bf16x8 pb = __builtin_bit_cast(bf16x8, pw);
; #pragma unroll
;     for (int db = 0; db < 4; ++db) {
;         const s16x4 lo = vtr(vp[db] + off), hi = vtr(vp[db] + off + 2048);
;         const bf16x8 vt = (bf16x8){lo[0], lo[1], lo[2], lo[3], hi[0], hi[1], hi[2], hi[3]};
;         O[db] = MFMA16(vt, pb, O[db]);
;     }
; }
	v_mfma_f32_16x16x32_bf16 v[224:227], v[198:201], v[236:239], v[224:227]
	v_cvt_pk_bf16_f32 v240, v74, v75
	v_cvt_pk_bf16_f32 v241, v76, v77
	v_cvt_pk_bf16_f32 v242, v78, v79
	v_cvt_pk_bf16_f32 v243, v80, v81
	s_waitcnt lgkmcnt(7)
	ds_read_b64_tr_b16 v[186:187], v124 offset:18432
	ds_read_b64_tr_b16 v[188:189], v124 offset:20480
	ds_read_b64_tr_b16 v[190:191], v125 offset:18432
	ds_read_b64_tr_b16 v[192:193], v125 offset:20480
	ds_read_b64_tr_b16 v[194:195], v126 offset:18432
	ds_read_b64_tr_b16 v[196:197], v126 offset:20480
	ds_read_b64_tr_b16 v[198:199], v127 offset:18432
	ds_read_b64_tr_b16 v[200:201], v127 offset:20480
	s_waitcnt lgkmcnt(14)
	v_mfma_f32_16x16x32_bf16 v[210:213], v[202:205], v[240:243], v[210:213]
	s_waitcnt lgkmcnt(12)
	v_mfma_f32_16x16x32_bf16 v[214:217], v[206:209], v[240:243], v[214:217]
	s_waitcnt lgkmcnt(10)
	v_mfma_f32_16x16x32_bf16 v[220:223], v[228:231], v[240:243], v[220:223]
	s_waitcnt lgkmcnt(8)
	v_mfma_f32_16x16x32_bf16 v[224:227], v[232:235], v[240:243], v[224:227]
	v_cvt_pk_bf16_f32 v236, v82, v83
	v_cvt_pk_bf16_f32 v237, v84, v85
	v_cvt_pk_bf16_f32 v238, v86, v87
	v_cvt_pk_bf16_f32 v239, v88, v89
	s_waitcnt lgkmcnt(7)
	ds_read_b64_tr_b16 v[202:203], v124 offset:22528
	ds_read_b64_tr_b16 v[204:205], v124 offset:24576
	ds_read_b64_tr_b16 v[206:207], v125 offset:22528
	ds_read_b64_tr_b16 v[208:209], v125 offset:24576
	ds_read_b64_tr_b16 v[228:229], v126 offset:22528
	ds_read_b64_tr_b16 v[230:231], v126 offset:24576
	ds_read_b64_tr_b16 v[232:233], v127 offset:22528
	ds_read_b64_tr_b16 v[234:235], v127 offset:24576
	s_waitcnt lgkmcnt(14)
	v_mfma_f32_16x16x32_bf16 v[210:213], v[186:189], v[236:239], v[210:213]
	s_waitcnt lgkmcnt(12)
	v_mfma_f32_16x16x32_bf16 v[214:217], v[190:193], v[236:239], v[214:217]
	s_waitcnt lgkmcnt(10)
	v_mfma_f32_16x16x32_bf16 v[220:223], v[194:197], v[236:239], v[220:223]
	s_waitcnt lgkmcnt(8)
	v_mfma_f32_16x16x32_bf16 v[224:227], v[198:201], v[236:239], v[224:227]
	v_cvt_pk_bf16_f32 v240, v90, v91
	v_cvt_pk_bf16_f32 v241, v92, v93
	v_cvt_pk_bf16_f32 v242, v94, v95
	v_cvt_pk_bf16_f32 v243, v96, v97
	s_waitcnt lgkmcnt(7)
	ds_read_b64_tr_b16 v[186:187], v124 offset:26624
	ds_read_b64_tr_b16 v[188:189], v124 offset:28672
	ds_read_b64_tr_b16 v[190:191], v125 offset:26624
	ds_read_b64_tr_b16 v[192:193], v125 offset:28672
	ds_read_b64_tr_b16 v[194:195], v126 offset:26624
	ds_read_b64_tr_b16 v[196:197], v126 offset:28672
	ds_read_b64_tr_b16 v[198:199], v127 offset:26624
	ds_read_b64_tr_b16 v[200:201], v127 offset:28672
	s_waitcnt lgkmcnt(14)
	v_mfma_f32_16x16x32_bf16 v[210:213], v[202:205], v[240:243], v[210:213]
	s_waitcnt lgkmcnt(12)
	v_mfma_f32_16x16x32_bf16 v[214:217], v[206:209], v[240:243], v[214:217]
	s_waitcnt lgkmcnt(10)
	v_mfma_f32_16x16x32_bf16 v[220:223], v[228:231], v[240:243], v[220:223]
	s_waitcnt lgkmcnt(8)
	v_mfma_f32_16x16x32_bf16 v[224:227], v[232:235], v[240:243], v[224:227]
	v_cvt_pk_bf16_f32 v236, v98, v99
	v_cvt_pk_bf16_f32 v237, v100, v101
	v_cvt_pk_bf16_f32 v238, v102, v103
	v_cvt_pk_bf16_f32 v239, v104, v105
	s_waitcnt lgkmcnt(7)
	ds_read_b64_tr_b16 v[202:203], v124 offset:30720
	ds_read_b64_tr_b16 v[204:205], v124 offset:32768
	ds_read_b64_tr_b16 v[206:207], v125 offset:30720
	ds_read_b64_tr_b16 v[208:209], v125 offset:32768
	ds_read_b64_tr_b16 v[228:229], v126 offset:30720
	ds_read_b64_tr_b16 v[230:231], v126 offset:32768
	ds_read_b64_tr_b16 v[232:233], v127 offset:30720
	ds_read_b64_tr_b16 v[234:235], v127 offset:32768
	s_waitcnt lgkmcnt(14)
	v_mfma_f32_16x16x32_bf16 v[210:213], v[186:189], v[236:239], v[210:213]
	s_waitcnt lgkmcnt(12)
	v_mfma_f32_16x16x32_bf16 v[214:217], v[190:193], v[236:239], v[214:217]
	s_waitcnt lgkmcnt(10)
	v_mfma_f32_16x16x32_bf16 v[220:223], v[194:197], v[236:239], v[220:223]
	s_waitcnt lgkmcnt(8)
	v_mfma_f32_16x16x32_bf16 v[224:227], v[198:201], v[236:239], v[224:227]
	v_cvt_pk_bf16_f32 v240, v106, v107
	v_cvt_pk_bf16_f32 v241, v108, v109
	v_cvt_pk_bf16_f32 v242, v110, v111
	v_cvt_pk_bf16_f32 v243, v112, v113
	s_waitcnt lgkmcnt(7)
	ds_read_b64_tr_b16 v[186:187], v124 offset:34816
	ds_read_b64_tr_b16 v[188:189], v124 offset:36864
	ds_read_b64_tr_b16 v[190:191], v125 offset:34816
	ds_read_b64_tr_b16 v[192:193], v125 offset:36864
	ds_read_b64_tr_b16 v[194:195], v126 offset:34816
	ds_read_b64_tr_b16 v[196:197], v126 offset:36864
	ds_read_b64_tr_b16 v[198:199], v127 offset:34816
	ds_read_b64_tr_b16 v[200:201], v127 offset:36864
	s_waitcnt lgkmcnt(14)
	v_mfma_f32_16x16x32_bf16 v[210:213], v[202:205], v[240:243], v[210:213]
	s_waitcnt lgkmcnt(12)
	v_mfma_f32_16x16x32_bf16 v[214:217], v[206:209], v[240:243], v[214:217]
	s_waitcnt lgkmcnt(10)
	v_mfma_f32_16x16x32_bf16 v[220:223], v[228:231], v[240:243], v[220:223]
	s_waitcnt lgkmcnt(8)
	v_mfma_f32_16x16x32_bf16 v[224:227], v[232:235], v[240:243], v[224:227]
	v_cvt_pk_bf16_f32 v236, v114, v115
	v_cvt_pk_bf16_f32 v237, v116, v117
	v_mov_b32_e32 v238, 0
	v_mov_b32_e32 v239, 0
	s_nop 1
	s_waitcnt lgkmcnt(6)
	v_mfma_f32_16x16x32_bf16 v[210:213], v[186:189], v[236:239], v[210:213]
	s_waitcnt lgkmcnt(4)
	v_mfma_f32_16x16x32_bf16 v[214:217], v[190:193], v[236:239], v[214:217]
	s_waitcnt lgkmcnt(2)
	v_mfma_f32_16x16x32_bf16 v[220:223], v[194:197], v[236:239], v[220:223]
	s_waitcnt lgkmcnt(0)
; #define LAS __attribute__((address_space(3)))
; #define MFMA16(a, b, c) __builtin_amdgcn_mfma_f32_16x16x32_bf16((a), (b), (c), 0, 0, 0)
; __device__ __forceinline__ void qk_at(const LAS unsigned char* kp0, const LAS unsigned char* kp1, int off, bf16x8 qf0, bf16x8 qf1, f32x4& S0, f32x4& S1) {
;     const bf16x8 k00 = *(const LAS bf16x8*)(kp0 + off), k01 = *(const LAS bf16x8*)(kp1 + off);
;     const bf16x8 k10 = *(const LAS bf16x8*)(kp0 + off + 2048), k11 = *(const LAS bf16x8*)(kp1 + off + 2048);
;     const f32x4 z = {0.f, 0.f, 0.f, 0.f};
;     S0 = MFMA16(k00, qf0, z); S0 = MFMA16(k01, qf1, S0);
;     S1 = MFMA16(k10, qf0, z); S1 = MFMA16(k11, qf1, S1);
; }
; __device__ __forceinline__ void store_o(bf16* yrow, int g, float l, const f32x4 (&O)[4]) {
;     const float inv = 1.0f / xrow16_sum(l);
;     unsigned wx[4], wy[4];
; #pragma unroll
;     for (int db = 0; db < 4; ++db) { wx[db] = pk2(O[db][0] * inv, O[db][1] * inv); wy[db] = pk2(O[db][2] * inv, O[db][3] * inv); }
; #pragma unroll
;     for (int p = 0; p < 2; ++p) {
;         auto rx = __builtin_amdgcn_permlane16_swap(wx[2 * p], wx[2 * p + 1], false, false); wx[2 * p] = rx[0]; wx[2 * p + 1] = rx[1];
;         auto ry = __builtin_amdgcn_permlane16_swap(wy[2 * p], wy[2 * p + 1], false, false); wy[2 * p] = ry[0]; wy[2 * p + 1] = ry[1]; }
; #pragma unroll
;     for (int p = 0; p < 2; ++p) {
;         auto rx = __builtin_amdgcn_permlane32_swap(wx[p], wx[p + 2], false, false); wx[p] = rx[0]; wx[p + 2] = rx[1];
;         auto ry = __builtin_amdgcn_permlane32_swap(wy[p], wy[p + 2], false, false); wy[p] = ry[0]; wy[p + 2] = ry[1]; }
;     v4u lo = {wx[0], wy[0], wx[1], wy[1]}, hi = {wx[2], wy[2], wx[3], wy[3]};
;     *(v4u*)(yrow + 16 * g) = lo; *(v4u*)(yrow + 16 * g + 8) = hi;
; }
; template <bool MASK> __device__ __forceinline__ void a_scores(f32x4& S0, f32x4& S1, float basef, float c1, float slope2, int krow0, int kstart) {
; #pragma unroll
;     for (int r = 0; r < 4; ++r) {
;         const float d0 = fabsf(basef - (float)r), d1 = fabsf(basef - (float)(16 + r));
;         const float v0 = S0[r] - slope2 * d0, v1 = S1[r] - slope2 * d1;
;         if (MASK) { const int p0 = kstart + krow0 + r, p1 = p0 + 16;
;             S0[r] = (d0 <= 128.f && p0 >= 0 && p0 < SEQ) ? v0 : -INFINITY; S1[r] = (d1 <= 128.f && p1 >= 0 && p1 < SEQ) ? v1 : -INFINITY; }
;         else { S0[r] = v0; S1[r] = v1; }
;     }
; }
	v_mfma_f32_16x16x32_bf16 v[224:227], v[198:201], v[236:239], v[224:227]
	v_mov_b32_e32 v219, v185
	s_nop 1
	v_permlane16_swap_b32_e32 v185, v219
	v_add_f32_e32 v185, v185, v219
	v_mov_b32_e32 v219, v185
	s_nop 1
	v_permlane32_swap_b32_e32 v185, v219
	v_add_f32_e32 v185, v185, v219
	v_div_scale_f32 v236, s[78:79], v185, v185, 1.0
	v_div_scale_f32 v237, vcc, 1.0, v185, 1.0
	v_rcp_f32_e32 v238, v236
	s_nop 0
	v_fma_f32 v239, -v236, v238, 1.0
	v_fmac_f32_e32 v238, v239, v238
	v_mul_f32_e32 v240, v237, v238
	v_fma_f32 v241, -v236, v240, v237
	v_fmac_f32_e32 v240, v241, v238
	v_fma_f32 v237, -v236, v240, v237
	v_div_fmas_f32 v237, v237, v238, v240
	v_div_fixup_f32 v244, v237, v185, 1.0
	v_mul_f32_e32 v240, v210, v244
	v_mul_f32_e32 v241, v211, v244
	v_mul_f32_e32 v242, v212, v244
	v_mul_f32_e32 v243, v213, v244
	v_cvt_pk_bf16_f32 v186, v240, v241
	v_cvt_pk_bf16_f32 v187, v242, v243
	v_mul_f32_e32 v240, v214, v244
	v_mul_f32_e32 v241, v215, v244
	v_mul_f32_e32 v242, v216, v244
	v_mul_f32_e32 v243, v217, v244
	v_cvt_pk_bf16_f32 v188, v240, v241
	v_cvt_pk_bf16_f32 v189, v242, v243
	v_mul_f32_e32 v240, v220, v244
	v_mul_f32_e32 v241, v221, v244
	v_mul_f32_e32 v242, v222, v244
	v_mul_f32_e32 v243, v223, v244
	v_cvt_pk_bf16_f32 v190, v240, v241
	v_cvt_pk_bf16_f32 v191, v242, v243
	v_mul_f32_e32 v240, v224, v244
	v_mul_f32_e32 v241, v225, v244
	v_mul_f32_e32 v242, v226, v244
	v_mul_f32_e32 v243, v227, v244
	v_cvt_pk_bf16_f32 v192, v240, v241
	v_cvt_pk_bf16_f32 v193, v242, v243
	s_nop 1
	v_permlane16_swap_b32_e32 v186, v188
	v_permlane16_swap_b32_e32 v187, v189
	v_permlane16_swap_b32_e32 v190, v192
	v_permlane16_swap_b32_e32 v191, v193
	s_nop 0
	v_permlane32_swap_b32_e32 v186, v190
	v_permlane32_swap_b32_e32 v187, v191
	v_permlane32_swap_b32_e32 v188, v192
	v_permlane32_swap_b32_e32 v189, v193
	global_store_dwordx4 v128, v[186:189], s[82:83] offset:2048 sc1
	global_store_dwordx4 v128, v[190:193], s[82:83] offset:2064 sc1
	s_nop 1
	v_fmamk_f32 v50, v130, 0x43000000, v132
	v_fmamk_f32 v51, v130, 0x42fe0000, v132
	v_fmamk_f32 v52, v130, 0x42fc0000, v132
	v_fmamk_f32 v53, v130, 0x42fa0000, v132
	v_fmamk_f32 v54, v130, 0x42e00000, v132
	v_fmamk_f32 v55, v130, 0x42de0000, v132
	v_fmamk_f32 v56, v130, 0x42dc0000, v132
	v_fmamk_f32 v57, v130, 0x42da0000, v132
	v_fmamk_f32 v58, v130, 0x42c00000, v132
	v_fmamk_f32 v59, v130, 0x42be0000, v132
	v_fmamk_f32 v60, v130, 0x42bc0000, v132
	v_fmamk_f32 v61, v130, 0x42ba0000, v132
	v_fmamk_f32 v62, v130, 0x42a00000, v132
	v_fmamk_f32 v63, v130, 0x429e0000, v132
	v_fmamk_f32 v64, v130, 0x429c0000, v132
	v_fmamk_f32 v65, v130, 0x429a0000, v132
	v_fmamk_f32 v66, v130, 0x42800000, v132
	v_fmamk_f32 v67, v130, 0x427c0000, v132
	v_fmamk_f32 v68, v130, 0x42780000, v132
	v_fmamk_f32 v69, v130, 0x42740000, v132
	v_fmamk_f32 v70, v130, 0x42400000, v132
	v_fmamk_f32 v71, v130, 0x423c0000, v132
	v_fmamk_f32 v72, v130, 0x42380000, v132
	v_fmamk_f32 v73, v130, 0x42340000, v132
	v_fmamk_f32 v74, v130, 0x42000000, v132
	v_fmamk_f32 v75, v130, 0x41f80000, v132
	v_fmamk_f32 v76, v130, 0x41f00000, v132
	v_fmamk_f32 v77, v130, 0x41e80000, v132
	v_fmamk_f32 v78, v130, 0x41800000, v132
	v_fmamk_f32 v79, v130, 0x41700000, v132
	v_fmamk_f32 v80, v130, 0x41600000, v132
	v_fmamk_f32 v81, v130, 0x41500000, v132
	v_add_f32_e32 v219, 0, v129
	v_mul_f32_e64 v82, v130, |v219|
	v_add_f32_e32 v244, 0xbf800000, v129
	v_mul_f32_e64 v83, v130, |v244|
	v_add_f32_e32 v219, 0xc0000000, v129
	v_mul_f32_e64 v84, v130, |v219|
	v_add_f32_e32 v244, 0xc0400000, v129
	v_mul_f32_e64 v85, v130, |v244|
	v_fmamk_f32 v86, v131, 0xc1800000, v133
	v_fmamk_f32 v87, v131, 0xc1880000, v133
	v_fmamk_f32 v88, v131, 0xc1900000, v133
	v_fmamk_f32 v89, v131, 0xc1980000, v133
	v_fmamk_f32 v90, v131, 0xc2000000, v133
	v_fmamk_f32 v91, v131, 0xc2040000, v133
	v_fmamk_f32 v92, v131, 0xc2080000, v133
	v_fmamk_f32 v93, v131, 0xc20c0000, v133
	v_fmamk_f32 v94, v131, 0xc2400000, v133
	v_fmamk_f32 v95, v131, 0xc2440000, v133
	v_fmamk_f32 v96, v131, 0xc2480000, v133
	v_fmamk_f32 v97, v131, 0xc24c0000, v133
	v_fmamk_f32 v98, v131, 0xc2800000, v133
	v_fmamk_f32 v99, v131, 0xc2820000, v133
	v_fmamk_f32 v100, v131, 0xc2840000, v133
	v_fmamk_f32 v101, v131, 0xc2860000, v133
	v_fmamk_f32 v102, v131, 0xc2a00000, v133
	v_fmamk_f32 v103, v131, 0xc2a20000, v133
	v_fmamk_f32 v104, v131, 0xc2a40000, v133
	v_fmamk_f32 v105, v131, 0xc2a60000, v133
	v_fmamk_f32 v106, v131, 0xc2c00000, v133
	v_fmamk_f32 v107, v131, 0xc2c20000, v133
	v_fmamk_f32 v108, v131, 0xc2c40000, v133
	v_fmamk_f32 v109, v131, 0xc2c60000, v133
	v_fmamk_f32 v110, v131, 0xc2e00000, v133
	v_fmamk_f32 v111, v131, 0xc2e20000, v133
	v_fmamk_f32 v112, v131, 0xc2e40000, v133
	v_fmamk_f32 v113, v131, 0xc2e60000, v133
	v_fmamk_f32 v114, v131, 0xc3000000, v133
	v_fmamk_f32 v115, v131, 0xc3010000, v133
	v_fmamk_f32 v116, v131, 0xc3020000, v133
	v_fmamk_f32 v117, v131, 0xc3030000, v133
	v_mov_b32_e32 v245, 0xff800000
	v_cndmask_b32_e64 v50, v245, v50, s[16:17]
	v_cndmask_b32_e64 v51, v245, v51, s[18:19]
	v_cndmask_b32_e64 v52, v245, v52, s[22:23]
	v_cndmask_b32_e64 v53, v245, v53, s[24:25]
	v_cndmask_b32_e64 v114, v245, v114, s[28:29]
	v_cndmask_b32_e64 v115, v245, v115, s[52:53]
	v_cndmask_b32_e64 v116, v245, v116, s[54:55]
	v_cndmask_b32_e64 v117, v245, v117, s[88:89]
	ds_read_b128 v[186:189], v122 offset:4096
	ds_read_b128 v[190:193], v123 offset:4096
	ds_read_b128 v[194:197], v122 offset:6144
	ds_read_b128 v[198:201], v123 offset:6144
	ds_read_b128 v[202:205], v122 offset:8192
	ds_read_b128 v[206:209], v123 offset:8192
	s_waitcnt lgkmcnt(5)
	v_mfma_f32_16x16x32_bf16 v[50:53], v[186:189], v[162:165], v[50:53]
	s_waitcnt lgkmcnt(4)
; #define LAS __attribute__((address_space(3)))
; #define MFMA16(a, b, c) __builtin_amdgcn_mfma_f32_16x16x32_bf16((a), (b), (c), 0, 0, 0)
; __device__ __forceinline__ void qk_at(const LAS unsigned char* kp0, const LAS unsigned char* kp1, int off, bf16x8 qf0, bf16x8 qf1, f32x4& S0, f32x4& S1) {
;     const bf16x8 k00 = *(const LAS bf16x8*)(kp0 + off), k01 = *(const LAS bf16x8*)(kp1 + off);
;     const bf16x8 k10 = *(const LAS bf16x8*)(kp0 + off + 2048), k11 = *(const LAS bf16x8*)(kp1 + off + 2048);
;     const f32x4 z = {0.f, 0.f, 0.f, 0.f};
;     S0 = MFMA16(k00, qf0, z); S0 = MFMA16(k01, qf1, S0);
;     S1 = MFMA16(k10, qf0, z); S1 = MFMA16(k11, qf1, S1);
; }
; __device__ __forceinline__ void softmax_step(f32x4& s0, f32x4& s1, float& m, float& l, f32x4 (&O)[4]) {
;     float t = fmaxf(fmaxf(fmaxf(s0[0], s0[1]), fmaxf(s0[2], s0[3])), fmaxf(fmaxf(s1[0], s1[1]), fmaxf(s1[2], s1[3])));
;     t = xrow16_max(t);
	v_mfma_f32_16x16x32_bf16 v[50:53], v[190:193], v[166:169], v[50:53]
	ds_read_b128 v[186:189], v122 offset:10240
	ds_read_b128 v[190:193], v123 offset:10240
	s_waitcnt lgkmcnt(5)
	v_mfma_f32_16x16x32_bf16 v[54:57], v[194:197], v[162:165], v[54:57]
	s_waitcnt lgkmcnt(4)
	v_mfma_f32_16x16x32_bf16 v[54:57], v[198:201], v[166:169], v[54:57]
	ds_read_b128 v[194:197], v122 offset:12288
	ds_read_b128 v[198:201], v123 offset:12288
	s_waitcnt lgkmcnt(5)
	v_mfma_f32_16x16x32_bf16 v[58:61], v[202:205], v[162:165], v[58:61]
	s_waitcnt lgkmcnt(4)
	v_mfma_f32_16x16x32_bf16 v[58:61], v[206:209], v[166:169], v[58:61]
	ds_read_b128 v[202:205], v122 offset:14336
	ds_read_b128 v[206:209], v123 offset:14336
	s_waitcnt lgkmcnt(5)
	v_mfma_f32_16x16x32_bf16 v[62:65], v[186:189], v[162:165], v[62:65]
	s_waitcnt lgkmcnt(4)
	v_mfma_f32_16x16x32_bf16 v[62:65], v[190:193], v[166:169], v[62:65]
	ds_read_b128 v[186:189], v122 offset:16384
	ds_read_b128 v[190:193], v123 offset:16384
	s_waitcnt lgkmcnt(5)
	v_mfma_f32_16x16x32_bf16 v[66:69], v[194:197], v[162:165], v[66:69]
	s_waitcnt lgkmcnt(4)
	v_mfma_f32_16x16x32_bf16 v[66:69], v[198:201], v[166:169], v[66:69]
	ds_read_b128 v[194:197], v122 offset:18432
	ds_read_b128 v[198:201], v123 offset:18432
	s_waitcnt lgkmcnt(5)
	v_mfma_f32_16x16x32_bf16 v[70:73], v[202:205], v[162:165], v[70:73]
	s_waitcnt lgkmcnt(4)
	v_mfma_f32_16x16x32_bf16 v[70:73], v[206:209], v[166:169], v[70:73]
	ds_read_b128 v[202:205], v122 offset:20480
	ds_read_b128 v[206:209], v123 offset:20480
	s_waitcnt lgkmcnt(5)
	v_mfma_f32_16x16x32_bf16 v[74:77], v[186:189], v[162:165], v[74:77]
	s_waitcnt lgkmcnt(4)
	v_mfma_f32_16x16x32_bf16 v[74:77], v[190:193], v[166:169], v[74:77]
	ds_read_b128 v[186:189], v122 offset:22528
	ds_read_b128 v[190:193], v123 offset:22528
	s_waitcnt lgkmcnt(5)
	v_mfma_f32_16x16x32_bf16 v[78:81], v[194:197], v[162:165], v[78:81]
	s_waitcnt lgkmcnt(4)
	v_mfma_f32_16x16x32_bf16 v[78:81], v[198:201], v[166:169], v[78:81]
	ds_read_b128 v[194:197], v122 offset:24576
	ds_read_b128 v[198:201], v123 offset:24576
	s_waitcnt lgkmcnt(5)
	v_mfma_f32_16x16x32_bf16 v[82:85], v[202:205], v[162:165], v[82:85]
	s_waitcnt lgkmcnt(4)
	v_mfma_f32_16x16x32_bf16 v[82:85], v[206:209], v[166:169], v[82:85]
	ds_read_b128 v[202:205], v122 offset:26624
	ds_read_b128 v[206:209], v123 offset:26624
	s_waitcnt lgkmcnt(5)
	v_mfma_f32_16x16x32_bf16 v[86:89], v[186:189], v[162:165], v[86:89]
	s_waitcnt lgkmcnt(4)
	v_mfma_f32_16x16x32_bf16 v[86:89], v[190:193], v[166:169], v[86:89]
	ds_read_b128 v[186:189], v122 offset:28672
	ds_read_b128 v[190:193], v123 offset:28672
	s_waitcnt lgkmcnt(5)
	v_mfma_f32_16x16x32_bf16 v[90:93], v[194:197], v[162:165], v[90:93]
	s_waitcnt lgkmcnt(4)
	v_mfma_f32_16x16x32_bf16 v[90:93], v[198:201], v[166:169], v[90:93]
	ds_read_b128 v[194:197], v122 offset:30720
	ds_read_b128 v[198:201], v123 offset:30720
	s_waitcnt lgkmcnt(5)
	v_mfma_f32_16x16x32_bf16 v[94:97], v[202:205], v[162:165], v[94:97]
	s_waitcnt lgkmcnt(4)
	v_mfma_f32_16x16x32_bf16 v[94:97], v[206:209], v[166:169], v[94:97]
	ds_read_b128 v[202:205], v122 offset:32768
	ds_read_b128 v[206:209], v123 offset:32768
	s_waitcnt lgkmcnt(5)
	v_mfma_f32_16x16x32_bf16 v[98:101], v[186:189], v[162:165], v[98:101]
	s_waitcnt lgkmcnt(4)
	v_mfma_f32_16x16x32_bf16 v[98:101], v[190:193], v[166:169], v[98:101]
	ds_read_b128 v[186:189], v122 offset:34816
	ds_read_b128 v[190:193], v123 offset:34816
	s_waitcnt lgkmcnt(5)
	v_mfma_f32_16x16x32_bf16 v[102:105], v[194:197], v[162:165], v[102:105]
	s_waitcnt lgkmcnt(4)
	v_mfma_f32_16x16x32_bf16 v[102:105], v[198:201], v[166:169], v[102:105]
	ds_read_b128 v[194:197], v122 offset:36864
	ds_read_b128 v[198:201], v123 offset:36864
	s_waitcnt lgkmcnt(5)
	v_mfma_f32_16x16x32_bf16 v[106:109], v[202:205], v[162:165], v[106:109]
	s_waitcnt lgkmcnt(4)
	v_mfma_f32_16x16x32_bf16 v[106:109], v[206:209], v[166:169], v[106:109]
	s_waitcnt lgkmcnt(3)
	v_mfma_f32_16x16x32_bf16 v[110:113], v[186:189], v[162:165], v[110:113]
	s_waitcnt lgkmcnt(2)
	v_mfma_f32_16x16x32_bf16 v[110:113], v[190:193], v[166:169], v[110:113]
	s_waitcnt lgkmcnt(1)
	v_mfma_f32_16x16x32_bf16 v[114:117], v[194:197], v[162:165], v[114:117]
	s_waitcnt lgkmcnt(0)
	v_mfma_f32_16x16x32_bf16 v[114:117], v[198:201], v[166:169], v[114:117]
	v_max3_f32 v219, v50, v51, v52
	v_max3_f32 v244, v54, v55, v56
	v_max3_f32 v245, v58, v59, v60
	v_max3_f32 v120, v62, v63, v64
	v_max3_f32 v219, v219, v53, v66
	v_max3_f32 v244, v244, v57, v70
	v_max3_f32 v245, v245, v61, v74
	v_max3_f32 v120, v120, v65, v78
	v_max3_f32 v219, v219, v67, v68
	v_max3_f32 v244, v244, v71, v72
	v_max3_f32 v245, v245, v75, v76
	v_max3_f32 v120, v120, v79, v80
	ds_read_b64_tr_b16 v[186:187], v124 offset:4096
	ds_read_b64_tr_b16 v[188:189], v124 offset:6144
	ds_read_b64_tr_b16 v[190:191], v125 offset:4096
	ds_read_b64_tr_b16 v[192:193], v125 offset:6144
	ds_read_b64_tr_b16 v[194:195], v126 offset:4096
	ds_read_b64_tr_b16 v[196:197], v126 offset:6144
	ds_read_b64_tr_b16 v[198:199], v127 offset:4096
	ds_read_b64_tr_b16 v[200:201], v127 offset:6144
	v_max3_f32 v219, v219, v69, v82
	v_max3_f32 v244, v244, v73, v86
	v_max3_f32 v245, v245, v77, v90
	v_max3_f32 v120, v120, v81, v94
	v_max3_f32 v219, v219, v83, v84
	v_max3_f32 v244, v244, v87, v88
	v_max3_f32 v245, v245, v91, v92
	v_max3_f32 v120, v120, v95, v96
	v_max3_f32 v219, v219, v85, v98
	v_max3_f32 v244, v244, v89, v102
	v_max3_f32 v245, v245, v93, v106
	v_max3_f32 v120, v120, v97, v110
	v_max3_f32 v219, v219, v99, v100
	v_max3_f32 v244, v244, v103, v104
	v_max3_f32 v245, v245, v107, v108
	v_max3_f32 v120, v120, v111, v112
	v_max3_f32 v219, v219, v101, v114
	v_max3_f32 v219, v219, v115, v116
	v_max_f32_e32 v219, v219, v117
	v_max_f32_e32 v244, v244, v105
	v_max_f32_e32 v245, v245, v109
	v_max_f32_e32 v120, v120, v113
	v_max3_f32 v178, v219, v244, v245
	v_max_f32_e32 v178, v178, v120
	v_mov_b32_e32 v219, v178
	s_nop 1
	v_permlane16_swap_b32_e32 v178, v219
	v_max_f32_e32 v178, v178, v219
	v_mov_b32_e32 v219, v178
	s_nop 1
	v_permlane32_swap_b32_e32 v178, v219
	v_max3_f32 v178, v178, v219, v145
	s_waitcnt lgkmcnt(7)
; __device__ __forceinline__ void softmax_step(f32x4& s0, f32x4& s1, float& m, float& l, f32x4 (&O)[4]) {
;     float t = fmaxf(fmaxf(fmaxf(s0[0], s0[1]), fmaxf(s0[2], s0[3])), fmaxf(fmaxf(s1[0], s1[1]), fmaxf(s1[2], s1[3])));
;     t = xrow16_max(t);
;     const float mn = fmaxf(m, t), alpha = __builtin_amdgcn_exp2f(m - mn);
;     m = mn;
; #pragma unroll
;     for (int k = 0; k < 4; ++k) { s0[k] = __builtin_amdgcn_exp2f(s0[k] - mn); s1[k] = __builtin_amdgcn_exp2f(s1[k] - mn); }
;     l = l * alpha + ((s0[0] + s0[1]) + (s0[2] + s0[3])) + ((s1[0] + s1[1]) + (s1[2] + s1[3]));
	ds_read_b64_tr_b16 v[202:203], v124 offset:8192
	ds_read_b64_tr_b16 v[204:205], v124 offset:10240
	ds_read_b64_tr_b16 v[206:207], v125 offset:8192
	ds_read_b64_tr_b16 v[208:209], v125 offset:10240
	ds_read_b64_tr_b16 v[228:229], v126 offset:8192
	ds_read_b64_tr_b16 v[230:231], v126 offset:10240
	ds_read_b64_tr_b16 v[232:233], v127 offset:8192
	ds_read_b64_tr_b16 v[234:235], v127 offset:10240
	v_mov_b32_e32 v244, v178
	v_pk_add_f32 v[50:51], v[50:51], v[244:245] op_sel_hi:[1,0] neg_lo:[0,1] neg_hi:[0,1]
	v_pk_add_f32 v[52:53], v[52:53], v[244:245] op_sel_hi:[1,0] neg_lo:[0,1] neg_hi:[0,1]
	v_pk_add_f32 v[54:55], v[54:55], v[244:245] op_sel_hi:[1,0] neg_lo:[0,1] neg_hi:[0,1]
	v_pk_add_f32 v[56:57], v[56:57], v[244:245] op_sel_hi:[1,0] neg_lo:[0,1] neg_hi:[0,1]
	v_pk_add_f32 v[58:59], v[58:59], v[244:245] op_sel_hi:[1,0] neg_lo:[0,1] neg_hi:[0,1]
	v_pk_add_f32 v[60:61], v[60:61], v[244:245] op_sel_hi:[1,0] neg_lo:[0,1] neg_hi:[0,1]
	v_pk_add_f32 v[62:63], v[62:63], v[244:245] op_sel_hi:[1,0] neg_lo:[0,1] neg_hi:[0,1]
	v_pk_add_f32 v[64:65], v[64:65], v[244:245] op_sel_hi:[1,0] neg_lo:[0,1] neg_hi:[0,1]
	v_pk_add_f32 v[66:67], v[66:67], v[244:245] op_sel_hi:[1,0] neg_lo:[0,1] neg_hi:[0,1]
	v_pk_add_f32 v[68:69], v[68:69], v[244:245] op_sel_hi:[1,0] neg_lo:[0,1] neg_hi:[0,1]
	v_pk_add_f32 v[70:71], v[70:71], v[244:245] op_sel_hi:[1,0] neg_lo:[0,1] neg_hi:[0,1]
	v_pk_add_f32 v[72:73], v[72:73], v[244:245] op_sel_hi:[1,0] neg_lo:[0,1] neg_hi:[0,1]
	v_pk_add_f32 v[74:75], v[74:75], v[244:245] op_sel_hi:[1,0] neg_lo:[0,1] neg_hi:[0,1]
	v_pk_add_f32 v[76:77], v[76:77], v[244:245] op_sel_hi:[1,0] neg_lo:[0,1] neg_hi:[0,1]
	v_pk_add_f32 v[78:79], v[78:79], v[244:245] op_sel_hi:[1,0] neg_lo:[0,1] neg_hi:[0,1]
	v_pk_add_f32 v[80:81], v[80:81], v[244:245] op_sel_hi:[1,0] neg_lo:[0,1] neg_hi:[0,1]
	v_pk_add_f32 v[82:83], v[82:83], v[244:245] op_sel_hi:[1,0] neg_lo:[0,1] neg_hi:[0,1]
	v_pk_add_f32 v[84:85], v[84:85], v[244:245] op_sel_hi:[1,0] neg_lo:[0,1] neg_hi:[0,1]
	v_pk_add_f32 v[86:87], v[86:87], v[244:245] op_sel_hi:[1,0] neg_lo:[0,1] neg_hi:[0,1]
	v_pk_add_f32 v[88:89], v[88:89], v[244:245] op_sel_hi:[1,0] neg_lo:[0,1] neg_hi:[0,1]
	v_pk_add_f32 v[90:91], v[90:91], v[244:245] op_sel_hi:[1,0] neg_lo:[0,1] neg_hi:[0,1]
	v_pk_add_f32 v[92:93], v[92:93], v[244:245] op_sel_hi:[1,0] neg_lo:[0,1] neg_hi:[0,1]
	v_pk_add_f32 v[94:95], v[94:95], v[244:245] op_sel_hi:[1,0] neg_lo:[0,1] neg_hi:[0,1]
	v_pk_add_f32 v[96:97], v[96:97], v[244:245] op_sel_hi:[1,0] neg_lo:[0,1] neg_hi:[0,1]
	v_pk_add_f32 v[98:99], v[98:99], v[244:245] op_sel_hi:[1,0] neg_lo:[0,1] neg_hi:[0,1]
	v_pk_add_f32 v[100:101], v[100:101], v[244:245] op_sel_hi:[1,0] neg_lo:[0,1] neg_hi:[0,1]
	v_pk_add_f32 v[102:103], v[102:103], v[244:245] op_sel_hi:[1,0] neg_lo:[0,1] neg_hi:[0,1]
	v_pk_add_f32 v[104:105], v[104:105], v[244:245] op_sel_hi:[1,0] neg_lo:[0,1] neg_hi:[0,1]
	v_pk_add_f32 v[106:107], v[106:107], v[244:245] op_sel_hi:[1,0] neg_lo:[0,1] neg_hi:[0,1]
	v_pk_add_f32 v[108:109], v[108:109], v[244:245] op_sel_hi:[1,0] neg_lo:[0,1] neg_hi:[0,1]
	v_pk_add_f32 v[110:111], v[110:111], v[244:245] op_sel_hi:[1,0] neg_lo:[0,1] neg_hi:[0,1]
	v_pk_add_f32 v[112:113], v[112:113], v[244:245] op_sel_hi:[1,0] neg_lo:[0,1] neg_hi:[0,1]
	v_pk_add_f32 v[114:115], v[114:115], v[244:245] op_sel_hi:[1,0] neg_lo:[0,1] neg_hi:[0,1]
	v_pk_add_f32 v[116:117], v[116:117], v[244:245] op_sel_hi:[1,0] neg_lo:[0,1] neg_hi:[0,1]
	v_sub_f32_e32 v219, v145, v178
	v_exp_f32_e32 v50, v50
	v_exp_f32_e32 v51, v51
	v_exp_f32_e32 v52, v52
	v_exp_f32_e32 v53, v53
	v_exp_f32_e32 v54, v54
	v_exp_f32_e32 v55, v55
	v_exp_f32_e32 v56, v56
	v_exp_f32_e32 v57, v57
	v_exp_f32_e32 v58, v58
	v_exp_f32_e32 v59, v59
	v_exp_f32_e32 v60, v60
	v_exp_f32_e32 v61, v61
	v_exp_f32_e32 v62, v62
	v_exp_f32_e32 v63, v63
	v_exp_f32_e32 v64, v64
	v_exp_f32_e32 v65, v65
	v_exp_f32_e32 v66, v66
	v_exp_f32_e32 v67, v67
	v_exp_f32_e32 v68, v68
	v_exp_f32_e32 v69, v69
	v_exp_f32_e32 v70, v70
	v_exp_f32_e32 v71, v71
	v_exp_f32_e32 v72, v72
	v_exp_f32_e32 v73, v73
	v_exp_f32_e32 v74, v74
	v_exp_f32_e32 v75, v75
	v_exp_f32_e32 v76, v76
	v_exp_f32_e32 v77, v77
	v_exp_f32_e32 v78, v78
	v_exp_f32_e32 v79, v79
	v_exp_f32_e32 v80, v80
	v_exp_f32_e32 v81, v81
	v_exp_f32_e32 v82, v82
	v_exp_f32_e32 v83, v83
	v_exp_f32_e32 v84, v84
	v_exp_f32_e32 v85, v85
	v_exp_f32_e32 v86, v86
	v_exp_f32_e32 v87, v87
	v_exp_f32_e32 v88, v88
	v_exp_f32_e32 v89, v89
	v_exp_f32_e32 v90, v90
	v_exp_f32_e32 v91, v91
	v_exp_f32_e32 v92, v92
	v_exp_f32_e32 v93, v93
	v_exp_f32_e32 v94, v94
	v_exp_f32_e32 v95, v95
	v_exp_f32_e32 v96, v96
	v_exp_f32_e32 v97, v97
	v_exp_f32_e32 v98, v98
	v_exp_f32_e32 v99, v99
	v_exp_f32_e32 v100, v100
	v_exp_f32_e32 v101, v101
	v_exp_f32_e32 v102, v102
	v_exp_f32_e32 v103, v103
	v_exp_f32_e32 v104, v104
	v_exp_f32_e32 v105, v105
	v_exp_f32_e32 v106, v106
	v_exp_f32_e32 v107, v107
	v_exp_f32_e32 v108, v108
	v_exp_f32_e32 v109, v109
	v_exp_f32_e32 v110, v110
	v_exp_f32_e32 v111, v111
	v_exp_f32_e32 v112, v112
	v_exp_f32_e32 v113, v113
	v_exp_f32_e32 v114, v114
	v_exp_f32_e32 v115, v115
	v_exp_f32_e32 v116, v116
	v_exp_f32_e32 v117, v117
	v_exp_f32_e32 v219, v219
	v_pk_add_f32 v[236:237], v[50:51], v[52:53]
	v_pk_add_f32 v[238:239], v[54:55], v[56:57]
	v_pk_add_f32 v[240:241], v[58:59], v[60:61]
	v_pk_add_f32 v[242:243], v[62:63], v[64:65]
	v_pk_add_f32 v[236:237], v[236:237], v[66:67]
	v_pk_add_f32 v[238:239], v[238:239], v[70:71]
	v_pk_add_f32 v[240:241], v[240:241], v[74:75]
	v_pk_add_f32 v[242:243], v[242:243], v[78:79]
	v_pk_add_f32 v[236:237], v[236:237], v[68:69]
	v_pk_add_f32 v[238:239], v[238:239], v[72:73]
	v_pk_add_f32 v[240:241], v[240:241], v[76:77]
	v_pk_add_f32 v[242:243], v[242:243], v[80:81]
	v_pk_add_f32 v[236:237], v[236:237], v[82:83]
	v_pk_add_f32 v[238:239], v[238:239], v[86:87]
	v_pk_add_f32 v[240:241], v[240:241], v[90:91]
	v_pk_add_f32 v[242:243], v[242:243], v[94:95]
	v_pk_add_f32 v[236:237], v[236:237], v[84:85]
	v_pk_add_f32 v[238:239], v[238:239], v[88:89]
	v_pk_add_f32 v[240:241], v[240:241], v[92:93]
	v_pk_add_f32 v[242:243], v[242:243], v[96:97]
	v_pk_add_f32 v[236:237], v[236:237], v[98:99]
	v_pk_add_f32 v[238:239], v[238:239], v[102:103]
	v_pk_add_f32 v[240:241], v[240:241], v[106:107]
	v_pk_add_f32 v[242:243], v[242:243], v[110:111]
	v_pk_add_f32 v[236:237], v[236:237], v[100:101]
	v_pk_add_f32 v[238:239], v[238:239], v[104:105]
	v_pk_add_f32 v[240:241], v[240:241], v[108:109]
	v_pk_add_f32 v[242:243], v[242:243], v[112:113]
	v_pk_add_f32 v[236:237], v[236:237], v[114:115]
	v_pk_add_f32 v[236:237], v[236:237], v[116:117]
	v_pk_add_f32 v[236:237], v[236:237], v[238:239]
	v_pk_add_f32 v[240:241], v[240:241], v[242:243]
	v_cndmask_b32_e64 v219, 0, v219, s[74:75]
	v_pk_add_f32 v[236:237], v[236:237], v[240:241]
	v_add_f32_e32 v185, v236, v237
	v_add_f32_e32 v185, v185, v219
	v_cvt_pk_bf16_f32 v236, v50, v51
	v_cvt_pk_bf16_f32 v237, v52, v53
	v_cvt_pk_bf16_f32 v238, v54, v55
	v_cvt_pk_bf16_f32 v239, v56, v57
	s_nop 1
	s_waitcnt lgkmcnt(14)
; #define LAS __attribute__((address_space(3)))
; __device__ __forceinline__ unsigned pk2(float lo, float hi) { return pg8::cvt_pk_bf16(lo, hi); }
; __device__ __forceinline__ s16x4 vtr(const LAS unsigned char* p) { return __builtin_bit_cast(s16x4, __builtin_amdgcn_ds_read_tr16_b64_v4i16((LAS s16x4*)p)); }
; #define MFMA16(a, b, c) __builtin_amdgcn_mfma_f32_16x16x32_bf16((a), (b), (c), 0, 0, 0)
; __device__ __forceinline__ void pv_at(const LAS unsigned char* const (&vp)[4], int off, const f32x4& P0, const f32x4& P1, f32x4 (&O)[4]) {
;     v4u pw; pw.x = pk2(P0[0], P0[1]); pw.y = pk2(P0[2], P0[3]); pw.z = pk2(P1[0], P1[1]); pw.w = pk2(P1[2], P1[3]);
;     const bf16x8 pb = __builtin_bit_cast(bf16x8, pw);
; #pragma unroll
;     for (int db = 0; db < 4; ++db) {
;         const s16x4 lo = vtr(vp[db] + off), hi = vtr(vp[db] + off + 2048);
;         const bf16x8 vt = (bf16x8){lo[0], lo[1], lo[2], lo[3], hi[0], hi[1], hi[2], hi[3]};
;         O[db] = MFMA16(vt, pb, O[db]);
;     }
; }
	v_mfma_f32_16x16x32_bf16 v[210:213], v[186:189], v[236:239], 0
	s_waitcnt lgkmcnt(12)
	v_mfma_f32_16x16x32_bf16 v[214:217], v[190:193], v[236:239], 0
	s_waitcnt lgkmcnt(10)
	v_mfma_f32_16x16x32_bf16 v[220:223], v[194:197], v[236:239], 0
	s_waitcnt lgkmcnt(8)
	v_mfma_f32_16x16x32_bf16 v[224:227], v[198:201], v[236:239], 0
	v_cvt_pk_bf16_f32 v240, v58, v59
	v_cvt_pk_bf16_f32 v241, v60, v61
	v_cvt_pk_bf16_f32 v242, v62, v63
	v_cvt_pk_bf16_f32 v243, v64, v65
	s_waitcnt lgkmcnt(7)
	ds_read_b64_tr_b16 v[186:187], v124 offset:12288
	ds_read_b64_tr_b16 v[188:189], v124 offset:14336
	ds_read_b64_tr_b16 v[190:191], v125 offset:12288
	ds_read_b64_tr_b16 v[192:193], v125 offset:14336
	ds_read_b64_tr_b16 v[194:195], v126 offset:12288
	ds_read_b64_tr_b16 v[196:197], v126 offset:14336
	ds_read_b64_tr_b16 v[198:199], v127 offset:12288
	ds_read_b64_tr_b16 v[200:201], v127 offset:14336
	s_waitcnt lgkmcnt(14)
	v_mfma_f32_16x16x32_bf16 v[210:213], v[202:205], v[240:243], v[210:213]
	s_waitcnt lgkmcnt(12)
	v_mfma_f32_16x16x32_bf16 v[214:217], v[206:209], v[240:243], v[214:217]
	s_waitcnt lgkmcnt(10)
	v_mfma_f32_16x16x32_bf16 v[220:223], v[228:231], v[240:243], v[220:223]
	s_waitcnt lgkmcnt(8)
	v_mfma_f32_16x16x32_bf16 v[224:227], v[232:235], v[240:243], v[224:227]
	v_cvt_pk_bf16_f32 v236, v66, v67
	v_cvt_pk_bf16_f32 v237, v68, v69
	v_cvt_pk_bf16_f32 v238, v70, v71
	v_cvt_pk_bf16_f32 v239, v72, v73
	s_waitcnt lgkmcnt(7)
	ds_read_b64_tr_b16 v[202:203], v124 offset:16384
	ds_read_b64_tr_b16 v[204:205], v124 offset:18432
	ds_read_b64_tr_b16 v[206:207], v125 offset:16384
	ds_read_b64_tr_b16 v[208:209], v125 offset:18432
	ds_read_b64_tr_b16 v[228:229], v126 offset:16384
	ds_read_b64_tr_b16 v[230:231], v126 offset:18432
	ds_read_b64_tr_b16 v[232:233], v127 offset:16384
	ds_read_b64_tr_b16 v[234:235], v127 offset:18432
	s_waitcnt lgkmcnt(14)
	v_mfma_f32_16x16x32_bf16 v[210:213], v[186:189], v[236:239], v[210:213]
	s_waitcnt lgkmcnt(12)
	v_mfma_f32_16x16x32_bf16 v[214:217], v[190:193], v[236:239], v[214:217]
	s_waitcnt lgkmcnt(10)
	v_mfma_f32_16x16x32_bf16 v[220:223], v[194:197], v[236:239], v[220:223]
	s_waitcnt lgkmcnt(8)
	v_mfma_f32_16x16x32_bf16 v[224:227], v[198:201], v[236:239], v[224:227]
	v_cvt_pk_bf16_f32 v240, v74, v75
	v_cvt_pk_bf16_f32 v241, v76, v77
	v_cvt_pk_bf16_f32 v242, v78, v79
	v_cvt_pk_bf16_f32 v243, v80, v81
	s_waitcnt lgkmcnt(7)
	ds_read_b64_tr_b16 v[186:187], v124 offset:20480
	ds_read_b64_tr_b16 v[188:189], v124 offset:22528
	ds_read_b64_tr_b16 v[190:191], v125 offset:20480
	ds_read_b64_tr_b16 v[192:193], v125 offset:22528
	ds_read_b64_tr_b16 v[194:195], v126 offset:20480
	ds_read_b64_tr_b16 v[196:197], v126 offset:22528
	ds_read_b64_tr_b16 v[198:199], v127 offset:20480
	ds_read_b64_tr_b16 v[200:201], v127 offset:22528
	s_waitcnt lgkmcnt(14)
	v_mfma_f32_16x16x32_bf16 v[210:213], v[202:205], v[240:243], v[210:213]
	s_waitcnt lgkmcnt(12)
	v_mfma_f32_16x16x32_bf16 v[214:217], v[206:209], v[240:243], v[214:217]
	s_waitcnt lgkmcnt(10)
	v_mfma_f32_16x16x32_bf16 v[220:223], v[228:231], v[240:243], v[220:223]
	s_waitcnt lgkmcnt(8)
	v_mfma_f32_16x16x32_bf16 v[224:227], v[232:235], v[240:243], v[224:227]
	v_cvt_pk_bf16_f32 v236, v82, v83
	v_cvt_pk_bf16_f32 v237, v84, v85
	v_cvt_pk_bf16_f32 v238, v86, v87
	v_cvt_pk_bf16_f32 v239, v88, v89
	s_waitcnt lgkmcnt(7)
	ds_read_b64_tr_b16 v[202:203], v124 offset:24576
	ds_read_b64_tr_b16 v[204:205], v124 offset:26624
	ds_read_b64_tr_b16 v[206:207], v125 offset:24576
	ds_read_b64_tr_b16 v[208:209], v125 offset:26624
	ds_read_b64_tr_b16 v[228:229], v126 offset:24576
	ds_read_b64_tr_b16 v[230:231], v126 offset:26624
	ds_read_b64_tr_b16 v[232:233], v127 offset:24576
	ds_read_b64_tr_b16 v[234:235], v127 offset:26624
	s_waitcnt lgkmcnt(14)
	v_mfma_f32_16x16x32_bf16 v[210:213], v[186:189], v[236:239], v[210:213]
	s_waitcnt lgkmcnt(12)
	v_mfma_f32_16x16x32_bf16 v[214:217], v[190:193], v[236:239], v[214:217]
	s_waitcnt lgkmcnt(10)
	v_mfma_f32_16x16x32_bf16 v[220:223], v[194:197], v[236:239], v[220:223]
	s_waitcnt lgkmcnt(8)
	v_mfma_f32_16x16x32_bf16 v[224:227], v[198:201], v[236:239], v[224:227]
	v_cvt_pk_bf16_f32 v240, v90, v91
	v_cvt_pk_bf16_f32 v241, v92, v93
	v_cvt_pk_bf16_f32 v242, v94, v95
	v_cvt_pk_bf16_f32 v243, v96, v97
	s_waitcnt lgkmcnt(7)
	ds_read_b64_tr_b16 v[186:187], v124 offset:28672
	ds_read_b64_tr_b16 v[188:189], v124 offset:30720
	ds_read_b64_tr_b16 v[190:191], v125 offset:28672
	ds_read_b64_tr_b16 v[192:193], v125 offset:30720
	ds_read_b64_tr_b16 v[194:195], v126 offset:28672
	ds_read_b64_tr_b16 v[196:197], v126 offset:30720
	ds_read_b64_tr_b16 v[198:199], v127 offset:28672
	ds_read_b64_tr_b16 v[200:201], v127 offset:30720
	s_waitcnt lgkmcnt(14)
	v_mfma_f32_16x16x32_bf16 v[210:213], v[202:205], v[240:243], v[210:213]
	s_waitcnt lgkmcnt(12)
	v_mfma_f32_16x16x32_bf16 v[214:217], v[206:209], v[240:243], v[214:217]
	s_waitcnt lgkmcnt(10)
	v_mfma_f32_16x16x32_bf16 v[220:223], v[228:231], v[240:243], v[220:223]
	s_waitcnt lgkmcnt(8)
	v_mfma_f32_16x16x32_bf16 v[224:227], v[232:235], v[240:243], v[224:227]
	v_cvt_pk_bf16_f32 v236, v98, v99
	v_cvt_pk_bf16_f32 v237, v100, v101
	v_cvt_pk_bf16_f32 v238, v102, v103
	v_cvt_pk_bf16_f32 v239, v104, v105
	s_waitcnt lgkmcnt(7)
	ds_read_b64_tr_b16 v[202:203], v124 offset:32768
	ds_read_b64_tr_b16 v[204:205], v124 offset:34816
	ds_read_b64_tr_b16 v[206:207], v125 offset:32768
	ds_read_b64_tr_b16 v[208:209], v125 offset:34816
	ds_read_b64_tr_b16 v[228:229], v126 offset:32768
	ds_read_b64_tr_b16 v[230:231], v126 offset:34816
	ds_read_b64_tr_b16 v[232:233], v127 offset:32768
	ds_read_b64_tr_b16 v[234:235], v127 offset:34816
	s_waitcnt lgkmcnt(14)
; __device__ __forceinline__ unsigned pk2(float lo, float hi) { return pg8::cvt_pk_bf16(lo, hi); }
; __device__ __forceinline__ void store_o(bf16* yrow, int g, float l, const f32x4 (&O)[4]) {
;     const float inv = 1.0f / xrow16_sum(l);
;     unsigned wx[4], wy[4];
; #pragma unroll
;     for (int db = 0; db < 4; ++db) { wx[db] = pk2(O[db][0] * inv, O[db][1] * inv); wy[db] = pk2(O[db][2] * inv, O[db][3] * inv); }
; #pragma unroll
;     for (int p = 0; p < 2; ++p) {
;         auto rx = __builtin_amdgcn_permlane16_swap(wx[2 * p], wx[2 * p + 1], false, false); wx[2 * p] = rx[0]; wx[2 * p + 1] = rx[1];
;         auto ry = __builtin_amdgcn_permlane16_swap(wy[2 * p], wy[2 * p + 1], false, false); wy[2 * p] = ry[0]; wy[2 * p + 1] = ry[1]; }
; #pragma unroll
;     for (int p = 0; p < 2; ++p) {
;         auto rx = __builtin_amdgcn_permlane32_swap(wx[p], wx[p + 2], false, false); wx[p] = rx[0]; wx[p + 2] = rx[1];
;         auto ry = __builtin_amdgcn_permlane32_swap(wy[p], wy[p + 2], false, false); wy[p] = ry[0]; wy[p + 2] = ry[1]; }
;     v4u lo = {wx[0], wy[0], wx[1], wy[1]}, hi = {wx[2], wy[2], wx[3], wy[3]};
;     *(v4u*)(yrow + 16 * g) = lo; *(v4u*)(yrow + 16 * g + 8) = hi;
; }
; template <bool MASK> __device__ __forceinline__ void a_scores(f32x4& S0, f32x4& S1, float basef, float c1, float slope2, int krow0, int kstart) {
; #pragma unroll
;     for (int r = 0; r < 4; ++r) {
;         const float d0 = fabsf(basef - (float)r), d1 = fabsf(basef - (float)(16 + r));
;         const float v0 = S0[r] - slope2 * d0, v1 = S1[r] - slope2 * d1;
;         if (MASK) { const int p0 = kstart + krow0 + r, p1 = p0 + 16;
;             S0[r] = (d0 <= 128.f && p0 >= 0 && p0 < SEQ) ? v0 : -INFINITY; S1[r] = (d1 <= 128.f && p1 >= 0 && p1 < SEQ) ? v1 : -INFINITY; }
;         else { S0[r] = v0; S1[r] = v1; }
;     }
; }
	v_mfma_f32_16x16x32_bf16 v[210:213], v[186:189], v[236:239], v[210:213]
	s_waitcnt lgkmcnt(12)
	v_mfma_f32_16x16x32_bf16 v[214:217], v[190:193], v[236:239], v[214:217]
	s_waitcnt lgkmcnt(10)
	v_mfma_f32_16x16x32_bf16 v[220:223], v[194:197], v[236:239], v[220:223]
	s_waitcnt lgkmcnt(8)
	v_mfma_f32_16x16x32_bf16 v[224:227], v[198:201], v[236:239], v[224:227]
	v_cvt_pk_bf16_f32 v240, v106, v107
	v_cvt_pk_bf16_f32 v241, v108, v109
	v_cvt_pk_bf16_f32 v242, v110, v111
	v_cvt_pk_bf16_f32 v243, v112, v113
	s_waitcnt lgkmcnt(7)
	ds_read_b64_tr_b16 v[186:187], v124 offset:36864
	ds_read_b64_tr_b16 v[188:189], v124 offset:38912
	ds_read_b64_tr_b16 v[190:191], v125 offset:36864
	ds_read_b64_tr_b16 v[192:193], v125 offset:38912
	ds_read_b64_tr_b16 v[194:195], v126 offset:36864
	ds_read_b64_tr_b16 v[196:197], v126 offset:38912
	ds_read_b64_tr_b16 v[198:199], v127 offset:36864
	ds_read_b64_tr_b16 v[200:201], v127 offset:38912
	s_waitcnt lgkmcnt(14)
	v_mfma_f32_16x16x32_bf16 v[210:213], v[202:205], v[240:243], v[210:213]
	s_waitcnt lgkmcnt(12)
	v_mfma_f32_16x16x32_bf16 v[214:217], v[206:209], v[240:243], v[214:217]
	s_waitcnt lgkmcnt(10)
	v_mfma_f32_16x16x32_bf16 v[220:223], v[228:231], v[240:243], v[220:223]
	s_waitcnt lgkmcnt(8)
	v_mfma_f32_16x16x32_bf16 v[224:227], v[232:235], v[240:243], v[224:227]
	v_cvt_pk_bf16_f32 v236, v114, v115
	v_cvt_pk_bf16_f32 v237, v116, v117
	v_mov_b32_e32 v238, 0
	v_mov_b32_e32 v239, 0
	s_nop 1
	s_waitcnt lgkmcnt(6)
	v_mfma_f32_16x16x32_bf16 v[210:213], v[186:189], v[236:239], v[210:213]
	s_waitcnt lgkmcnt(4)
	v_mfma_f32_16x16x32_bf16 v[214:217], v[190:193], v[236:239], v[214:217]
	s_waitcnt lgkmcnt(2)
	v_mfma_f32_16x16x32_bf16 v[220:223], v[194:197], v[236:239], v[220:223]
	s_waitcnt lgkmcnt(0)
	v_mfma_f32_16x16x32_bf16 v[224:227], v[198:201], v[236:239], v[224:227]
	v_mov_b32_e32 v219, v185
	s_nop 1
	v_permlane16_swap_b32_e32 v185, v219
	v_add_f32_e32 v185, v185, v219
	v_mov_b32_e32 v219, v185
	s_nop 1
	v_permlane32_swap_b32_e32 v185, v219
	v_add_f32_e32 v185, v185, v219
	v_div_scale_f32 v236, s[78:79], v185, v185, 1.0
	v_div_scale_f32 v237, vcc, 1.0, v185, 1.0
	v_rcp_f32_e32 v238, v236
	s_nop 0
	v_fma_f32 v239, -v236, v238, 1.0
	v_fmac_f32_e32 v238, v239, v238
	v_mul_f32_e32 v240, v237, v238
	v_fma_f32 v241, -v236, v240, v237
	v_fmac_f32_e32 v240, v241, v238
	v_fma_f32 v237, -v236, v240, v237
	v_div_fmas_f32 v237, v237, v238, v240
	v_div_fixup_f32 v244, v237, v185, 1.0
	v_mul_f32_e32 v240, v210, v244
	v_mul_f32_e32 v241, v211, v244
	v_mul_f32_e32 v242, v212, v244
	v_mul_f32_e32 v243, v213, v244
	v_cvt_pk_bf16_f32 v186, v240, v241
	v_cvt_pk_bf16_f32 v187, v242, v243
	v_mul_f32_e32 v240, v214, v244
	v_mul_f32_e32 v241, v215, v244
	v_mul_f32_e32 v242, v216, v244
	v_mul_f32_e32 v243, v217, v244
	v_cvt_pk_bf16_f32 v188, v240, v241
	v_cvt_pk_bf16_f32 v189, v242, v243
	v_mul_f32_e32 v240, v220, v244
	v_mul_f32_e32 v241, v221, v244
	v_mul_f32_e32 v242, v222, v244
	v_mul_f32_e32 v243, v223, v244
	v_cvt_pk_bf16_f32 v190, v240, v241
	v_cvt_pk_bf16_f32 v191, v242, v243
	v_mul_f32_e32 v240, v224, v244
	v_mul_f32_e32 v241, v225, v244
	v_mul_f32_e32 v242, v226, v244
	v_mul_f32_e32 v243, v227, v244
	v_cvt_pk_bf16_f32 v192, v240, v241
	v_cvt_pk_bf16_f32 v193, v242, v243
	s_nop 1
	v_permlane16_swap_b32_e32 v186, v188
	v_permlane16_swap_b32_e32 v187, v189
	v_permlane16_swap_b32_e32 v190, v192
	v_permlane16_swap_b32_e32 v191, v193
	s_nop 0
	v_permlane32_swap_b32_e32 v186, v190
	v_permlane32_swap_b32_e32 v187, v191
	v_permlane32_swap_b32_e32 v188, v192
	v_permlane32_swap_b32_e32 v189, v193
	v_add_u32_e32 v219, 0x1000, v128
	global_store_dwordx4 v219, v[186:189], s[82:83] offset:0 sc1
	global_store_dwordx4 v219, v[190:193], s[82:83] offset:16 sc1
	s_nop 1
	v_fmamk_f32 v50, v130, 0x43000000, v132
	v_fmamk_f32 v51, v130, 0x42fe0000, v132
	v_fmamk_f32 v52, v130, 0x42fc0000, v132
	v_fmamk_f32 v53, v130, 0x42fa0000, v132
	v_fmamk_f32 v54, v130, 0x42e00000, v132
	v_fmamk_f32 v55, v130, 0x42de0000, v132
	v_fmamk_f32 v56, v130, 0x42dc0000, v132
	v_fmamk_f32 v57, v130, 0x42da0000, v132
	v_fmamk_f32 v58, v130, 0x42c00000, v132
	v_fmamk_f32 v59, v130, 0x42be0000, v132
	v_fmamk_f32 v60, v130, 0x42bc0000, v132
	v_fmamk_f32 v61, v130, 0x42ba0000, v132
	v_fmamk_f32 v62, v130, 0x42a00000, v132
	v_fmamk_f32 v63, v130, 0x429e0000, v132
	v_fmamk_f32 v64, v130, 0x429c0000, v132
	v_fmamk_f32 v65, v130, 0x429a0000, v132
	v_fmamk_f32 v66, v130, 0x42800000, v132
	v_fmamk_f32 v67, v130, 0x427c0000, v132
	v_fmamk_f32 v68, v130, 0x42780000, v132
	v_fmamk_f32 v69, v130, 0x42740000, v132
	v_fmamk_f32 v70, v130, 0x42400000, v132
	v_fmamk_f32 v71, v130, 0x423c0000, v132
	v_fmamk_f32 v72, v130, 0x42380000, v132
	v_fmamk_f32 v73, v130, 0x42340000, v132
	v_fmamk_f32 v74, v130, 0x42000000, v132
	v_fmamk_f32 v75, v130, 0x41f80000, v132
	v_fmamk_f32 v76, v130, 0x41f00000, v132
	v_fmamk_f32 v77, v130, 0x41e80000, v132
	v_fmamk_f32 v78, v130, 0x41800000, v132
	v_fmamk_f32 v79, v130, 0x41700000, v132
	v_fmamk_f32 v80, v130, 0x41600000, v132
	v_fmamk_f32 v81, v130, 0x41500000, v132
	v_add_f32_e32 v219, 0, v129
	v_mul_f32_e64 v82, v130, |v219|
	v_add_f32_e32 v244, 0xbf800000, v129
	v_mul_f32_e64 v83, v130, |v244|
	v_add_f32_e32 v219, 0xc0000000, v129
	v_mul_f32_e64 v84, v130, |v219|
	v_add_f32_e32 v244, 0xc0400000, v129
	v_mul_f32_e64 v85, v130, |v244|
	v_fmamk_f32 v86, v131, 0xc1800000, v133
	v_fmamk_f32 v87, v131, 0xc1880000, v133
	v_fmamk_f32 v88, v131, 0xc1900000, v133
	v_fmamk_f32 v89, v131, 0xc1980000, v133
	v_fmamk_f32 v90, v131, 0xc2000000, v133
	v_fmamk_f32 v91, v131, 0xc2040000, v133
	v_fmamk_f32 v92, v131, 0xc2080000, v133
	v_fmamk_f32 v93, v131, 0xc20c0000, v133
; #define LAS __attribute__((address_space(3)))
; #define MFMA16(a, b, c) __builtin_amdgcn_mfma_f32_16x16x32_bf16((a), (b), (c), 0, 0, 0)
; __device__ __forceinline__ void qk_at(const LAS unsigned char* kp0, const LAS unsigned char* kp1, int off, bf16x8 qf0, bf16x8 qf1, f32x4& S0, f32x4& S1) {
;     const bf16x8 k00 = *(const LAS bf16x8*)(kp0 + off), k01 = *(const LAS bf16x8*)(kp1 + off);
;     const bf16x8 k10 = *(const LAS bf16x8*)(kp0 + off + 2048), k11 = *(const LAS bf16x8*)(kp1 + off + 2048);
;     const f32x4 z = {0.f, 0.f, 0.f, 0.f};
;     S0 = MFMA16(k00, qf0, z); S0 = MFMA16(k01, qf1, S0);
;     S1 = MFMA16(k10, qf0, z); S1 = MFMA16(k11, qf1, S1);
; }
; template <bool MASK> __device__ __forceinline__ void a_scores(f32x4& S0, f32x4& S1, float basef, float c1, float slope2, int krow0, int kstart) {
; #pragma unroll
;     for (int r = 0; r < 4; ++r) {
;         const float d0 = fabsf(basef - (float)r), d1 = fabsf(basef - (float)(16 + r));
;         const float v0 = S0[r] - slope2 * d0, v1 = S1[r] - slope2 * d1;
;         if (MASK) { const int p0 = kstart + krow0 + r, p1 = p0 + 16;
;             S0[r] = (d0 <= 128.f && p0 >= 0 && p0 < SEQ) ? v0 : -INFINITY; S1[r] = (d1 <= 128.f && p1 >= 0 && p1 < SEQ) ? v1 : -INFINITY; }
;         else { S0[r] = v0; S1[r] = v1; }
;     }
; }
	v_fmamk_f32 v94, v131, 0xc2400000, v133
	v_fmamk_f32 v95, v131, 0xc2440000, v133
	v_fmamk_f32 v96, v131, 0xc2480000, v133
	v_fmamk_f32 v97, v131, 0xc24c0000, v133
	v_fmamk_f32 v98, v131, 0xc2800000, v133
	v_fmamk_f32 v99, v131, 0xc2820000, v133
	v_fmamk_f32 v100, v131, 0xc2840000, v133
	v_fmamk_f32 v101, v131, 0xc2860000, v133
	v_fmamk_f32 v102, v131, 0xc2a00000, v133
	v_fmamk_f32 v103, v131, 0xc2a20000, v133
	v_fmamk_f32 v104, v131, 0xc2a40000, v133
	v_fmamk_f32 v105, v131, 0xc2a60000, v133
	v_fmamk_f32 v106, v131, 0xc2c00000, v133
	v_fmamk_f32 v107, v131, 0xc2c20000, v133
	v_fmamk_f32 v108, v131, 0xc2c40000, v133
	v_fmamk_f32 v109, v131, 0xc2c60000, v133
	v_fmamk_f32 v110, v131, 0xc2e00000, v133
	v_fmamk_f32 v111, v131, 0xc2e20000, v133
	v_fmamk_f32 v112, v131, 0xc2e40000, v133
	v_fmamk_f32 v113, v131, 0xc2e60000, v133
	v_fmamk_f32 v114, v131, 0xc3000000, v133
	v_fmamk_f32 v115, v131, 0xc3010000, v133
	v_fmamk_f32 v116, v131, 0xc3020000, v133
	v_fmamk_f32 v117, v131, 0xc3030000, v133
	v_mov_b32_e32 v245, 0xff800000
	v_cndmask_b32_e64 v50, v245, v50, s[16:17]
	v_cndmask_b32_e64 v51, v245, v51, s[18:19]
	v_cndmask_b32_e64 v52, v245, v52, s[22:23]
	v_cndmask_b32_e64 v53, v245, v53, s[24:25]
	v_cndmask_b32_e64 v114, v245, v114, s[28:29]
	v_cndmask_b32_e64 v115, v245, v115, s[52:53]
	v_cndmask_b32_e64 v116, v245, v116, s[54:55]
	v_cndmask_b32_e64 v117, v245, v117, s[88:89]
	ds_read_b128 v[186:189], v122 offset:6144
	ds_read_b128 v[190:193], v123 offset:6144
	ds_read_b128 v[194:197], v122 offset:8192
	ds_read_b128 v[198:201], v123 offset:8192
	ds_read_b128 v[202:205], v122 offset:10240
	ds_read_b128 v[206:209], v123 offset:10240
	s_waitcnt lgkmcnt(5)
	v_mfma_f32_16x16x32_bf16 v[50:53], v[186:189], v[170:173], v[50:53]
	s_waitcnt lgkmcnt(4)
	v_mfma_f32_16x16x32_bf16 v[50:53], v[190:193], v[174:177], v[50:53]
	ds_read_b128 v[186:189], v122 offset:12288
	ds_read_b128 v[190:193], v123 offset:12288
	s_waitcnt lgkmcnt(5)
	v_mfma_f32_16x16x32_bf16 v[54:57], v[194:197], v[170:173], v[54:57]
	s_waitcnt lgkmcnt(4)
	v_mfma_f32_16x16x32_bf16 v[54:57], v[198:201], v[174:177], v[54:57]
	ds_read_b128 v[194:197], v122 offset:14336
	ds_read_b128 v[198:201], v123 offset:14336
	s_waitcnt lgkmcnt(5)
	v_mfma_f32_16x16x32_bf16 v[58:61], v[202:205], v[170:173], v[58:61]
	s_waitcnt lgkmcnt(4)
	v_mfma_f32_16x16x32_bf16 v[58:61], v[206:209], v[174:177], v[58:61]
	ds_read_b128 v[202:205], v122 offset:16384
	ds_read_b128 v[206:209], v123 offset:16384
	s_waitcnt lgkmcnt(5)
	v_mfma_f32_16x16x32_bf16 v[62:65], v[186:189], v[170:173], v[62:65]
	s_waitcnt lgkmcnt(4)
	v_mfma_f32_16x16x32_bf16 v[62:65], v[190:193], v[174:177], v[62:65]
	ds_read_b128 v[186:189], v122 offset:18432
	ds_read_b128 v[190:193], v123 offset:18432
	s_waitcnt lgkmcnt(5)
	v_mfma_f32_16x16x32_bf16 v[66:69], v[194:197], v[170:173], v[66:69]
	s_waitcnt lgkmcnt(4)
	v_mfma_f32_16x16x32_bf16 v[66:69], v[198:201], v[174:177], v[66:69]
	ds_read_b128 v[194:197], v122 offset:20480
	ds_read_b128 v[198:201], v123 offset:20480
	s_waitcnt lgkmcnt(5)
	v_mfma_f32_16x16x32_bf16 v[70:73], v[202:205], v[170:173], v[70:73]
	s_waitcnt lgkmcnt(4)
	v_mfma_f32_16x16x32_bf16 v[70:73], v[206:209], v[174:177], v[70:73]
	ds_read_b128 v[202:205], v122 offset:22528
	ds_read_b128 v[206:209], v123 offset:22528
	s_waitcnt lgkmcnt(5)
	v_mfma_f32_16x16x32_bf16 v[74:77], v[186:189], v[170:173], v[74:77]
	s_waitcnt lgkmcnt(4)
	v_mfma_f32_16x16x32_bf16 v[74:77], v[190:193], v[174:177], v[74:77]
	ds_read_b128 v[186:189], v122 offset:24576
	ds_read_b128 v[190:193], v123 offset:24576
	s_waitcnt lgkmcnt(5)
	v_mfma_f32_16x16x32_bf16 v[78:81], v[194:197], v[170:173], v[78:81]
	s_waitcnt lgkmcnt(4)
	v_mfma_f32_16x16x32_bf16 v[78:81], v[198:201], v[174:177], v[78:81]
	ds_read_b128 v[194:197], v122 offset:26624
	ds_read_b128 v[198:201], v123 offset:26624
	s_waitcnt lgkmcnt(5)
	v_mfma_f32_16x16x32_bf16 v[82:85], v[202:205], v[170:173], v[82:85]
	s_waitcnt lgkmcnt(4)
	v_mfma_f32_16x16x32_bf16 v[82:85], v[206:209], v[174:177], v[82:85]
	ds_read_b128 v[202:205], v122 offset:28672
	ds_read_b128 v[206:209], v123 offset:28672
	s_waitcnt lgkmcnt(5)
	v_mfma_f32_16x16x32_bf16 v[86:89], v[186:189], v[170:173], v[86:89]
	s_waitcnt lgkmcnt(4)
	v_mfma_f32_16x16x32_bf16 v[86:89], v[190:193], v[174:177], v[86:89]
	ds_read_b128 v[186:189], v122 offset:30720
	ds_read_b128 v[190:193], v123 offset:30720
	s_waitcnt lgkmcnt(5)
	v_mfma_f32_16x16x32_bf16 v[90:93], v[194:197], v[170:173], v[90:93]
	s_waitcnt lgkmcnt(4)
	v_mfma_f32_16x16x32_bf16 v[90:93], v[198:201], v[174:177], v[90:93]
	ds_read_b128 v[194:197], v122 offset:32768
	ds_read_b128 v[198:201], v123 offset:32768
	s_waitcnt lgkmcnt(5)
	v_mfma_f32_16x16x32_bf16 v[94:97], v[202:205], v[170:173], v[94:97]
	s_waitcnt lgkmcnt(4)
	v_mfma_f32_16x16x32_bf16 v[94:97], v[206:209], v[174:177], v[94:97]
	ds_read_b128 v[202:205], v122 offset:34816
	ds_read_b128 v[206:209], v123 offset:34816
	s_waitcnt lgkmcnt(5)
	v_mfma_f32_16x16x32_bf16 v[98:101], v[186:189], v[170:173], v[98:101]
	s_waitcnt lgkmcnt(4)
	v_mfma_f32_16x16x32_bf16 v[98:101], v[190:193], v[174:177], v[98:101]
	ds_read_b128 v[186:189], v122 offset:36864
	ds_read_b128 v[190:193], v123 offset:36864
	s_waitcnt lgkmcnt(5)
	v_mfma_f32_16x16x32_bf16 v[102:105], v[194:197], v[170:173], v[102:105]
	s_waitcnt lgkmcnt(4)
	v_mfma_f32_16x16x32_bf16 v[102:105], v[198:201], v[174:177], v[102:105]
	ds_read_b128 v[194:197], v122 offset:38912
	ds_read_b128 v[198:201], v123 offset:38912
	s_waitcnt lgkmcnt(5)
	v_mfma_f32_16x16x32_bf16 v[106:109], v[202:205], v[170:173], v[106:109]
	s_waitcnt lgkmcnt(4)
	v_mfma_f32_16x16x32_bf16 v[106:109], v[206:209], v[174:177], v[106:109]
	s_waitcnt lgkmcnt(3)
; #define LAS __attribute__((address_space(3)))
; #define MFMA16(a, b, c) __builtin_amdgcn_mfma_f32_16x16x32_bf16((a), (b), (c), 0, 0, 0)
; __device__ __forceinline__ void qk_at(const LAS unsigned char* kp0, const LAS unsigned char* kp1, int off, bf16x8 qf0, bf16x8 qf1, f32x4& S0, f32x4& S1) {
;     const bf16x8 k00 = *(const LAS bf16x8*)(kp0 + off), k01 = *(const LAS bf16x8*)(kp1 + off);
;     const bf16x8 k10 = *(const LAS bf16x8*)(kp0 + off + 2048), k11 = *(const LAS bf16x8*)(kp1 + off + 2048);
;     const f32x4 z = {0.f, 0.f, 0.f, 0.f};
;     S0 = MFMA16(k00, qf0, z); S0 = MFMA16(k01, qf1, S0);
;     S1 = MFMA16(k10, qf0, z); S1 = MFMA16(k11, qf1, S1);
; }
; __device__ __forceinline__ void softmax_step(f32x4& s0, f32x4& s1, float& m, float& l, f32x4 (&O)[4]) {
;     float t = fmaxf(fmaxf(fmaxf(s0[0], s0[1]), fmaxf(s0[2], s0[3])), fmaxf(fmaxf(s1[0], s1[1]), fmaxf(s1[2], s1[3])));
;     t = xrow16_max(t);
;     const float mn = fmaxf(m, t), alpha = __builtin_amdgcn_exp2f(m - mn);
;     m = mn;
; #pragma unroll
;     for (int k = 0; k < 4; ++k) { s0[k] = __builtin_amdgcn_exp2f(s0[k] - mn); s1[k] = __builtin_amdgcn_exp2f(s1[k] - mn); }
	v_mfma_f32_16x16x32_bf16 v[110:113], v[186:189], v[170:173], v[110:113]
	s_waitcnt lgkmcnt(2)
	v_mfma_f32_16x16x32_bf16 v[110:113], v[190:193], v[174:177], v[110:113]
	s_waitcnt lgkmcnt(1)
	v_mfma_f32_16x16x32_bf16 v[114:117], v[194:197], v[170:173], v[114:117]
	s_waitcnt lgkmcnt(0)
	v_mfma_f32_16x16x32_bf16 v[114:117], v[198:201], v[174:177], v[114:117]
	v_max3_f32 v219, v50, v51, v52
	v_max3_f32 v244, v54, v55, v56
	v_max3_f32 v245, v58, v59, v60
	v_max3_f32 v120, v62, v63, v64
	v_max3_f32 v219, v219, v53, v66
	v_max3_f32 v244, v244, v57, v70
	v_max3_f32 v245, v245, v61, v74
	v_max3_f32 v120, v120, v65, v78
	v_max3_f32 v219, v219, v67, v68
	v_max3_f32 v244, v244, v71, v72
	v_max3_f32 v245, v245, v75, v76
	v_max3_f32 v120, v120, v79, v80
	ds_read_b64_tr_b16 v[186:187], v124 offset:6144
	ds_read_b64_tr_b16 v[188:189], v124 offset:8192
	ds_read_b64_tr_b16 v[190:191], v125 offset:6144
	ds_read_b64_tr_b16 v[192:193], v125 offset:8192
	ds_read_b64_tr_b16 v[194:195], v126 offset:6144
	ds_read_b64_tr_b16 v[196:197], v126 offset:8192
	ds_read_b64_tr_b16 v[198:199], v127 offset:6144
	ds_read_b64_tr_b16 v[200:201], v127 offset:8192
	v_max3_f32 v219, v219, v69, v82
	v_max3_f32 v244, v244, v73, v86
	v_max3_f32 v245, v245, v77, v90
	v_max3_f32 v120, v120, v81, v94
	v_max3_f32 v219, v219, v83, v84
	v_max3_f32 v244, v244, v87, v88
	v_max3_f32 v245, v245, v91, v92
	v_max3_f32 v120, v120, v95, v96
	v_max3_f32 v219, v219, v85, v98
	v_max3_f32 v244, v244, v89, v102
	v_max3_f32 v245, v245, v93, v106
	v_max3_f32 v120, v120, v97, v110
	v_max3_f32 v219, v219, v99, v100
	v_max3_f32 v244, v244, v103, v104
	v_max3_f32 v245, v245, v107, v108
	v_max3_f32 v120, v120, v111, v112
	v_max3_f32 v219, v219, v101, v114
	v_max3_f32 v219, v219, v115, v116
	v_max_f32_e32 v219, v219, v117
	v_max_f32_e32 v244, v244, v105
	v_max_f32_e32 v245, v245, v109
	v_max_f32_e32 v120, v120, v113
	v_max3_f32 v178, v219, v244, v245
	v_max_f32_e32 v178, v178, v120
	v_mov_b32_e32 v219, v178
	s_nop 1
	v_permlane16_swap_b32_e32 v178, v219
	v_max_f32_e32 v178, v178, v219
	v_mov_b32_e32 v219, v178
	s_nop 1
	v_permlane32_swap_b32_e32 v178, v219
	v_max3_f32 v178, v178, v219, v145
	s_waitcnt lgkmcnt(7)
	ds_read_b64_tr_b16 v[202:203], v124 offset:10240
	ds_read_b64_tr_b16 v[204:205], v124 offset:12288
	ds_read_b64_tr_b16 v[206:207], v125 offset:10240
	ds_read_b64_tr_b16 v[208:209], v125 offset:12288
	ds_read_b64_tr_b16 v[228:229], v126 offset:10240
	ds_read_b64_tr_b16 v[230:231], v126 offset:12288
	ds_read_b64_tr_b16 v[232:233], v127 offset:10240
	ds_read_b64_tr_b16 v[234:235], v127 offset:12288
	v_mov_b32_e32 v244, v178
	v_pk_add_f32 v[50:51], v[50:51], v[244:245] op_sel_hi:[1,0] neg_lo:[0,1] neg_hi:[0,1]
	v_pk_add_f32 v[52:53], v[52:53], v[244:245] op_sel_hi:[1,0] neg_lo:[0,1] neg_hi:[0,1]
	v_pk_add_f32 v[54:55], v[54:55], v[244:245] op_sel_hi:[1,0] neg_lo:[0,1] neg_hi:[0,1]
	v_pk_add_f32 v[56:57], v[56:57], v[244:245] op_sel_hi:[1,0] neg_lo:[0,1] neg_hi:[0,1]
	v_pk_add_f32 v[58:59], v[58:59], v[244:245] op_sel_hi:[1,0] neg_lo:[0,1] neg_hi:[0,1]
	v_pk_add_f32 v[60:61], v[60:61], v[244:245] op_sel_hi:[1,0] neg_lo:[0,1] neg_hi:[0,1]
	v_pk_add_f32 v[62:63], v[62:63], v[244:245] op_sel_hi:[1,0] neg_lo:[0,1] neg_hi:[0,1]
	v_pk_add_f32 v[64:65], v[64:65], v[244:245] op_sel_hi:[1,0] neg_lo:[0,1] neg_hi:[0,1]
	v_pk_add_f32 v[66:67], v[66:67], v[244:245] op_sel_hi:[1,0] neg_lo:[0,1] neg_hi:[0,1]
	v_pk_add_f32 v[68:69], v[68:69], v[244:245] op_sel_hi:[1,0] neg_lo:[0,1] neg_hi:[0,1]
	v_pk_add_f32 v[70:71], v[70:71], v[244:245] op_sel_hi:[1,0] neg_lo:[0,1] neg_hi:[0,1]
	v_pk_add_f32 v[72:73], v[72:73], v[244:245] op_sel_hi:[1,0] neg_lo:[0,1] neg_hi:[0,1]
	v_pk_add_f32 v[74:75], v[74:75], v[244:245] op_sel_hi:[1,0] neg_lo:[0,1] neg_hi:[0,1]
	v_pk_add_f32 v[76:77], v[76:77], v[244:245] op_sel_hi:[1,0] neg_lo:[0,1] neg_hi:[0,1]
	v_pk_add_f32 v[78:79], v[78:79], v[244:245] op_sel_hi:[1,0] neg_lo:[0,1] neg_hi:[0,1]
	v_pk_add_f32 v[80:81], v[80:81], v[244:245] op_sel_hi:[1,0] neg_lo:[0,1] neg_hi:[0,1]
	v_pk_add_f32 v[82:83], v[82:83], v[244:245] op_sel_hi:[1,0] neg_lo:[0,1] neg_hi:[0,1]
	v_pk_add_f32 v[84:85], v[84:85], v[244:245] op_sel_hi:[1,0] neg_lo:[0,1] neg_hi:[0,1]
	v_pk_add_f32 v[86:87], v[86:87], v[244:245] op_sel_hi:[1,0] neg_lo:[0,1] neg_hi:[0,1]
	v_pk_add_f32 v[88:89], v[88:89], v[244:245] op_sel_hi:[1,0] neg_lo:[0,1] neg_hi:[0,1]
	v_pk_add_f32 v[90:91], v[90:91], v[244:245] op_sel_hi:[1,0] neg_lo:[0,1] neg_hi:[0,1]
	v_pk_add_f32 v[92:93], v[92:93], v[244:245] op_sel_hi:[1,0] neg_lo:[0,1] neg_hi:[0,1]
	v_pk_add_f32 v[94:95], v[94:95], v[244:245] op_sel_hi:[1,0] neg_lo:[0,1] neg_hi:[0,1]
	v_pk_add_f32 v[96:97], v[96:97], v[244:245] op_sel_hi:[1,0] neg_lo:[0,1] neg_hi:[0,1]
	v_pk_add_f32 v[98:99], v[98:99], v[244:245] op_sel_hi:[1,0] neg_lo:[0,1] neg_hi:[0,1]
	v_pk_add_f32 v[100:101], v[100:101], v[244:245] op_sel_hi:[1,0] neg_lo:[0,1] neg_hi:[0,1]
	v_pk_add_f32 v[102:103], v[102:103], v[244:245] op_sel_hi:[1,0] neg_lo:[0,1] neg_hi:[0,1]
	v_pk_add_f32 v[104:105], v[104:105], v[244:245] op_sel_hi:[1,0] neg_lo:[0,1] neg_hi:[0,1]
	v_pk_add_f32 v[106:107], v[106:107], v[244:245] op_sel_hi:[1,0] neg_lo:[0,1] neg_hi:[0,1]
	v_pk_add_f32 v[108:109], v[108:109], v[244:245] op_sel_hi:[1,0] neg_lo:[0,1] neg_hi:[0,1]
	v_pk_add_f32 v[110:111], v[110:111], v[244:245] op_sel_hi:[1,0] neg_lo:[0,1] neg_hi:[0,1]
	v_pk_add_f32 v[112:113], v[112:113], v[244:245] op_sel_hi:[1,0] neg_lo:[0,1] neg_hi:[0,1]
	v_pk_add_f32 v[114:115], v[114:115], v[244:245] op_sel_hi:[1,0] neg_lo:[0,1] neg_hi:[0,1]
	v_pk_add_f32 v[116:117], v[116:117], v[244:245] op_sel_hi:[1,0] neg_lo:[0,1] neg_hi:[0,1]
	v_sub_f32_e32 v219, v145, v178
; #define LAS __attribute__((address_space(3)))
; __device__ __forceinline__ unsigned pk2(float lo, float hi) { return pg8::cvt_pk_bf16(lo, hi); }
; __device__ __forceinline__ s16x4 vtr(const LAS unsigned char* p) { return __builtin_bit_cast(s16x4, __builtin_amdgcn_ds_read_tr16_b64_v4i16((LAS s16x4*)p)); }
; #define MFMA16(a, b, c) __builtin_amdgcn_mfma_f32_16x16x32_bf16((a), (b), (c), 0, 0, 0)
; __device__ __forceinline__ void pv_at(const LAS unsigned char* const (&vp)[4], int off, const f32x4& P0, const f32x4& P1, f32x4 (&O)[4]) {
;     v4u pw; pw.x = pk2(P0[0], P0[1]); pw.y = pk2(P0[2], P0[3]); pw.z = pk2(P1[0], P1[1]); pw.w = pk2(P1[2], P1[3]);
;     const bf16x8 pb = __builtin_bit_cast(bf16x8, pw);
; #pragma unroll
;     for (int db = 0; db < 4; ++db) {
;         const s16x4 lo = vtr(vp[db] + off), hi = vtr(vp[db] + off + 2048);
;         const bf16x8 vt = (bf16x8){lo[0], lo[1], lo[2], lo[3], hi[0], hi[1], hi[2], hi[3]};
;         O[db] = MFMA16(vt, pb, O[db]);
;     }
; }
; __device__ __forceinline__ void softmax_step(f32x4& s0, f32x4& s1, float& m, float& l, f32x4 (&O)[4]) {
;     float t = fmaxf(fmaxf(fmaxf(s0[0], s0[1]), fmaxf(s0[2], s0[3])), fmaxf(fmaxf(s1[0], s1[1]), fmaxf(s1[2], s1[3])));
;     t = xrow16_max(t);
;     const float mn = fmaxf(m, t), alpha = __builtin_amdgcn_exp2f(m - mn);
;     m = mn;
; #pragma unroll
;     for (int k = 0; k < 4; ++k) { s0[k] = __builtin_amdgcn_exp2f(s0[k] - mn); s1[k] = __builtin_amdgcn_exp2f(s1[k] - mn); }
;     l = l * alpha + ((s0[0] + s0[1]) + (s0[2] + s0[3])) + ((s1[0] + s1[1]) + (s1[2] + s1[3]));
	v_exp_f32_e32 v50, v50
	v_exp_f32_e32 v51, v51
	v_exp_f32_e32 v52, v52
	v_exp_f32_e32 v53, v53
	v_exp_f32_e32 v54, v54
	v_exp_f32_e32 v55, v55
	v_exp_f32_e32 v56, v56
	v_exp_f32_e32 v57, v57
	v_exp_f32_e32 v58, v58
	v_exp_f32_e32 v59, v59
	v_exp_f32_e32 v60, v60
	v_exp_f32_e32 v61, v61
	v_exp_f32_e32 v62, v62
	v_exp_f32_e32 v63, v63
	v_exp_f32_e32 v64, v64
	v_exp_f32_e32 v65, v65
	v_exp_f32_e32 v66, v66
	v_exp_f32_e32 v67, v67
	v_exp_f32_e32 v68, v68
	v_exp_f32_e32 v69, v69
	v_exp_f32_e32 v70, v70
	v_exp_f32_e32 v71, v71
	v_exp_f32_e32 v72, v72
	v_exp_f32_e32 v73, v73
	v_exp_f32_e32 v74, v74
	v_exp_f32_e32 v75, v75
	v_exp_f32_e32 v76, v76
	v_exp_f32_e32 v77, v77
	v_exp_f32_e32 v78, v78
	v_exp_f32_e32 v79, v79
	v_exp_f32_e32 v80, v80
	v_exp_f32_e32 v81, v81
	v_exp_f32_e32 v82, v82
	v_exp_f32_e32 v83, v83
	v_exp_f32_e32 v84, v84
	v_exp_f32_e32 v85, v85
	v_exp_f32_e32 v86, v86
	v_exp_f32_e32 v87, v87
	v_exp_f32_e32 v88, v88
	v_exp_f32_e32 v89, v89
	v_exp_f32_e32 v90, v90
	v_exp_f32_e32 v91, v91
	v_exp_f32_e32 v92, v92
	v_exp_f32_e32 v93, v93
	v_exp_f32_e32 v94, v94
	v_exp_f32_e32 v95, v95
	v_exp_f32_e32 v96, v96
	v_exp_f32_e32 v97, v97
	v_exp_f32_e32 v98, v98
	v_exp_f32_e32 v99, v99
	v_exp_f32_e32 v100, v100
	v_exp_f32_e32 v101, v101
	v_exp_f32_e32 v102, v102
	v_exp_f32_e32 v103, v103
	v_exp_f32_e32 v104, v104
	v_exp_f32_e32 v105, v105
	v_exp_f32_e32 v106, v106
	v_exp_f32_e32 v107, v107
	v_exp_f32_e32 v108, v108
	v_exp_f32_e32 v109, v109
	v_exp_f32_e32 v110, v110
	v_exp_f32_e32 v111, v111
	v_exp_f32_e32 v112, v112
	v_exp_f32_e32 v113, v113
	v_exp_f32_e32 v114, v114
	v_exp_f32_e32 v115, v115
	v_exp_f32_e32 v116, v116
	v_exp_f32_e32 v117, v117
	v_exp_f32_e32 v219, v219
	v_pk_add_f32 v[236:237], v[50:51], v[52:53]
	v_pk_add_f32 v[238:239], v[54:55], v[56:57]
	v_pk_add_f32 v[240:241], v[58:59], v[60:61]
	v_pk_add_f32 v[242:243], v[62:63], v[64:65]
	v_pk_add_f32 v[236:237], v[236:237], v[66:67]
	v_pk_add_f32 v[238:239], v[238:239], v[70:71]
	v_pk_add_f32 v[240:241], v[240:241], v[74:75]
	v_pk_add_f32 v[242:243], v[242:243], v[78:79]
	v_pk_add_f32 v[236:237], v[236:237], v[68:69]
	v_pk_add_f32 v[238:239], v[238:239], v[72:73]
	v_pk_add_f32 v[240:241], v[240:241], v[76:77]
	v_pk_add_f32 v[242:243], v[242:243], v[80:81]
	v_pk_add_f32 v[236:237], v[236:237], v[82:83]
	v_pk_add_f32 v[238:239], v[238:239], v[86:87]
	v_pk_add_f32 v[240:241], v[240:241], v[90:91]
	v_pk_add_f32 v[242:243], v[242:243], v[94:95]
	v_pk_add_f32 v[236:237], v[236:237], v[84:85]
	v_pk_add_f32 v[238:239], v[238:239], v[88:89]
	v_pk_add_f32 v[240:241], v[240:241], v[92:93]
	v_pk_add_f32 v[242:243], v[242:243], v[96:97]
	v_pk_add_f32 v[236:237], v[236:237], v[98:99]
	v_pk_add_f32 v[238:239], v[238:239], v[102:103]
	v_pk_add_f32 v[240:241], v[240:241], v[106:107]
	v_pk_add_f32 v[242:243], v[242:243], v[110:111]
	v_pk_add_f32 v[236:237], v[236:237], v[100:101]
	v_pk_add_f32 v[238:239], v[238:239], v[104:105]
	v_pk_add_f32 v[240:241], v[240:241], v[108:109]
	v_pk_add_f32 v[242:243], v[242:243], v[112:113]
	v_pk_add_f32 v[236:237], v[236:237], v[114:115]
	v_pk_add_f32 v[236:237], v[236:237], v[116:117]
	v_pk_add_f32 v[236:237], v[236:237], v[238:239]
	v_pk_add_f32 v[240:241], v[240:241], v[242:243]
	v_cndmask_b32_e64 v219, 0, v219, s[74:75]
	v_pk_add_f32 v[236:237], v[236:237], v[240:241]
	v_add_f32_e32 v185, v236, v237
	v_add_f32_e32 v185, v185, v219
	v_cvt_pk_bf16_f32 v236, v50, v51
	v_cvt_pk_bf16_f32 v237, v52, v53
	v_cvt_pk_bf16_f32 v238, v54, v55
	v_cvt_pk_bf16_f32 v239, v56, v57
	s_nop 1
	s_waitcnt lgkmcnt(14)
	v_mfma_f32_16x16x32_bf16 v[210:213], v[186:189], v[236:239], 0
	s_waitcnt lgkmcnt(12)
	v_mfma_f32_16x16x32_bf16 v[214:217], v[190:193], v[236:239], 0
	s_waitcnt lgkmcnt(10)
	v_mfma_f32_16x16x32_bf16 v[220:223], v[194:197], v[236:239], 0
	s_waitcnt lgkmcnt(8)
	v_mfma_f32_16x16x32_bf16 v[224:227], v[198:201], v[236:239], 0
	v_cvt_pk_bf16_f32 v240, v58, v59
	v_cvt_pk_bf16_f32 v241, v60, v61
	v_cvt_pk_bf16_f32 v242, v62, v63
	v_cvt_pk_bf16_f32 v243, v64, v65
	s_waitcnt lgkmcnt(7)
	ds_read_b64_tr_b16 v[186:187], v124 offset:14336
	ds_read_b64_tr_b16 v[188:189], v124 offset:16384
	ds_read_b64_tr_b16 v[190:191], v125 offset:14336
	ds_read_b64_tr_b16 v[192:193], v125 offset:16384
	ds_read_b64_tr_b16 v[194:195], v126 offset:14336
	ds_read_b64_tr_b16 v[196:197], v126 offset:16384
	ds_read_b64_tr_b16 v[198:199], v127 offset:14336
	ds_read_b64_tr_b16 v[200:201], v127 offset:16384
	s_waitcnt lgkmcnt(14)
	v_mfma_f32_16x16x32_bf16 v[210:213], v[202:205], v[240:243], v[210:213]
	s_waitcnt lgkmcnt(12)
	v_mfma_f32_16x16x32_bf16 v[214:217], v[206:209], v[240:243], v[214:217]
	s_waitcnt lgkmcnt(10)
	v_mfma_f32_16x16x32_bf16 v[220:223], v[228:231], v[240:243], v[220:223]
	s_waitcnt lgkmcnt(8)
	v_mfma_f32_16x16x32_bf16 v[224:227], v[232:235], v[240:243], v[224:227]
	v_cvt_pk_bf16_f32 v236, v66, v67
	v_cvt_pk_bf16_f32 v237, v68, v69
	v_cvt_pk_bf16_f32 v238, v70, v71
	v_cvt_pk_bf16_f32 v239, v72, v73
	s_waitcnt lgkmcnt(7)
	ds_read_b64_tr_b16 v[202:203], v124 offset:18432
	ds_read_b64_tr_b16 v[204:205], v124 offset:20480
	ds_read_b64_tr_b16 v[206:207], v125 offset:18432
	ds_read_b64_tr_b16 v[208:209], v125 offset:20480
	ds_read_b64_tr_b16 v[228:229], v126 offset:18432
	ds_read_b64_tr_b16 v[230:231], v126 offset:20480
	ds_read_b64_tr_b16 v[232:233], v127 offset:18432
	ds_read_b64_tr_b16 v[234:235], v127 offset:20480
	s_waitcnt lgkmcnt(14)
	v_mfma_f32_16x16x32_bf16 v[210:213], v[186:189], v[236:239], v[210:213]
	s_waitcnt lgkmcnt(12)
	v_mfma_f32_16x16x32_bf16 v[214:217], v[190:193], v[236:239], v[214:217]
	s_waitcnt lgkmcnt(10)
	v_mfma_f32_16x16x32_bf16 v[220:223], v[194:197], v[236:239], v[220:223]
	s_waitcnt lgkmcnt(8)
; #define LAS __attribute__((address_space(3)))
; __device__ __forceinline__ unsigned pk2(float lo, float hi) { return pg8::cvt_pk_bf16(lo, hi); }
; __device__ __forceinline__ s16x4 vtr(const LAS unsigned char* p) { return __builtin_bit_cast(s16x4, __builtin_amdgcn_ds_read_tr16_b64_v4i16((LAS s16x4*)p)); }
; #define MFMA16(a, b, c) __builtin_amdgcn_mfma_f32_16x16x32_bf16((a), (b), (c), 0, 0, 0)
; __device__ __forceinline__ void pv_at(const LAS unsigned char* const (&vp)[4], int off, const f32x4& P0, const f32x4& P1, f32x4 (&O)[4]) {
;     v4u pw; pw.x = pk2(P0[0], P0[1]); pw.y = pk2(P0[2], P0[3]); pw.z = pk2(P1[0], P1[1]); pw.w = pk2(P1[2], P1[3]);
;     const bf16x8 pb = __builtin_bit_cast(bf16x8, pw);
; #pragma unroll
;     for (int db = 0; db < 4; ++db) {
;         const s16x4 lo = vtr(vp[db] + off), hi = vtr(vp[db] + off + 2048);
;         const bf16x8 vt = (bf16x8){lo[0], lo[1], lo[2], lo[3], hi[0], hi[1], hi[2], hi[3]};
;         O[db] = MFMA16(vt, pb, O[db]);
;     }
; }
	v_mfma_f32_16x16x32_bf16 v[224:227], v[198:201], v[236:239], v[224:227]
	v_cvt_pk_bf16_f32 v240, v74, v75
	v_cvt_pk_bf16_f32 v241, v76, v77
	v_cvt_pk_bf16_f32 v242, v78, v79
	v_cvt_pk_bf16_f32 v243, v80, v81
	s_waitcnt lgkmcnt(7)
	ds_read_b64_tr_b16 v[186:187], v124 offset:22528
	ds_read_b64_tr_b16 v[188:189], v124 offset:24576
	ds_read_b64_tr_b16 v[190:191], v125 offset:22528
	ds_read_b64_tr_b16 v[192:193], v125 offset:24576
	ds_read_b64_tr_b16 v[194:195], v126 offset:22528
	ds_read_b64_tr_b16 v[196:197], v126 offset:24576
	ds_read_b64_tr_b16 v[198:199], v127 offset:22528
	ds_read_b64_tr_b16 v[200:201], v127 offset:24576
	s_waitcnt lgkmcnt(14)
	v_mfma_f32_16x16x32_bf16 v[210:213], v[202:205], v[240:243], v[210:213]
	s_waitcnt lgkmcnt(12)
	v_mfma_f32_16x16x32_bf16 v[214:217], v[206:209], v[240:243], v[214:217]
	s_waitcnt lgkmcnt(10)
	v_mfma_f32_16x16x32_bf16 v[220:223], v[228:231], v[240:243], v[220:223]
	s_waitcnt lgkmcnt(8)
	v_mfma_f32_16x16x32_bf16 v[224:227], v[232:235], v[240:243], v[224:227]
	v_cvt_pk_bf16_f32 v236, v82, v83
	v_cvt_pk_bf16_f32 v237, v84, v85
	v_cvt_pk_bf16_f32 v238, v86, v87
	v_cvt_pk_bf16_f32 v239, v88, v89
	s_waitcnt lgkmcnt(7)
	ds_read_b64_tr_b16 v[202:203], v124 offset:26624
	ds_read_b64_tr_b16 v[204:205], v124 offset:28672
	ds_read_b64_tr_b16 v[206:207], v125 offset:26624
	ds_read_b64_tr_b16 v[208:209], v125 offset:28672
	ds_read_b64_tr_b16 v[228:229], v126 offset:26624
	ds_read_b64_tr_b16 v[230:231], v126 offset:28672
	ds_read_b64_tr_b16 v[232:233], v127 offset:26624
	ds_read_b64_tr_b16 v[234:235], v127 offset:28672
	s_waitcnt lgkmcnt(14)
	v_mfma_f32_16x16x32_bf16 v[210:213], v[186:189], v[236:239], v[210:213]
	s_waitcnt lgkmcnt(12)
	v_mfma_f32_16x16x32_bf16 v[214:217], v[190:193], v[236:239], v[214:217]
	s_waitcnt lgkmcnt(10)
	v_mfma_f32_16x16x32_bf16 v[220:223], v[194:197], v[236:239], v[220:223]
	s_waitcnt lgkmcnt(8)
	v_mfma_f32_16x16x32_bf16 v[224:227], v[198:201], v[236:239], v[224:227]
	v_cvt_pk_bf16_f32 v240, v90, v91
	v_cvt_pk_bf16_f32 v241, v92, v93
	v_cvt_pk_bf16_f32 v242, v94, v95
	v_cvt_pk_bf16_f32 v243, v96, v97
	s_waitcnt lgkmcnt(7)
	ds_read_b64_tr_b16 v[186:187], v124 offset:30720
	ds_read_b64_tr_b16 v[188:189], v124 offset:32768
	ds_read_b64_tr_b16 v[190:191], v125 offset:30720
	ds_read_b64_tr_b16 v[192:193], v125 offset:32768
	ds_read_b64_tr_b16 v[194:195], v126 offset:30720
	ds_read_b64_tr_b16 v[196:197], v126 offset:32768
	ds_read_b64_tr_b16 v[198:199], v127 offset:30720
	ds_read_b64_tr_b16 v[200:201], v127 offset:32768
	s_waitcnt lgkmcnt(14)
	v_mfma_f32_16x16x32_bf16 v[210:213], v[202:205], v[240:243], v[210:213]
	s_waitcnt lgkmcnt(12)
	v_mfma_f32_16x16x32_bf16 v[214:217], v[206:209], v[240:243], v[214:217]
	s_waitcnt lgkmcnt(10)
	v_mfma_f32_16x16x32_bf16 v[220:223], v[228:231], v[240:243], v[220:223]
	s_waitcnt lgkmcnt(8)
	v_mfma_f32_16x16x32_bf16 v[224:227], v[232:235], v[240:243], v[224:227]
	v_cvt_pk_bf16_f32 v236, v98, v99
	v_cvt_pk_bf16_f32 v237, v100, v101
	v_cvt_pk_bf16_f32 v238, v102, v103
	v_cvt_pk_bf16_f32 v239, v104, v105
	s_waitcnt lgkmcnt(7)
	ds_read_b64_tr_b16 v[202:203], v124 offset:34816
	ds_read_b64_tr_b16 v[204:205], v124 offset:36864
	ds_read_b64_tr_b16 v[206:207], v125 offset:34816
	ds_read_b64_tr_b16 v[208:209], v125 offset:36864
	ds_read_b64_tr_b16 v[228:229], v126 offset:34816
	ds_read_b64_tr_b16 v[230:231], v126 offset:36864
	ds_read_b64_tr_b16 v[232:233], v127 offset:34816
	ds_read_b64_tr_b16 v[234:235], v127 offset:36864
	s_waitcnt lgkmcnt(14)
	v_mfma_f32_16x16x32_bf16 v[210:213], v[186:189], v[236:239], v[210:213]
	s_waitcnt lgkmcnt(12)
; #define LAS __attribute__((address_space(3)))
; __device__ __forceinline__ unsigned pk2(float lo, float hi) { return pg8::cvt_pk_bf16(lo, hi); }
; __device__ __forceinline__ s16x4 vtr(const LAS unsigned char* p) { return __builtin_bit_cast(s16x4, __builtin_amdgcn_ds_read_tr16_b64_v4i16((LAS s16x4*)p)); }
; #define MFMA16(a, b, c) __builtin_amdgcn_mfma_f32_16x16x32_bf16((a), (b), (c), 0, 0, 0)
; __device__ __forceinline__ void pv_at(const LAS unsigned char* const (&vp)[4], int off, const f32x4& P0, const f32x4& P1, f32x4 (&O)[4]) {
;     v4u pw; pw.x = pk2(P0[0], P0[1]); pw.y = pk2(P0[2], P0[3]); pw.z = pk2(P1[0], P1[1]); pw.w = pk2(P1[2], P1[3]);
;     const bf16x8 pb = __builtin_bit_cast(bf16x8, pw);
; #pragma unroll
;     for (int db = 0; db < 4; ++db) {
;         const s16x4 lo = vtr(vp[db] + off), hi = vtr(vp[db] + off + 2048);
;         const bf16x8 vt = (bf16x8){lo[0], lo[1], lo[2], lo[3], hi[0], hi[1], hi[2], hi[3]};
;         O[db] = MFMA16(vt, pb, O[db]);
;     }
; }
; __device__ __forceinline__ void store_o(bf16* yrow, int g, float l, const f32x4 (&O)[4]) {
;     const float inv = 1.0f / xrow16_sum(l);
;     unsigned wx[4], wy[4];
; #pragma unroll
;     for (int db = 0; db < 4; ++db) { wx[db] = pk2(O[db][0] * inv, O[db][1] * inv); wy[db] = pk2(O[db][2] * inv, O[db][3] * inv); }
; #pragma unroll
;     for (int p = 0; p < 2; ++p) {
;         auto rx = __builtin_amdgcn_permlane16_swap(wx[2 * p], wx[2 * p + 1], false, false); wx[2 * p] = rx[0]; wx[2 * p + 1] = rx[1];
;         auto ry = __builtin_amdgcn_permlane16_swap(wy[2 * p], wy[2 * p + 1], false, false); wy[2 * p] = ry[0]; wy[2 * p + 1] = ry[1]; }
; #pragma unroll
;     for (int p = 0; p < 2; ++p) {
;         auto rx = __builtin_amdgcn_permlane32_swap(wx[p], wx[p + 2], false, false); wx[p] = rx[0]; wx[p + 2] = rx[1];
;         auto ry = __builtin_amdgcn_permlane32_swap(wy[p], wy[p + 2], false, false); wy[p] = ry[0]; wy[p + 2] = ry[1]; }
;     v4u lo = {wx[0], wy[0], wx[1], wy[1]}, hi = {wx[2], wy[2], wx[3], wy[3]};
;     *(v4u*)(yrow + 16 * g) = lo; *(v4u*)(yrow + 16 * g + 8) = hi;
; }
	v_mfma_f32_16x16x32_bf16 v[214:217], v[190:193], v[236:239], v[214:217]
	s_waitcnt lgkmcnt(10)
	v_mfma_f32_16x16x32_bf16 v[220:223], v[194:197], v[236:239], v[220:223]
	s_waitcnt lgkmcnt(8)
	v_mfma_f32_16x16x32_bf16 v[224:227], v[198:201], v[236:239], v[224:227]
	v_cvt_pk_bf16_f32 v240, v106, v107
	v_cvt_pk_bf16_f32 v241, v108, v109
	v_cvt_pk_bf16_f32 v242, v110, v111
	v_cvt_pk_bf16_f32 v243, v112, v113
	s_waitcnt lgkmcnt(7)
	ds_read_b64_tr_b16 v[186:187], v124 offset:38912
	ds_read_b64_tr_b16 v[188:189], v124 offset:40960
	ds_read_b64_tr_b16 v[190:191], v125 offset:38912
	ds_read_b64_tr_b16 v[192:193], v125 offset:40960
	ds_read_b64_tr_b16 v[194:195], v126 offset:38912
	ds_read_b64_tr_b16 v[196:197], v126 offset:40960
	ds_read_b64_tr_b16 v[198:199], v127 offset:38912
	ds_read_b64_tr_b16 v[200:201], v127 offset:40960
	s_waitcnt lgkmcnt(14)
	v_mfma_f32_16x16x32_bf16 v[210:213], v[202:205], v[240:243], v[210:213]
	s_waitcnt lgkmcnt(12)
	v_mfma_f32_16x16x32_bf16 v[214:217], v[206:209], v[240:243], v[214:217]
	s_waitcnt lgkmcnt(10)
	v_mfma_f32_16x16x32_bf16 v[220:223], v[228:231], v[240:243], v[220:223]
	s_waitcnt lgkmcnt(8)
	v_mfma_f32_16x16x32_bf16 v[224:227], v[232:235], v[240:243], v[224:227]
	v_cvt_pk_bf16_f32 v236, v114, v115
	v_cvt_pk_bf16_f32 v237, v116, v117
	v_mov_b32_e32 v238, 0
	v_mov_b32_e32 v239, 0
	s_nop 1
	s_waitcnt lgkmcnt(6)
	v_mfma_f32_16x16x32_bf16 v[210:213], v[186:189], v[236:239], v[210:213]
	s_waitcnt lgkmcnt(4)
	v_mfma_f32_16x16x32_bf16 v[214:217], v[190:193], v[236:239], v[214:217]
	s_waitcnt lgkmcnt(2)
	v_mfma_f32_16x16x32_bf16 v[220:223], v[194:197], v[236:239], v[220:223]
	s_waitcnt lgkmcnt(0)
	v_mfma_f32_16x16x32_bf16 v[224:227], v[198:201], v[236:239], v[224:227]
	v_mov_b32_e32 v219, v185
	s_nop 1
	v_permlane16_swap_b32_e32 v185, v219
	v_add_f32_e32 v185, v185, v219
	v_mov_b32_e32 v219, v185
	s_nop 1
	v_permlane32_swap_b32_e32 v185, v219
	v_add_f32_e32 v185, v185, v219
	v_div_scale_f32 v236, s[78:79], v185, v185, 1.0
	v_div_scale_f32 v237, vcc, 1.0, v185, 1.0
	v_rcp_f32_e32 v238, v236
	s_nop 0
	v_fma_f32 v239, -v236, v238, 1.0
	v_fmac_f32_e32 v238, v239, v238
	v_mul_f32_e32 v240, v237, v238
	v_fma_f32 v241, -v236, v240, v237
	v_fmac_f32_e32 v240, v241, v238
	v_fma_f32 v237, -v236, v240, v237
	v_div_fmas_f32 v237, v237, v238, v240
	v_div_fixup_f32 v244, v237, v185, 1.0
	v_mul_f32_e32 v240, v210, v244
	v_mul_f32_e32 v241, v211, v244
	v_mul_f32_e32 v242, v212, v244
	v_mul_f32_e32 v243, v213, v244
	v_cvt_pk_bf16_f32 v186, v240, v241
	v_cvt_pk_bf16_f32 v187, v242, v243
	v_mul_f32_e32 v240, v214, v244
	v_mul_f32_e32 v241, v215, v244
	v_mul_f32_e32 v242, v216, v244
	v_mul_f32_e32 v243, v217, v244
	v_cvt_pk_bf16_f32 v188, v240, v241
	v_cvt_pk_bf16_f32 v189, v242, v243
	v_mul_f32_e32 v240, v220, v244
	v_mul_f32_e32 v241, v221, v244
	v_mul_f32_e32 v242, v222, v244
	v_mul_f32_e32 v243, v223, v244
	v_cvt_pk_bf16_f32 v190, v240, v241
	v_cvt_pk_bf16_f32 v191, v242, v243
	v_mul_f32_e32 v240, v224, v244
	v_mul_f32_e32 v241, v225, v244
	v_mul_f32_e32 v242, v226, v244
	v_mul_f32_e32 v243, v227, v244
	v_cvt_pk_bf16_f32 v192, v240, v241
	v_cvt_pk_bf16_f32 v193, v242, v243
	s_nop 1
	v_permlane16_swap_b32_e32 v186, v188
	v_permlane16_swap_b32_e32 v187, v189
	v_permlane16_swap_b32_e32 v190, v192
	v_permlane16_swap_b32_e32 v191, v193
	s_nop 0
	v_permlane32_swap_b32_e32 v186, v190
	v_permlane32_swap_b32_e32 v187, v191
	v_permlane32_swap_b32_e32 v188, v192
	v_permlane32_swap_b32_e32 v189, v193
	v_add_u32_e32 v219, 0x1000, v128
	global_store_dwordx4 v219, v[186:189], s[82:83] offset:2048 sc1
	global_store_dwordx4 v219, v[190:193], s[82:83] offset:2064 sc1
	s_nop 1
	s_branch .LBB0_240

; #define LAS __attribute__((address_space(3)))
; #define MFMA16(a, b, c) __builtin_amdgcn_mfma_f32_16x16x32_bf16((a), (b), (c), 0, 0, 0)
; __device__ __forceinline__ void qk_at(const LAS unsigned char* kp0, const LAS unsigned char* kp1, int off, bf16x8 qf0, bf16x8 qf1, f32x4& S0, f32x4& S1) {
;     const bf16x8 k00 = *(const LAS bf16x8*)(kp0 + off), k01 = *(const LAS bf16x8*)(kp1 + off);
;     const bf16x8 k10 = *(const LAS bf16x8*)(kp0 + off + 2048), k11 = *(const LAS bf16x8*)(kp1 + off + 2048);
;     const f32x4 z = {0.f, 0.f, 0.f, 0.f};
;     S0 = MFMA16(k00, qf0, z); S0 = MFMA16(k01, qf1, S0);
;     S1 = MFMA16(k10, qf0, z); S1 = MFMA16(k11, qf1, S1);
; }
; template <bool MASK> __device__ __forceinline__ void a_scores(f32x4& S0, f32x4& S1, float basef, float c1, float slope2, int krow0, int kstart) {
; #pragma unroll
;     for (int r = 0; r < 4; ++r) {
;         const float d0 = fabsf(basef - (float)r), d1 = fabsf(basef - (float)(16 + r));
;         const float v0 = S0[r] - slope2 * d0, v1 = S1[r] - slope2 * d1;
;         if (MASK) { const int p0 = kstart + krow0 + r, p1 = p0 + 16;
;             S0[r] = (d0 <= 128.f && p0 >= 0 && p0 < SEQ) ? v0 : -INFINITY; S1[r] = (d1 <= 128.f && p1 >= 0 && p1 < SEQ) ? v1 : -INFINITY; }
;         else { S0[r] = v0; S1[r] = v1; }
;     }
; }
.La_edge_go:
	s_bitcmp1_b32 s87, 0
	s_cselect_b32 s21, 0, 0xff800000
	v_add_f32_e32 v120, s21, v132
	v_fmamk_f32 v50, v130, 0x43000000, v120
	v_fmamk_f32 v51, v130, 0x42fe0000, v120
	v_fmamk_f32 v52, v130, 0x42fc0000, v120
	v_fmamk_f32 v53, v130, 0x42fa0000, v120
	s_bitcmp1_b32 s87, 1
	s_cselect_b32 s21, 0, 0xff800000
	v_add_f32_e32 v120, s21, v132
	v_fmamk_f32 v54, v130, 0x42e00000, v120
	v_fmamk_f32 v55, v130, 0x42de0000, v120
	v_fmamk_f32 v56, v130, 0x42dc0000, v120
	v_fmamk_f32 v57, v130, 0x42da0000, v120
	s_bitcmp1_b32 s87, 2
	s_cselect_b32 s21, 0, 0xff800000
	v_add_f32_e32 v120, s21, v132
	v_fmamk_f32 v58, v130, 0x42c00000, v120
	v_fmamk_f32 v59, v130, 0x42be0000, v120
	v_fmamk_f32 v60, v130, 0x42bc0000, v120
	v_fmamk_f32 v61, v130, 0x42ba0000, v120
	s_bitcmp1_b32 s87, 3
	s_cselect_b32 s21, 0, 0xff800000
	v_add_f32_e32 v120, s21, v132
	v_fmamk_f32 v62, v130, 0x42a00000, v120
	v_fmamk_f32 v63, v130, 0x429e0000, v120
	v_fmamk_f32 v64, v130, 0x429c0000, v120
	v_fmamk_f32 v65, v130, 0x429a0000, v120
	s_bitcmp1_b32 s87, 4
	s_cselect_b32 s21, 0, 0xff800000
	v_add_f32_e32 v120, s21, v132
	v_fmamk_f32 v66, v130, 0x42800000, v120
	v_fmamk_f32 v67, v130, 0x427c0000, v120
	v_fmamk_f32 v68, v130, 0x42780000, v120
	v_fmamk_f32 v69, v130, 0x42740000, v120
	s_bitcmp1_b32 s87, 5
	s_cselect_b32 s21, 0, 0xff800000
	v_add_f32_e32 v120, s21, v132
	v_fmamk_f32 v70, v130, 0x42400000, v120
	v_fmamk_f32 v71, v130, 0x423c0000, v120
	v_fmamk_f32 v72, v130, 0x42380000, v120
	v_fmamk_f32 v73, v130, 0x42340000, v120
	s_bitcmp1_b32 s87, 6
	s_cselect_b32 s21, 0, 0xff800000
	v_add_f32_e32 v120, s21, v132
	v_fmamk_f32 v74, v130, 0x42000000, v120
	v_fmamk_f32 v75, v130, 0x41f80000, v120
	v_fmamk_f32 v76, v130, 0x41f00000, v120
	v_fmamk_f32 v77, v130, 0x41e80000, v120
	s_bitcmp1_b32 s87, 7
	s_cselect_b32 s21, 0, 0xff800000
	v_add_f32_e32 v120, s21, v132
	v_fmamk_f32 v78, v130, 0x41800000, v120
	v_fmamk_f32 v79, v130, 0x41700000, v120
	v_fmamk_f32 v80, v130, 0x41600000, v120
	v_fmamk_f32 v81, v130, 0x41500000, v120
	s_bitcmp1_b32 s87, 8
	s_cselect_b32 s21, 0, 0xff800000
	v_add_f32_e32 v219, 0, v129
	v_fma_f32 v82, v130, |v219|, s21
	v_add_f32_e32 v244, 0xbf800000, v129
	v_fma_f32 v83, v130, |v244|, s21
	v_add_f32_e32 v219, 0xc0000000, v129
	v_fma_f32 v84, v130, |v219|, s21
	v_add_f32_e32 v244, 0xc0400000, v129
	v_fma_f32 v85, v130, |v244|, s21
	s_bitcmp1_b32 s87, 9
	s_cselect_b32 s21, 0, 0xff800000
	v_add_f32_e32 v120, s21, v133
	v_fmamk_f32 v86, v131, 0xc1800000, v120
	v_fmamk_f32 v87, v131, 0xc1880000, v120
	v_fmamk_f32 v88, v131, 0xc1900000, v120
	v_fmamk_f32 v89, v131, 0xc1980000, v120
	s_bitcmp1_b32 s87, 10
	s_cselect_b32 s21, 0, 0xff800000
	v_add_f32_e32 v120, s21, v133
	v_fmamk_f32 v90, v131, 0xc2000000, v120
	v_fmamk_f32 v91, v131, 0xc2040000, v120
	v_fmamk_f32 v92, v131, 0xc2080000, v120
	v_fmamk_f32 v93, v131, 0xc20c0000, v120
	s_bitcmp1_b32 s87, 11
	s_cselect_b32 s21, 0, 0xff800000
	v_add_f32_e32 v120, s21, v133
	v_fmamk_f32 v94, v131, 0xc2400000, v120
	v_fmamk_f32 v95, v131, 0xc2440000, v120
	v_fmamk_f32 v96, v131, 0xc2480000, v120
	v_fmamk_f32 v97, v131, 0xc24c0000, v120
	s_bitcmp1_b32 s87, 12
	s_cselect_b32 s21, 0, 0xff800000
	v_add_f32_e32 v120, s21, v133
	v_fmamk_f32 v98, v131, 0xc2800000, v120
	v_fmamk_f32 v99, v131, 0xc2820000, v120
	v_fmamk_f32 v100, v131, 0xc2840000, v120
	v_fmamk_f32 v101, v131, 0xc2860000, v120
	s_bitcmp1_b32 s87, 13
	s_cselect_b32 s21, 0, 0xff800000
	v_add_f32_e32 v120, s21, v133
	v_fmamk_f32 v102, v131, 0xc2a00000, v120
	v_fmamk_f32 v103, v131, 0xc2a20000, v120
	v_fmamk_f32 v104, v131, 0xc2a40000, v120
	v_fmamk_f32 v105, v131, 0xc2a60000, v120
	s_bitcmp1_b32 s87, 14
	s_cselect_b32 s21, 0, 0xff800000
	v_add_f32_e32 v120, s21, v133
	v_fmamk_f32 v106, v131, 0xc2c00000, v120
	v_fmamk_f32 v107, v131, 0xc2c20000, v120
	v_fmamk_f32 v108, v131, 0xc2c40000, v120
	v_fmamk_f32 v109, v131, 0xc2c60000, v120
	s_bitcmp1_b32 s87, 15
	s_cselect_b32 s21, 0, 0xff800000
	v_add_f32_e32 v120, s21, v133
	v_fmamk_f32 v110, v131, 0xc2e00000, v120
	v_fmamk_f32 v111, v131, 0xc2e20000, v120
	v_fmamk_f32 v112, v131, 0xc2e40000, v120
	v_fmamk_f32 v113, v131, 0xc2e60000, v120
	s_bitcmp1_b32 s87, 16
	s_cselect_b32 s21, 0, 0xff800000
	v_add_f32_e32 v120, s21, v133
	v_fmamk_f32 v114, v131, 0xc3000000, v120
	v_fmamk_f32 v115, v131, 0xc3010000, v120
	v_fmamk_f32 v116, v131, 0xc3020000, v120
	v_fmamk_f32 v117, v131, 0xc3030000, v120
	v_mov_b32_e32 v245, 0xff800000
	v_cndmask_b32_e64 v50, v245, v50, s[16:17]
	v_cndmask_b32_e64 v51, v245, v51, s[18:19]
	v_cndmask_b32_e64 v52, v245, v52, s[22:23]
	v_cndmask_b32_e64 v53, v245, v53, s[24:25]
	v_cndmask_b32_e64 v114, v245, v114, s[28:29]
	v_cndmask_b32_e64 v115, v245, v115, s[52:53]
	v_cndmask_b32_e64 v116, v245, v116, s[54:55]
	v_cndmask_b32_e64 v117, v245, v117, s[88:89]
	ds_read_b128 v[186:189], v122 offset:0
	ds_read_b128 v[190:193], v123 offset:0
	ds_read_b128 v[194:197], v122 offset:2048
	ds_read_b128 v[198:201], v123 offset:2048
	ds_read_b128 v[202:205], v122 offset:4096
	ds_read_b128 v[206:209], v123 offset:4096
	s_waitcnt lgkmcnt(5)
	v_mfma_f32_16x16x32_bf16 v[50:53], v[186:189], v[146:149], v[50:53]
	s_waitcnt lgkmcnt(4)
	v_mfma_f32_16x16x32_bf16 v[50:53], v[190:193], v[150:153], v[50:53]
	ds_read_b128 v[186:189], v122 offset:6144
	ds_read_b128 v[190:193], v123 offset:6144
	s_waitcnt lgkmcnt(5)
	v_mfma_f32_16x16x32_bf16 v[54:57], v[194:197], v[146:149], v[54:57]
	s_waitcnt lgkmcnt(4)
	v_mfma_f32_16x16x32_bf16 v[54:57], v[198:201], v[150:153], v[54:57]
	ds_read_b128 v[194:197], v122 offset:8192
	ds_read_b128 v[198:201], v123 offset:8192
	s_waitcnt lgkmcnt(5)
	v_mfma_f32_16x16x32_bf16 v[58:61], v[202:205], v[146:149], v[58:61]
	s_waitcnt lgkmcnt(4)
; #define LAS __attribute__((address_space(3)))
; #define MFMA16(a, b, c) __builtin_amdgcn_mfma_f32_16x16x32_bf16((a), (b), (c), 0, 0, 0)
; __device__ __forceinline__ void qk_at(const LAS unsigned char* kp0, const LAS unsigned char* kp1, int off, bf16x8 qf0, bf16x8 qf1, f32x4& S0, f32x4& S1) {
;     const bf16x8 k00 = *(const LAS bf16x8*)(kp0 + off), k01 = *(const LAS bf16x8*)(kp1 + off);
;     const bf16x8 k10 = *(const LAS bf16x8*)(kp0 + off + 2048), k11 = *(const LAS bf16x8*)(kp1 + off + 2048);
;     const f32x4 z = {0.f, 0.f, 0.f, 0.f};
;     S0 = MFMA16(k00, qf0, z); S0 = MFMA16(k01, qf1, S0);
;     S1 = MFMA16(k10, qf0, z); S1 = MFMA16(k11, qf1, S1);
; }
; __device__ __forceinline__ void softmax_step(f32x4& s0, f32x4& s1, float& m, float& l, f32x4 (&O)[4]) {
;     float t = fmaxf(fmaxf(fmaxf(s0[0], s0[1]), fmaxf(s0[2], s0[3])), fmaxf(fmaxf(s1[0], s1[1]), fmaxf(s1[2], s1[3])));
;     t = xrow16_max(t);
	v_mfma_f32_16x16x32_bf16 v[58:61], v[206:209], v[150:153], v[58:61]
	ds_read_b128 v[202:205], v122 offset:10240
	ds_read_b128 v[206:209], v123 offset:10240
	s_waitcnt lgkmcnt(5)
	v_mfma_f32_16x16x32_bf16 v[62:65], v[186:189], v[146:149], v[62:65]
	s_waitcnt lgkmcnt(4)
	v_mfma_f32_16x16x32_bf16 v[62:65], v[190:193], v[150:153], v[62:65]
	ds_read_b128 v[186:189], v122 offset:12288
	ds_read_b128 v[190:193], v123 offset:12288
	s_waitcnt lgkmcnt(5)
	v_mfma_f32_16x16x32_bf16 v[66:69], v[194:197], v[146:149], v[66:69]
	s_waitcnt lgkmcnt(4)
	v_mfma_f32_16x16x32_bf16 v[66:69], v[198:201], v[150:153], v[66:69]
	ds_read_b128 v[194:197], v122 offset:14336
	ds_read_b128 v[198:201], v123 offset:14336
	s_waitcnt lgkmcnt(5)
	v_mfma_f32_16x16x32_bf16 v[70:73], v[202:205], v[146:149], v[70:73]
	s_waitcnt lgkmcnt(4)
	v_mfma_f32_16x16x32_bf16 v[70:73], v[206:209], v[150:153], v[70:73]
	ds_read_b128 v[202:205], v122 offset:16384
	ds_read_b128 v[206:209], v123 offset:16384
	s_waitcnt lgkmcnt(5)
	v_mfma_f32_16x16x32_bf16 v[74:77], v[186:189], v[146:149], v[74:77]
	s_waitcnt lgkmcnt(4)
	v_mfma_f32_16x16x32_bf16 v[74:77], v[190:193], v[150:153], v[74:77]
	ds_read_b128 v[186:189], v122 offset:18432
	ds_read_b128 v[190:193], v123 offset:18432
	s_waitcnt lgkmcnt(5)
	v_mfma_f32_16x16x32_bf16 v[78:81], v[194:197], v[146:149], v[78:81]
	s_waitcnt lgkmcnt(4)
	v_mfma_f32_16x16x32_bf16 v[78:81], v[198:201], v[150:153], v[78:81]
	ds_read_b128 v[194:197], v122 offset:20480
	ds_read_b128 v[198:201], v123 offset:20480
	s_waitcnt lgkmcnt(5)
	v_mfma_f32_16x16x32_bf16 v[82:85], v[202:205], v[146:149], v[82:85]
	s_waitcnt lgkmcnt(4)
	v_mfma_f32_16x16x32_bf16 v[82:85], v[206:209], v[150:153], v[82:85]
	ds_read_b128 v[202:205], v122 offset:22528
	ds_read_b128 v[206:209], v123 offset:22528
	s_waitcnt lgkmcnt(5)
	v_mfma_f32_16x16x32_bf16 v[86:89], v[186:189], v[146:149], v[86:89]
	s_waitcnt lgkmcnt(4)
	v_mfma_f32_16x16x32_bf16 v[86:89], v[190:193], v[150:153], v[86:89]
	ds_read_b128 v[186:189], v122 offset:24576
	ds_read_b128 v[190:193], v123 offset:24576
	s_waitcnt lgkmcnt(5)
	v_mfma_f32_16x16x32_bf16 v[90:93], v[194:197], v[146:149], v[90:93]
	s_waitcnt lgkmcnt(4)
	v_mfma_f32_16x16x32_bf16 v[90:93], v[198:201], v[150:153], v[90:93]
	ds_read_b128 v[194:197], v122 offset:26624
	ds_read_b128 v[198:201], v123 offset:26624
	s_waitcnt lgkmcnt(5)
	v_mfma_f32_16x16x32_bf16 v[94:97], v[202:205], v[146:149], v[94:97]
	s_waitcnt lgkmcnt(4)
	v_mfma_f32_16x16x32_bf16 v[94:97], v[206:209], v[150:153], v[94:97]
	ds_read_b128 v[202:205], v122 offset:28672
	ds_read_b128 v[206:209], v123 offset:28672
	s_waitcnt lgkmcnt(5)
	v_mfma_f32_16x16x32_bf16 v[98:101], v[186:189], v[146:149], v[98:101]
	s_waitcnt lgkmcnt(4)
	v_mfma_f32_16x16x32_bf16 v[98:101], v[190:193], v[150:153], v[98:101]
	ds_read_b128 v[186:189], v122 offset:30720
	ds_read_b128 v[190:193], v123 offset:30720
	s_waitcnt lgkmcnt(5)
	v_mfma_f32_16x16x32_bf16 v[102:105], v[194:197], v[146:149], v[102:105]
	s_waitcnt lgkmcnt(4)
	v_mfma_f32_16x16x32_bf16 v[102:105], v[198:201], v[150:153], v[102:105]
	ds_read_b128 v[194:197], v122 offset:32768
	ds_read_b128 v[198:201], v123 offset:32768
	s_waitcnt lgkmcnt(5)
	v_mfma_f32_16x16x32_bf16 v[106:109], v[202:205], v[146:149], v[106:109]
	s_waitcnt lgkmcnt(4)
	v_mfma_f32_16x16x32_bf16 v[106:109], v[206:209], v[150:153], v[106:109]
	s_waitcnt lgkmcnt(3)
	v_mfma_f32_16x16x32_bf16 v[110:113], v[186:189], v[146:149], v[110:113]
	s_waitcnt lgkmcnt(2)
	v_mfma_f32_16x16x32_bf16 v[110:113], v[190:193], v[150:153], v[110:113]
	s_waitcnt lgkmcnt(1)
	v_mfma_f32_16x16x32_bf16 v[114:117], v[194:197], v[146:149], v[114:117]
	s_waitcnt lgkmcnt(0)
	v_mfma_f32_16x16x32_bf16 v[114:117], v[198:201], v[150:153], v[114:117]
	v_max3_f32 v219, v50, v51, v52
	v_max3_f32 v244, v54, v55, v56
	v_max3_f32 v245, v58, v59, v60
	v_max3_f32 v120, v62, v63, v64
	v_max3_f32 v219, v219, v53, v66
	v_max3_f32 v244, v244, v57, v70
	v_max3_f32 v245, v245, v61, v74
	v_max3_f32 v120, v120, v65, v78
	v_max3_f32 v219, v219, v67, v68
	v_max3_f32 v244, v244, v71, v72
	v_max3_f32 v245, v245, v75, v76
	v_max3_f32 v120, v120, v79, v80
	ds_read_b64_tr_b16 v[186:187], v124 offset:0
	ds_read_b64_tr_b16 v[188:189], v124 offset:2048
	ds_read_b64_tr_b16 v[190:191], v125 offset:0
	ds_read_b64_tr_b16 v[192:193], v125 offset:2048
	ds_read_b64_tr_b16 v[194:195], v126 offset:0
	ds_read_b64_tr_b16 v[196:197], v126 offset:2048
	ds_read_b64_tr_b16 v[198:199], v127 offset:0
	ds_read_b64_tr_b16 v[200:201], v127 offset:2048
	v_max3_f32 v219, v219, v69, v82
	v_max3_f32 v244, v244, v73, v86
	v_max3_f32 v245, v245, v77, v90
	v_max3_f32 v120, v120, v81, v94
	v_max3_f32 v219, v219, v83, v84
	v_max3_f32 v244, v244, v87, v88
	v_max3_f32 v245, v245, v91, v92
	v_max3_f32 v120, v120, v95, v96
	v_max3_f32 v219, v219, v85, v98
	v_max3_f32 v244, v244, v89, v102
	v_max3_f32 v245, v245, v93, v106
	v_max3_f32 v120, v120, v97, v110
	v_max3_f32 v219, v219, v99, v100
	v_max3_f32 v244, v244, v103, v104
	v_max3_f32 v245, v245, v107, v108
	v_max3_f32 v120, v120, v111, v112
	v_max3_f32 v219, v219, v101, v114
	v_max3_f32 v219, v219, v115, v116
	v_max_f32_e32 v219, v219, v117
	v_max_f32_e32 v244, v244, v105
	v_max_f32_e32 v245, v245, v109
	v_max_f32_e32 v120, v120, v113
	v_max3_f32 v178, v219, v244, v245
	v_max_f32_e32 v178, v178, v120
	v_mov_b32_e32 v219, v178
	s_nop 1
	v_permlane16_swap_b32_e32 v178, v219
	v_max_f32_e32 v178, v178, v219
	v_mov_b32_e32 v219, v178
	s_nop 1
	v_permlane32_swap_b32_e32 v178, v219
	v_max3_f32 v178, v178, v219, v145
	s_waitcnt lgkmcnt(7)
; __device__ __forceinline__ void softmax_step(f32x4& s0, f32x4& s1, float& m, float& l, f32x4 (&O)[4]) {
;     float t = fmaxf(fmaxf(fmaxf(s0[0], s0[1]), fmaxf(s0[2], s0[3])), fmaxf(fmaxf(s1[0], s1[1]), fmaxf(s1[2], s1[3])));
;     t = xrow16_max(t);
;     const float mn = fmaxf(m, t), alpha = __builtin_amdgcn_exp2f(m - mn);
;     m = mn;
; #pragma unroll
;     for (int k = 0; k < 4; ++k) { s0[k] = __builtin_amdgcn_exp2f(s0[k] - mn); s1[k] = __builtin_amdgcn_exp2f(s1[k] - mn); }
;     l = l * alpha + ((s0[0] + s0[1]) + (s0[2] + s0[3])) + ((s1[0] + s1[1]) + (s1[2] + s1[3]));
	ds_read_b64_tr_b16 v[202:203], v124 offset:4096
	ds_read_b64_tr_b16 v[204:205], v124 offset:6144
	ds_read_b64_tr_b16 v[206:207], v125 offset:4096
	ds_read_b64_tr_b16 v[208:209], v125 offset:6144
	ds_read_b64_tr_b16 v[228:229], v126 offset:4096
	ds_read_b64_tr_b16 v[230:231], v126 offset:6144
	ds_read_b64_tr_b16 v[232:233], v127 offset:4096
	ds_read_b64_tr_b16 v[234:235], v127 offset:6144
	v_mov_b32_e32 v244, v178
	v_pk_add_f32 v[50:51], v[50:51], v[244:245] op_sel_hi:[1,0] neg_lo:[0,1] neg_hi:[0,1]
	v_pk_add_f32 v[52:53], v[52:53], v[244:245] op_sel_hi:[1,0] neg_lo:[0,1] neg_hi:[0,1]
	v_pk_add_f32 v[54:55], v[54:55], v[244:245] op_sel_hi:[1,0] neg_lo:[0,1] neg_hi:[0,1]
	v_pk_add_f32 v[56:57], v[56:57], v[244:245] op_sel_hi:[1,0] neg_lo:[0,1] neg_hi:[0,1]
	v_pk_add_f32 v[58:59], v[58:59], v[244:245] op_sel_hi:[1,0] neg_lo:[0,1] neg_hi:[0,1]
	v_pk_add_f32 v[60:61], v[60:61], v[244:245] op_sel_hi:[1,0] neg_lo:[0,1] neg_hi:[0,1]
	v_pk_add_f32 v[62:63], v[62:63], v[244:245] op_sel_hi:[1,0] neg_lo:[0,1] neg_hi:[0,1]
	v_pk_add_f32 v[64:65], v[64:65], v[244:245] op_sel_hi:[1,0] neg_lo:[0,1] neg_hi:[0,1]
	v_pk_add_f32 v[66:67], v[66:67], v[244:245] op_sel_hi:[1,0] neg_lo:[0,1] neg_hi:[0,1]
	v_pk_add_f32 v[68:69], v[68:69], v[244:245] op_sel_hi:[1,0] neg_lo:[0,1] neg_hi:[0,1]
	v_pk_add_f32 v[70:71], v[70:71], v[244:245] op_sel_hi:[1,0] neg_lo:[0,1] neg_hi:[0,1]
	v_pk_add_f32 v[72:73], v[72:73], v[244:245] op_sel_hi:[1,0] neg_lo:[0,1] neg_hi:[0,1]
	v_pk_add_f32 v[74:75], v[74:75], v[244:245] op_sel_hi:[1,0] neg_lo:[0,1] neg_hi:[0,1]
	v_pk_add_f32 v[76:77], v[76:77], v[244:245] op_sel_hi:[1,0] neg_lo:[0,1] neg_hi:[0,1]
	v_pk_add_f32 v[78:79], v[78:79], v[244:245] op_sel_hi:[1,0] neg_lo:[0,1] neg_hi:[0,1]
	v_pk_add_f32 v[80:81], v[80:81], v[244:245] op_sel_hi:[1,0] neg_lo:[0,1] neg_hi:[0,1]
	v_pk_add_f32 v[82:83], v[82:83], v[244:245] op_sel_hi:[1,0] neg_lo:[0,1] neg_hi:[0,1]
	v_pk_add_f32 v[84:85], v[84:85], v[244:245] op_sel_hi:[1,0] neg_lo:[0,1] neg_hi:[0,1]
	v_pk_add_f32 v[86:87], v[86:87], v[244:245] op_sel_hi:[1,0] neg_lo:[0,1] neg_hi:[0,1]
	v_pk_add_f32 v[88:89], v[88:89], v[244:245] op_sel_hi:[1,0] neg_lo:[0,1] neg_hi:[0,1]
	v_pk_add_f32 v[90:91], v[90:91], v[244:245] op_sel_hi:[1,0] neg_lo:[0,1] neg_hi:[0,1]
	v_pk_add_f32 v[92:93], v[92:93], v[244:245] op_sel_hi:[1,0] neg_lo:[0,1] neg_hi:[0,1]
	v_pk_add_f32 v[94:95], v[94:95], v[244:245] op_sel_hi:[1,0] neg_lo:[0,1] neg_hi:[0,1]
	v_pk_add_f32 v[96:97], v[96:97], v[244:245] op_sel_hi:[1,0] neg_lo:[0,1] neg_hi:[0,1]
	v_pk_add_f32 v[98:99], v[98:99], v[244:245] op_sel_hi:[1,0] neg_lo:[0,1] neg_hi:[0,1]
	v_pk_add_f32 v[100:101], v[100:101], v[244:245] op_sel_hi:[1,0] neg_lo:[0,1] neg_hi:[0,1]
	v_pk_add_f32 v[102:103], v[102:103], v[244:245] op_sel_hi:[1,0] neg_lo:[0,1] neg_hi:[0,1]
	v_pk_add_f32 v[104:105], v[104:105], v[244:245] op_sel_hi:[1,0] neg_lo:[0,1] neg_hi:[0,1]
	v_pk_add_f32 v[106:107], v[106:107], v[244:245] op_sel_hi:[1,0] neg_lo:[0,1] neg_hi:[0,1]
	v_pk_add_f32 v[108:109], v[108:109], v[244:245] op_sel_hi:[1,0] neg_lo:[0,1] neg_hi:[0,1]
	v_pk_add_f32 v[110:111], v[110:111], v[244:245] op_sel_hi:[1,0] neg_lo:[0,1] neg_hi:[0,1]
	v_pk_add_f32 v[112:113], v[112:113], v[244:245] op_sel_hi:[1,0] neg_lo:[0,1] neg_hi:[0,1]
	v_pk_add_f32 v[114:115], v[114:115], v[244:245] op_sel_hi:[1,0] neg_lo:[0,1] neg_hi:[0,1]
	v_pk_add_f32 v[116:117], v[116:117], v[244:245] op_sel_hi:[1,0] neg_lo:[0,1] neg_hi:[0,1]
	v_sub_f32_e32 v219, v145, v178
	v_exp_f32_e32 v50, v50
	v_exp_f32_e32 v51, v51
	v_exp_f32_e32 v52, v52
	v_exp_f32_e32 v53, v53
	v_exp_f32_e32 v54, v54
	v_exp_f32_e32 v55, v55
	v_exp_f32_e32 v56, v56
	v_exp_f32_e32 v57, v57
	v_exp_f32_e32 v58, v58
	v_exp_f32_e32 v59, v59
	v_exp_f32_e32 v60, v60
	v_exp_f32_e32 v61, v61
	v_exp_f32_e32 v62, v62
	v_exp_f32_e32 v63, v63
	v_exp_f32_e32 v64, v64
	v_exp_f32_e32 v65, v65
	v_exp_f32_e32 v66, v66
	v_exp_f32_e32 v67, v67
	v_exp_f32_e32 v68, v68
	v_exp_f32_e32 v69, v69
	v_exp_f32_e32 v70, v70
	v_exp_f32_e32 v71, v71
	v_exp_f32_e32 v72, v72
	v_exp_f32_e32 v73, v73
	v_exp_f32_e32 v74, v74
	v_exp_f32_e32 v75, v75
	v_exp_f32_e32 v76, v76
	v_exp_f32_e32 v77, v77
	v_exp_f32_e32 v78, v78
	v_exp_f32_e32 v79, v79
	v_exp_f32_e32 v80, v80
	v_exp_f32_e32 v81, v81
	v_exp_f32_e32 v82, v82
	v_exp_f32_e32 v83, v83
	v_exp_f32_e32 v84, v84
	v_exp_f32_e32 v85, v85
	v_exp_f32_e32 v86, v86
	v_exp_f32_e32 v87, v87
	v_exp_f32_e32 v88, v88
	v_exp_f32_e32 v89, v89
	v_exp_f32_e32 v90, v90
	v_exp_f32_e32 v91, v91
	v_exp_f32_e32 v92, v92
	v_exp_f32_e32 v93, v93
	v_exp_f32_e32 v94, v94
	v_exp_f32_e32 v95, v95
	v_exp_f32_e32 v96, v96
	v_exp_f32_e32 v97, v97
	v_exp_f32_e32 v98, v98
	v_exp_f32_e32 v99, v99
	v_exp_f32_e32 v100, v100
	v_exp_f32_e32 v101, v101
	v_exp_f32_e32 v102, v102
	v_exp_f32_e32 v103, v103
	v_exp_f32_e32 v104, v104
	v_exp_f32_e32 v105, v105
	v_exp_f32_e32 v106, v106
	v_exp_f32_e32 v107, v107
	v_exp_f32_e32 v108, v108
	v_exp_f32_e32 v109, v109
	v_exp_f32_e32 v110, v110
	v_exp_f32_e32 v111, v111
	v_exp_f32_e32 v112, v112
	v_exp_f32_e32 v113, v113
	v_exp_f32_e32 v114, v114
	v_exp_f32_e32 v115, v115
	v_exp_f32_e32 v116, v116
	v_exp_f32_e32 v117, v117
	v_exp_f32_e32 v219, v219
	v_pk_add_f32 v[236:237], v[50:51], v[52:53]
	v_pk_add_f32 v[238:239], v[54:55], v[56:57]
	v_pk_add_f32 v[240:241], v[58:59], v[60:61]
	v_pk_add_f32 v[242:243], v[62:63], v[64:65]
	v_pk_add_f32 v[236:237], v[236:237], v[66:67]
	v_pk_add_f32 v[238:239], v[238:239], v[70:71]
	v_pk_add_f32 v[240:241], v[240:241], v[74:75]
	v_pk_add_f32 v[242:243], v[242:243], v[78:79]
	v_pk_add_f32 v[236:237], v[236:237], v[68:69]
	v_pk_add_f32 v[238:239], v[238:239], v[72:73]
	v_pk_add_f32 v[240:241], v[240:241], v[76:77]
	v_pk_add_f32 v[242:243], v[242:243], v[80:81]
	v_pk_add_f32 v[236:237], v[236:237], v[82:83]
	v_pk_add_f32 v[238:239], v[238:239], v[86:87]
	v_pk_add_f32 v[240:241], v[240:241], v[90:91]
	v_pk_add_f32 v[242:243], v[242:243], v[94:95]
	v_pk_add_f32 v[236:237], v[236:237], v[84:85]
	v_pk_add_f32 v[238:239], v[238:239], v[88:89]
	v_pk_add_f32 v[240:241], v[240:241], v[92:93]
	v_pk_add_f32 v[242:243], v[242:243], v[96:97]
	v_pk_add_f32 v[236:237], v[236:237], v[98:99]
	v_pk_add_f32 v[238:239], v[238:239], v[102:103]
	v_pk_add_f32 v[240:241], v[240:241], v[106:107]
	v_pk_add_f32 v[242:243], v[242:243], v[110:111]
	v_pk_add_f32 v[236:237], v[236:237], v[100:101]
	v_pk_add_f32 v[238:239], v[238:239], v[104:105]
	v_pk_add_f32 v[240:241], v[240:241], v[108:109]
	v_pk_add_f32 v[242:243], v[242:243], v[112:113]
	v_pk_add_f32 v[236:237], v[236:237], v[114:115]
	v_pk_add_f32 v[236:237], v[236:237], v[116:117]
	v_pk_add_f32 v[236:237], v[236:237], v[238:239]
	v_pk_add_f32 v[240:241], v[240:241], v[242:243]
	v_cndmask_b32_e64 v219, 0, v219, s[74:75]
	v_pk_add_f32 v[236:237], v[236:237], v[240:241]
	v_add_f32_e32 v185, v236, v237
	v_add_f32_e32 v185, v185, v219
	v_cvt_pk_bf16_f32 v236, v50, v51
	v_cvt_pk_bf16_f32 v237, v52, v53
	v_cvt_pk_bf16_f32 v238, v54, v55
	v_cvt_pk_bf16_f32 v239, v56, v57
	s_nop 1
	s_waitcnt lgkmcnt(14)
; #define LAS __attribute__((address_space(3)))
; __device__ __forceinline__ unsigned pk2(float lo, float hi) { return pg8::cvt_pk_bf16(lo, hi); }
; __device__ __forceinline__ s16x4 vtr(const LAS unsigned char* p) { return __builtin_bit_cast(s16x4, __builtin_amdgcn_ds_read_tr16_b64_v4i16((LAS s16x4*)p)); }
; #define MFMA16(a, b, c) __builtin_amdgcn_mfma_f32_16x16x32_bf16((a), (b), (c), 0, 0, 0)
; __device__ __forceinline__ void pv_at(const LAS unsigned char* const (&vp)[4], int off, const f32x4& P0, const f32x4& P1, f32x4 (&O)[4]) {
;     v4u pw; pw.x = pk2(P0[0], P0[1]); pw.y = pk2(P0[2], P0[3]); pw.z = pk2(P1[0], P1[1]); pw.w = pk2(P1[2], P1[3]);
;     const bf16x8 pb = __builtin_bit_cast(bf16x8, pw);
; #pragma unroll
;     for (int db = 0; db < 4; ++db) {
;         const s16x4 lo = vtr(vp[db] + off), hi = vtr(vp[db] + off + 2048);
;         const bf16x8 vt = (bf16x8){lo[0], lo[1], lo[2], lo[3], hi[0], hi[1], hi[2], hi[3]};
;         O[db] = MFMA16(vt, pb, O[db]);
;     }
; }
; __device__ __forceinline__ void softmax_step(f32x4& s0, f32x4& s1, float& m, float& l, f32x4 (&O)[4]) {
;     float t = fmaxf(fmaxf(fmaxf(s0[0], s0[1]), fmaxf(s0[2], s0[3])), fmaxf(fmaxf(s1[0], s1[1]), fmaxf(s1[2], s1[3])));
;     t = xrow16_max(t);
;     const float mn = fmaxf(m, t), alpha = __builtin_amdgcn_exp2f(m - mn);
;     m = mn;
; #pragma unroll
;     for (int k = 0; k < 4; ++k) { s0[k] = __builtin_amdgcn_exp2f(s0[k] - mn); s1[k] = __builtin_amdgcn_exp2f(s1[k] - mn); }
;     l = l * alpha + ((s0[0] + s0[1]) + (s0[2] + s0[3])) + ((s1[0] + s1[1]) + (s1[2] + s1[3]));
; #pragma unroll
;     for (int db = 0; db < 4; ++db) O[db] *= alpha;
; }
	v_mfma_f32_16x16x32_bf16 v[210:213], v[186:189], v[236:239], 0
	s_waitcnt lgkmcnt(12)
	v_mfma_f32_16x16x32_bf16 v[214:217], v[190:193], v[236:239], 0
	s_waitcnt lgkmcnt(10)
	v_mfma_f32_16x16x32_bf16 v[220:223], v[194:197], v[236:239], 0
	s_waitcnt lgkmcnt(8)
	v_mfma_f32_16x16x32_bf16 v[224:227], v[198:201], v[236:239], 0
	v_cvt_pk_bf16_f32 v240, v58, v59
	v_cvt_pk_bf16_f32 v241, v60, v61
	v_cvt_pk_bf16_f32 v242, v62, v63
	v_cvt_pk_bf16_f32 v243, v64, v65
	s_waitcnt lgkmcnt(7)
	ds_read_b64_tr_b16 v[186:187], v124 offset:8192
	ds_read_b64_tr_b16 v[188:189], v124 offset:10240
	ds_read_b64_tr_b16 v[190:191], v125 offset:8192
	ds_read_b64_tr_b16 v[192:193], v125 offset:10240
	ds_read_b64_tr_b16 v[194:195], v126 offset:8192
	ds_read_b64_tr_b16 v[196:197], v126 offset:10240
	ds_read_b64_tr_b16 v[198:199], v127 offset:8192
	ds_read_b64_tr_b16 v[200:201], v127 offset:10240
	s_waitcnt lgkmcnt(14)
	v_mfma_f32_16x16x32_bf16 v[210:213], v[202:205], v[240:243], v[210:213]
	s_waitcnt lgkmcnt(12)
	v_mfma_f32_16x16x32_bf16 v[214:217], v[206:209], v[240:243], v[214:217]
	s_waitcnt lgkmcnt(10)
	v_mfma_f32_16x16x32_bf16 v[220:223], v[228:231], v[240:243], v[220:223]
	s_waitcnt lgkmcnt(8)
	v_mfma_f32_16x16x32_bf16 v[224:227], v[232:235], v[240:243], v[224:227]
	v_cvt_pk_bf16_f32 v236, v66, v67
	v_cvt_pk_bf16_f32 v237, v68, v69
	v_cvt_pk_bf16_f32 v238, v70, v71
	v_cvt_pk_bf16_f32 v239, v72, v73
	s_waitcnt lgkmcnt(7)
	ds_read_b64_tr_b16 v[202:203], v124 offset:12288
	ds_read_b64_tr_b16 v[204:205], v124 offset:14336
	ds_read_b64_tr_b16 v[206:207], v125 offset:12288
	ds_read_b64_tr_b16 v[208:209], v125 offset:14336
	ds_read_b64_tr_b16 v[228:229], v126 offset:12288
	ds_read_b64_tr_b16 v[230:231], v126 offset:14336
	ds_read_b64_tr_b16 v[232:233], v127 offset:12288
	ds_read_b64_tr_b16 v[234:235], v127 offset:14336
	s_waitcnt lgkmcnt(14)
	v_mfma_f32_16x16x32_bf16 v[210:213], v[186:189], v[236:239], v[210:213]
	s_waitcnt lgkmcnt(12)
	v_mfma_f32_16x16x32_bf16 v[214:217], v[190:193], v[236:239], v[214:217]
	s_waitcnt lgkmcnt(10)
	v_mfma_f32_16x16x32_bf16 v[220:223], v[194:197], v[236:239], v[220:223]
	s_waitcnt lgkmcnt(8)
	v_mfma_f32_16x16x32_bf16 v[224:227], v[198:201], v[236:239], v[224:227]
	v_cvt_pk_bf16_f32 v240, v74, v75
	v_cvt_pk_bf16_f32 v241, v76, v77
	v_cvt_pk_bf16_f32 v242, v78, v79
	v_cvt_pk_bf16_f32 v243, v80, v81
	s_waitcnt lgkmcnt(7)
	ds_read_b64_tr_b16 v[186:187], v124 offset:16384
	ds_read_b64_tr_b16 v[188:189], v124 offset:18432
	ds_read_b64_tr_b16 v[190:191], v125 offset:16384
	ds_read_b64_tr_b16 v[192:193], v125 offset:18432
	ds_read_b64_tr_b16 v[194:195], v126 offset:16384
	ds_read_b64_tr_b16 v[196:197], v126 offset:18432
	ds_read_b64_tr_b16 v[198:199], v127 offset:16384
	ds_read_b64_tr_b16 v[200:201], v127 offset:18432
	s_waitcnt lgkmcnt(14)
	v_mfma_f32_16x16x32_bf16 v[210:213], v[202:205], v[240:243], v[210:213]
	s_waitcnt lgkmcnt(12)
	v_mfma_f32_16x16x32_bf16 v[214:217], v[206:209], v[240:243], v[214:217]
	s_waitcnt lgkmcnt(10)
	v_mfma_f32_16x16x32_bf16 v[220:223], v[228:231], v[240:243], v[220:223]
	s_waitcnt lgkmcnt(8)
	v_mfma_f32_16x16x32_bf16 v[224:227], v[232:235], v[240:243], v[224:227]
	v_cvt_pk_bf16_f32 v236, v82, v83
	v_cvt_pk_bf16_f32 v237, v84, v85
	v_cvt_pk_bf16_f32 v238, v86, v87
	v_cvt_pk_bf16_f32 v239, v88, v89
	s_waitcnt lgkmcnt(7)
	ds_read_b64_tr_b16 v[202:203], v124 offset:20480
	ds_read_b64_tr_b16 v[204:205], v124 offset:22528
	ds_read_b64_tr_b16 v[206:207], v125 offset:20480
	ds_read_b64_tr_b16 v[208:209], v125 offset:22528
	ds_read_b64_tr_b16 v[228:229], v126 offset:20480
	ds_read_b64_tr_b16 v[230:231], v126 offset:22528
	ds_read_b64_tr_b16 v[232:233], v127 offset:20480
	ds_read_b64_tr_b16 v[234:235], v127 offset:22528
	s_waitcnt lgkmcnt(14)
	v_mfma_f32_16x16x32_bf16 v[210:213], v[186:189], v[236:239], v[210:213]
	s_waitcnt lgkmcnt(12)
	v_mfma_f32_16x16x32_bf16 v[214:217], v[190:193], v[236:239], v[214:217]
	s_waitcnt lgkmcnt(10)
	v_mfma_f32_16x16x32_bf16 v[220:223], v[194:197], v[236:239], v[220:223]
	s_waitcnt lgkmcnt(8)
	v_mfma_f32_16x16x32_bf16 v[224:227], v[198:201], v[236:239], v[224:227]
	v_cvt_pk_bf16_f32 v240, v90, v91
	v_cvt_pk_bf16_f32 v241, v92, v93
	v_cvt_pk_bf16_f32 v242, v94, v95
	v_cvt_pk_bf16_f32 v243, v96, v97
	s_waitcnt lgkmcnt(7)
	ds_read_b64_tr_b16 v[186:187], v124 offset:24576
	ds_read_b64_tr_b16 v[188:189], v124 offset:26624
	ds_read_b64_tr_b16 v[190:191], v125 offset:24576
	ds_read_b64_tr_b16 v[192:193], v125 offset:26624
	ds_read_b64_tr_b16 v[194:195], v126 offset:24576
	ds_read_b64_tr_b16 v[196:197], v126 offset:26624
	ds_read_b64_tr_b16 v[198:199], v127 offset:24576
	ds_read_b64_tr_b16 v[200:201], v127 offset:26624
	s_waitcnt lgkmcnt(14)
	v_mfma_f32_16x16x32_bf16 v[210:213], v[202:205], v[240:243], v[210:213]
	s_waitcnt lgkmcnt(12)
	v_mfma_f32_16x16x32_bf16 v[214:217], v[206:209], v[240:243], v[214:217]
	s_waitcnt lgkmcnt(10)
	v_mfma_f32_16x16x32_bf16 v[220:223], v[228:231], v[240:243], v[220:223]
	s_waitcnt lgkmcnt(8)
	v_mfma_f32_16x16x32_bf16 v[224:227], v[232:235], v[240:243], v[224:227]
	v_cvt_pk_bf16_f32 v236, v98, v99
	v_cvt_pk_bf16_f32 v237, v100, v101
	v_cvt_pk_bf16_f32 v238, v102, v103
	v_cvt_pk_bf16_f32 v239, v104, v105
	s_waitcnt lgkmcnt(7)
	ds_read_b64_tr_b16 v[202:203], v124 offset:28672
	ds_read_b64_tr_b16 v[204:205], v124 offset:30720
	ds_read_b64_tr_b16 v[206:207], v125 offset:28672
	ds_read_b64_tr_b16 v[208:209], v125 offset:30720
	ds_read_b64_tr_b16 v[228:229], v126 offset:28672
	ds_read_b64_tr_b16 v[230:231], v126 offset:30720
	ds_read_b64_tr_b16 v[232:233], v127 offset:28672
	ds_read_b64_tr_b16 v[234:235], v127 offset:30720
	s_waitcnt lgkmcnt(14)
; __device__ __forceinline__ unsigned pk2(float lo, float hi) { return pg8::cvt_pk_bf16(lo, hi); }
; __device__ __forceinline__ void store_o(bf16* yrow, int g, float l, const f32x4 (&O)[4]) {
;     const float inv = 1.0f / xrow16_sum(l);
;     unsigned wx[4], wy[4];
; #pragma unroll
;     for (int db = 0; db < 4; ++db) { wx[db] = pk2(O[db][0] * inv, O[db][1] * inv); wy[db] = pk2(O[db][2] * inv, O[db][3] * inv); }
; #pragma unroll
;     for (int p = 0; p < 2; ++p) {
;         auto rx = __builtin_amdgcn_permlane16_swap(wx[2 * p], wx[2 * p + 1], false, false); wx[2 * p] = rx[0]; wx[2 * p + 1] = rx[1];
;         auto ry = __builtin_amdgcn_permlane16_swap(wy[2 * p], wy[2 * p + 1], false, false); wy[2 * p] = ry[0]; wy[2 * p + 1] = ry[1]; }
; #pragma unroll
;     for (int p = 0; p < 2; ++p) {
;         auto rx = __builtin_amdgcn_permlane32_swap(wx[p], wx[p + 2], false, false); wx[p] = rx[0]; wx[p + 2] = rx[1];
;         auto ry = __builtin_amdgcn_permlane32_swap(wy[p], wy[p + 2], false, false); wy[p] = ry[0]; wy[p + 2] = ry[1]; }
;     v4u lo = {wx[0], wy[0], wx[1], wy[1]}, hi = {wx[2], wy[2], wx[3], wy[3]};
;     *(v4u*)(yrow + 16 * g) = lo; *(v4u*)(yrow + 16 * g + 8) = hi;
; }
; template <bool MASK> __device__ __forceinline__ void a_scores(f32x4& S0, f32x4& S1, float basef, float c1, float slope2, int krow0, int kstart) {
; #pragma unroll
;     for (int r = 0; r < 4; ++r) {
;         const float d0 = fabsf(basef - (float)r), d1 = fabsf(basef - (float)(16 + r));
;         const float v0 = S0[r] - slope2 * d0, v1 = S1[r] - slope2 * d1;
;         if (MASK) { const int p0 = kstart + krow0 + r, p1 = p0 + 16;
;             S0[r] = (d0 <= 128.f && p0 >= 0 && p0 < SEQ) ? v0 : -INFINITY; S1[r] = (d1 <= 128.f && p1 >= 0 && p1 < SEQ) ? v1 : -INFINITY; }
;         else { S0[r] = v0; S1[r] = v1; }
;     }
; }
	v_mfma_f32_16x16x32_bf16 v[210:213], v[186:189], v[236:239], v[210:213]
	s_waitcnt lgkmcnt(12)
	v_mfma_f32_16x16x32_bf16 v[214:217], v[190:193], v[236:239], v[214:217]
	s_waitcnt lgkmcnt(10)
	v_mfma_f32_16x16x32_bf16 v[220:223], v[194:197], v[236:239], v[220:223]
	s_waitcnt lgkmcnt(8)
	v_mfma_f32_16x16x32_bf16 v[224:227], v[198:201], v[236:239], v[224:227]
	v_cvt_pk_bf16_f32 v240, v106, v107
	v_cvt_pk_bf16_f32 v241, v108, v109
	v_cvt_pk_bf16_f32 v242, v110, v111
	v_cvt_pk_bf16_f32 v243, v112, v113
	s_waitcnt lgkmcnt(7)
	ds_read_b64_tr_b16 v[186:187], v124 offset:32768
	ds_read_b64_tr_b16 v[188:189], v124 offset:34816
	ds_read_b64_tr_b16 v[190:191], v125 offset:32768
	ds_read_b64_tr_b16 v[192:193], v125 offset:34816
	ds_read_b64_tr_b16 v[194:195], v126 offset:32768
	ds_read_b64_tr_b16 v[196:197], v126 offset:34816
	ds_read_b64_tr_b16 v[198:199], v127 offset:32768
	ds_read_b64_tr_b16 v[200:201], v127 offset:34816
	s_waitcnt lgkmcnt(14)
	v_mfma_f32_16x16x32_bf16 v[210:213], v[202:205], v[240:243], v[210:213]
	s_waitcnt lgkmcnt(12)
	v_mfma_f32_16x16x32_bf16 v[214:217], v[206:209], v[240:243], v[214:217]
	s_waitcnt lgkmcnt(10)
	v_mfma_f32_16x16x32_bf16 v[220:223], v[228:231], v[240:243], v[220:223]
	s_waitcnt lgkmcnt(8)
	v_mfma_f32_16x16x32_bf16 v[224:227], v[232:235], v[240:243], v[224:227]
	v_cvt_pk_bf16_f32 v236, v114, v115
	v_cvt_pk_bf16_f32 v237, v116, v117
	v_mov_b32_e32 v238, 0
	v_mov_b32_e32 v239, 0
	s_nop 1
	s_waitcnt lgkmcnt(6)
	v_mfma_f32_16x16x32_bf16 v[210:213], v[186:189], v[236:239], v[210:213]
	s_waitcnt lgkmcnt(4)
	v_mfma_f32_16x16x32_bf16 v[214:217], v[190:193], v[236:239], v[214:217]
	s_waitcnt lgkmcnt(2)
	v_mfma_f32_16x16x32_bf16 v[220:223], v[194:197], v[236:239], v[220:223]
	s_waitcnt lgkmcnt(0)
	v_mfma_f32_16x16x32_bf16 v[224:227], v[198:201], v[236:239], v[224:227]
	v_mov_b32_e32 v219, v185
	s_nop 1
	v_permlane16_swap_b32_e32 v185, v219
	v_add_f32_e32 v185, v185, v219
	v_mov_b32_e32 v219, v185
	s_nop 1
	v_permlane32_swap_b32_e32 v185, v219
	v_add_f32_e32 v185, v185, v219
	v_div_scale_f32 v236, s[78:79], v185, v185, 1.0
	v_div_scale_f32 v237, vcc, 1.0, v185, 1.0
	v_rcp_f32_e32 v238, v236
	s_nop 0
	v_fma_f32 v239, -v236, v238, 1.0
	v_fmac_f32_e32 v238, v239, v238
	v_mul_f32_e32 v240, v237, v238
	v_fma_f32 v241, -v236, v240, v237
	v_fmac_f32_e32 v240, v241, v238
	v_fma_f32 v237, -v236, v240, v237
	v_div_fmas_f32 v237, v237, v238, v240
	v_div_fixup_f32 v244, v237, v185, 1.0
	v_mul_f32_e32 v240, v210, v244
	v_mul_f32_e32 v241, v211, v244
	v_mul_f32_e32 v242, v212, v244
	v_mul_f32_e32 v243, v213, v244
	v_cvt_pk_bf16_f32 v186, v240, v241
	v_cvt_pk_bf16_f32 v187, v242, v243
	v_mul_f32_e32 v240, v214, v244
	v_mul_f32_e32 v241, v215, v244
	v_mul_f32_e32 v242, v216, v244
	v_mul_f32_e32 v243, v217, v244
	v_cvt_pk_bf16_f32 v188, v240, v241
	v_cvt_pk_bf16_f32 v189, v242, v243
	v_mul_f32_e32 v240, v220, v244
	v_mul_f32_e32 v241, v221, v244
	v_mul_f32_e32 v242, v222, v244
	v_mul_f32_e32 v243, v223, v244
	v_cvt_pk_bf16_f32 v190, v240, v241
	v_cvt_pk_bf16_f32 v191, v242, v243
	v_mul_f32_e32 v240, v224, v244
	v_mul_f32_e32 v241, v225, v244
	v_mul_f32_e32 v242, v226, v244
	v_mul_f32_e32 v243, v227, v244
	v_cvt_pk_bf16_f32 v192, v240, v241
	v_cvt_pk_bf16_f32 v193, v242, v243
	s_nop 1
	v_permlane16_swap_b32_e32 v186, v188
	v_permlane16_swap_b32_e32 v187, v189
	v_permlane16_swap_b32_e32 v190, v192
	v_permlane16_swap_b32_e32 v191, v193
	s_nop 0
	v_permlane32_swap_b32_e32 v186, v190
	v_permlane32_swap_b32_e32 v187, v191
	v_permlane32_swap_b32_e32 v188, v192
	v_permlane32_swap_b32_e32 v189, v193
	global_store_dwordx4 v128, v[186:189], s[82:83] offset:0 sc1
	global_store_dwordx4 v128, v[190:193], s[82:83] offset:16 sc1
	s_nop 1
	s_bitcmp1_b32 s87, 1
	s_cselect_b32 s21, 0, 0xff800000
	v_add_f32_e32 v120, s21, v132
	v_fmamk_f32 v50, v130, 0x43000000, v120
	v_fmamk_f32 v51, v130, 0x42fe0000, v120
	v_fmamk_f32 v52, v130, 0x42fc0000, v120
	v_fmamk_f32 v53, v130, 0x42fa0000, v120
	s_bitcmp1_b32 s87, 2
	s_cselect_b32 s21, 0, 0xff800000
	v_add_f32_e32 v120, s21, v132
	v_fmamk_f32 v54, v130, 0x42e00000, v120
	v_fmamk_f32 v55, v130, 0x42de0000, v120
	v_fmamk_f32 v56, v130, 0x42dc0000, v120
	v_fmamk_f32 v57, v130, 0x42da0000, v120
	s_bitcmp1_b32 s87, 3
	s_cselect_b32 s21, 0, 0xff800000
	v_add_f32_e32 v120, s21, v132
	v_fmamk_f32 v58, v130, 0x42c00000, v120
	v_fmamk_f32 v59, v130, 0x42be0000, v120
	v_fmamk_f32 v60, v130, 0x42bc0000, v120
	v_fmamk_f32 v61, v130, 0x42ba0000, v120
	s_bitcmp1_b32 s87, 4
	s_cselect_b32 s21, 0, 0xff800000
	v_add_f32_e32 v120, s21, v132
	v_fmamk_f32 v62, v130, 0x42a00000, v120
	v_fmamk_f32 v63, v130, 0x429e0000, v120
	v_fmamk_f32 v64, v130, 0x429c0000, v120
	v_fmamk_f32 v65, v130, 0x429a0000, v120
	s_bitcmp1_b32 s87, 5
	s_cselect_b32 s21, 0, 0xff800000
	v_add_f32_e32 v120, s21, v132
	v_fmamk_f32 v66, v130, 0x42800000, v120
	v_fmamk_f32 v67, v130, 0x427c0000, v120
	v_fmamk_f32 v68, v130, 0x42780000, v120
	v_fmamk_f32 v69, v130, 0x42740000, v120
	s_bitcmp1_b32 s87, 6
	s_cselect_b32 s21, 0, 0xff800000
	v_add_f32_e32 v120, s21, v132
	v_fmamk_f32 v70, v130, 0x42400000, v120
	v_fmamk_f32 v71, v130, 0x423c0000, v120
	v_fmamk_f32 v72, v130, 0x42380000, v120
	v_fmamk_f32 v73, v130, 0x42340000, v120
	s_bitcmp1_b32 s87, 7
	s_cselect_b32 s21, 0, 0xff800000
	v_add_f32_e32 v120, s21, v132
	v_fmamk_f32 v74, v130, 0x42000000, v120
	v_fmamk_f32 v75, v130, 0x41f80000, v120
	v_fmamk_f32 v76, v130, 0x41f00000, v120
	v_fmamk_f32 v77, v130, 0x41e80000, v120
	s_bitcmp1_b32 s87, 8
	s_cselect_b32 s21, 0, 0xff800000
	v_add_f32_e32 v120, s21, v132
	v_fmamk_f32 v78, v130, 0x41800000, v120
	v_fmamk_f32 v79, v130, 0x41700000, v120
	v_fmamk_f32 v80, v130, 0x41600000, v120
; #define LAS __attribute__((address_space(3)))
; #define MFMA16(a, b, c) __builtin_amdgcn_mfma_f32_16x16x32_bf16((a), (b), (c), 0, 0, 0)
; __device__ __forceinline__ void qk_at(const LAS unsigned char* kp0, const LAS unsigned char* kp1, int off, bf16x8 qf0, bf16x8 qf1, f32x4& S0, f32x4& S1) {
;     const bf16x8 k00 = *(const LAS bf16x8*)(kp0 + off), k01 = *(const LAS bf16x8*)(kp1 + off);
;     const bf16x8 k10 = *(const LAS bf16x8*)(kp0 + off + 2048), k11 = *(const LAS bf16x8*)(kp1 + off + 2048);
;     const f32x4 z = {0.f, 0.f, 0.f, 0.f};
;     S0 = MFMA16(k00, qf0, z); S0 = MFMA16(k01, qf1, S0);
;     S1 = MFMA16(k10, qf0, z); S1 = MFMA16(k11, qf1, S1);
; }
; template <bool MASK> __device__ __forceinline__ void a_scores(f32x4& S0, f32x4& S1, float basef, float c1, float slope2, int krow0, int kstart) {
; #pragma unroll
;     for (int r = 0; r < 4; ++r) {
;         const float d0 = fabsf(basef - (float)r), d1 = fabsf(basef - (float)(16 + r));
;         const float v0 = S0[r] - slope2 * d0, v1 = S1[r] - slope2 * d1;
;         if (MASK) { const int p0 = kstart + krow0 + r, p1 = p0 + 16;
;             S0[r] = (d0 <= 128.f && p0 >= 0 && p0 < SEQ) ? v0 : -INFINITY; S1[r] = (d1 <= 128.f && p1 >= 0 && p1 < SEQ) ? v1 : -INFINITY; }
;         else { S0[r] = v0; S1[r] = v1; }
;     }
; }
	v_fmamk_f32 v81, v130, 0x41500000, v120
	s_bitcmp1_b32 s87, 9
	s_cselect_b32 s21, 0, 0xff800000
	v_add_f32_e32 v219, 0, v129
	v_fma_f32 v82, v130, |v219|, s21
	v_add_f32_e32 v244, 0xbf800000, v129
	v_fma_f32 v83, v130, |v244|, s21
	v_add_f32_e32 v219, 0xc0000000, v129
	v_fma_f32 v84, v130, |v219|, s21
	v_add_f32_e32 v244, 0xc0400000, v129
	v_fma_f32 v85, v130, |v244|, s21
	s_bitcmp1_b32 s87, 10
	s_cselect_b32 s21, 0, 0xff800000
	v_add_f32_e32 v120, s21, v133
	v_fmamk_f32 v86, v131, 0xc1800000, v120
	v_fmamk_f32 v87, v131, 0xc1880000, v120
	v_fmamk_f32 v88, v131, 0xc1900000, v120
	v_fmamk_f32 v89, v131, 0xc1980000, v120
	s_bitcmp1_b32 s87, 11
	s_cselect_b32 s21, 0, 0xff800000
	v_add_f32_e32 v120, s21, v133
	v_fmamk_f32 v90, v131, 0xc2000000, v120
	v_fmamk_f32 v91, v131, 0xc2040000, v120
	v_fmamk_f32 v92, v131, 0xc2080000, v120
	v_fmamk_f32 v93, v131, 0xc20c0000, v120
	s_bitcmp1_b32 s87, 12
	s_cselect_b32 s21, 0, 0xff800000
	v_add_f32_e32 v120, s21, v133
	v_fmamk_f32 v94, v131, 0xc2400000, v120
	v_fmamk_f32 v95, v131, 0xc2440000, v120
	v_fmamk_f32 v96, v131, 0xc2480000, v120
	v_fmamk_f32 v97, v131, 0xc24c0000, v120
	s_bitcmp1_b32 s87, 13
	s_cselect_b32 s21, 0, 0xff800000
	v_add_f32_e32 v120, s21, v133
	v_fmamk_f32 v98, v131, 0xc2800000, v120
	v_fmamk_f32 v99, v131, 0xc2820000, v120
	v_fmamk_f32 v100, v131, 0xc2840000, v120
	v_fmamk_f32 v101, v131, 0xc2860000, v120
	s_bitcmp1_b32 s87, 14
	s_cselect_b32 s21, 0, 0xff800000
	v_add_f32_e32 v120, s21, v133
	v_fmamk_f32 v102, v131, 0xc2a00000, v120
	v_fmamk_f32 v103, v131, 0xc2a20000, v120
	v_fmamk_f32 v104, v131, 0xc2a40000, v120
	v_fmamk_f32 v105, v131, 0xc2a60000, v120
	s_bitcmp1_b32 s87, 15
	s_cselect_b32 s21, 0, 0xff800000
	v_add_f32_e32 v120, s21, v133
	v_fmamk_f32 v106, v131, 0xc2c00000, v120
	v_fmamk_f32 v107, v131, 0xc2c20000, v120
	v_fmamk_f32 v108, v131, 0xc2c40000, v120
	v_fmamk_f32 v109, v131, 0xc2c60000, v120
	s_bitcmp1_b32 s87, 16
	s_cselect_b32 s21, 0, 0xff800000
	v_add_f32_e32 v120, s21, v133
	v_fmamk_f32 v110, v131, 0xc2e00000, v120
	v_fmamk_f32 v111, v131, 0xc2e20000, v120
	v_fmamk_f32 v112, v131, 0xc2e40000, v120
	v_fmamk_f32 v113, v131, 0xc2e60000, v120
	s_bitcmp1_b32 s87, 17
	s_cselect_b32 s21, 0, 0xff800000
	v_add_f32_e32 v120, s21, v133
	v_fmamk_f32 v114, v131, 0xc3000000, v120
	v_fmamk_f32 v115, v131, 0xc3010000, v120
	v_fmamk_f32 v116, v131, 0xc3020000, v120
	v_fmamk_f32 v117, v131, 0xc3030000, v120
	v_mov_b32_e32 v245, 0xff800000
	v_cndmask_b32_e64 v50, v245, v50, s[16:17]
	v_cndmask_b32_e64 v51, v245, v51, s[18:19]
	v_cndmask_b32_e64 v52, v245, v52, s[22:23]
	v_cndmask_b32_e64 v53, v245, v53, s[24:25]
	v_cndmask_b32_e64 v114, v245, v114, s[28:29]
	v_cndmask_b32_e64 v115, v245, v115, s[52:53]
	v_cndmask_b32_e64 v116, v245, v116, s[54:55]
	v_cndmask_b32_e64 v117, v245, v117, s[88:89]
	ds_read_b128 v[186:189], v122 offset:2048
	ds_read_b128 v[190:193], v123 offset:2048
	ds_read_b128 v[194:197], v122 offset:4096
	ds_read_b128 v[198:201], v123 offset:4096
	ds_read_b128 v[202:205], v122 offset:6144
	ds_read_b128 v[206:209], v123 offset:6144
	s_waitcnt lgkmcnt(5)
	v_mfma_f32_16x16x32_bf16 v[50:53], v[186:189], v[154:157], v[50:53]
	s_waitcnt lgkmcnt(4)
	v_mfma_f32_16x16x32_bf16 v[50:53], v[190:193], v[158:161], v[50:53]
	ds_read_b128 v[186:189], v122 offset:8192
	ds_read_b128 v[190:193], v123 offset:8192
	s_waitcnt lgkmcnt(5)
	v_mfma_f32_16x16x32_bf16 v[54:57], v[194:197], v[154:157], v[54:57]
	s_waitcnt lgkmcnt(4)
	v_mfma_f32_16x16x32_bf16 v[54:57], v[198:201], v[158:161], v[54:57]
	ds_read_b128 v[194:197], v122 offset:10240
	ds_read_b128 v[198:201], v123 offset:10240
	s_waitcnt lgkmcnt(5)
	v_mfma_f32_16x16x32_bf16 v[58:61], v[202:205], v[154:157], v[58:61]
	s_waitcnt lgkmcnt(4)
	v_mfma_f32_16x16x32_bf16 v[58:61], v[206:209], v[158:161], v[58:61]
	ds_read_b128 v[202:205], v122 offset:12288
	ds_read_b128 v[206:209], v123 offset:12288
	s_waitcnt lgkmcnt(5)
	v_mfma_f32_16x16x32_bf16 v[62:65], v[186:189], v[154:157], v[62:65]
	s_waitcnt lgkmcnt(4)
	v_mfma_f32_16x16x32_bf16 v[62:65], v[190:193], v[158:161], v[62:65]
	ds_read_b128 v[186:189], v122 offset:14336
	ds_read_b128 v[190:193], v123 offset:14336
	s_waitcnt lgkmcnt(5)
	v_mfma_f32_16x16x32_bf16 v[66:69], v[194:197], v[154:157], v[66:69]
	s_waitcnt lgkmcnt(4)
	v_mfma_f32_16x16x32_bf16 v[66:69], v[198:201], v[158:161], v[66:69]
	ds_read_b128 v[194:197], v122 offset:16384
	ds_read_b128 v[198:201], v123 offset:16384
	s_waitcnt lgkmcnt(5)
	v_mfma_f32_16x16x32_bf16 v[70:73], v[202:205], v[154:157], v[70:73]
	s_waitcnt lgkmcnt(4)
	v_mfma_f32_16x16x32_bf16 v[70:73], v[206:209], v[158:161], v[70:73]
	ds_read_b128 v[202:205], v122 offset:18432
	ds_read_b128 v[206:209], v123 offset:18432
	s_waitcnt lgkmcnt(5)
	v_mfma_f32_16x16x32_bf16 v[74:77], v[186:189], v[154:157], v[74:77]
	s_waitcnt lgkmcnt(4)
	v_mfma_f32_16x16x32_bf16 v[74:77], v[190:193], v[158:161], v[74:77]
	ds_read_b128 v[186:189], v122 offset:20480
	ds_read_b128 v[190:193], v123 offset:20480
	s_waitcnt lgkmcnt(5)
	v_mfma_f32_16x16x32_bf16 v[78:81], v[194:197], v[154:157], v[78:81]
	s_waitcnt lgkmcnt(4)
	v_mfma_f32_16x16x32_bf16 v[78:81], v[198:201], v[158:161], v[78:81]
	ds_read_b128 v[194:197], v122 offset:22528
	ds_read_b128 v[198:201], v123 offset:22528
	s_waitcnt lgkmcnt(5)
	v_mfma_f32_16x16x32_bf16 v[82:85], v[202:205], v[154:157], v[82:85]
	s_waitcnt lgkmcnt(4)
	v_mfma_f32_16x16x32_bf16 v[82:85], v[206:209], v[158:161], v[82:85]
	ds_read_b128 v[202:205], v122 offset:24576
	ds_read_b128 v[206:209], v123 offset:24576
	s_waitcnt lgkmcnt(5)
	v_mfma_f32_16x16x32_bf16 v[86:89], v[186:189], v[154:157], v[86:89]
	s_waitcnt lgkmcnt(4)
; #define LAS __attribute__((address_space(3)))
; #define MFMA16(a, b, c) __builtin_amdgcn_mfma_f32_16x16x32_bf16((a), (b), (c), 0, 0, 0)
; __device__ __forceinline__ void qk_at(const LAS unsigned char* kp0, const LAS unsigned char* kp1, int off, bf16x8 qf0, bf16x8 qf1, f32x4& S0, f32x4& S1) {
;     const bf16x8 k00 = *(const LAS bf16x8*)(kp0 + off), k01 = *(const LAS bf16x8*)(kp1 + off);
;     const bf16x8 k10 = *(const LAS bf16x8*)(kp0 + off + 2048), k11 = *(const LAS bf16x8*)(kp1 + off + 2048);
;     const f32x4 z = {0.f, 0.f, 0.f, 0.f};
;     S0 = MFMA16(k00, qf0, z); S0 = MFMA16(k01, qf1, S0);
;     S1 = MFMA16(k10, qf0, z); S1 = MFMA16(k11, qf1, S1);
; }
; __device__ __forceinline__ void softmax_step(f32x4& s0, f32x4& s1, float& m, float& l, f32x4 (&O)[4]) {
;     float t = fmaxf(fmaxf(fmaxf(s0[0], s0[1]), fmaxf(s0[2], s0[3])), fmaxf(fmaxf(s1[0], s1[1]), fmaxf(s1[2], s1[3])));
;     t = xrow16_max(t);
;     const float mn = fmaxf(m, t), alpha = __builtin_amdgcn_exp2f(m - mn);
;     m = mn;
	v_mfma_f32_16x16x32_bf16 v[86:89], v[190:193], v[158:161], v[86:89]
	ds_read_b128 v[186:189], v122 offset:26624
	ds_read_b128 v[190:193], v123 offset:26624
	s_waitcnt lgkmcnt(5)
	v_mfma_f32_16x16x32_bf16 v[90:93], v[194:197], v[154:157], v[90:93]
	s_waitcnt lgkmcnt(4)
	v_mfma_f32_16x16x32_bf16 v[90:93], v[198:201], v[158:161], v[90:93]
	ds_read_b128 v[194:197], v122 offset:28672
	ds_read_b128 v[198:201], v123 offset:28672
	s_waitcnt lgkmcnt(5)
	v_mfma_f32_16x16x32_bf16 v[94:97], v[202:205], v[154:157], v[94:97]
	s_waitcnt lgkmcnt(4)
	v_mfma_f32_16x16x32_bf16 v[94:97], v[206:209], v[158:161], v[94:97]
	ds_read_b128 v[202:205], v122 offset:30720
	ds_read_b128 v[206:209], v123 offset:30720
	s_waitcnt lgkmcnt(5)
	v_mfma_f32_16x16x32_bf16 v[98:101], v[186:189], v[154:157], v[98:101]
	s_waitcnt lgkmcnt(4)
	v_mfma_f32_16x16x32_bf16 v[98:101], v[190:193], v[158:161], v[98:101]
	ds_read_b128 v[186:189], v122 offset:32768
	ds_read_b128 v[190:193], v123 offset:32768
	s_waitcnt lgkmcnt(5)
	v_mfma_f32_16x16x32_bf16 v[102:105], v[194:197], v[154:157], v[102:105]
	s_waitcnt lgkmcnt(4)
	v_mfma_f32_16x16x32_bf16 v[102:105], v[198:201], v[158:161], v[102:105]
	ds_read_b128 v[194:197], v122 offset:34816
	ds_read_b128 v[198:201], v123 offset:34816
	s_waitcnt lgkmcnt(5)
	v_mfma_f32_16x16x32_bf16 v[106:109], v[202:205], v[154:157], v[106:109]
	s_waitcnt lgkmcnt(4)
	v_mfma_f32_16x16x32_bf16 v[106:109], v[206:209], v[158:161], v[106:109]
	s_waitcnt lgkmcnt(3)
	v_mfma_f32_16x16x32_bf16 v[110:113], v[186:189], v[154:157], v[110:113]
	s_waitcnt lgkmcnt(2)
	v_mfma_f32_16x16x32_bf16 v[110:113], v[190:193], v[158:161], v[110:113]
	s_waitcnt lgkmcnt(1)
	v_mfma_f32_16x16x32_bf16 v[114:117], v[194:197], v[154:157], v[114:117]
	s_waitcnt lgkmcnt(0)
	v_mfma_f32_16x16x32_bf16 v[114:117], v[198:201], v[158:161], v[114:117]
	v_max3_f32 v219, v50, v51, v52
	v_max3_f32 v244, v54, v55, v56
	v_max3_f32 v245, v58, v59, v60
	v_max3_f32 v120, v62, v63, v64
	v_max3_f32 v219, v219, v53, v66
	v_max3_f32 v244, v244, v57, v70
	v_max3_f32 v245, v245, v61, v74
	v_max3_f32 v120, v120, v65, v78
	v_max3_f32 v219, v219, v67, v68
	v_max3_f32 v244, v244, v71, v72
	v_max3_f32 v245, v245, v75, v76
	v_max3_f32 v120, v120, v79, v80
	ds_read_b64_tr_b16 v[186:187], v124 offset:2048
	ds_read_b64_tr_b16 v[188:189], v124 offset:4096
	ds_read_b64_tr_b16 v[190:191], v125 offset:2048
	ds_read_b64_tr_b16 v[192:193], v125 offset:4096
	ds_read_b64_tr_b16 v[194:195], v126 offset:2048
	ds_read_b64_tr_b16 v[196:197], v126 offset:4096
	ds_read_b64_tr_b16 v[198:199], v127 offset:2048
	ds_read_b64_tr_b16 v[200:201], v127 offset:4096
	v_max3_f32 v219, v219, v69, v82
	v_max3_f32 v244, v244, v73, v86
	v_max3_f32 v245, v245, v77, v90
	v_max3_f32 v120, v120, v81, v94
	v_max3_f32 v219, v219, v83, v84
	v_max3_f32 v244, v244, v87, v88
	v_max3_f32 v245, v245, v91, v92
	v_max3_f32 v120, v120, v95, v96
	v_max3_f32 v219, v219, v85, v98
	v_max3_f32 v244, v244, v89, v102
	v_max3_f32 v245, v245, v93, v106
	v_max3_f32 v120, v120, v97, v110
	v_max3_f32 v219, v219, v99, v100
	v_max3_f32 v244, v244, v103, v104
	v_max3_f32 v245, v245, v107, v108
	v_max3_f32 v120, v120, v111, v112
	v_max3_f32 v219, v219, v101, v114
	v_max3_f32 v219, v219, v115, v116
	v_max_f32_e32 v219, v219, v117
	v_max_f32_e32 v244, v244, v105
	v_max_f32_e32 v245, v245, v109
	v_max_f32_e32 v120, v120, v113
	v_max3_f32 v178, v219, v244, v245
	v_max_f32_e32 v178, v178, v120
	v_mov_b32_e32 v219, v178
	s_nop 1
	v_permlane16_swap_b32_e32 v178, v219
	v_max_f32_e32 v178, v178, v219
	v_mov_b32_e32 v219, v178
	s_nop 1
	v_permlane32_swap_b32_e32 v178, v219
	v_max3_f32 v178, v178, v219, v145
	s_waitcnt lgkmcnt(7)
	ds_read_b64_tr_b16 v[202:203], v124 offset:6144
	ds_read_b64_tr_b16 v[204:205], v124 offset:8192
	ds_read_b64_tr_b16 v[206:207], v125 offset:6144
	ds_read_b64_tr_b16 v[208:209], v125 offset:8192
	ds_read_b64_tr_b16 v[228:229], v126 offset:6144
	ds_read_b64_tr_b16 v[230:231], v126 offset:8192
	ds_read_b64_tr_b16 v[232:233], v127 offset:6144
	ds_read_b64_tr_b16 v[234:235], v127 offset:8192
	v_mov_b32_e32 v244, v178
	v_pk_add_f32 v[50:51], v[50:51], v[244:245] op_sel_hi:[1,0] neg_lo:[0,1] neg_hi:[0,1]
	v_pk_add_f32 v[52:53], v[52:53], v[244:245] op_sel_hi:[1,0] neg_lo:[0,1] neg_hi:[0,1]
	v_pk_add_f32 v[54:55], v[54:55], v[244:245] op_sel_hi:[1,0] neg_lo:[0,1] neg_hi:[0,1]
	v_pk_add_f32 v[56:57], v[56:57], v[244:245] op_sel_hi:[1,0] neg_lo:[0,1] neg_hi:[0,1]
	v_pk_add_f32 v[58:59], v[58:59], v[244:245] op_sel_hi:[1,0] neg_lo:[0,1] neg_hi:[0,1]
	v_pk_add_f32 v[60:61], v[60:61], v[244:245] op_sel_hi:[1,0] neg_lo:[0,1] neg_hi:[0,1]
	v_pk_add_f32 v[62:63], v[62:63], v[244:245] op_sel_hi:[1,0] neg_lo:[0,1] neg_hi:[0,1]
	v_pk_add_f32 v[64:65], v[64:65], v[244:245] op_sel_hi:[1,0] neg_lo:[0,1] neg_hi:[0,1]
	v_pk_add_f32 v[66:67], v[66:67], v[244:245] op_sel_hi:[1,0] neg_lo:[0,1] neg_hi:[0,1]
	v_pk_add_f32 v[68:69], v[68:69], v[244:245] op_sel_hi:[1,0] neg_lo:[0,1] neg_hi:[0,1]
	v_pk_add_f32 v[70:71], v[70:71], v[244:245] op_sel_hi:[1,0] neg_lo:[0,1] neg_hi:[0,1]
	v_pk_add_f32 v[72:73], v[72:73], v[244:245] op_sel_hi:[1,0] neg_lo:[0,1] neg_hi:[0,1]
	v_pk_add_f32 v[74:75], v[74:75], v[244:245] op_sel_hi:[1,0] neg_lo:[0,1] neg_hi:[0,1]
	v_pk_add_f32 v[76:77], v[76:77], v[244:245] op_sel_hi:[1,0] neg_lo:[0,1] neg_hi:[0,1]
	v_pk_add_f32 v[78:79], v[78:79], v[244:245] op_sel_hi:[1,0] neg_lo:[0,1] neg_hi:[0,1]
	v_pk_add_f32 v[80:81], v[80:81], v[244:245] op_sel_hi:[1,0] neg_lo:[0,1] neg_hi:[0,1]
	v_pk_add_f32 v[82:83], v[82:83], v[244:245] op_sel_hi:[1,0] neg_lo:[0,1] neg_hi:[0,1]
	v_pk_add_f32 v[84:85], v[84:85], v[244:245] op_sel_hi:[1,0] neg_lo:[0,1] neg_hi:[0,1]
; #define LAS __attribute__((address_space(3)))
; __device__ __forceinline__ unsigned pk2(float lo, float hi) { return pg8::cvt_pk_bf16(lo, hi); }
; __device__ __forceinline__ s16x4 vtr(const LAS unsigned char* p) { return __builtin_bit_cast(s16x4, __builtin_amdgcn_ds_read_tr16_b64_v4i16((LAS s16x4*)p)); }
; #define MFMA16(a, b, c) __builtin_amdgcn_mfma_f32_16x16x32_bf16((a), (b), (c), 0, 0, 0)
; __device__ __forceinline__ void pv_at(const LAS unsigned char* const (&vp)[4], int off, const f32x4& P0, const f32x4& P1, f32x4 (&O)[4]) {
;     v4u pw; pw.x = pk2(P0[0], P0[1]); pw.y = pk2(P0[2], P0[3]); pw.z = pk2(P1[0], P1[1]); pw.w = pk2(P1[2], P1[3]);
;     const bf16x8 pb = __builtin_bit_cast(bf16x8, pw);
; #pragma unroll
;     for (int db = 0; db < 4; ++db) {
;         const s16x4 lo = vtr(vp[db] + off), hi = vtr(vp[db] + off + 2048);
;         const bf16x8 vt = (bf16x8){lo[0], lo[1], lo[2], lo[3], hi[0], hi[1], hi[2], hi[3]};
;         O[db] = MFMA16(vt, pb, O[db]);
;     }
; }
; __device__ __forceinline__ void softmax_step(f32x4& s0, f32x4& s1, float& m, float& l, f32x4 (&O)[4]) {
;     float t = fmaxf(fmaxf(fmaxf(s0[0], s0[1]), fmaxf(s0[2], s0[3])), fmaxf(fmaxf(s1[0], s1[1]), fmaxf(s1[2], s1[3])));
;     t = xrow16_max(t);
;     const float mn = fmaxf(m, t), alpha = __builtin_amdgcn_exp2f(m - mn);
;     m = mn;
; #pragma unroll
;     for (int k = 0; k < 4; ++k) { s0[k] = __builtin_amdgcn_exp2f(s0[k] - mn); s1[k] = __builtin_amdgcn_exp2f(s1[k] - mn); }
;     l = l * alpha + ((s0[0] + s0[1]) + (s0[2] + s0[3])) + ((s1[0] + s1[1]) + (s1[2] + s1[3]));
; #pragma unroll
;     for (int db = 0; db < 4; ++db) O[db] *= alpha;
; }
	v_pk_add_f32 v[86:87], v[86:87], v[244:245] op_sel_hi:[1,0] neg_lo:[0,1] neg_hi:[0,1]
	v_pk_add_f32 v[88:89], v[88:89], v[244:245] op_sel_hi:[1,0] neg_lo:[0,1] neg_hi:[0,1]
	v_pk_add_f32 v[90:91], v[90:91], v[244:245] op_sel_hi:[1,0] neg_lo:[0,1] neg_hi:[0,1]
	v_pk_add_f32 v[92:93], v[92:93], v[244:245] op_sel_hi:[1,0] neg_lo:[0,1] neg_hi:[0,1]
	v_pk_add_f32 v[94:95], v[94:95], v[244:245] op_sel_hi:[1,0] neg_lo:[0,1] neg_hi:[0,1]
	v_pk_add_f32 v[96:97], v[96:97], v[244:245] op_sel_hi:[1,0] neg_lo:[0,1] neg_hi:[0,1]
	v_pk_add_f32 v[98:99], v[98:99], v[244:245] op_sel_hi:[1,0] neg_lo:[0,1] neg_hi:[0,1]
	v_pk_add_f32 v[100:101], v[100:101], v[244:245] op_sel_hi:[1,0] neg_lo:[0,1] neg_hi:[0,1]
	v_pk_add_f32 v[102:103], v[102:103], v[244:245] op_sel_hi:[1,0] neg_lo:[0,1] neg_hi:[0,1]
	v_pk_add_f32 v[104:105], v[104:105], v[244:245] op_sel_hi:[1,0] neg_lo:[0,1] neg_hi:[0,1]
	v_pk_add_f32 v[106:107], v[106:107], v[244:245] op_sel_hi:[1,0] neg_lo:[0,1] neg_hi:[0,1]
	v_pk_add_f32 v[108:109], v[108:109], v[244:245] op_sel_hi:[1,0] neg_lo:[0,1] neg_hi:[0,1]
	v_pk_add_f32 v[110:111], v[110:111], v[244:245] op_sel_hi:[1,0] neg_lo:[0,1] neg_hi:[0,1]
	v_pk_add_f32 v[112:113], v[112:113], v[244:245] op_sel_hi:[1,0] neg_lo:[0,1] neg_hi:[0,1]
	v_pk_add_f32 v[114:115], v[114:115], v[244:245] op_sel_hi:[1,0] neg_lo:[0,1] neg_hi:[0,1]
	v_pk_add_f32 v[116:117], v[116:117], v[244:245] op_sel_hi:[1,0] neg_lo:[0,1] neg_hi:[0,1]
	v_sub_f32_e32 v219, v145, v178
	v_exp_f32_e32 v50, v50
	v_exp_f32_e32 v51, v51
	v_exp_f32_e32 v52, v52
	v_exp_f32_e32 v53, v53
	v_exp_f32_e32 v54, v54
	v_exp_f32_e32 v55, v55
	v_exp_f32_e32 v56, v56
	v_exp_f32_e32 v57, v57
	v_exp_f32_e32 v58, v58
	v_exp_f32_e32 v59, v59
	v_exp_f32_e32 v60, v60
	v_exp_f32_e32 v61, v61
	v_exp_f32_e32 v62, v62
	v_exp_f32_e32 v63, v63
	v_exp_f32_e32 v64, v64
	v_exp_f32_e32 v65, v65
	v_exp_f32_e32 v66, v66
	v_exp_f32_e32 v67, v67
	v_exp_f32_e32 v68, v68
	v_exp_f32_e32 v69, v69
	v_exp_f32_e32 v70, v70
	v_exp_f32_e32 v71, v71
	v_exp_f32_e32 v72, v72
	v_exp_f32_e32 v73, v73
	v_exp_f32_e32 v74, v74
	v_exp_f32_e32 v75, v75
	v_exp_f32_e32 v76, v76
	v_exp_f32_e32 v77, v77
	v_exp_f32_e32 v78, v78
	v_exp_f32_e32 v79, v79
	v_exp_f32_e32 v80, v80
	v_exp_f32_e32 v81, v81
	v_exp_f32_e32 v82, v82
	v_exp_f32_e32 v83, v83
	v_exp_f32_e32 v84, v84
	v_exp_f32_e32 v85, v85
	v_exp_f32_e32 v86, v86
	v_exp_f32_e32 v87, v87
	v_exp_f32_e32 v88, v88
	v_exp_f32_e32 v89, v89
	v_exp_f32_e32 v90, v90
	v_exp_f32_e32 v91, v91
	v_exp_f32_e32 v92, v92
	v_exp_f32_e32 v93, v93
	v_exp_f32_e32 v94, v94
	v_exp_f32_e32 v95, v95
	v_exp_f32_e32 v96, v96
	v_exp_f32_e32 v97, v97
	v_exp_f32_e32 v98, v98
	v_exp_f32_e32 v99, v99
	v_exp_f32_e32 v100, v100
	v_exp_f32_e32 v101, v101
	v_exp_f32_e32 v102, v102
	v_exp_f32_e32 v103, v103
	v_exp_f32_e32 v104, v104
	v_exp_f32_e32 v105, v105
	v_exp_f32_e32 v106, v106
	v_exp_f32_e32 v107, v107
	v_exp_f32_e32 v108, v108
	v_exp_f32_e32 v109, v109
	v_exp_f32_e32 v110, v110
	v_exp_f32_e32 v111, v111
	v_exp_f32_e32 v112, v112
	v_exp_f32_e32 v113, v113
	v_exp_f32_e32 v114, v114
	v_exp_f32_e32 v115, v115
	v_exp_f32_e32 v116, v116
	v_exp_f32_e32 v117, v117
	v_exp_f32_e32 v219, v219
	v_pk_add_f32 v[236:237], v[50:51], v[52:53]
	v_pk_add_f32 v[238:239], v[54:55], v[56:57]
	v_pk_add_f32 v[240:241], v[58:59], v[60:61]
	v_pk_add_f32 v[242:243], v[62:63], v[64:65]
	v_pk_add_f32 v[236:237], v[236:237], v[66:67]
	v_pk_add_f32 v[238:239], v[238:239], v[70:71]
	v_pk_add_f32 v[240:241], v[240:241], v[74:75]
	v_pk_add_f32 v[242:243], v[242:243], v[78:79]
	v_pk_add_f32 v[236:237], v[236:237], v[68:69]
	v_pk_add_f32 v[238:239], v[238:239], v[72:73]
	v_pk_add_f32 v[240:241], v[240:241], v[76:77]
	v_pk_add_f32 v[242:243], v[242:243], v[80:81]
	v_pk_add_f32 v[236:237], v[236:237], v[82:83]
	v_pk_add_f32 v[238:239], v[238:239], v[86:87]
	v_pk_add_f32 v[240:241], v[240:241], v[90:91]
	v_pk_add_f32 v[242:243], v[242:243], v[94:95]
	v_pk_add_f32 v[236:237], v[236:237], v[84:85]
	v_pk_add_f32 v[238:239], v[238:239], v[88:89]
	v_pk_add_f32 v[240:241], v[240:241], v[92:93]
	v_pk_add_f32 v[242:243], v[242:243], v[96:97]
	v_pk_add_f32 v[236:237], v[236:237], v[98:99]
	v_pk_add_f32 v[238:239], v[238:239], v[102:103]
	v_pk_add_f32 v[240:241], v[240:241], v[106:107]
	v_pk_add_f32 v[242:243], v[242:243], v[110:111]
	v_pk_add_f32 v[236:237], v[236:237], v[100:101]
	v_pk_add_f32 v[238:239], v[238:239], v[104:105]
	v_pk_add_f32 v[240:241], v[240:241], v[108:109]
	v_pk_add_f32 v[242:243], v[242:243], v[112:113]
	v_pk_add_f32 v[236:237], v[236:237], v[114:115]
	v_pk_add_f32 v[236:237], v[236:237], v[116:117]
	v_pk_add_f32 v[236:237], v[236:237], v[238:239]
	v_pk_add_f32 v[240:241], v[240:241], v[242:243]
	v_cndmask_b32_e64 v219, 0, v219, s[74:75]
	v_pk_add_f32 v[236:237], v[236:237], v[240:241]
	v_add_f32_e32 v185, v236, v237
	v_add_f32_e32 v185, v185, v219
	v_cvt_pk_bf16_f32 v236, v50, v51
	v_cvt_pk_bf16_f32 v237, v52, v53
	v_cvt_pk_bf16_f32 v238, v54, v55
	v_cvt_pk_bf16_f32 v239, v56, v57
	s_nop 1
	s_waitcnt lgkmcnt(14)
	v_mfma_f32_16x16x32_bf16 v[210:213], v[186:189], v[236:239], 0
	s_waitcnt lgkmcnt(12)
	v_mfma_f32_16x16x32_bf16 v[214:217], v[190:193], v[236:239], 0
	s_waitcnt lgkmcnt(10)
	v_mfma_f32_16x16x32_bf16 v[220:223], v[194:197], v[236:239], 0
	s_waitcnt lgkmcnt(8)
	v_mfma_f32_16x16x32_bf16 v[224:227], v[198:201], v[236:239], 0
	v_cvt_pk_bf16_f32 v240, v58, v59
	v_cvt_pk_bf16_f32 v241, v60, v61
	v_cvt_pk_bf16_f32 v242, v62, v63
	v_cvt_pk_bf16_f32 v243, v64, v65
	s_waitcnt lgkmcnt(7)
; #define LAS __attribute__((address_space(3)))
; __device__ __forceinline__ unsigned pk2(float lo, float hi) { return pg8::cvt_pk_bf16(lo, hi); }
; __device__ __forceinline__ s16x4 vtr(const LAS unsigned char* p) { return __builtin_bit_cast(s16x4, __builtin_amdgcn_ds_read_tr16_b64_v4i16((LAS s16x4*)p)); }
; #define MFMA16(a, b, c) __builtin_amdgcn_mfma_f32_16x16x32_bf16((a), (b), (c), 0, 0, 0)
; __device__ __forceinline__ void pv_at(const LAS unsigned char* const (&vp)[4], int off, const f32x4& P0, const f32x4& P1, f32x4 (&O)[4]) {
;     v4u pw; pw.x = pk2(P0[0], P0[1]); pw.y = pk2(P0[2], P0[3]); pw.z = pk2(P1[0], P1[1]); pw.w = pk2(P1[2], P1[3]);
;     const bf16x8 pb = __builtin_bit_cast(bf16x8, pw);
; #pragma unroll
;     for (int db = 0; db < 4; ++db) {
;         const s16x4 lo = vtr(vp[db] + off), hi = vtr(vp[db] + off + 2048);
;         const bf16x8 vt = (bf16x8){lo[0], lo[1], lo[2], lo[3], hi[0], hi[1], hi[2], hi[3]};
;         O[db] = MFMA16(vt, pb, O[db]);
;     }
; }
	ds_read_b64_tr_b16 v[186:187], v124 offset:10240
	ds_read_b64_tr_b16 v[188:189], v124 offset:12288
	ds_read_b64_tr_b16 v[190:191], v125 offset:10240
	ds_read_b64_tr_b16 v[192:193], v125 offset:12288
	ds_read_b64_tr_b16 v[194:195], v126 offset:10240
	ds_read_b64_tr_b16 v[196:197], v126 offset:12288
	ds_read_b64_tr_b16 v[198:199], v127 offset:10240
	ds_read_b64_tr_b16 v[200:201], v127 offset:12288
	s_waitcnt lgkmcnt(14)
	v_mfma_f32_16x16x32_bf16 v[210:213], v[202:205], v[240:243], v[210:213]
	s_waitcnt lgkmcnt(12)
	v_mfma_f32_16x16x32_bf16 v[214:217], v[206:209], v[240:243], v[214:217]
	s_waitcnt lgkmcnt(10)
	v_mfma_f32_16x16x32_bf16 v[220:223], v[228:231], v[240:243], v[220:223]
	s_waitcnt lgkmcnt(8)
	v_mfma_f32_16x16x32_bf16 v[224:227], v[232:235], v[240:243], v[224:227]
	v_cvt_pk_bf16_f32 v236, v66, v67
	v_cvt_pk_bf16_f32 v237, v68, v69
	v_cvt_pk_bf16_f32 v238, v70, v71
	v_cvt_pk_bf16_f32 v239, v72, v73
	s_waitcnt lgkmcnt(7)
	ds_read_b64_tr_b16 v[202:203], v124 offset:14336
	ds_read_b64_tr_b16 v[204:205], v124 offset:16384
	ds_read_b64_tr_b16 v[206:207], v125 offset:14336
	ds_read_b64_tr_b16 v[208:209], v125 offset:16384
	ds_read_b64_tr_b16 v[228:229], v126 offset:14336
	ds_read_b64_tr_b16 v[230:231], v126 offset:16384
	ds_read_b64_tr_b16 v[232:233], v127 offset:14336
	ds_read_b64_tr_b16 v[234:235], v127 offset:16384
	s_waitcnt lgkmcnt(14)
	v_mfma_f32_16x16x32_bf16 v[210:213], v[186:189], v[236:239], v[210:213]
	s_waitcnt lgkmcnt(12)
	v_mfma_f32_16x16x32_bf16 v[214:217], v[190:193], v[236:239], v[214:217]
	s_waitcnt lgkmcnt(10)
	v_mfma_f32_16x16x32_bf16 v[220:223], v[194:197], v[236:239], v[220:223]
	s_waitcnt lgkmcnt(8)
	v_mfma_f32_16x16x32_bf16 v[224:227], v[198:201], v[236:239], v[224:227]
	v_cvt_pk_bf16_f32 v240, v74, v75
	v_cvt_pk_bf16_f32 v241, v76, v77
	v_cvt_pk_bf16_f32 v242, v78, v79
	v_cvt_pk_bf16_f32 v243, v80, v81
	s_waitcnt lgkmcnt(7)
	ds_read_b64_tr_b16 v[186:187], v124 offset:18432
	ds_read_b64_tr_b16 v[188:189], v124 offset:20480
	ds_read_b64_tr_b16 v[190:191], v125 offset:18432
	ds_read_b64_tr_b16 v[192:193], v125 offset:20480
	ds_read_b64_tr_b16 v[194:195], v126 offset:18432
	ds_read_b64_tr_b16 v[196:197], v126 offset:20480
	ds_read_b64_tr_b16 v[198:199], v127 offset:18432
	ds_read_b64_tr_b16 v[200:201], v127 offset:20480
	s_waitcnt lgkmcnt(14)
	v_mfma_f32_16x16x32_bf16 v[210:213], v[202:205], v[240:243], v[210:213]
	s_waitcnt lgkmcnt(12)
	v_mfma_f32_16x16x32_bf16 v[214:217], v[206:209], v[240:243], v[214:217]
	s_waitcnt lgkmcnt(10)
	v_mfma_f32_16x16x32_bf16 v[220:223], v[228:231], v[240:243], v[220:223]
	s_waitcnt lgkmcnt(8)
	v_mfma_f32_16x16x32_bf16 v[224:227], v[232:235], v[240:243], v[224:227]
	v_cvt_pk_bf16_f32 v236, v82, v83
	v_cvt_pk_bf16_f32 v237, v84, v85
	v_cvt_pk_bf16_f32 v238, v86, v87
	v_cvt_pk_bf16_f32 v239, v88, v89
	s_waitcnt lgkmcnt(7)
	ds_read_b64_tr_b16 v[202:203], v124 offset:22528
	ds_read_b64_tr_b16 v[204:205], v124 offset:24576
	ds_read_b64_tr_b16 v[206:207], v125 offset:22528
	ds_read_b64_tr_b16 v[208:209], v125 offset:24576
	ds_read_b64_tr_b16 v[228:229], v126 offset:22528
	ds_read_b64_tr_b16 v[230:231], v126 offset:24576
	ds_read_b64_tr_b16 v[232:233], v127 offset:22528
	ds_read_b64_tr_b16 v[234:235], v127 offset:24576
	s_waitcnt lgkmcnt(14)
	v_mfma_f32_16x16x32_bf16 v[210:213], v[186:189], v[236:239], v[210:213]
	s_waitcnt lgkmcnt(12)
	v_mfma_f32_16x16x32_bf16 v[214:217], v[190:193], v[236:239], v[214:217]
	s_waitcnt lgkmcnt(10)
	v_mfma_f32_16x16x32_bf16 v[220:223], v[194:197], v[236:239], v[220:223]
	s_waitcnt lgkmcnt(8)
	v_mfma_f32_16x16x32_bf16 v[224:227], v[198:201], v[236:239], v[224:227]
	v_cvt_pk_bf16_f32 v240, v90, v91
	v_cvt_pk_bf16_f32 v241, v92, v93
	v_cvt_pk_bf16_f32 v242, v94, v95
	v_cvt_pk_bf16_f32 v243, v96, v97
	s_waitcnt lgkmcnt(7)
	ds_read_b64_tr_b16 v[186:187], v124 offset:26624
	ds_read_b64_tr_b16 v[188:189], v124 offset:28672
	ds_read_b64_tr_b16 v[190:191], v125 offset:26624
	ds_read_b64_tr_b16 v[192:193], v125 offset:28672
	ds_read_b64_tr_b16 v[194:195], v126 offset:26624
	ds_read_b64_tr_b16 v[196:197], v126 offset:28672
	ds_read_b64_tr_b16 v[198:199], v127 offset:26624
	ds_read_b64_tr_b16 v[200:201], v127 offset:28672
	s_waitcnt lgkmcnt(14)
	v_mfma_f32_16x16x32_bf16 v[210:213], v[202:205], v[240:243], v[210:213]
	s_waitcnt lgkmcnt(12)
	v_mfma_f32_16x16x32_bf16 v[214:217], v[206:209], v[240:243], v[214:217]
	s_waitcnt lgkmcnt(10)
	v_mfma_f32_16x16x32_bf16 v[220:223], v[228:231], v[240:243], v[220:223]
	s_waitcnt lgkmcnt(8)
	v_mfma_f32_16x16x32_bf16 v[224:227], v[232:235], v[240:243], v[224:227]
	v_cvt_pk_bf16_f32 v236, v98, v99
	v_cvt_pk_bf16_f32 v237, v100, v101
	v_cvt_pk_bf16_f32 v238, v102, v103
	v_cvt_pk_bf16_f32 v239, v104, v105
	s_waitcnt lgkmcnt(7)
	ds_read_b64_tr_b16 v[202:203], v124 offset:30720
	ds_read_b64_tr_b16 v[204:205], v124 offset:32768
	ds_read_b64_tr_b16 v[206:207], v125 offset:30720
	ds_read_b64_tr_b16 v[208:209], v125 offset:32768
	ds_read_b64_tr_b16 v[228:229], v126 offset:30720
	ds_read_b64_tr_b16 v[230:231], v126 offset:32768
	ds_read_b64_tr_b16 v[232:233], v127 offset:30720
	ds_read_b64_tr_b16 v[234:235], v127 offset:32768
	s_waitcnt lgkmcnt(14)
	v_mfma_f32_16x16x32_bf16 v[210:213], v[186:189], v[236:239], v[210:213]
	s_waitcnt lgkmcnt(12)
	v_mfma_f32_16x16x32_bf16 v[214:217], v[190:193], v[236:239], v[214:217]
	s_waitcnt lgkmcnt(10)
	v_mfma_f32_16x16x32_bf16 v[220:223], v[194:197], v[236:239], v[220:223]
	s_waitcnt lgkmcnt(8)
	v_mfma_f32_16x16x32_bf16 v[224:227], v[198:201], v[236:239], v[224:227]
	v_cvt_pk_bf16_f32 v240, v106, v107
	v_cvt_pk_bf16_f32 v241, v108, v109
	v_cvt_pk_bf16_f32 v242, v110, v111
	v_cvt_pk_bf16_f32 v243, v112, v113
	s_waitcnt lgkmcnt(7)
; __device__ __forceinline__ unsigned pk2(float lo, float hi) { return pg8::cvt_pk_bf16(lo, hi); }
; __device__ __forceinline__ void store_o(bf16* yrow, int g, float l, const f32x4 (&O)[4]) {
;     const float inv = 1.0f / xrow16_sum(l);
;     unsigned wx[4], wy[4];
; #pragma unroll
;     for (int db = 0; db < 4; ++db) { wx[db] = pk2(O[db][0] * inv, O[db][1] * inv); wy[db] = pk2(O[db][2] * inv, O[db][3] * inv); }
; #pragma unroll
;     for (int p = 0; p < 2; ++p) {
;         auto rx = __builtin_amdgcn_permlane16_swap(wx[2 * p], wx[2 * p + 1], false, false); wx[2 * p] = rx[0]; wx[2 * p + 1] = rx[1];
;         auto ry = __builtin_amdgcn_permlane16_swap(wy[2 * p], wy[2 * p + 1], false, false); wy[2 * p] = ry[0]; wy[2 * p + 1] = ry[1]; }
; #pragma unroll
;     for (int p = 0; p < 2; ++p) {
;         auto rx = __builtin_amdgcn_permlane32_swap(wx[p], wx[p + 2], false, false); wx[p] = rx[0]; wx[p + 2] = rx[1];
;         auto ry = __builtin_amdgcn_permlane32_swap(wy[p], wy[p + 2], false, false); wy[p] = ry[0]; wy[p + 2] = ry[1]; }
;     v4u lo = {wx[0], wy[0], wx[1], wy[1]}, hi = {wx[2], wy[2], wx[3], wy[3]};
;     *(v4u*)(yrow + 16 * g) = lo; *(v4u*)(yrow + 16 * g + 8) = hi;
; }
; template <bool MASK> __device__ __forceinline__ void a_scores(f32x4& S0, f32x4& S1, float basef, float c1, float slope2, int krow0, int kstart) {
; #pragma unroll
;     for (int r = 0; r < 4; ++r) {
;         const float d0 = fabsf(basef - (float)r), d1 = fabsf(basef - (float)(16 + r));
;         const float v0 = S0[r] - slope2 * d0, v1 = S1[r] - slope2 * d1;
;         if (MASK) { const int p0 = kstart + krow0 + r, p1 = p0 + 16;
;             S0[r] = (d0 <= 128.f && p0 >= 0 && p0 < SEQ) ? v0 : -INFINITY; S1[r] = (d1 <= 128.f && p1 >= 0 && p1 < SEQ) ? v1 : -INFINITY; }
;         else { S0[r] = v0; S1[r] = v1; }
;     }
; }
	ds_read_b64_tr_b16 v[186:187], v124 offset:34816
	ds_read_b64_tr_b16 v[188:189], v124 offset:36864
	ds_read_b64_tr_b16 v[190:191], v125 offset:34816
	ds_read_b64_tr_b16 v[192:193], v125 offset:36864
	ds_read_b64_tr_b16 v[194:195], v126 offset:34816
	ds_read_b64_tr_b16 v[196:197], v126 offset:36864
	ds_read_b64_tr_b16 v[198:199], v127 offset:34816
	ds_read_b64_tr_b16 v[200:201], v127 offset:36864
	s_waitcnt lgkmcnt(14)
	v_mfma_f32_16x16x32_bf16 v[210:213], v[202:205], v[240:243], v[210:213]
	s_waitcnt lgkmcnt(12)
	v_mfma_f32_16x16x32_bf16 v[214:217], v[206:209], v[240:243], v[214:217]
	s_waitcnt lgkmcnt(10)
	v_mfma_f32_16x16x32_bf16 v[220:223], v[228:231], v[240:243], v[220:223]
	s_waitcnt lgkmcnt(8)
	v_mfma_f32_16x16x32_bf16 v[224:227], v[232:235], v[240:243], v[224:227]
	v_cvt_pk_bf16_f32 v236, v114, v115
	v_cvt_pk_bf16_f32 v237, v116, v117
	v_mov_b32_e32 v238, 0
	v_mov_b32_e32 v239, 0
	s_nop 1
	s_waitcnt lgkmcnt(6)
	v_mfma_f32_16x16x32_bf16 v[210:213], v[186:189], v[236:239], v[210:213]
	s_waitcnt lgkmcnt(4)
	v_mfma_f32_16x16x32_bf16 v[214:217], v[190:193], v[236:239], v[214:217]
	s_waitcnt lgkmcnt(2)
	v_mfma_f32_16x16x32_bf16 v[220:223], v[194:197], v[236:239], v[220:223]
	s_waitcnt lgkmcnt(0)
	v_mfma_f32_16x16x32_bf16 v[224:227], v[198:201], v[236:239], v[224:227]
	v_mov_b32_e32 v219, v185
	s_nop 1
	v_permlane16_swap_b32_e32 v185, v219
	v_add_f32_e32 v185, v185, v219
	v_mov_b32_e32 v219, v185
	s_nop 1
	v_permlane32_swap_b32_e32 v185, v219
	v_add_f32_e32 v185, v185, v219
	v_div_scale_f32 v236, s[78:79], v185, v185, 1.0
	v_div_scale_f32 v237, vcc, 1.0, v185, 1.0
	v_rcp_f32_e32 v238, v236
	s_nop 0
	v_fma_f32 v239, -v236, v238, 1.0
	v_fmac_f32_e32 v238, v239, v238
	v_mul_f32_e32 v240, v237, v238
	v_fma_f32 v241, -v236, v240, v237
	v_fmac_f32_e32 v240, v241, v238
	v_fma_f32 v237, -v236, v240, v237
	v_div_fmas_f32 v237, v237, v238, v240
	v_div_fixup_f32 v244, v237, v185, 1.0
	v_mul_f32_e32 v240, v210, v244
	v_mul_f32_e32 v241, v211, v244
	v_mul_f32_e32 v242, v212, v244
	v_mul_f32_e32 v243, v213, v244
	v_cvt_pk_bf16_f32 v186, v240, v241
	v_cvt_pk_bf16_f32 v187, v242, v243
	v_mul_f32_e32 v240, v214, v244
	v_mul_f32_e32 v241, v215, v244
	v_mul_f32_e32 v242, v216, v244
	v_mul_f32_e32 v243, v217, v244
	v_cvt_pk_bf16_f32 v188, v240, v241
	v_cvt_pk_bf16_f32 v189, v242, v243
	v_mul_f32_e32 v240, v220, v244
	v_mul_f32_e32 v241, v221, v244
	v_mul_f32_e32 v242, v222, v244
	v_mul_f32_e32 v243, v223, v244
	v_cvt_pk_bf16_f32 v190, v240, v241
	v_cvt_pk_bf16_f32 v191, v242, v243
	v_mul_f32_e32 v240, v224, v244
	v_mul_f32_e32 v241, v225, v244
	v_mul_f32_e32 v242, v226, v244
	v_mul_f32_e32 v243, v227, v244
	v_cvt_pk_bf16_f32 v192, v240, v241
	v_cvt_pk_bf16_f32 v193, v242, v243
	s_nop 1
	v_permlane16_swap_b32_e32 v186, v188
	v_permlane16_swap_b32_e32 v187, v189
	v_permlane16_swap_b32_e32 v190, v192
	v_permlane16_swap_b32_e32 v191, v193
	s_nop 0
	v_permlane32_swap_b32_e32 v186, v190
	v_permlane32_swap_b32_e32 v187, v191
	v_permlane32_swap_b32_e32 v188, v192
	v_permlane32_swap_b32_e32 v189, v193
	global_store_dwordx4 v128, v[186:189], s[82:83] offset:2048 sc1
	global_store_dwordx4 v128, v[190:193], s[82:83] offset:2064 sc1
	s_nop 1
	s_bitcmp1_b32 s87, 2
	s_cselect_b32 s21, 0, 0xff800000
	v_add_f32_e32 v120, s21, v132
	v_fmamk_f32 v50, v130, 0x43000000, v120
	v_fmamk_f32 v51, v130, 0x42fe0000, v120
	v_fmamk_f32 v52, v130, 0x42fc0000, v120
	v_fmamk_f32 v53, v130, 0x42fa0000, v120
	s_bitcmp1_b32 s87, 3
	s_cselect_b32 s21, 0, 0xff800000
	v_add_f32_e32 v120, s21, v132
	v_fmamk_f32 v54, v130, 0x42e00000, v120
	v_fmamk_f32 v55, v130, 0x42de0000, v120
	v_fmamk_f32 v56, v130, 0x42dc0000, v120
	v_fmamk_f32 v57, v130, 0x42da0000, v120
	s_bitcmp1_b32 s87, 4
	s_cselect_b32 s21, 0, 0xff800000
	v_add_f32_e32 v120, s21, v132
	v_fmamk_f32 v58, v130, 0x42c00000, v120
	v_fmamk_f32 v59, v130, 0x42be0000, v120
	v_fmamk_f32 v60, v130, 0x42bc0000, v120
	v_fmamk_f32 v61, v130, 0x42ba0000, v120
	s_bitcmp1_b32 s87, 5
	s_cselect_b32 s21, 0, 0xff800000
	v_add_f32_e32 v120, s21, v132
	v_fmamk_f32 v62, v130, 0x42a00000, v120
	v_fmamk_f32 v63, v130, 0x429e0000, v120
	v_fmamk_f32 v64, v130, 0x429c0000, v120
	v_fmamk_f32 v65, v130, 0x429a0000, v120
	s_bitcmp1_b32 s87, 6
	s_cselect_b32 s21, 0, 0xff800000
	v_add_f32_e32 v120, s21, v132
	v_fmamk_f32 v66, v130, 0x42800000, v120
	v_fmamk_f32 v67, v130, 0x427c0000, v120
	v_fmamk_f32 v68, v130, 0x42780000, v120
	v_fmamk_f32 v69, v130, 0x42740000, v120
	s_bitcmp1_b32 s87, 7
	s_cselect_b32 s21, 0, 0xff800000
	v_add_f32_e32 v120, s21, v132
	v_fmamk_f32 v70, v130, 0x42400000, v120
	v_fmamk_f32 v71, v130, 0x423c0000, v120
	v_fmamk_f32 v72, v130, 0x42380000, v120
	v_fmamk_f32 v73, v130, 0x42340000, v120
	s_bitcmp1_b32 s87, 8
	s_cselect_b32 s21, 0, 0xff800000
	v_add_f32_e32 v120, s21, v132
	v_fmamk_f32 v74, v130, 0x42000000, v120
	v_fmamk_f32 v75, v130, 0x41f80000, v120
	v_fmamk_f32 v76, v130, 0x41f00000, v120
	v_fmamk_f32 v77, v130, 0x41e80000, v120
	s_bitcmp1_b32 s87, 9
	s_cselect_b32 s21, 0, 0xff800000
	v_add_f32_e32 v120, s21, v132
	v_fmamk_f32 v78, v130, 0x41800000, v120
	v_fmamk_f32 v79, v130, 0x41700000, v120
	v_fmamk_f32 v80, v130, 0x41600000, v120
	v_fmamk_f32 v81, v130, 0x41500000, v120
	s_bitcmp1_b32 s87, 10
	s_cselect_b32 s21, 0, 0xff800000
	v_add_f32_e32 v219, 0, v129
	v_fma_f32 v82, v130, |v219|, s21
	v_add_f32_e32 v244, 0xbf800000, v129
	v_fma_f32 v83, v130, |v244|, s21
	v_add_f32_e32 v219, 0xc0000000, v129
	v_fma_f32 v84, v130, |v219|, s21
	v_add_f32_e32 v244, 0xc0400000, v129
	v_fma_f32 v85, v130, |v244|, s21
	s_bitcmp1_b32 s87, 11
	s_cselect_b32 s21, 0, 0xff800000
	v_add_f32_e32 v120, s21, v133
	v_fmamk_f32 v86, v131, 0xc1800000, v120
; #define LAS __attribute__((address_space(3)))
; #define MFMA16(a, b, c) __builtin_amdgcn_mfma_f32_16x16x32_bf16((a), (b), (c), 0, 0, 0)
; __device__ __forceinline__ void qk_at(const LAS unsigned char* kp0, const LAS unsigned char* kp1, int off, bf16x8 qf0, bf16x8 qf1, f32x4& S0, f32x4& S1) {
;     const bf16x8 k00 = *(const LAS bf16x8*)(kp0 + off), k01 = *(const LAS bf16x8*)(kp1 + off);
;     const bf16x8 k10 = *(const LAS bf16x8*)(kp0 + off + 2048), k11 = *(const LAS bf16x8*)(kp1 + off + 2048);
;     const f32x4 z = {0.f, 0.f, 0.f, 0.f};
;     S0 = MFMA16(k00, qf0, z); S0 = MFMA16(k01, qf1, S0);
;     S1 = MFMA16(k10, qf0, z); S1 = MFMA16(k11, qf1, S1);
; }
; template <bool MASK> __device__ __forceinline__ void a_scores(f32x4& S0, f32x4& S1, float basef, float c1, float slope2, int krow0, int kstart) {
; #pragma unroll
;     for (int r = 0; r < 4; ++r) {
;         const float d0 = fabsf(basef - (float)r), d1 = fabsf(basef - (float)(16 + r));
;         const float v0 = S0[r] - slope2 * d0, v1 = S1[r] - slope2 * d1;
;         if (MASK) { const int p0 = kstart + krow0 + r, p1 = p0 + 16;
;             S0[r] = (d0 <= 128.f && p0 >= 0 && p0 < SEQ) ? v0 : -INFINITY; S1[r] = (d1 <= 128.f && p1 >= 0 && p1 < SEQ) ? v1 : -INFINITY; }
;         else { S0[r] = v0; S1[r] = v1; }
;     }
; }
	v_fmamk_f32 v87, v131, 0xc1880000, v120
	v_fmamk_f32 v88, v131, 0xc1900000, v120
	v_fmamk_f32 v89, v131, 0xc1980000, v120
	s_bitcmp1_b32 s87, 12
	s_cselect_b32 s21, 0, 0xff800000
	v_add_f32_e32 v120, s21, v133
	v_fmamk_f32 v90, v131, 0xc2000000, v120
	v_fmamk_f32 v91, v131, 0xc2040000, v120
	v_fmamk_f32 v92, v131, 0xc2080000, v120
	v_fmamk_f32 v93, v131, 0xc20c0000, v120
	s_bitcmp1_b32 s87, 13
	s_cselect_b32 s21, 0, 0xff800000
	v_add_f32_e32 v120, s21, v133
	v_fmamk_f32 v94, v131, 0xc2400000, v120
	v_fmamk_f32 v95, v131, 0xc2440000, v120
	v_fmamk_f32 v96, v131, 0xc2480000, v120
	v_fmamk_f32 v97, v131, 0xc24c0000, v120
	s_bitcmp1_b32 s87, 14
	s_cselect_b32 s21, 0, 0xff800000
	v_add_f32_e32 v120, s21, v133
	v_fmamk_f32 v98, v131, 0xc2800000, v120
	v_fmamk_f32 v99, v131, 0xc2820000, v120
	v_fmamk_f32 v100, v131, 0xc2840000, v120
	v_fmamk_f32 v101, v131, 0xc2860000, v120
	s_bitcmp1_b32 s87, 15
	s_cselect_b32 s21, 0, 0xff800000
	v_add_f32_e32 v120, s21, v133
	v_fmamk_f32 v102, v131, 0xc2a00000, v120
	v_fmamk_f32 v103, v131, 0xc2a20000, v120
	v_fmamk_f32 v104, v131, 0xc2a40000, v120
	v_fmamk_f32 v105, v131, 0xc2a60000, v120
	s_bitcmp1_b32 s87, 16
	s_cselect_b32 s21, 0, 0xff800000
	v_add_f32_e32 v120, s21, v133
	v_fmamk_f32 v106, v131, 0xc2c00000, v120
	v_fmamk_f32 v107, v131, 0xc2c20000, v120
	v_fmamk_f32 v108, v131, 0xc2c40000, v120
	v_fmamk_f32 v109, v131, 0xc2c60000, v120
	s_bitcmp1_b32 s87, 17
	s_cselect_b32 s21, 0, 0xff800000
	v_add_f32_e32 v120, s21, v133
	v_fmamk_f32 v110, v131, 0xc2e00000, v120
	v_fmamk_f32 v111, v131, 0xc2e20000, v120
	v_fmamk_f32 v112, v131, 0xc2e40000, v120
	v_fmamk_f32 v113, v131, 0xc2e60000, v120
	s_bitcmp1_b32 s87, 18
	s_cselect_b32 s21, 0, 0xff800000
	v_add_f32_e32 v120, s21, v133
	v_fmamk_f32 v114, v131, 0xc3000000, v120
	v_fmamk_f32 v115, v131, 0xc3010000, v120
	v_fmamk_f32 v116, v131, 0xc3020000, v120
	v_fmamk_f32 v117, v131, 0xc3030000, v120
	v_mov_b32_e32 v245, 0xff800000
	v_cndmask_b32_e64 v50, v245, v50, s[16:17]
	v_cndmask_b32_e64 v51, v245, v51, s[18:19]
	v_cndmask_b32_e64 v52, v245, v52, s[22:23]
	v_cndmask_b32_e64 v53, v245, v53, s[24:25]
	v_cndmask_b32_e64 v114, v245, v114, s[28:29]
	v_cndmask_b32_e64 v115, v245, v115, s[52:53]
	v_cndmask_b32_e64 v116, v245, v116, s[54:55]
	v_cndmask_b32_e64 v117, v245, v117, s[88:89]
	ds_read_b128 v[186:189], v122 offset:4096
	ds_read_b128 v[190:193], v123 offset:4096
	ds_read_b128 v[194:197], v122 offset:6144
	ds_read_b128 v[198:201], v123 offset:6144
	ds_read_b128 v[202:205], v122 offset:8192
	ds_read_b128 v[206:209], v123 offset:8192
	s_waitcnt lgkmcnt(5)
	v_mfma_f32_16x16x32_bf16 v[50:53], v[186:189], v[162:165], v[50:53]
	s_waitcnt lgkmcnt(4)
	v_mfma_f32_16x16x32_bf16 v[50:53], v[190:193], v[166:169], v[50:53]
	ds_read_b128 v[186:189], v122 offset:10240
	ds_read_b128 v[190:193], v123 offset:10240
	s_waitcnt lgkmcnt(5)
	v_mfma_f32_16x16x32_bf16 v[54:57], v[194:197], v[162:165], v[54:57]
	s_waitcnt lgkmcnt(4)
	v_mfma_f32_16x16x32_bf16 v[54:57], v[198:201], v[166:169], v[54:57]
	ds_read_b128 v[194:197], v122 offset:12288
	ds_read_b128 v[198:201], v123 offset:12288
	s_waitcnt lgkmcnt(5)
	v_mfma_f32_16x16x32_bf16 v[58:61], v[202:205], v[162:165], v[58:61]
	s_waitcnt lgkmcnt(4)
	v_mfma_f32_16x16x32_bf16 v[58:61], v[206:209], v[166:169], v[58:61]
	ds_read_b128 v[202:205], v122 offset:14336
	ds_read_b128 v[206:209], v123 offset:14336
	s_waitcnt lgkmcnt(5)
	v_mfma_f32_16x16x32_bf16 v[62:65], v[186:189], v[162:165], v[62:65]
	s_waitcnt lgkmcnt(4)
	v_mfma_f32_16x16x32_bf16 v[62:65], v[190:193], v[166:169], v[62:65]
	ds_read_b128 v[186:189], v122 offset:16384
	ds_read_b128 v[190:193], v123 offset:16384
	s_waitcnt lgkmcnt(5)
	v_mfma_f32_16x16x32_bf16 v[66:69], v[194:197], v[162:165], v[66:69]
	s_waitcnt lgkmcnt(4)
	v_mfma_f32_16x16x32_bf16 v[66:69], v[198:201], v[166:169], v[66:69]
	ds_read_b128 v[194:197], v122 offset:18432
	ds_read_b128 v[198:201], v123 offset:18432
	s_waitcnt lgkmcnt(5)
	v_mfma_f32_16x16x32_bf16 v[70:73], v[202:205], v[162:165], v[70:73]
	s_waitcnt lgkmcnt(4)
	v_mfma_f32_16x16x32_bf16 v[70:73], v[206:209], v[166:169], v[70:73]
	ds_read_b128 v[202:205], v122 offset:20480
	ds_read_b128 v[206:209], v123 offset:20480
	s_waitcnt lgkmcnt(5)
	v_mfma_f32_16x16x32_bf16 v[74:77], v[186:189], v[162:165], v[74:77]
	s_waitcnt lgkmcnt(4)
	v_mfma_f32_16x16x32_bf16 v[74:77], v[190:193], v[166:169], v[74:77]
	ds_read_b128 v[186:189], v122 offset:22528
	ds_read_b128 v[190:193], v123 offset:22528
	s_waitcnt lgkmcnt(5)
	v_mfma_f32_16x16x32_bf16 v[78:81], v[194:197], v[162:165], v[78:81]
	s_waitcnt lgkmcnt(4)
	v_mfma_f32_16x16x32_bf16 v[78:81], v[198:201], v[166:169], v[78:81]
	ds_read_b128 v[194:197], v122 offset:24576
	ds_read_b128 v[198:201], v123 offset:24576
	s_waitcnt lgkmcnt(5)
	v_mfma_f32_16x16x32_bf16 v[82:85], v[202:205], v[162:165], v[82:85]
	s_waitcnt lgkmcnt(4)
	v_mfma_f32_16x16x32_bf16 v[82:85], v[206:209], v[166:169], v[82:85]
	ds_read_b128 v[202:205], v122 offset:26624
	ds_read_b128 v[206:209], v123 offset:26624
	s_waitcnt lgkmcnt(5)
	v_mfma_f32_16x16x32_bf16 v[86:89], v[186:189], v[162:165], v[86:89]
	s_waitcnt lgkmcnt(4)
	v_mfma_f32_16x16x32_bf16 v[86:89], v[190:193], v[166:169], v[86:89]
	ds_read_b128 v[186:189], v122 offset:28672
	ds_read_b128 v[190:193], v123 offset:28672
	s_waitcnt lgkmcnt(5)
	v_mfma_f32_16x16x32_bf16 v[90:93], v[194:197], v[162:165], v[90:93]
	s_waitcnt lgkmcnt(4)
	v_mfma_f32_16x16x32_bf16 v[90:93], v[198:201], v[166:169], v[90:93]
	ds_read_b128 v[194:197], v122 offset:30720
	ds_read_b128 v[198:201], v123 offset:30720
	s_waitcnt lgkmcnt(5)
	v_mfma_f32_16x16x32_bf16 v[94:97], v[202:205], v[162:165], v[94:97]
	s_waitcnt lgkmcnt(4)
; #define LAS __attribute__((address_space(3)))
; #define MFMA16(a, b, c) __builtin_amdgcn_mfma_f32_16x16x32_bf16((a), (b), (c), 0, 0, 0)
; __device__ __forceinline__ void qk_at(const LAS unsigned char* kp0, const LAS unsigned char* kp1, int off, bf16x8 qf0, bf16x8 qf1, f32x4& S0, f32x4& S1) {
;     const bf16x8 k00 = *(const LAS bf16x8*)(kp0 + off), k01 = *(const LAS bf16x8*)(kp1 + off);
;     const bf16x8 k10 = *(const LAS bf16x8*)(kp0 + off + 2048), k11 = *(const LAS bf16x8*)(kp1 + off + 2048);
;     const f32x4 z = {0.f, 0.f, 0.f, 0.f};
;     S0 = MFMA16(k00, qf0, z); S0 = MFMA16(k01, qf1, S0);
;     S1 = MFMA16(k10, qf0, z); S1 = MFMA16(k11, qf1, S1);
; }
; __device__ __forceinline__ void softmax_step(f32x4& s0, f32x4& s1, float& m, float& l, f32x4 (&O)[4]) {
;     float t = fmaxf(fmaxf(fmaxf(s0[0], s0[1]), fmaxf(s0[2], s0[3])), fmaxf(fmaxf(s1[0], s1[1]), fmaxf(s1[2], s1[3])));
;     t = xrow16_max(t);
;     const float mn = fmaxf(m, t), alpha = __builtin_amdgcn_exp2f(m - mn);
;     m = mn;
	v_mfma_f32_16x16x32_bf16 v[94:97], v[206:209], v[166:169], v[94:97]
	ds_read_b128 v[202:205], v122 offset:32768
	ds_read_b128 v[206:209], v123 offset:32768
	s_waitcnt lgkmcnt(5)
	v_mfma_f32_16x16x32_bf16 v[98:101], v[186:189], v[162:165], v[98:101]
	s_waitcnt lgkmcnt(4)
	v_mfma_f32_16x16x32_bf16 v[98:101], v[190:193], v[166:169], v[98:101]
	ds_read_b128 v[186:189], v122 offset:34816
	ds_read_b128 v[190:193], v123 offset:34816
	s_waitcnt lgkmcnt(5)
	v_mfma_f32_16x16x32_bf16 v[102:105], v[194:197], v[162:165], v[102:105]
	s_waitcnt lgkmcnt(4)
	v_mfma_f32_16x16x32_bf16 v[102:105], v[198:201], v[166:169], v[102:105]
	ds_read_b128 v[194:197], v122 offset:36864
	ds_read_b128 v[198:201], v123 offset:36864
	s_waitcnt lgkmcnt(5)
	v_mfma_f32_16x16x32_bf16 v[106:109], v[202:205], v[162:165], v[106:109]
	s_waitcnt lgkmcnt(4)
	v_mfma_f32_16x16x32_bf16 v[106:109], v[206:209], v[166:169], v[106:109]
	s_waitcnt lgkmcnt(3)
	v_mfma_f32_16x16x32_bf16 v[110:113], v[186:189], v[162:165], v[110:113]
	s_waitcnt lgkmcnt(2)
	v_mfma_f32_16x16x32_bf16 v[110:113], v[190:193], v[166:169], v[110:113]
	s_waitcnt lgkmcnt(1)
	v_mfma_f32_16x16x32_bf16 v[114:117], v[194:197], v[162:165], v[114:117]
	s_waitcnt lgkmcnt(0)
	v_mfma_f32_16x16x32_bf16 v[114:117], v[198:201], v[166:169], v[114:117]
	v_max3_f32 v219, v50, v51, v52
	v_max3_f32 v244, v54, v55, v56
	v_max3_f32 v245, v58, v59, v60
	v_max3_f32 v120, v62, v63, v64
	v_max3_f32 v219, v219, v53, v66
	v_max3_f32 v244, v244, v57, v70
	v_max3_f32 v245, v245, v61, v74
	v_max3_f32 v120, v120, v65, v78
	v_max3_f32 v219, v219, v67, v68
	v_max3_f32 v244, v244, v71, v72
	v_max3_f32 v245, v245, v75, v76
	v_max3_f32 v120, v120, v79, v80
	ds_read_b64_tr_b16 v[186:187], v124 offset:4096
	ds_read_b64_tr_b16 v[188:189], v124 offset:6144
	ds_read_b64_tr_b16 v[190:191], v125 offset:4096
	ds_read_b64_tr_b16 v[192:193], v125 offset:6144
	ds_read_b64_tr_b16 v[194:195], v126 offset:4096
	ds_read_b64_tr_b16 v[196:197], v126 offset:6144
	ds_read_b64_tr_b16 v[198:199], v127 offset:4096
	ds_read_b64_tr_b16 v[200:201], v127 offset:6144
	v_max3_f32 v219, v219, v69, v82
	v_max3_f32 v244, v244, v73, v86
	v_max3_f32 v245, v245, v77, v90
	v_max3_f32 v120, v120, v81, v94
	v_max3_f32 v219, v219, v83, v84
	v_max3_f32 v244, v244, v87, v88
	v_max3_f32 v245, v245, v91, v92
	v_max3_f32 v120, v120, v95, v96
	v_max3_f32 v219, v219, v85, v98
	v_max3_f32 v244, v244, v89, v102
	v_max3_f32 v245, v245, v93, v106
	v_max3_f32 v120, v120, v97, v110
	v_max3_f32 v219, v219, v99, v100
	v_max3_f32 v244, v244, v103, v104
	v_max3_f32 v245, v245, v107, v108
	v_max3_f32 v120, v120, v111, v112
	v_max3_f32 v219, v219, v101, v114
	v_max3_f32 v219, v219, v115, v116
	v_max_f32_e32 v219, v219, v117
	v_max_f32_e32 v244, v244, v105
	v_max_f32_e32 v245, v245, v109
	v_max_f32_e32 v120, v120, v113
	v_max3_f32 v178, v219, v244, v245
	v_max_f32_e32 v178, v178, v120
	v_mov_b32_e32 v219, v178
	s_nop 1
	v_permlane16_swap_b32_e32 v178, v219
	v_max_f32_e32 v178, v178, v219
	v_mov_b32_e32 v219, v178
	s_nop 1
	v_permlane32_swap_b32_e32 v178, v219
	v_max3_f32 v178, v178, v219, v145
	s_waitcnt lgkmcnt(7)
	ds_read_b64_tr_b16 v[202:203], v124 offset:8192
	ds_read_b64_tr_b16 v[204:205], v124 offset:10240
	ds_read_b64_tr_b16 v[206:207], v125 offset:8192
	ds_read_b64_tr_b16 v[208:209], v125 offset:10240
	ds_read_b64_tr_b16 v[228:229], v126 offset:8192
	ds_read_b64_tr_b16 v[230:231], v126 offset:10240
	ds_read_b64_tr_b16 v[232:233], v127 offset:8192
	ds_read_b64_tr_b16 v[234:235], v127 offset:10240
	v_mov_b32_e32 v244, v178
	v_pk_add_f32 v[50:51], v[50:51], v[244:245] op_sel_hi:[1,0] neg_lo:[0,1] neg_hi:[0,1]
	v_pk_add_f32 v[52:53], v[52:53], v[244:245] op_sel_hi:[1,0] neg_lo:[0,1] neg_hi:[0,1]
	v_pk_add_f32 v[54:55], v[54:55], v[244:245] op_sel_hi:[1,0] neg_lo:[0,1] neg_hi:[0,1]
	v_pk_add_f32 v[56:57], v[56:57], v[244:245] op_sel_hi:[1,0] neg_lo:[0,1] neg_hi:[0,1]
	v_pk_add_f32 v[58:59], v[58:59], v[244:245] op_sel_hi:[1,0] neg_lo:[0,1] neg_hi:[0,1]
	v_pk_add_f32 v[60:61], v[60:61], v[244:245] op_sel_hi:[1,0] neg_lo:[0,1] neg_hi:[0,1]
	v_pk_add_f32 v[62:63], v[62:63], v[244:245] op_sel_hi:[1,0] neg_lo:[0,1] neg_hi:[0,1]
	v_pk_add_f32 v[64:65], v[64:65], v[244:245] op_sel_hi:[1,0] neg_lo:[0,1] neg_hi:[0,1]
	v_pk_add_f32 v[66:67], v[66:67], v[244:245] op_sel_hi:[1,0] neg_lo:[0,1] neg_hi:[0,1]
	v_pk_add_f32 v[68:69], v[68:69], v[244:245] op_sel_hi:[1,0] neg_lo:[0,1] neg_hi:[0,1]
	v_pk_add_f32 v[70:71], v[70:71], v[244:245] op_sel_hi:[1,0] neg_lo:[0,1] neg_hi:[0,1]
	v_pk_add_f32 v[72:73], v[72:73], v[244:245] op_sel_hi:[1,0] neg_lo:[0,1] neg_hi:[0,1]
	v_pk_add_f32 v[74:75], v[74:75], v[244:245] op_sel_hi:[1,0] neg_lo:[0,1] neg_hi:[0,1]
	v_pk_add_f32 v[76:77], v[76:77], v[244:245] op_sel_hi:[1,0] neg_lo:[0,1] neg_hi:[0,1]
	v_pk_add_f32 v[78:79], v[78:79], v[244:245] op_sel_hi:[1,0] neg_lo:[0,1] neg_hi:[0,1]
	v_pk_add_f32 v[80:81], v[80:81], v[244:245] op_sel_hi:[1,0] neg_lo:[0,1] neg_hi:[0,1]
	v_pk_add_f32 v[82:83], v[82:83], v[244:245] op_sel_hi:[1,0] neg_lo:[0,1] neg_hi:[0,1]
	v_pk_add_f32 v[84:85], v[84:85], v[244:245] op_sel_hi:[1,0] neg_lo:[0,1] neg_hi:[0,1]
	v_pk_add_f32 v[86:87], v[86:87], v[244:245] op_sel_hi:[1,0] neg_lo:[0,1] neg_hi:[0,1]
	v_pk_add_f32 v[88:89], v[88:89], v[244:245] op_sel_hi:[1,0] neg_lo:[0,1] neg_hi:[0,1]
	v_pk_add_f32 v[90:91], v[90:91], v[244:245] op_sel_hi:[1,0] neg_lo:[0,1] neg_hi:[0,1]
	v_pk_add_f32 v[92:93], v[92:93], v[244:245] op_sel_hi:[1,0] neg_lo:[0,1] neg_hi:[0,1]
	v_pk_add_f32 v[94:95], v[94:95], v[244:245] op_sel_hi:[1,0] neg_lo:[0,1] neg_hi:[0,1]
	v_pk_add_f32 v[96:97], v[96:97], v[244:245] op_sel_hi:[1,0] neg_lo:[0,1] neg_hi:[0,1]
; #define LAS __attribute__((address_space(3)))
; __device__ __forceinline__ unsigned pk2(float lo, float hi) { return pg8::cvt_pk_bf16(lo, hi); }
; __device__ __forceinline__ s16x4 vtr(const LAS unsigned char* p) { return __builtin_bit_cast(s16x4, __builtin_amdgcn_ds_read_tr16_b64_v4i16((LAS s16x4*)p)); }
; #define MFMA16(a, b, c) __builtin_amdgcn_mfma_f32_16x16x32_bf16((a), (b), (c), 0, 0, 0)
; __device__ __forceinline__ void pv_at(const LAS unsigned char* const (&vp)[4], int off, const f32x4& P0, const f32x4& P1, f32x4 (&O)[4]) {
;     v4u pw; pw.x = pk2(P0[0], P0[1]); pw.y = pk2(P0[2], P0[3]); pw.z = pk2(P1[0], P1[1]); pw.w = pk2(P1[2], P1[3]);
;     const bf16x8 pb = __builtin_bit_cast(bf16x8, pw);
; #pragma unroll
;     for (int db = 0; db < 4; ++db) {
;         const s16x4 lo = vtr(vp[db] + off), hi = vtr(vp[db] + off + 2048);
;         const bf16x8 vt = (bf16x8){lo[0], lo[1], lo[2], lo[3], hi[0], hi[1], hi[2], hi[3]};
;         O[db] = MFMA16(vt, pb, O[db]);
;     }
; }
; __device__ __forceinline__ void softmax_step(f32x4& s0, f32x4& s1, float& m, float& l, f32x4 (&O)[4]) {
;     float t = fmaxf(fmaxf(fmaxf(s0[0], s0[1]), fmaxf(s0[2], s0[3])), fmaxf(fmaxf(s1[0], s1[1]), fmaxf(s1[2], s1[3])));
;     t = xrow16_max(t);
;     const float mn = fmaxf(m, t), alpha = __builtin_amdgcn_exp2f(m - mn);
;     m = mn;
; #pragma unroll
;     for (int k = 0; k < 4; ++k) { s0[k] = __builtin_amdgcn_exp2f(s0[k] - mn); s1[k] = __builtin_amdgcn_exp2f(s1[k] - mn); }
;     l = l * alpha + ((s0[0] + s0[1]) + (s0[2] + s0[3])) + ((s1[0] + s1[1]) + (s1[2] + s1[3]));
; #pragma unroll
;     for (int db = 0; db < 4; ++db) O[db] *= alpha;
; }
	v_pk_add_f32 v[98:99], v[98:99], v[244:245] op_sel_hi:[1,0] neg_lo:[0,1] neg_hi:[0,1]
	v_pk_add_f32 v[100:101], v[100:101], v[244:245] op_sel_hi:[1,0] neg_lo:[0,1] neg_hi:[0,1]
	v_pk_add_f32 v[102:103], v[102:103], v[244:245] op_sel_hi:[1,0] neg_lo:[0,1] neg_hi:[0,1]
	v_pk_add_f32 v[104:105], v[104:105], v[244:245] op_sel_hi:[1,0] neg_lo:[0,1] neg_hi:[0,1]
	v_pk_add_f32 v[106:107], v[106:107], v[244:245] op_sel_hi:[1,0] neg_lo:[0,1] neg_hi:[0,1]
	v_pk_add_f32 v[108:109], v[108:109], v[244:245] op_sel_hi:[1,0] neg_lo:[0,1] neg_hi:[0,1]
	v_pk_add_f32 v[110:111], v[110:111], v[244:245] op_sel_hi:[1,0] neg_lo:[0,1] neg_hi:[0,1]
	v_pk_add_f32 v[112:113], v[112:113], v[244:245] op_sel_hi:[1,0] neg_lo:[0,1] neg_hi:[0,1]
	v_pk_add_f32 v[114:115], v[114:115], v[244:245] op_sel_hi:[1,0] neg_lo:[0,1] neg_hi:[0,1]
	v_pk_add_f32 v[116:117], v[116:117], v[244:245] op_sel_hi:[1,0] neg_lo:[0,1] neg_hi:[0,1]
	v_sub_f32_e32 v219, v145, v178
	v_exp_f32_e32 v50, v50
	v_exp_f32_e32 v51, v51
	v_exp_f32_e32 v52, v52
	v_exp_f32_e32 v53, v53
	v_exp_f32_e32 v54, v54
	v_exp_f32_e32 v55, v55
	v_exp_f32_e32 v56, v56
	v_exp_f32_e32 v57, v57
	v_exp_f32_e32 v58, v58
	v_exp_f32_e32 v59, v59
	v_exp_f32_e32 v60, v60
	v_exp_f32_e32 v61, v61
	v_exp_f32_e32 v62, v62
	v_exp_f32_e32 v63, v63
	v_exp_f32_e32 v64, v64
	v_exp_f32_e32 v65, v65
	v_exp_f32_e32 v66, v66
	v_exp_f32_e32 v67, v67
	v_exp_f32_e32 v68, v68
	v_exp_f32_e32 v69, v69
	v_exp_f32_e32 v70, v70
	v_exp_f32_e32 v71, v71
	v_exp_f32_e32 v72, v72
	v_exp_f32_e32 v73, v73
	v_exp_f32_e32 v74, v74
	v_exp_f32_e32 v75, v75
	v_exp_f32_e32 v76, v76
	v_exp_f32_e32 v77, v77
	v_exp_f32_e32 v78, v78
	v_exp_f32_e32 v79, v79
	v_exp_f32_e32 v80, v80
	v_exp_f32_e32 v81, v81
	v_exp_f32_e32 v82, v82
	v_exp_f32_e32 v83, v83
	v_exp_f32_e32 v84, v84
	v_exp_f32_e32 v85, v85
	v_exp_f32_e32 v86, v86
	v_exp_f32_e32 v87, v87
	v_exp_f32_e32 v88, v88
	v_exp_f32_e32 v89, v89
	v_exp_f32_e32 v90, v90
	v_exp_f32_e32 v91, v91
	v_exp_f32_e32 v92, v92
	v_exp_f32_e32 v93, v93
	v_exp_f32_e32 v94, v94
	v_exp_f32_e32 v95, v95
	v_exp_f32_e32 v96, v96
	v_exp_f32_e32 v97, v97
	v_exp_f32_e32 v98, v98
	v_exp_f32_e32 v99, v99
	v_exp_f32_e32 v100, v100
	v_exp_f32_e32 v101, v101
	v_exp_f32_e32 v102, v102
	v_exp_f32_e32 v103, v103
	v_exp_f32_e32 v104, v104
	v_exp_f32_e32 v105, v105
	v_exp_f32_e32 v106, v106
	v_exp_f32_e32 v107, v107
	v_exp_f32_e32 v108, v108
	v_exp_f32_e32 v109, v109
	v_exp_f32_e32 v110, v110
	v_exp_f32_e32 v111, v111
	v_exp_f32_e32 v112, v112
	v_exp_f32_e32 v113, v113
	v_exp_f32_e32 v114, v114
	v_exp_f32_e32 v115, v115
	v_exp_f32_e32 v116, v116
	v_exp_f32_e32 v117, v117
	v_exp_f32_e32 v219, v219
	v_pk_add_f32 v[236:237], v[50:51], v[52:53]
	v_pk_add_f32 v[238:239], v[54:55], v[56:57]
	v_pk_add_f32 v[240:241], v[58:59], v[60:61]
	v_pk_add_f32 v[242:243], v[62:63], v[64:65]
	v_pk_add_f32 v[236:237], v[236:237], v[66:67]
	v_pk_add_f32 v[238:239], v[238:239], v[70:71]
	v_pk_add_f32 v[240:241], v[240:241], v[74:75]
	v_pk_add_f32 v[242:243], v[242:243], v[78:79]
	v_pk_add_f32 v[236:237], v[236:237], v[68:69]
	v_pk_add_f32 v[238:239], v[238:239], v[72:73]
	v_pk_add_f32 v[240:241], v[240:241], v[76:77]
	v_pk_add_f32 v[242:243], v[242:243], v[80:81]
	v_pk_add_f32 v[236:237], v[236:237], v[82:83]
	v_pk_add_f32 v[238:239], v[238:239], v[86:87]
	v_pk_add_f32 v[240:241], v[240:241], v[90:91]
	v_pk_add_f32 v[242:243], v[242:243], v[94:95]
	v_pk_add_f32 v[236:237], v[236:237], v[84:85]
	v_pk_add_f32 v[238:239], v[238:239], v[88:89]
	v_pk_add_f32 v[240:241], v[240:241], v[92:93]
	v_pk_add_f32 v[242:243], v[242:243], v[96:97]
	v_pk_add_f32 v[236:237], v[236:237], v[98:99]
	v_pk_add_f32 v[238:239], v[238:239], v[102:103]
	v_pk_add_f32 v[240:241], v[240:241], v[106:107]
	v_pk_add_f32 v[242:243], v[242:243], v[110:111]
	v_pk_add_f32 v[236:237], v[236:237], v[100:101]
	v_pk_add_f32 v[238:239], v[238:239], v[104:105]
	v_pk_add_f32 v[240:241], v[240:241], v[108:109]
	v_pk_add_f32 v[242:243], v[242:243], v[112:113]
	v_pk_add_f32 v[236:237], v[236:237], v[114:115]
	v_pk_add_f32 v[236:237], v[236:237], v[116:117]
	v_pk_add_f32 v[236:237], v[236:237], v[238:239]
	v_pk_add_f32 v[240:241], v[240:241], v[242:243]
	v_cndmask_b32_e64 v219, 0, v219, s[74:75]
	v_pk_add_f32 v[236:237], v[236:237], v[240:241]
	v_add_f32_e32 v185, v236, v237
	v_add_f32_e32 v185, v185, v219
	v_cvt_pk_bf16_f32 v236, v50, v51
	v_cvt_pk_bf16_f32 v237, v52, v53
	v_cvt_pk_bf16_f32 v238, v54, v55
	v_cvt_pk_bf16_f32 v239, v56, v57
	s_nop 1
	s_waitcnt lgkmcnt(14)
	v_mfma_f32_16x16x32_bf16 v[210:213], v[186:189], v[236:239], 0
	s_waitcnt lgkmcnt(12)
	v_mfma_f32_16x16x32_bf16 v[214:217], v[190:193], v[236:239], 0
	s_waitcnt lgkmcnt(10)
	v_mfma_f32_16x16x32_bf16 v[220:223], v[194:197], v[236:239], 0
	s_waitcnt lgkmcnt(8)
	v_mfma_f32_16x16x32_bf16 v[224:227], v[198:201], v[236:239], 0
	v_cvt_pk_bf16_f32 v240, v58, v59
	v_cvt_pk_bf16_f32 v241, v60, v61
	v_cvt_pk_bf16_f32 v242, v62, v63
	v_cvt_pk_bf16_f32 v243, v64, v65
	s_waitcnt lgkmcnt(7)
	ds_read_b64_tr_b16 v[186:187], v124 offset:12288
	ds_read_b64_tr_b16 v[188:189], v124 offset:14336
	ds_read_b64_tr_b16 v[190:191], v125 offset:12288
	ds_read_b64_tr_b16 v[192:193], v125 offset:14336
	ds_read_b64_tr_b16 v[194:195], v126 offset:12288
	ds_read_b64_tr_b16 v[196:197], v126 offset:14336
	ds_read_b64_tr_b16 v[198:199], v127 offset:12288
	ds_read_b64_tr_b16 v[200:201], v127 offset:14336
	s_waitcnt lgkmcnt(14)
	v_mfma_f32_16x16x32_bf16 v[210:213], v[202:205], v[240:243], v[210:213]
	s_waitcnt lgkmcnt(12)
	v_mfma_f32_16x16x32_bf16 v[214:217], v[206:209], v[240:243], v[214:217]
	s_waitcnt lgkmcnt(10)
	v_mfma_f32_16x16x32_bf16 v[220:223], v[228:231], v[240:243], v[220:223]
	s_waitcnt lgkmcnt(8)
; #define LAS __attribute__((address_space(3)))
; __device__ __forceinline__ unsigned pk2(float lo, float hi) { return pg8::cvt_pk_bf16(lo, hi); }
; __device__ __forceinline__ s16x4 vtr(const LAS unsigned char* p) { return __builtin_bit_cast(s16x4, __builtin_amdgcn_ds_read_tr16_b64_v4i16((LAS s16x4*)p)); }
; #define MFMA16(a, b, c) __builtin_amdgcn_mfma_f32_16x16x32_bf16((a), (b), (c), 0, 0, 0)
; __device__ __forceinline__ void pv_at(const LAS unsigned char* const (&vp)[4], int off, const f32x4& P0, const f32x4& P1, f32x4 (&O)[4]) {
;     v4u pw; pw.x = pk2(P0[0], P0[1]); pw.y = pk2(P0[2], P0[3]); pw.z = pk2(P1[0], P1[1]); pw.w = pk2(P1[2], P1[3]);
;     const bf16x8 pb = __builtin_bit_cast(bf16x8, pw);
; #pragma unroll
;     for (int db = 0; db < 4; ++db) {
;         const s16x4 lo = vtr(vp[db] + off), hi = vtr(vp[db] + off + 2048);
;         const bf16x8 vt = (bf16x8){lo[0], lo[1], lo[2], lo[3], hi[0], hi[1], hi[2], hi[3]};
;         O[db] = MFMA16(vt, pb, O[db]);
;     }
; }
	v_mfma_f32_16x16x32_bf16 v[224:227], v[232:235], v[240:243], v[224:227]
	v_cvt_pk_bf16_f32 v236, v66, v67
	v_cvt_pk_bf16_f32 v237, v68, v69
	v_cvt_pk_bf16_f32 v238, v70, v71
	v_cvt_pk_bf16_f32 v239, v72, v73
	s_waitcnt lgkmcnt(7)
	ds_read_b64_tr_b16 v[202:203], v124 offset:16384
	ds_read_b64_tr_b16 v[204:205], v124 offset:18432
	ds_read_b64_tr_b16 v[206:207], v125 offset:16384
	ds_read_b64_tr_b16 v[208:209], v125 offset:18432
	ds_read_b64_tr_b16 v[228:229], v126 offset:16384
	ds_read_b64_tr_b16 v[230:231], v126 offset:18432
	ds_read_b64_tr_b16 v[232:233], v127 offset:16384
	ds_read_b64_tr_b16 v[234:235], v127 offset:18432
	s_waitcnt lgkmcnt(14)
	v_mfma_f32_16x16x32_bf16 v[210:213], v[186:189], v[236:239], v[210:213]
	s_waitcnt lgkmcnt(12)
	v_mfma_f32_16x16x32_bf16 v[214:217], v[190:193], v[236:239], v[214:217]
	s_waitcnt lgkmcnt(10)
	v_mfma_f32_16x16x32_bf16 v[220:223], v[194:197], v[236:239], v[220:223]
	s_waitcnt lgkmcnt(8)
	v_mfma_f32_16x16x32_bf16 v[224:227], v[198:201], v[236:239], v[224:227]
	v_cvt_pk_bf16_f32 v240, v74, v75
	v_cvt_pk_bf16_f32 v241, v76, v77
	v_cvt_pk_bf16_f32 v242, v78, v79
	v_cvt_pk_bf16_f32 v243, v80, v81
	s_waitcnt lgkmcnt(7)
	ds_read_b64_tr_b16 v[186:187], v124 offset:20480
	ds_read_b64_tr_b16 v[188:189], v124 offset:22528
	ds_read_b64_tr_b16 v[190:191], v125 offset:20480
	ds_read_b64_tr_b16 v[192:193], v125 offset:22528
	ds_read_b64_tr_b16 v[194:195], v126 offset:20480
	ds_read_b64_tr_b16 v[196:197], v126 offset:22528
	ds_read_b64_tr_b16 v[198:199], v127 offset:20480
	ds_read_b64_tr_b16 v[200:201], v127 offset:22528
	s_waitcnt lgkmcnt(14)
	v_mfma_f32_16x16x32_bf16 v[210:213], v[202:205], v[240:243], v[210:213]
	s_waitcnt lgkmcnt(12)
	v_mfma_f32_16x16x32_bf16 v[214:217], v[206:209], v[240:243], v[214:217]
	s_waitcnt lgkmcnt(10)
	v_mfma_f32_16x16x32_bf16 v[220:223], v[228:231], v[240:243], v[220:223]
	s_waitcnt lgkmcnt(8)
	v_mfma_f32_16x16x32_bf16 v[224:227], v[232:235], v[240:243], v[224:227]
	v_cvt_pk_bf16_f32 v236, v82, v83
	v_cvt_pk_bf16_f32 v237, v84, v85
	v_cvt_pk_bf16_f32 v238, v86, v87
	v_cvt_pk_bf16_f32 v239, v88, v89
	s_waitcnt lgkmcnt(7)
	ds_read_b64_tr_b16 v[202:203], v124 offset:24576
	ds_read_b64_tr_b16 v[204:205], v124 offset:26624
	ds_read_b64_tr_b16 v[206:207], v125 offset:24576
	ds_read_b64_tr_b16 v[208:209], v125 offset:26624
	ds_read_b64_tr_b16 v[228:229], v126 offset:24576
	ds_read_b64_tr_b16 v[230:231], v126 offset:26624
	ds_read_b64_tr_b16 v[232:233], v127 offset:24576
	ds_read_b64_tr_b16 v[234:235], v127 offset:26624
	s_waitcnt lgkmcnt(14)
	v_mfma_f32_16x16x32_bf16 v[210:213], v[186:189], v[236:239], v[210:213]
	s_waitcnt lgkmcnt(12)
	v_mfma_f32_16x16x32_bf16 v[214:217], v[190:193], v[236:239], v[214:217]
	s_waitcnt lgkmcnt(10)
	v_mfma_f32_16x16x32_bf16 v[220:223], v[194:197], v[236:239], v[220:223]
	s_waitcnt lgkmcnt(8)
	v_mfma_f32_16x16x32_bf16 v[224:227], v[198:201], v[236:239], v[224:227]
	v_cvt_pk_bf16_f32 v240, v90, v91
	v_cvt_pk_bf16_f32 v241, v92, v93
	v_cvt_pk_bf16_f32 v242, v94, v95
	v_cvt_pk_bf16_f32 v243, v96, v97
	s_waitcnt lgkmcnt(7)
	ds_read_b64_tr_b16 v[186:187], v124 offset:28672
	ds_read_b64_tr_b16 v[188:189], v124 offset:30720
	ds_read_b64_tr_b16 v[190:191], v125 offset:28672
	ds_read_b64_tr_b16 v[192:193], v125 offset:30720
	ds_read_b64_tr_b16 v[194:195], v126 offset:28672
	ds_read_b64_tr_b16 v[196:197], v126 offset:30720
	ds_read_b64_tr_b16 v[198:199], v127 offset:28672
	ds_read_b64_tr_b16 v[200:201], v127 offset:30720
	s_waitcnt lgkmcnt(14)
	v_mfma_f32_16x16x32_bf16 v[210:213], v[202:205], v[240:243], v[210:213]
	s_waitcnt lgkmcnt(12)
	v_mfma_f32_16x16x32_bf16 v[214:217], v[206:209], v[240:243], v[214:217]
	s_waitcnt lgkmcnt(10)
	v_mfma_f32_16x16x32_bf16 v[220:223], v[228:231], v[240:243], v[220:223]
	s_waitcnt lgkmcnt(8)
	v_mfma_f32_16x16x32_bf16 v[224:227], v[232:235], v[240:243], v[224:227]
	v_cvt_pk_bf16_f32 v236, v98, v99
	v_cvt_pk_bf16_f32 v237, v100, v101
	v_cvt_pk_bf16_f32 v238, v102, v103
	v_cvt_pk_bf16_f32 v239, v104, v105
	s_waitcnt lgkmcnt(7)
	ds_read_b64_tr_b16 v[202:203], v124 offset:32768
	ds_read_b64_tr_b16 v[204:205], v124 offset:34816
	ds_read_b64_tr_b16 v[206:207], v125 offset:32768
	ds_read_b64_tr_b16 v[208:209], v125 offset:34816
	ds_read_b64_tr_b16 v[228:229], v126 offset:32768
	ds_read_b64_tr_b16 v[230:231], v126 offset:34816
	ds_read_b64_tr_b16 v[232:233], v127 offset:32768
	ds_read_b64_tr_b16 v[234:235], v127 offset:34816
	s_waitcnt lgkmcnt(14)
	v_mfma_f32_16x16x32_bf16 v[210:213], v[186:189], v[236:239], v[210:213]
	s_waitcnt lgkmcnt(12)
	v_mfma_f32_16x16x32_bf16 v[214:217], v[190:193], v[236:239], v[214:217]
	s_waitcnt lgkmcnt(10)
	v_mfma_f32_16x16x32_bf16 v[220:223], v[194:197], v[236:239], v[220:223]
	s_waitcnt lgkmcnt(8)
	v_mfma_f32_16x16x32_bf16 v[224:227], v[198:201], v[236:239], v[224:227]
	v_cvt_pk_bf16_f32 v240, v106, v107
	v_cvt_pk_bf16_f32 v241, v108, v109
	v_cvt_pk_bf16_f32 v242, v110, v111
	v_cvt_pk_bf16_f32 v243, v112, v113
	s_waitcnt lgkmcnt(7)
	ds_read_b64_tr_b16 v[186:187], v124 offset:36864
	ds_read_b64_tr_b16 v[188:189], v124 offset:38912
	ds_read_b64_tr_b16 v[190:191], v125 offset:36864
	ds_read_b64_tr_b16 v[192:193], v125 offset:38912
	ds_read_b64_tr_b16 v[194:195], v126 offset:36864
	ds_read_b64_tr_b16 v[196:197], v126 offset:38912
	ds_read_b64_tr_b16 v[198:199], v127 offset:36864
	ds_read_b64_tr_b16 v[200:201], v127 offset:38912
	s_waitcnt lgkmcnt(14)
	v_mfma_f32_16x16x32_bf16 v[210:213], v[202:205], v[240:243], v[210:213]
	s_waitcnt lgkmcnt(12)
	v_mfma_f32_16x16x32_bf16 v[214:217], v[206:209], v[240:243], v[214:217]
	s_waitcnt lgkmcnt(10)
	v_mfma_f32_16x16x32_bf16 v[220:223], v[228:231], v[240:243], v[220:223]
	s_waitcnt lgkmcnt(8)
; __device__ __forceinline__ unsigned pk2(float lo, float hi) { return pg8::cvt_pk_bf16(lo, hi); }
; __device__ __forceinline__ void store_o(bf16* yrow, int g, float l, const f32x4 (&O)[4]) {
;     const float inv = 1.0f / xrow16_sum(l);
;     unsigned wx[4], wy[4];
; #pragma unroll
;     for (int db = 0; db < 4; ++db) { wx[db] = pk2(O[db][0] * inv, O[db][1] * inv); wy[db] = pk2(O[db][2] * inv, O[db][3] * inv); }
; #pragma unroll
;     for (int p = 0; p < 2; ++p) {
;         auto rx = __builtin_amdgcn_permlane16_swap(wx[2 * p], wx[2 * p + 1], false, false); wx[2 * p] = rx[0]; wx[2 * p + 1] = rx[1];
;         auto ry = __builtin_amdgcn_permlane16_swap(wy[2 * p], wy[2 * p + 1], false, false); wy[2 * p] = ry[0]; wy[2 * p + 1] = ry[1]; }
; #pragma unroll
;     for (int p = 0; p < 2; ++p) {
;         auto rx = __builtin_amdgcn_permlane32_swap(wx[p], wx[p + 2], false, false); wx[p] = rx[0]; wx[p + 2] = rx[1];
;         auto ry = __builtin_amdgcn_permlane32_swap(wy[p], wy[p + 2], false, false); wy[p] = ry[0]; wy[p + 2] = ry[1]; }
;     v4u lo = {wx[0], wy[0], wx[1], wy[1]}, hi = {wx[2], wy[2], wx[3], wy[3]};
;     *(v4u*)(yrow + 16 * g) = lo; *(v4u*)(yrow + 16 * g + 8) = hi;
; }
; template <bool MASK> __device__ __forceinline__ void a_scores(f32x4& S0, f32x4& S1, float basef, float c1, float slope2, int krow0, int kstart) {
; #pragma unroll
;     for (int r = 0; r < 4; ++r) {
;         const float d0 = fabsf(basef - (float)r), d1 = fabsf(basef - (float)(16 + r));
;         const float v0 = S0[r] - slope2 * d0, v1 = S1[r] - slope2 * d1;
;         if (MASK) { const int p0 = kstart + krow0 + r, p1 = p0 + 16;
;             S0[r] = (d0 <= 128.f && p0 >= 0 && p0 < SEQ) ? v0 : -INFINITY; S1[r] = (d1 <= 128.f && p1 >= 0 && p1 < SEQ) ? v1 : -INFINITY; }
;         else { S0[r] = v0; S1[r] = v1; }
;     }
; }
	v_mfma_f32_16x16x32_bf16 v[224:227], v[232:235], v[240:243], v[224:227]
	v_cvt_pk_bf16_f32 v236, v114, v115
	v_cvt_pk_bf16_f32 v237, v116, v117
	v_mov_b32_e32 v238, 0
	v_mov_b32_e32 v239, 0
	s_nop 1
	s_waitcnt lgkmcnt(6)
	v_mfma_f32_16x16x32_bf16 v[210:213], v[186:189], v[236:239], v[210:213]
	s_waitcnt lgkmcnt(4)
	v_mfma_f32_16x16x32_bf16 v[214:217], v[190:193], v[236:239], v[214:217]
	s_waitcnt lgkmcnt(2)
	v_mfma_f32_16x16x32_bf16 v[220:223], v[194:197], v[236:239], v[220:223]
	s_waitcnt lgkmcnt(0)
	v_mfma_f32_16x16x32_bf16 v[224:227], v[198:201], v[236:239], v[224:227]
	v_mov_b32_e32 v219, v185
	s_nop 1
	v_permlane16_swap_b32_e32 v185, v219
	v_add_f32_e32 v185, v185, v219
	v_mov_b32_e32 v219, v185
	s_nop 1
	v_permlane32_swap_b32_e32 v185, v219
	v_add_f32_e32 v185, v185, v219
	v_div_scale_f32 v236, s[78:79], v185, v185, 1.0
	v_div_scale_f32 v237, vcc, 1.0, v185, 1.0
	v_rcp_f32_e32 v238, v236
	s_nop 0
	v_fma_f32 v239, -v236, v238, 1.0
	v_fmac_f32_e32 v238, v239, v238
	v_mul_f32_e32 v240, v237, v238
	v_fma_f32 v241, -v236, v240, v237
	v_fmac_f32_e32 v240, v241, v238
	v_fma_f32 v237, -v236, v240, v237
	v_div_fmas_f32 v237, v237, v238, v240
	v_div_fixup_f32 v244, v237, v185, 1.0
	v_mul_f32_e32 v240, v210, v244
	v_mul_f32_e32 v241, v211, v244
	v_mul_f32_e32 v242, v212, v244
	v_mul_f32_e32 v243, v213, v244
	v_cvt_pk_bf16_f32 v186, v240, v241
	v_cvt_pk_bf16_f32 v187, v242, v243
	v_mul_f32_e32 v240, v214, v244
	v_mul_f32_e32 v241, v215, v244
	v_mul_f32_e32 v242, v216, v244
	v_mul_f32_e32 v243, v217, v244
	v_cvt_pk_bf16_f32 v188, v240, v241
	v_cvt_pk_bf16_f32 v189, v242, v243
	v_mul_f32_e32 v240, v220, v244
	v_mul_f32_e32 v241, v221, v244
	v_mul_f32_e32 v242, v222, v244
	v_mul_f32_e32 v243, v223, v244
	v_cvt_pk_bf16_f32 v190, v240, v241
	v_cvt_pk_bf16_f32 v191, v242, v243
	v_mul_f32_e32 v240, v224, v244
	v_mul_f32_e32 v241, v225, v244
	v_mul_f32_e32 v242, v226, v244
	v_mul_f32_e32 v243, v227, v244
	v_cvt_pk_bf16_f32 v192, v240, v241
	v_cvt_pk_bf16_f32 v193, v242, v243
	s_nop 1
	v_permlane16_swap_b32_e32 v186, v188
	v_permlane16_swap_b32_e32 v187, v189
	v_permlane16_swap_b32_e32 v190, v192
	v_permlane16_swap_b32_e32 v191, v193
	s_nop 0
	v_permlane32_swap_b32_e32 v186, v190
	v_permlane32_swap_b32_e32 v187, v191
	v_permlane32_swap_b32_e32 v188, v192
	v_permlane32_swap_b32_e32 v189, v193
	v_add_u32_e32 v219, 0x1000, v128
	global_store_dwordx4 v219, v[186:189], s[82:83] offset:0 sc1
	global_store_dwordx4 v219, v[190:193], s[82:83] offset:16 sc1
	s_nop 1
	s_bitcmp1_b32 s87, 3
	s_cselect_b32 s21, 0, 0xff800000
	v_add_f32_e32 v120, s21, v132
	v_fmamk_f32 v50, v130, 0x43000000, v120
	v_fmamk_f32 v51, v130, 0x42fe0000, v120
	v_fmamk_f32 v52, v130, 0x42fc0000, v120
	v_fmamk_f32 v53, v130, 0x42fa0000, v120
	s_bitcmp1_b32 s87, 4
	s_cselect_b32 s21, 0, 0xff800000
	v_add_f32_e32 v120, s21, v132
	v_fmamk_f32 v54, v130, 0x42e00000, v120
	v_fmamk_f32 v55, v130, 0x42de0000, v120
	v_fmamk_f32 v56, v130, 0x42dc0000, v120
	v_fmamk_f32 v57, v130, 0x42da0000, v120
	s_bitcmp1_b32 s87, 5
	s_cselect_b32 s21, 0, 0xff800000
	v_add_f32_e32 v120, s21, v132
	v_fmamk_f32 v58, v130, 0x42c00000, v120
	v_fmamk_f32 v59, v130, 0x42be0000, v120
	v_fmamk_f32 v60, v130, 0x42bc0000, v120
	v_fmamk_f32 v61, v130, 0x42ba0000, v120
	s_bitcmp1_b32 s87, 6
	s_cselect_b32 s21, 0, 0xff800000
	v_add_f32_e32 v120, s21, v132
	v_fmamk_f32 v62, v130, 0x42a00000, v120
	v_fmamk_f32 v63, v130, 0x429e0000, v120
	v_fmamk_f32 v64, v130, 0x429c0000, v120
	v_fmamk_f32 v65, v130, 0x429a0000, v120
	s_bitcmp1_b32 s87, 7
	s_cselect_b32 s21, 0, 0xff800000
	v_add_f32_e32 v120, s21, v132
	v_fmamk_f32 v66, v130, 0x42800000, v120
	v_fmamk_f32 v67, v130, 0x427c0000, v120
	v_fmamk_f32 v68, v130, 0x42780000, v120
	v_fmamk_f32 v69, v130, 0x42740000, v120
	s_bitcmp1_b32 s87, 8
	s_cselect_b32 s21, 0, 0xff800000
	v_add_f32_e32 v120, s21, v132
	v_fmamk_f32 v70, v130, 0x42400000, v120
	v_fmamk_f32 v71, v130, 0x423c0000, v120
	v_fmamk_f32 v72, v130, 0x42380000, v120
	v_fmamk_f32 v73, v130, 0x42340000, v120
	s_bitcmp1_b32 s87, 9
	s_cselect_b32 s21, 0, 0xff800000
	v_add_f32_e32 v120, s21, v132
	v_fmamk_f32 v74, v130, 0x42000000, v120
	v_fmamk_f32 v75, v130, 0x41f80000, v120
	v_fmamk_f32 v76, v130, 0x41f00000, v120
	v_fmamk_f32 v77, v130, 0x41e80000, v120
	s_bitcmp1_b32 s87, 10
	s_cselect_b32 s21, 0, 0xff800000
	v_add_f32_e32 v120, s21, v132
	v_fmamk_f32 v78, v130, 0x41800000, v120
	v_fmamk_f32 v79, v130, 0x41700000, v120
	v_fmamk_f32 v80, v130, 0x41600000, v120
	v_fmamk_f32 v81, v130, 0x41500000, v120
	s_bitcmp1_b32 s87, 11
	s_cselect_b32 s21, 0, 0xff800000
	v_add_f32_e32 v219, 0, v129
	v_fma_f32 v82, v130, |v219|, s21
	v_add_f32_e32 v244, 0xbf800000, v129
	v_fma_f32 v83, v130, |v244|, s21
	v_add_f32_e32 v219, 0xc0000000, v129
	v_fma_f32 v84, v130, |v219|, s21
	v_add_f32_e32 v244, 0xc0400000, v129
	v_fma_f32 v85, v130, |v244|, s21
	s_bitcmp1_b32 s87, 12
	s_cselect_b32 s21, 0, 0xff800000
	v_add_f32_e32 v120, s21, v133
	v_fmamk_f32 v86, v131, 0xc1800000, v120
	v_fmamk_f32 v87, v131, 0xc1880000, v120
	v_fmamk_f32 v88, v131, 0xc1900000, v120
	v_fmamk_f32 v89, v131, 0xc1980000, v120
	s_bitcmp1_b32 s87, 13
	s_cselect_b32 s21, 0, 0xff800000
	v_add_f32_e32 v120, s21, v133
	v_fmamk_f32 v90, v131, 0xc2000000, v120
	v_fmamk_f32 v91, v131, 0xc2040000, v120
	v_fmamk_f32 v92, v131, 0xc2080000, v120
	v_fmamk_f32 v93, v131, 0xc20c0000, v120
	s_bitcmp1_b32 s87, 14
	s_cselect_b32 s21, 0, 0xff800000
	v_add_f32_e32 v120, s21, v133
	v_fmamk_f32 v94, v131, 0xc2400000, v120
	v_fmamk_f32 v95, v131, 0xc2440000, v120
	v_fmamk_f32 v96, v131, 0xc2480000, v120
	v_fmamk_f32 v97, v131, 0xc24c0000, v120
	s_bitcmp1_b32 s87, 15
	s_cselect_b32 s21, 0, 0xff800000
; #define LAS __attribute__((address_space(3)))
; #define MFMA16(a, b, c) __builtin_amdgcn_mfma_f32_16x16x32_bf16((a), (b), (c), 0, 0, 0)
; __device__ __forceinline__ void qk_at(const LAS unsigned char* kp0, const LAS unsigned char* kp1, int off, bf16x8 qf0, bf16x8 qf1, f32x4& S0, f32x4& S1) {
;     const bf16x8 k00 = *(const LAS bf16x8*)(kp0 + off), k01 = *(const LAS bf16x8*)(kp1 + off);
;     const bf16x8 k10 = *(const LAS bf16x8*)(kp0 + off + 2048), k11 = *(const LAS bf16x8*)(kp1 + off + 2048);
;     const f32x4 z = {0.f, 0.f, 0.f, 0.f};
;     S0 = MFMA16(k00, qf0, z); S0 = MFMA16(k01, qf1, S0);
;     S1 = MFMA16(k10, qf0, z); S1 = MFMA16(k11, qf1, S1);
; }
; template <bool MASK> __device__ __forceinline__ void a_scores(f32x4& S0, f32x4& S1, float basef, float c1, float slope2, int krow0, int kstart) {
; #pragma unroll
;     for (int r = 0; r < 4; ++r) {
;         const float d0 = fabsf(basef - (float)r), d1 = fabsf(basef - (float)(16 + r));
;         const float v0 = S0[r] - slope2 * d0, v1 = S1[r] - slope2 * d1;
;         if (MASK) { const int p0 = kstart + krow0 + r, p1 = p0 + 16;
;             S0[r] = (d0 <= 128.f && p0 >= 0 && p0 < SEQ) ? v0 : -INFINITY; S1[r] = (d1 <= 128.f && p1 >= 0 && p1 < SEQ) ? v1 : -INFINITY; }
;         else { S0[r] = v0; S1[r] = v1; }
;     }
; }
	v_add_f32_e32 v120, s21, v133
	v_fmamk_f32 v98, v131, 0xc2800000, v120
	v_fmamk_f32 v99, v131, 0xc2820000, v120
	v_fmamk_f32 v100, v131, 0xc2840000, v120
	v_fmamk_f32 v101, v131, 0xc2860000, v120
	s_bitcmp1_b32 s87, 16
	s_cselect_b32 s21, 0, 0xff800000
	v_add_f32_e32 v120, s21, v133
	v_fmamk_f32 v102, v131, 0xc2a00000, v120
	v_fmamk_f32 v103, v131, 0xc2a20000, v120
	v_fmamk_f32 v104, v131, 0xc2a40000, v120
	v_fmamk_f32 v105, v131, 0xc2a60000, v120
	s_bitcmp1_b32 s87, 17
	s_cselect_b32 s21, 0, 0xff800000
	v_add_f32_e32 v120, s21, v133
	v_fmamk_f32 v106, v131, 0xc2c00000, v120
	v_fmamk_f32 v107, v131, 0xc2c20000, v120
	v_fmamk_f32 v108, v131, 0xc2c40000, v120
	v_fmamk_f32 v109, v131, 0xc2c60000, v120
	s_bitcmp1_b32 s87, 18
	s_cselect_b32 s21, 0, 0xff800000
	v_add_f32_e32 v120, s21, v133
	v_fmamk_f32 v110, v131, 0xc2e00000, v120
	v_fmamk_f32 v111, v131, 0xc2e20000, v120
	v_fmamk_f32 v112, v131, 0xc2e40000, v120
	v_fmamk_f32 v113, v131, 0xc2e60000, v120
	s_bitcmp1_b32 s87, 19
	s_cselect_b32 s21, 0, 0xff800000
	v_add_f32_e32 v120, s21, v133
	v_fmamk_f32 v114, v131, 0xc3000000, v120
	v_fmamk_f32 v115, v131, 0xc3010000, v120
	v_fmamk_f32 v116, v131, 0xc3020000, v120
	v_fmamk_f32 v117, v131, 0xc3030000, v120
	v_mov_b32_e32 v245, 0xff800000
	v_cndmask_b32_e64 v50, v245, v50, s[16:17]
	v_cndmask_b32_e64 v51, v245, v51, s[18:19]
	v_cndmask_b32_e64 v52, v245, v52, s[22:23]
	v_cndmask_b32_e64 v53, v245, v53, s[24:25]
	v_cndmask_b32_e64 v114, v245, v114, s[28:29]
	v_cndmask_b32_e64 v115, v245, v115, s[52:53]
	v_cndmask_b32_e64 v116, v245, v116, s[54:55]
	v_cndmask_b32_e64 v117, v245, v117, s[88:89]
	ds_read_b128 v[186:189], v122 offset:6144
	ds_read_b128 v[190:193], v123 offset:6144
	ds_read_b128 v[194:197], v122 offset:8192
	ds_read_b128 v[198:201], v123 offset:8192
	ds_read_b128 v[202:205], v122 offset:10240
	ds_read_b128 v[206:209], v123 offset:10240
	s_waitcnt lgkmcnt(5)
	v_mfma_f32_16x16x32_bf16 v[50:53], v[186:189], v[170:173], v[50:53]
	s_waitcnt lgkmcnt(4)
	v_mfma_f32_16x16x32_bf16 v[50:53], v[190:193], v[174:177], v[50:53]
	ds_read_b128 v[186:189], v122 offset:12288
	ds_read_b128 v[190:193], v123 offset:12288
	s_waitcnt lgkmcnt(5)
	v_mfma_f32_16x16x32_bf16 v[54:57], v[194:197], v[170:173], v[54:57]
	s_waitcnt lgkmcnt(4)
	v_mfma_f32_16x16x32_bf16 v[54:57], v[198:201], v[174:177], v[54:57]
	ds_read_b128 v[194:197], v122 offset:14336
	ds_read_b128 v[198:201], v123 offset:14336
	s_waitcnt lgkmcnt(5)
	v_mfma_f32_16x16x32_bf16 v[58:61], v[202:205], v[170:173], v[58:61]
	s_waitcnt lgkmcnt(4)
	v_mfma_f32_16x16x32_bf16 v[58:61], v[206:209], v[174:177], v[58:61]
	ds_read_b128 v[202:205], v122 offset:16384
	ds_read_b128 v[206:209], v123 offset:16384
	s_waitcnt lgkmcnt(5)
	v_mfma_f32_16x16x32_bf16 v[62:65], v[186:189], v[170:173], v[62:65]
	s_waitcnt lgkmcnt(4)
	v_mfma_f32_16x16x32_bf16 v[62:65], v[190:193], v[174:177], v[62:65]
	ds_read_b128 v[186:189], v122 offset:18432
	ds_read_b128 v[190:193], v123 offset:18432
	s_waitcnt lgkmcnt(5)
	v_mfma_f32_16x16x32_bf16 v[66:69], v[194:197], v[170:173], v[66:69]
	s_waitcnt lgkmcnt(4)
	v_mfma_f32_16x16x32_bf16 v[66:69], v[198:201], v[174:177], v[66:69]
	ds_read_b128 v[194:197], v122 offset:20480
	ds_read_b128 v[198:201], v123 offset:20480
	s_waitcnt lgkmcnt(5)
	v_mfma_f32_16x16x32_bf16 v[70:73], v[202:205], v[170:173], v[70:73]
	s_waitcnt lgkmcnt(4)
	v_mfma_f32_16x16x32_bf16 v[70:73], v[206:209], v[174:177], v[70:73]
	ds_read_b128 v[202:205], v122 offset:22528
	ds_read_b128 v[206:209], v123 offset:22528
	s_waitcnt lgkmcnt(5)
	v_mfma_f32_16x16x32_bf16 v[74:77], v[186:189], v[170:173], v[74:77]
	s_waitcnt lgkmcnt(4)
	v_mfma_f32_16x16x32_bf16 v[74:77], v[190:193], v[174:177], v[74:77]
	ds_read_b128 v[186:189], v122 offset:24576
	ds_read_b128 v[190:193], v123 offset:24576
	s_waitcnt lgkmcnt(5)
	v_mfma_f32_16x16x32_bf16 v[78:81], v[194:197], v[170:173], v[78:81]
	s_waitcnt lgkmcnt(4)
	v_mfma_f32_16x16x32_bf16 v[78:81], v[198:201], v[174:177], v[78:81]
	ds_read_b128 v[194:197], v122 offset:26624
	ds_read_b128 v[198:201], v123 offset:26624
	s_waitcnt lgkmcnt(5)
	v_mfma_f32_16x16x32_bf16 v[82:85], v[202:205], v[170:173], v[82:85]
	s_waitcnt lgkmcnt(4)
	v_mfma_f32_16x16x32_bf16 v[82:85], v[206:209], v[174:177], v[82:85]
	ds_read_b128 v[202:205], v122 offset:28672
	ds_read_b128 v[206:209], v123 offset:28672
	s_waitcnt lgkmcnt(5)
	v_mfma_f32_16x16x32_bf16 v[86:89], v[186:189], v[170:173], v[86:89]
	s_waitcnt lgkmcnt(4)
	v_mfma_f32_16x16x32_bf16 v[86:89], v[190:193], v[174:177], v[86:89]
	ds_read_b128 v[186:189], v122 offset:30720
	ds_read_b128 v[190:193], v123 offset:30720
	s_waitcnt lgkmcnt(5)
	v_mfma_f32_16x16x32_bf16 v[90:93], v[194:197], v[170:173], v[90:93]
	s_waitcnt lgkmcnt(4)
	v_mfma_f32_16x16x32_bf16 v[90:93], v[198:201], v[174:177], v[90:93]
	ds_read_b128 v[194:197], v122 offset:32768
	ds_read_b128 v[198:201], v123 offset:32768
	s_waitcnt lgkmcnt(5)
	v_mfma_f32_16x16x32_bf16 v[94:97], v[202:205], v[170:173], v[94:97]
	s_waitcnt lgkmcnt(4)
	v_mfma_f32_16x16x32_bf16 v[94:97], v[206:209], v[174:177], v[94:97]
	ds_read_b128 v[202:205], v122 offset:34816
	ds_read_b128 v[206:209], v123 offset:34816
	s_waitcnt lgkmcnt(5)
	v_mfma_f32_16x16x32_bf16 v[98:101], v[186:189], v[170:173], v[98:101]
	s_waitcnt lgkmcnt(4)
	v_mfma_f32_16x16x32_bf16 v[98:101], v[190:193], v[174:177], v[98:101]
	ds_read_b128 v[186:189], v122 offset:36864
	ds_read_b128 v[190:193], v123 offset:36864
	s_waitcnt lgkmcnt(5)
	v_mfma_f32_16x16x32_bf16 v[102:105], v[194:197], v[170:173], v[102:105]
	s_waitcnt lgkmcnt(4)
	v_mfma_f32_16x16x32_bf16 v[102:105], v[198:201], v[174:177], v[102:105]
	ds_read_b128 v[194:197], v122 offset:38912
	ds_read_b128 v[198:201], v123 offset:38912
	s_waitcnt lgkmcnt(5)
; #define LAS __attribute__((address_space(3)))
; #define MFMA16(a, b, c) __builtin_amdgcn_mfma_f32_16x16x32_bf16((a), (b), (c), 0, 0, 0)
; __device__ __forceinline__ void qk_at(const LAS unsigned char* kp0, const LAS unsigned char* kp1, int off, bf16x8 qf0, bf16x8 qf1, f32x4& S0, f32x4& S1) {
;     const bf16x8 k00 = *(const LAS bf16x8*)(kp0 + off), k01 = *(const LAS bf16x8*)(kp1 + off);
;     const bf16x8 k10 = *(const LAS bf16x8*)(kp0 + off + 2048), k11 = *(const LAS bf16x8*)(kp1 + off + 2048);
;     const f32x4 z = {0.f, 0.f, 0.f, 0.f};
;     S0 = MFMA16(k00, qf0, z); S0 = MFMA16(k01, qf1, S0);
;     S1 = MFMA16(k10, qf0, z); S1 = MFMA16(k11, qf1, S1);
; }
; __device__ __forceinline__ void softmax_step(f32x4& s0, f32x4& s1, float& m, float& l, f32x4 (&O)[4]) {
;     float t = fmaxf(fmaxf(fmaxf(s0[0], s0[1]), fmaxf(s0[2], s0[3])), fmaxf(fmaxf(s1[0], s1[1]), fmaxf(s1[2], s1[3])));
;     t = xrow16_max(t);
;     const float mn = fmaxf(m, t), alpha = __builtin_amdgcn_exp2f(m - mn);
;     m = mn;
	v_mfma_f32_16x16x32_bf16 v[106:109], v[202:205], v[170:173], v[106:109]
	s_waitcnt lgkmcnt(4)
	v_mfma_f32_16x16x32_bf16 v[106:109], v[206:209], v[174:177], v[106:109]
	s_waitcnt lgkmcnt(3)
	v_mfma_f32_16x16x32_bf16 v[110:113], v[186:189], v[170:173], v[110:113]
	s_waitcnt lgkmcnt(2)
	v_mfma_f32_16x16x32_bf16 v[110:113], v[190:193], v[174:177], v[110:113]
	s_waitcnt lgkmcnt(1)
	v_mfma_f32_16x16x32_bf16 v[114:117], v[194:197], v[170:173], v[114:117]
	s_waitcnt lgkmcnt(0)
	v_mfma_f32_16x16x32_bf16 v[114:117], v[198:201], v[174:177], v[114:117]
	v_max3_f32 v219, v50, v51, v52
	v_max3_f32 v244, v54, v55, v56
	v_max3_f32 v245, v58, v59, v60
	v_max3_f32 v120, v62, v63, v64
	v_max3_f32 v219, v219, v53, v66
	v_max3_f32 v244, v244, v57, v70
	v_max3_f32 v245, v245, v61, v74
	v_max3_f32 v120, v120, v65, v78
	v_max3_f32 v219, v219, v67, v68
	v_max3_f32 v244, v244, v71, v72
	v_max3_f32 v245, v245, v75, v76
	v_max3_f32 v120, v120, v79, v80
	ds_read_b64_tr_b16 v[186:187], v124 offset:6144
	ds_read_b64_tr_b16 v[188:189], v124 offset:8192
	ds_read_b64_tr_b16 v[190:191], v125 offset:6144
	ds_read_b64_tr_b16 v[192:193], v125 offset:8192
	ds_read_b64_tr_b16 v[194:195], v126 offset:6144
	ds_read_b64_tr_b16 v[196:197], v126 offset:8192
	ds_read_b64_tr_b16 v[198:199], v127 offset:6144
	ds_read_b64_tr_b16 v[200:201], v127 offset:8192
	v_max3_f32 v219, v219, v69, v82
	v_max3_f32 v244, v244, v73, v86
	v_max3_f32 v245, v245, v77, v90
	v_max3_f32 v120, v120, v81, v94
	v_max3_f32 v219, v219, v83, v84
	v_max3_f32 v244, v244, v87, v88
	v_max3_f32 v245, v245, v91, v92
	v_max3_f32 v120, v120, v95, v96
	v_max3_f32 v219, v219, v85, v98
	v_max3_f32 v244, v244, v89, v102
	v_max3_f32 v245, v245, v93, v106
	v_max3_f32 v120, v120, v97, v110
	v_max3_f32 v219, v219, v99, v100
	v_max3_f32 v244, v244, v103, v104
	v_max3_f32 v245, v245, v107, v108
	v_max3_f32 v120, v120, v111, v112
	v_max3_f32 v219, v219, v101, v114
	v_max3_f32 v219, v219, v115, v116
	v_max_f32_e32 v219, v219, v117
	v_max_f32_e32 v244, v244, v105
	v_max_f32_e32 v245, v245, v109
	v_max_f32_e32 v120, v120, v113
	v_max3_f32 v178, v219, v244, v245
	v_max_f32_e32 v178, v178, v120
	v_mov_b32_e32 v219, v178
	s_nop 1
	v_permlane16_swap_b32_e32 v178, v219
	v_max_f32_e32 v178, v178, v219
	v_mov_b32_e32 v219, v178
	s_nop 1
	v_permlane32_swap_b32_e32 v178, v219
	v_max3_f32 v178, v178, v219, v145
	s_waitcnt lgkmcnt(7)
	ds_read_b64_tr_b16 v[202:203], v124 offset:10240
	ds_read_b64_tr_b16 v[204:205], v124 offset:12288
	ds_read_b64_tr_b16 v[206:207], v125 offset:10240
	ds_read_b64_tr_b16 v[208:209], v125 offset:12288
	ds_read_b64_tr_b16 v[228:229], v126 offset:10240
	ds_read_b64_tr_b16 v[230:231], v126 offset:12288
	ds_read_b64_tr_b16 v[232:233], v127 offset:10240
	ds_read_b64_tr_b16 v[234:235], v127 offset:12288
	v_mov_b32_e32 v244, v178
	v_pk_add_f32 v[50:51], v[50:51], v[244:245] op_sel_hi:[1,0] neg_lo:[0,1] neg_hi:[0,1]
	v_pk_add_f32 v[52:53], v[52:53], v[244:245] op_sel_hi:[1,0] neg_lo:[0,1] neg_hi:[0,1]
	v_pk_add_f32 v[54:55], v[54:55], v[244:245] op_sel_hi:[1,0] neg_lo:[0,1] neg_hi:[0,1]
	v_pk_add_f32 v[56:57], v[56:57], v[244:245] op_sel_hi:[1,0] neg_lo:[0,1] neg_hi:[0,1]
	v_pk_add_f32 v[58:59], v[58:59], v[244:245] op_sel_hi:[1,0] neg_lo:[0,1] neg_hi:[0,1]
	v_pk_add_f32 v[60:61], v[60:61], v[244:245] op_sel_hi:[1,0] neg_lo:[0,1] neg_hi:[0,1]
	v_pk_add_f32 v[62:63], v[62:63], v[244:245] op_sel_hi:[1,0] neg_lo:[0,1] neg_hi:[0,1]
	v_pk_add_f32 v[64:65], v[64:65], v[244:245] op_sel_hi:[1,0] neg_lo:[0,1] neg_hi:[0,1]
	v_pk_add_f32 v[66:67], v[66:67], v[244:245] op_sel_hi:[1,0] neg_lo:[0,1] neg_hi:[0,1]
	v_pk_add_f32 v[68:69], v[68:69], v[244:245] op_sel_hi:[1,0] neg_lo:[0,1] neg_hi:[0,1]
	v_pk_add_f32 v[70:71], v[70:71], v[244:245] op_sel_hi:[1,0] neg_lo:[0,1] neg_hi:[0,1]
	v_pk_add_f32 v[72:73], v[72:73], v[244:245] op_sel_hi:[1,0] neg_lo:[0,1] neg_hi:[0,1]
	v_pk_add_f32 v[74:75], v[74:75], v[244:245] op_sel_hi:[1,0] neg_lo:[0,1] neg_hi:[0,1]
	v_pk_add_f32 v[76:77], v[76:77], v[244:245] op_sel_hi:[1,0] neg_lo:[0,1] neg_hi:[0,1]
	v_pk_add_f32 v[78:79], v[78:79], v[244:245] op_sel_hi:[1,0] neg_lo:[0,1] neg_hi:[0,1]
	v_pk_add_f32 v[80:81], v[80:81], v[244:245] op_sel_hi:[1,0] neg_lo:[0,1] neg_hi:[0,1]
	v_pk_add_f32 v[82:83], v[82:83], v[244:245] op_sel_hi:[1,0] neg_lo:[0,1] neg_hi:[0,1]
	v_pk_add_f32 v[84:85], v[84:85], v[244:245] op_sel_hi:[1,0] neg_lo:[0,1] neg_hi:[0,1]
	v_pk_add_f32 v[86:87], v[86:87], v[244:245] op_sel_hi:[1,0] neg_lo:[0,1] neg_hi:[0,1]
	v_pk_add_f32 v[88:89], v[88:89], v[244:245] op_sel_hi:[1,0] neg_lo:[0,1] neg_hi:[0,1]
	v_pk_add_f32 v[90:91], v[90:91], v[244:245] op_sel_hi:[1,0] neg_lo:[0,1] neg_hi:[0,1]
	v_pk_add_f32 v[92:93], v[92:93], v[244:245] op_sel_hi:[1,0] neg_lo:[0,1] neg_hi:[0,1]
	v_pk_add_f32 v[94:95], v[94:95], v[244:245] op_sel_hi:[1,0] neg_lo:[0,1] neg_hi:[0,1]
	v_pk_add_f32 v[96:97], v[96:97], v[244:245] op_sel_hi:[1,0] neg_lo:[0,1] neg_hi:[0,1]
	v_pk_add_f32 v[98:99], v[98:99], v[244:245] op_sel_hi:[1,0] neg_lo:[0,1] neg_hi:[0,1]
	v_pk_add_f32 v[100:101], v[100:101], v[244:245] op_sel_hi:[1,0] neg_lo:[0,1] neg_hi:[0,1]
	v_pk_add_f32 v[102:103], v[102:103], v[244:245] op_sel_hi:[1,0] neg_lo:[0,1] neg_hi:[0,1]
	v_pk_add_f32 v[104:105], v[104:105], v[244:245] op_sel_hi:[1,0] neg_lo:[0,1] neg_hi:[0,1]
	v_pk_add_f32 v[106:107], v[106:107], v[244:245] op_sel_hi:[1,0] neg_lo:[0,1] neg_hi:[0,1]
	v_pk_add_f32 v[108:109], v[108:109], v[244:245] op_sel_hi:[1,0] neg_lo:[0,1] neg_hi:[0,1]
	v_pk_add_f32 v[110:111], v[110:111], v[244:245] op_sel_hi:[1,0] neg_lo:[0,1] neg_hi:[0,1]
	v_pk_add_f32 v[112:113], v[112:113], v[244:245] op_sel_hi:[1,0] neg_lo:[0,1] neg_hi:[0,1]
; #define LAS __attribute__((address_space(3)))
; __device__ __forceinline__ unsigned pk2(float lo, float hi) { return pg8::cvt_pk_bf16(lo, hi); }
; __device__ __forceinline__ s16x4 vtr(const LAS unsigned char* p) { return __builtin_bit_cast(s16x4, __builtin_amdgcn_ds_read_tr16_b64_v4i16((LAS s16x4*)p)); }
; #define MFMA16(a, b, c) __builtin_amdgcn_mfma_f32_16x16x32_bf16((a), (b), (c), 0, 0, 0)
; __device__ __forceinline__ void pv_at(const LAS unsigned char* const (&vp)[4], int off, const f32x4& P0, const f32x4& P1, f32x4 (&O)[4]) {
;     v4u pw; pw.x = pk2(P0[0], P0[1]); pw.y = pk2(P0[2], P0[3]); pw.z = pk2(P1[0], P1[1]); pw.w = pk2(P1[2], P1[3]);
;     const bf16x8 pb = __builtin_bit_cast(bf16x8, pw);
; #pragma unroll
;     for (int db = 0; db < 4; ++db) {
;         const s16x4 lo = vtr(vp[db] + off), hi = vtr(vp[db] + off + 2048);
;         const bf16x8 vt = (bf16x8){lo[0], lo[1], lo[2], lo[3], hi[0], hi[1], hi[2], hi[3]};
;         O[db] = MFMA16(vt, pb, O[db]);
;     }
; }
; __device__ __forceinline__ void softmax_step(f32x4& s0, f32x4& s1, float& m, float& l, f32x4 (&O)[4]) {
;     float t = fmaxf(fmaxf(fmaxf(s0[0], s0[1]), fmaxf(s0[2], s0[3])), fmaxf(fmaxf(s1[0], s1[1]), fmaxf(s1[2], s1[3])));
;     t = xrow16_max(t);
;     const float mn = fmaxf(m, t), alpha = __builtin_amdgcn_exp2f(m - mn);
;     m = mn;
; #pragma unroll
;     for (int k = 0; k < 4; ++k) { s0[k] = __builtin_amdgcn_exp2f(s0[k] - mn); s1[k] = __builtin_amdgcn_exp2f(s1[k] - mn); }
;     l = l * alpha + ((s0[0] + s0[1]) + (s0[2] + s0[3])) + ((s1[0] + s1[1]) + (s1[2] + s1[3]));
; #pragma unroll
;     for (int db = 0; db < 4; ++db) O[db] *= alpha;
; }
	v_pk_add_f32 v[114:115], v[114:115], v[244:245] op_sel_hi:[1,0] neg_lo:[0,1] neg_hi:[0,1]
	v_pk_add_f32 v[116:117], v[116:117], v[244:245] op_sel_hi:[1,0] neg_lo:[0,1] neg_hi:[0,1]
	v_sub_f32_e32 v219, v145, v178
	v_exp_f32_e32 v50, v50
	v_exp_f32_e32 v51, v51
	v_exp_f32_e32 v52, v52
	v_exp_f32_e32 v53, v53
	v_exp_f32_e32 v54, v54
	v_exp_f32_e32 v55, v55
	v_exp_f32_e32 v56, v56
	v_exp_f32_e32 v57, v57
	v_exp_f32_e32 v58, v58
	v_exp_f32_e32 v59, v59
	v_exp_f32_e32 v60, v60
	v_exp_f32_e32 v61, v61
	v_exp_f32_e32 v62, v62
	v_exp_f32_e32 v63, v63
	v_exp_f32_e32 v64, v64
	v_exp_f32_e32 v65, v65
	v_exp_f32_e32 v66, v66
	v_exp_f32_e32 v67, v67
	v_exp_f32_e32 v68, v68
	v_exp_f32_e32 v69, v69
	v_exp_f32_e32 v70, v70
	v_exp_f32_e32 v71, v71
	v_exp_f32_e32 v72, v72
	v_exp_f32_e32 v73, v73
	v_exp_f32_e32 v74, v74
	v_exp_f32_e32 v75, v75
	v_exp_f32_e32 v76, v76
	v_exp_f32_e32 v77, v77
	v_exp_f32_e32 v78, v78
	v_exp_f32_e32 v79, v79
	v_exp_f32_e32 v80, v80
	v_exp_f32_e32 v81, v81
	v_exp_f32_e32 v82, v82
	v_exp_f32_e32 v83, v83
	v_exp_f32_e32 v84, v84
	v_exp_f32_e32 v85, v85
	v_exp_f32_e32 v86, v86
	v_exp_f32_e32 v87, v87
	v_exp_f32_e32 v88, v88
	v_exp_f32_e32 v89, v89
	v_exp_f32_e32 v90, v90
	v_exp_f32_e32 v91, v91
	v_exp_f32_e32 v92, v92
	v_exp_f32_e32 v93, v93
	v_exp_f32_e32 v94, v94
	v_exp_f32_e32 v95, v95
	v_exp_f32_e32 v96, v96
	v_exp_f32_e32 v97, v97
	v_exp_f32_e32 v98, v98
	v_exp_f32_e32 v99, v99
	v_exp_f32_e32 v100, v100
	v_exp_f32_e32 v101, v101
	v_exp_f32_e32 v102, v102
	v_exp_f32_e32 v103, v103
	v_exp_f32_e32 v104, v104
	v_exp_f32_e32 v105, v105
	v_exp_f32_e32 v106, v106
	v_exp_f32_e32 v107, v107
	v_exp_f32_e32 v108, v108
	v_exp_f32_e32 v109, v109
	v_exp_f32_e32 v110, v110
	v_exp_f32_e32 v111, v111
	v_exp_f32_e32 v112, v112
	v_exp_f32_e32 v113, v113
	v_exp_f32_e32 v114, v114
	v_exp_f32_e32 v115, v115
	v_exp_f32_e32 v116, v116
	v_exp_f32_e32 v117, v117
	v_exp_f32_e32 v219, v219
	v_pk_add_f32 v[236:237], v[50:51], v[52:53]
	v_pk_add_f32 v[238:239], v[54:55], v[56:57]
	v_pk_add_f32 v[240:241], v[58:59], v[60:61]
	v_pk_add_f32 v[242:243], v[62:63], v[64:65]
	v_pk_add_f32 v[236:237], v[236:237], v[66:67]
	v_pk_add_f32 v[238:239], v[238:239], v[70:71]
	v_pk_add_f32 v[240:241], v[240:241], v[74:75]
	v_pk_add_f32 v[242:243], v[242:243], v[78:79]
	v_pk_add_f32 v[236:237], v[236:237], v[68:69]
	v_pk_add_f32 v[238:239], v[238:239], v[72:73]
	v_pk_add_f32 v[240:241], v[240:241], v[76:77]
	v_pk_add_f32 v[242:243], v[242:243], v[80:81]
	v_pk_add_f32 v[236:237], v[236:237], v[82:83]
	v_pk_add_f32 v[238:239], v[238:239], v[86:87]
	v_pk_add_f32 v[240:241], v[240:241], v[90:91]
	v_pk_add_f32 v[242:243], v[242:243], v[94:95]
	v_pk_add_f32 v[236:237], v[236:237], v[84:85]
	v_pk_add_f32 v[238:239], v[238:239], v[88:89]
	v_pk_add_f32 v[240:241], v[240:241], v[92:93]
	v_pk_add_f32 v[242:243], v[242:243], v[96:97]
	v_pk_add_f32 v[236:237], v[236:237], v[98:99]
	v_pk_add_f32 v[238:239], v[238:239], v[102:103]
	v_pk_add_f32 v[240:241], v[240:241], v[106:107]
	v_pk_add_f32 v[242:243], v[242:243], v[110:111]
	v_pk_add_f32 v[236:237], v[236:237], v[100:101]
	v_pk_add_f32 v[238:239], v[238:239], v[104:105]
	v_pk_add_f32 v[240:241], v[240:241], v[108:109]
	v_pk_add_f32 v[242:243], v[242:243], v[112:113]
	v_pk_add_f32 v[236:237], v[236:237], v[114:115]
	v_pk_add_f32 v[236:237], v[236:237], v[116:117]
	v_pk_add_f32 v[236:237], v[236:237], v[238:239]
	v_pk_add_f32 v[240:241], v[240:241], v[242:243]
	v_cndmask_b32_e64 v219, 0, v219, s[74:75]
	v_pk_add_f32 v[236:237], v[236:237], v[240:241]
	v_add_f32_e32 v185, v236, v237
	v_add_f32_e32 v185, v185, v219
	v_cvt_pk_bf16_f32 v236, v50, v51
	v_cvt_pk_bf16_f32 v237, v52, v53
	v_cvt_pk_bf16_f32 v238, v54, v55
	v_cvt_pk_bf16_f32 v239, v56, v57
	s_nop 1
	s_waitcnt lgkmcnt(14)
	v_mfma_f32_16x16x32_bf16 v[210:213], v[186:189], v[236:239], 0
	s_waitcnt lgkmcnt(12)
	v_mfma_f32_16x16x32_bf16 v[214:217], v[190:193], v[236:239], 0
	s_waitcnt lgkmcnt(10)
	v_mfma_f32_16x16x32_bf16 v[220:223], v[194:197], v[236:239], 0
	s_waitcnt lgkmcnt(8)
	v_mfma_f32_16x16x32_bf16 v[224:227], v[198:201], v[236:239], 0
	v_cvt_pk_bf16_f32 v240, v58, v59
	v_cvt_pk_bf16_f32 v241, v60, v61
	v_cvt_pk_bf16_f32 v242, v62, v63
	v_cvt_pk_bf16_f32 v243, v64, v65
	s_waitcnt lgkmcnt(7)
	ds_read_b64_tr_b16 v[186:187], v124 offset:14336
	ds_read_b64_tr_b16 v[188:189], v124 offset:16384
	ds_read_b64_tr_b16 v[190:191], v125 offset:14336
	ds_read_b64_tr_b16 v[192:193], v125 offset:16384
	ds_read_b64_tr_b16 v[194:195], v126 offset:14336
	ds_read_b64_tr_b16 v[196:197], v126 offset:16384
	ds_read_b64_tr_b16 v[198:199], v127 offset:14336
	ds_read_b64_tr_b16 v[200:201], v127 offset:16384
	s_waitcnt lgkmcnt(14)
	v_mfma_f32_16x16x32_bf16 v[210:213], v[202:205], v[240:243], v[210:213]
	s_waitcnt lgkmcnt(12)
	v_mfma_f32_16x16x32_bf16 v[214:217], v[206:209], v[240:243], v[214:217]
	s_waitcnt lgkmcnt(10)
	v_mfma_f32_16x16x32_bf16 v[220:223], v[228:231], v[240:243], v[220:223]
	s_waitcnt lgkmcnt(8)
	v_mfma_f32_16x16x32_bf16 v[224:227], v[232:235], v[240:243], v[224:227]
	v_cvt_pk_bf16_f32 v236, v66, v67
	v_cvt_pk_bf16_f32 v237, v68, v69
	v_cvt_pk_bf16_f32 v238, v70, v71
	v_cvt_pk_bf16_f32 v239, v72, v73
	s_waitcnt lgkmcnt(7)
	ds_read_b64_tr_b16 v[202:203], v124 offset:18432
	ds_read_b64_tr_b16 v[204:205], v124 offset:20480
	ds_read_b64_tr_b16 v[206:207], v125 offset:18432
	ds_read_b64_tr_b16 v[208:209], v125 offset:20480
	ds_read_b64_tr_b16 v[228:229], v126 offset:18432
	ds_read_b64_tr_b16 v[230:231], v126 offset:20480
	ds_read_b64_tr_b16 v[232:233], v127 offset:18432
	ds_read_b64_tr_b16 v[234:235], v127 offset:20480
	s_waitcnt lgkmcnt(14)
; #define LAS __attribute__((address_space(3)))
; __device__ __forceinline__ unsigned pk2(float lo, float hi) { return pg8::cvt_pk_bf16(lo, hi); }
; __device__ __forceinline__ s16x4 vtr(const LAS unsigned char* p) { return __builtin_bit_cast(s16x4, __builtin_amdgcn_ds_read_tr16_b64_v4i16((LAS s16x4*)p)); }
; #define MFMA16(a, b, c) __builtin_amdgcn_mfma_f32_16x16x32_bf16((a), (b), (c), 0, 0, 0)
; __device__ __forceinline__ void pv_at(const LAS unsigned char* const (&vp)[4], int off, const f32x4& P0, const f32x4& P1, f32x4 (&O)[4]) {
;     v4u pw; pw.x = pk2(P0[0], P0[1]); pw.y = pk2(P0[2], P0[3]); pw.z = pk2(P1[0], P1[1]); pw.w = pk2(P1[2], P1[3]);
;     const bf16x8 pb = __builtin_bit_cast(bf16x8, pw);
; #pragma unroll
;     for (int db = 0; db < 4; ++db) {
;         const s16x4 lo = vtr(vp[db] + off), hi = vtr(vp[db] + off + 2048);
;         const bf16x8 vt = (bf16x8){lo[0], lo[1], lo[2], lo[3], hi[0], hi[1], hi[2], hi[3]};
;         O[db] = MFMA16(vt, pb, O[db]);
;     }
; }
	v_mfma_f32_16x16x32_bf16 v[210:213], v[186:189], v[236:239], v[210:213]
	s_waitcnt lgkmcnt(12)
	v_mfma_f32_16x16x32_bf16 v[214:217], v[190:193], v[236:239], v[214:217]
	s_waitcnt lgkmcnt(10)
	v_mfma_f32_16x16x32_bf16 v[220:223], v[194:197], v[236:239], v[220:223]
	s_waitcnt lgkmcnt(8)
	v_mfma_f32_16x16x32_bf16 v[224:227], v[198:201], v[236:239], v[224:227]
	v_cvt_pk_bf16_f32 v240, v74, v75
	v_cvt_pk_bf16_f32 v241, v76, v77
	v_cvt_pk_bf16_f32 v242, v78, v79
	v_cvt_pk_bf16_f32 v243, v80, v81
	s_waitcnt lgkmcnt(7)
	ds_read_b64_tr_b16 v[186:187], v124 offset:22528
	ds_read_b64_tr_b16 v[188:189], v124 offset:24576
	ds_read_b64_tr_b16 v[190:191], v125 offset:22528
	ds_read_b64_tr_b16 v[192:193], v125 offset:24576
	ds_read_b64_tr_b16 v[194:195], v126 offset:22528
	ds_read_b64_tr_b16 v[196:197], v126 offset:24576
	ds_read_b64_tr_b16 v[198:199], v127 offset:22528
	ds_read_b64_tr_b16 v[200:201], v127 offset:24576
	s_waitcnt lgkmcnt(14)
	v_mfma_f32_16x16x32_bf16 v[210:213], v[202:205], v[240:243], v[210:213]
	s_waitcnt lgkmcnt(12)
	v_mfma_f32_16x16x32_bf16 v[214:217], v[206:209], v[240:243], v[214:217]
	s_waitcnt lgkmcnt(10)
	v_mfma_f32_16x16x32_bf16 v[220:223], v[228:231], v[240:243], v[220:223]
	s_waitcnt lgkmcnt(8)
	v_mfma_f32_16x16x32_bf16 v[224:227], v[232:235], v[240:243], v[224:227]
	v_cvt_pk_bf16_f32 v236, v82, v83
	v_cvt_pk_bf16_f32 v237, v84, v85
	v_cvt_pk_bf16_f32 v238, v86, v87
	v_cvt_pk_bf16_f32 v239, v88, v89
	s_waitcnt lgkmcnt(7)
	ds_read_b64_tr_b16 v[202:203], v124 offset:26624
	ds_read_b64_tr_b16 v[204:205], v124 offset:28672
	ds_read_b64_tr_b16 v[206:207], v125 offset:26624
	ds_read_b64_tr_b16 v[208:209], v125 offset:28672
	ds_read_b64_tr_b16 v[228:229], v126 offset:26624
	ds_read_b64_tr_b16 v[230:231], v126 offset:28672
	ds_read_b64_tr_b16 v[232:233], v127 offset:26624
	ds_read_b64_tr_b16 v[234:235], v127 offset:28672
	s_waitcnt lgkmcnt(14)
	v_mfma_f32_16x16x32_bf16 v[210:213], v[186:189], v[236:239], v[210:213]
	s_waitcnt lgkmcnt(12)
	v_mfma_f32_16x16x32_bf16 v[214:217], v[190:193], v[236:239], v[214:217]
	s_waitcnt lgkmcnt(10)
	v_mfma_f32_16x16x32_bf16 v[220:223], v[194:197], v[236:239], v[220:223]
	s_waitcnt lgkmcnt(8)
	v_mfma_f32_16x16x32_bf16 v[224:227], v[198:201], v[236:239], v[224:227]
	v_cvt_pk_bf16_f32 v240, v90, v91
	v_cvt_pk_bf16_f32 v241, v92, v93
	v_cvt_pk_bf16_f32 v242, v94, v95
	v_cvt_pk_bf16_f32 v243, v96, v97
	s_waitcnt lgkmcnt(7)
	ds_read_b64_tr_b16 v[186:187], v124 offset:30720
	ds_read_b64_tr_b16 v[188:189], v124 offset:32768
	ds_read_b64_tr_b16 v[190:191], v125 offset:30720
	ds_read_b64_tr_b16 v[192:193], v125 offset:32768
	ds_read_b64_tr_b16 v[194:195], v126 offset:30720
	ds_read_b64_tr_b16 v[196:197], v126 offset:32768
	ds_read_b64_tr_b16 v[198:199], v127 offset:30720
	ds_read_b64_tr_b16 v[200:201], v127 offset:32768
	s_waitcnt lgkmcnt(14)
	v_mfma_f32_16x16x32_bf16 v[210:213], v[202:205], v[240:243], v[210:213]
	s_waitcnt lgkmcnt(12)
	v_mfma_f32_16x16x32_bf16 v[214:217], v[206:209], v[240:243], v[214:217]
	s_waitcnt lgkmcnt(10)
	v_mfma_f32_16x16x32_bf16 v[220:223], v[228:231], v[240:243], v[220:223]
	s_waitcnt lgkmcnt(8)
	v_mfma_f32_16x16x32_bf16 v[224:227], v[232:235], v[240:243], v[224:227]
	v_cvt_pk_bf16_f32 v236, v98, v99
	v_cvt_pk_bf16_f32 v237, v100, v101
	v_cvt_pk_bf16_f32 v238, v102, v103
	v_cvt_pk_bf16_f32 v239, v104, v105
	s_waitcnt lgkmcnt(7)
	ds_read_b64_tr_b16 v[202:203], v124 offset:34816
	ds_read_b64_tr_b16 v[204:205], v124 offset:36864
	ds_read_b64_tr_b16 v[206:207], v125 offset:34816
	ds_read_b64_tr_b16 v[208:209], v125 offset:36864
	ds_read_b64_tr_b16 v[228:229], v126 offset:34816
	ds_read_b64_tr_b16 v[230:231], v126 offset:36864
	ds_read_b64_tr_b16 v[232:233], v127 offset:34816
	ds_read_b64_tr_b16 v[234:235], v127 offset:36864
	s_waitcnt lgkmcnt(14)
; __device__ __forceinline__ unsigned pk2(float lo, float hi) { return pg8::cvt_pk_bf16(lo, hi); }
; __device__ __forceinline__ void store_o(bf16* yrow, int g, float l, const f32x4 (&O)[4]) {
;     const float inv = 1.0f / xrow16_sum(l);
;     unsigned wx[4], wy[4];
; #pragma unroll
;     for (int db = 0; db < 4; ++db) { wx[db] = pk2(O[db][0] * inv, O[db][1] * inv); wy[db] = pk2(O[db][2] * inv, O[db][3] * inv); }
; #pragma unroll
;     for (int p = 0; p < 2; ++p) {
;         auto rx = __builtin_amdgcn_permlane16_swap(wx[2 * p], wx[2 * p + 1], false, false); wx[2 * p] = rx[0]; wx[2 * p + 1] = rx[1];
;         auto ry = __builtin_amdgcn_permlane16_swap(wy[2 * p], wy[2 * p + 1], false, false); wy[2 * p] = ry[0]; wy[2 * p + 1] = ry[1]; }
; #pragma unroll
;     for (int p = 0; p < 2; ++p) {
;         auto rx = __builtin_amdgcn_permlane32_swap(wx[p], wx[p + 2], false, false); wx[p] = rx[0]; wx[p + 2] = rx[1];
;         auto ry = __builtin_amdgcn_permlane32_swap(wy[p], wy[p + 2], false, false); wy[p] = ry[0]; wy[p + 2] = ry[1]; }
;     v4u lo = {wx[0], wy[0], wx[1], wy[1]}, hi = {wx[2], wy[2], wx[3], wy[3]};
;     *(v4u*)(yrow + 16 * g) = lo; *(v4u*)(yrow + 16 * g + 8) = hi;
; }
; template <bool MASK> __device__ __forceinline__ void a_scores(f32x4& S0, f32x4& S1, float basef, float c1, float slope2, int krow0, int kstart) {
; #pragma unroll
;     for (int r = 0; r < 4; ++r) {
;         const float d0 = fabsf(basef - (float)r), d1 = fabsf(basef - (float)(16 + r));
;         const float v0 = S0[r] - slope2 * d0, v1 = S1[r] - slope2 * d1;
;         if (MASK) { const int p0 = kstart + krow0 + r, p1 = p0 + 16;
;             S0[r] = (d0 <= 128.f && p0 >= 0 && p0 < SEQ) ? v0 : -INFINITY; S1[r] = (d1 <= 128.f && p1 >= 0 && p1 < SEQ) ? v1 : -INFINITY; }
;         else { S0[r] = v0; S1[r] = v1; }
;     }
; }
	v_mfma_f32_16x16x32_bf16 v[210:213], v[186:189], v[236:239], v[210:213]
	s_waitcnt lgkmcnt(12)
	v_mfma_f32_16x16x32_bf16 v[214:217], v[190:193], v[236:239], v[214:217]
	s_waitcnt lgkmcnt(10)
	v_mfma_f32_16x16x32_bf16 v[220:223], v[194:197], v[236:239], v[220:223]
	s_waitcnt lgkmcnt(8)
	v_mfma_f32_16x16x32_bf16 v[224:227], v[198:201], v[236:239], v[224:227]
	v_cvt_pk_bf16_f32 v240, v106, v107
	v_cvt_pk_bf16_f32 v241, v108, v109
	v_cvt_pk_bf16_f32 v242, v110, v111
	v_cvt_pk_bf16_f32 v243, v112, v113
	s_waitcnt lgkmcnt(7)
	ds_read_b64_tr_b16 v[186:187], v124 offset:38912
	ds_read_b64_tr_b16 v[188:189], v124 offset:40960
	ds_read_b64_tr_b16 v[190:191], v125 offset:38912
	ds_read_b64_tr_b16 v[192:193], v125 offset:40960
	ds_read_b64_tr_b16 v[194:195], v126 offset:38912
	ds_read_b64_tr_b16 v[196:197], v126 offset:40960
	ds_read_b64_tr_b16 v[198:199], v127 offset:38912
	ds_read_b64_tr_b16 v[200:201], v127 offset:40960
	s_waitcnt lgkmcnt(14)
	v_mfma_f32_16x16x32_bf16 v[210:213], v[202:205], v[240:243], v[210:213]
	s_waitcnt lgkmcnt(12)
	v_mfma_f32_16x16x32_bf16 v[214:217], v[206:209], v[240:243], v[214:217]
	s_waitcnt lgkmcnt(10)
	v_mfma_f32_16x16x32_bf16 v[220:223], v[228:231], v[240:243], v[220:223]
	s_waitcnt lgkmcnt(8)
	v_mfma_f32_16x16x32_bf16 v[224:227], v[232:235], v[240:243], v[224:227]
	v_cvt_pk_bf16_f32 v236, v114, v115
	v_cvt_pk_bf16_f32 v237, v116, v117
	v_mov_b32_e32 v238, 0
	v_mov_b32_e32 v239, 0
	s_nop 1
	s_waitcnt lgkmcnt(6)
	v_mfma_f32_16x16x32_bf16 v[210:213], v[186:189], v[236:239], v[210:213]
	s_waitcnt lgkmcnt(4)
	v_mfma_f32_16x16x32_bf16 v[214:217], v[190:193], v[236:239], v[214:217]
	s_waitcnt lgkmcnt(2)
	v_mfma_f32_16x16x32_bf16 v[220:223], v[194:197], v[236:239], v[220:223]
	s_waitcnt lgkmcnt(0)
	v_mfma_f32_16x16x32_bf16 v[224:227], v[198:201], v[236:239], v[224:227]
	v_mov_b32_e32 v219, v185
	s_nop 1
	v_permlane16_swap_b32_e32 v185, v219
	v_add_f32_e32 v185, v185, v219
	v_mov_b32_e32 v219, v185
	s_nop 1
	v_permlane32_swap_b32_e32 v185, v219
	v_add_f32_e32 v185, v185, v219
	v_div_scale_f32 v236, s[78:79], v185, v185, 1.0
	v_div_scale_f32 v237, vcc, 1.0, v185, 1.0
	v_rcp_f32_e32 v238, v236
	s_nop 0
	v_fma_f32 v239, -v236, v238, 1.0
	v_fmac_f32_e32 v238, v239, v238
	v_mul_f32_e32 v240, v237, v238
	v_fma_f32 v241, -v236, v240, v237
	v_fmac_f32_e32 v240, v241, v238
	v_fma_f32 v237, -v236, v240, v237
	v_div_fmas_f32 v237, v237, v238, v240
	v_div_fixup_f32 v244, v237, v185, 1.0
	v_mul_f32_e32 v240, v210, v244
	v_mul_f32_e32 v241, v211, v244
	v_mul_f32_e32 v242, v212, v244
	v_mul_f32_e32 v243, v213, v244
	v_cvt_pk_bf16_f32 v186, v240, v241
	v_cvt_pk_bf16_f32 v187, v242, v243
	v_mul_f32_e32 v240, v214, v244
	v_mul_f32_e32 v241, v215, v244
	v_mul_f32_e32 v242, v216, v244
	v_mul_f32_e32 v243, v217, v244
	v_cvt_pk_bf16_f32 v188, v240, v241
	v_cvt_pk_bf16_f32 v189, v242, v243
	v_mul_f32_e32 v240, v220, v244
	v_mul_f32_e32 v241, v221, v244
	v_mul_f32_e32 v242, v222, v244
	v_mul_f32_e32 v243, v223, v244
	v_cvt_pk_bf16_f32 v190, v240, v241
	v_cvt_pk_bf16_f32 v191, v242, v243
	v_mul_f32_e32 v240, v224, v244
	v_mul_f32_e32 v241, v225, v244
	v_mul_f32_e32 v242, v226, v244
	v_mul_f32_e32 v243, v227, v244
	v_cvt_pk_bf16_f32 v192, v240, v241
	v_cvt_pk_bf16_f32 v193, v242, v243
	s_nop 1
	v_permlane16_swap_b32_e32 v186, v188
	v_permlane16_swap_b32_e32 v187, v189
	v_permlane16_swap_b32_e32 v190, v192
	v_permlane16_swap_b32_e32 v191, v193
	s_nop 0
	v_permlane32_swap_b32_e32 v186, v190
	v_permlane32_swap_b32_e32 v187, v191
	v_permlane32_swap_b32_e32 v188, v192
	v_permlane32_swap_b32_e32 v189, v193
	v_add_u32_e32 v219, 0x1000, v128
	global_store_dwordx4 v219, v[186:189], s[82:83] offset:2048 sc1
	global_store_dwordx4 v219, v[190:193], s[82:83] offset:2064 sc1
	s_nop 1
	s_branch .LBB0_240

; __device__ __forceinline__ void attn_b_unit(LAS unsigned char* lds, const bf16* Z, bf16* Y, int unit) {
;     const int tid = threadIdx.x, lane = tid & 63, wid = tid >> 6, lq = lane & 15, g = lane >> 4;
;     const int rp = unit & 63, h = (unit >> 6) & 7, b = unit >> 9;
;     const size_t tok0 = (size_t)b * SEQ;
;     const int R0 = clampi(2 * rp - 4, 0, 120);
;     LAS unsigned char* Kl = lds + B_KOFF; LAS unsigned char* Vl = lds + B_VOFF; LAS float* T = (LAS float*)(lds + B_TOFF);
;     const int rq = 2 * rp + (wid >> 2), cb = wid & 3, c = 16 * cb + lq;
;     const int r0q = clampi(rq - 4, 0, 120), kc0 = clampi(16 * cb - 8, 0, 32), cs = clampi(c - 8, 0, 48);
;     const size_t qtok = tok0 + (size_t)rq * 64 + c;
;     const unsigned char* qp = (const unsigned char*)Z + tmo((int)qtok, Z_QB / 64 + h, ZLD / 64) + 16 * g;
;     const bf16x8 qf0 = *(const bf16x8*)qp, qf1 = *(const bf16x8*)(qp + 64);
;     float m0 = -1e30f, l0 = 0.f, m1 = -1e30f, l1 = 0.f;
;     f32x4 O0[4], O1[4];
; #pragma unroll
;     for (int d = 0; d < 4; ++d) { O0[d] = (f32x4){0.f, 0.f, 0.f, 0.f}; O1[d] = (f32x4){0.f, 0.f, 0.f, 0.f}; }
;     const int kcl = kc0 + 4 * g;
;     const int tb = 16 + (kcl - c + 15);
;     const int Rb = (r0q - R0) * 64 + kc0;
;     const LAS unsigned char* kp0 = Kl + swz(Rb + lq, g); const LAS unsigned char* kp1 = Kl + swz(Rb + lq, 4 + g);
;     const LAS unsigned char* vp[4];
;     { const int i = lane & 15, rq4 = i >> 2, p = i & 3;
; #pragma unroll
;       for (int db = 0; db < 4; ++db) vp[db] = Vl + swz(Rb + 4 * g + rq4, 2 * db + (p >> 1)) + 8 * (p & 1); }
;     const LAS float* T0 = T + tb + (r0q - rq + 7) * 32;
;     const LAS float* tpa[4]; const LAS float* tpb[4];
; #pragma unroll
;     for (int r = 0; r < 4; ++r) { const int kca = kcl + r, kcb = kca + 16;
;         tpa[r] = (kca >= cs && kca <= cs + 15) ? T0 + r : T + B_TREAL; tpb[r] = (kcb >= cs && kcb <= cs + 15) ? T0 + 16 + r : T + B_TREAL; }
; #pragma unroll
;     for (int st = 0; st < 4; ++st) {
;         const int offA = st * 8192, offB = offA + 4 * 8192;
;         f32x4 SA0, SA1, SB0, SB1;
;         qk_at(kp0, kp1, offA, qf0, qf1, SA0, SA1);
;         qk_at(kp0, kp1, offB, qf0, qf1, SB0, SB1);
; #pragma unroll
;         for (int r = 0; r < 4; ++r) {
;             SA0[r] += tpa[r][st * 32]; SA1[r] += tpb[r][st * 32]; SB0[r] += tpa[r][st * 32 + 128]; SB1[r] += tpb[r][st * 32 + 128];
;         }
.LBB0_280:
	v_readlane_b32 s26, v246, 7
	s_nop 3
	s_lshr_b32 s26, s26, 2
	s_and_b32 s51, s58, 0x7e
	s_add_i32 s50, s51, s26
	s_sub_i32 s73, s50, 4
	s_max_i32 s73, s73, 0
	s_min_i32 s73, s73, 0x78
	s_sub_i32 s74, s73, s50
	s_lshl_b32 s74, s74, 7
	s_sub_i32 s75, s73, s84
	s_mul_i32 s76, s75, 57
	s_lshr_b32 s76, s76, 9
	s_mul_i32 s76, s76, 9
	s_sub_i32 s75, s75, s76
	s_lshl_b32 s76, s75, 13
	s_add_i32 s77, s76, 0x2000
	s_cmp_eq_u32 s77, 0x12000
	s_cselect_b32 s77, 0, s77
	s_add_i32 s78, s77, 0x2000
	s_cmp_eq_u32 s78, 0x12000
	s_cselect_b32 s78, 0, s78
	s_add_i32 s79, s78, 0x2000
	s_cmp_eq_u32 s79, 0x12000
	s_cselect_b32 s79, 0, s79
	s_add_i32 s80, s79, 0x2000
	s_cmp_eq_u32 s80, 0x12000
	s_cselect_b32 s80, 0, s80
	s_add_i32 s81, s80, 0x2000
	s_cmp_eq_u32 s81, 0x12000
	s_cselect_b32 s81, 0, s81
	s_add_i32 s82, s81, 0x2000
	s_cmp_eq_u32 s82, 0x12000
	s_cselect_b32 s82, 0, s82
	s_add_i32 s83, s82, 0x2000
	s_cmp_eq_u32 s83, 0x12000
	s_cselect_b32 s83, 0, s83
	v_add_u32_e32 v61, s51, v115
	s_and_b32 s26, s59, 0xffffe000
	v_lshlrev_b32_e32 v58, 6, v61
	v_add_u32_e32 v60, s26, v58
	s_bfe_u32 s50, s72, 0x30006
	v_ashrrev_i32_e32 v60, 8, v60
	v_or_b32_e32 v58, v58, v116
	v_lshlrev_b32_e32 v58, 7, v58
	v_and_b32_e32 v58, 0x7f80, v58
	v_add_u32_e32 v101, v117, v113
	v_add_u32_e32 v216, v117, v119
	v_bitop3_b32 v100, v101, v114, 7 bitop3:0x6c
	v_lshlrev_b32_e32 v217, 7, v101
	v_lshlrev_b32_e32 v100, 4, v100
	v_add_u32_e32 v61, s74, v121
	v_add3_u32 v86, 0, v100, v217
	v_bitop3_b32 v100, v101, v118, 7 bitop3:0x6c
	v_lshlrev_b32_e32 v100, 4, v100
	v_add3_u32 v87, 0, v100, v217
	v_add_u32_e32 v100, 0x3fc, v61
	v_add_u32_e32 v101, 0x43c, v61
	v_cndmask_b32_e64 v92, v100, v101, s[6:7]
	v_add_u32_e32 v100, 0x400, v61
	v_add_u32_e32 v101, 0x440, v61
	v_cndmask_b32_e64 v93, v100, v101, s[10:11]
	v_add_u32_e32 v100, 0x404, v61
	v_add_u32_e32 v101, 0x444, v61
	v_cndmask_b32_e64 v94, v100, v101, s[14:15]
	v_add_u32_e32 v100, 0x408, v61
	v_add_u32_e32 v101, 0x448, v61
	v_cndmask_b32_e64 v95, v100, v101, s[18:19]
	v_lshl_add_u32 v217, v216, 7, v120
	v_bitop3_b32 v100, v216, v134, 7 bitop3:0x6c
	v_lshl_add_u32 v88, v100, 4, v217
	v_bitop3_b32 v100, v216, v135, 7 bitop3:0x6c
	v_lshl_add_u32 v89, v100, 4, v217
	v_bitop3_b32 v100, v216, v136, 7 bitop3:0x6c
	v_lshl_add_u32 v90, v100, 4, v217
	v_bitop3_b32 v100, v216, v137, 7 bitop3:0x6c
	v_lshl_add_u32 v91, v100, 4, v217
	s_lshl_b32 s26, s50, 15
	v_ashrrev_i32_e32 v61, 31, v60
	v_lshlrev_b64 v[60:61], 19, v[60:61]
	v_lshl_add_u64 v[60:61], s[40:41], 0, v[60:61]
	v_lshl_add_u64 v[60:61], v[60:61], 0, s[26:27]
	v_lshl_add_u64 v[60:61], v[60:61], 0, v[58:59]
	v_lshlrev_b32_e32 v58, 1, v104
	v_lshl_add_u64 v[60:61], v[60:61], 0, v[58:59]
	v_lshl_add_u64 v[60:61], v[60:61], 0, s[28:29]
	s_lshl_b32 s58, s55, 1
	s_lshl_b32 s59, s55, 4
	s_mov_b32 s72, s55
	ds_read_b32 v156, v92 offset:0
	ds_read_b32 v157, v93 offset:0
	ds_read_b32 v158, v94 offset:0
	ds_read_b32 v159, v95 offset:0
	v_add_u32_e32 v100, s76, v86
	v_add_u32_e32 v101, s76, v87
	ds_read_b128 v[204:207], v100
	ds_read_b128 v[208:211], v100 offset:2048
	ds_read_b128 v[212:215], v101
	ds_read_b128 v[220:223], v101 offset:2048
	s_waitcnt lgkmcnt(7)
	ds_read_b32 v160, v92 offset:128
	ds_read_b32 v161, v93 offset:128
	ds_read_b32 v162, v94 offset:128
	ds_read_b32 v163, v95 offset:128
	v_add_u32_e32 v100, s77, v86
	v_add_u32_e32 v101, s77, v87
	ds_read_b128 v[224:227], v100
	ds_read_b128 v[228:231], v100 offset:2048
	ds_read_b128 v[232:235], v101
	ds_read_b128 v[236:239], v101 offset:2048
	s_waitcnt vmcnt(4)
	s_waitcnt lgkmcnt(11)
	v_mfma_f32_16x16x32_bf16 v[188:191], v[204:207], v[82:85], v[156:159]
	s_waitcnt lgkmcnt(10)
	v_mfma_f32_16x16x32_bf16 v[192:195], v[208:211], v[82:85], v[156:159]
	s_waitcnt lgkmcnt(9)
	v_mfma_f32_16x16x32_bf16 v[188:191], v[212:215], v[78:81], v[188:191]
	s_waitcnt lgkmcnt(8)
	v_mfma_f32_16x16x32_bf16 v[192:195], v[220:223], v[78:81], v[192:195]
	s_waitcnt lgkmcnt(7)
	ds_read_b32 v164, v92 offset:256
	ds_read_b32 v165, v93 offset:256
	ds_read_b32 v166, v94 offset:256
	ds_read_b32 v167, v95 offset:256
	v_add_u32_e32 v100, s78, v86
	v_add_u32_e32 v101, s78, v87
	ds_read_b128 v[240:243], v100
	ds_read_b128 v[144:147], v100 offset:2048
	ds_read_b128 v[148:151], v101
	ds_read_b128 v[152:155], v101 offset:2048
	s_waitcnt lgkmcnt(11)
	v_mfma_f32_16x16x32_bf16 v[196:199], v[224:227], v[82:85], v[160:163]
	s_waitcnt lgkmcnt(10)
	v_mfma_f32_16x16x32_bf16 v[200:203], v[228:231], v[82:85], v[160:163]
	s_waitcnt lgkmcnt(9)
	v_mfma_f32_16x16x32_bf16 v[196:199], v[232:235], v[78:81], v[196:199]
	s_waitcnt lgkmcnt(8)
	v_mfma_f32_16x16x32_bf16 v[200:203], v[236:239], v[78:81], v[200:203]
	s_waitcnt lgkmcnt(7)
	ds_read_b32 v168, v92 offset:384
	ds_read_b32 v169, v93 offset:384
	ds_read_b32 v170, v94 offset:384
	ds_read_b32 v171, v95 offset:384
	v_add_u32_e32 v100, s79, v86
	v_add_u32_e32 v101, s79, v87
	ds_read_b128 v[204:207], v100
	ds_read_b128 v[208:211], v100 offset:2048
	ds_read_b128 v[212:215], v101
	ds_read_b128 v[220:223], v101 offset:2048
	v_cndmask_b32_e64 v156, v188, v192, s[6:7]
	v_cndmask_b32_e64 v157, v189, v193, s[10:11]
	v_cndmask_b32_e64 v158, v190, v194, s[14:15]
	v_cndmask_b32_e64 v159, v191, v195, s[18:19]
	s_waitcnt lgkmcnt(11)
	v_mfma_f32_16x16x32_bf16 v[188:191], v[240:243], v[82:85], v[164:167]
	s_waitcnt lgkmcnt(10)
	v_mfma_f32_16x16x32_bf16 v[192:195], v[144:147], v[82:85], v[164:167]
	s_waitcnt lgkmcnt(9)
	v_mfma_f32_16x16x32_bf16 v[188:191], v[148:151], v[78:81], v[188:191]
	s_waitcnt lgkmcnt(8)
	v_mfma_f32_16x16x32_bf16 v[192:195], v[152:155], v[78:81], v[192:195]
	s_waitcnt lgkmcnt(7)
; #define LAS __attribute__((address_space(3)))
; __device__ __forceinline__ unsigned pk2(float lo, float hi) { return pg8::cvt_pk_bf16(lo, hi); }
; __device__ __forceinline__ s16x4 vtr(const LAS unsigned char* p) { return __builtin_bit_cast(s16x4, __builtin_amdgcn_ds_read_tr16_b64_v4i16((LAS s16x4*)p)); }
; #define MFMA16(a, b, c) __builtin_amdgcn_mfma_f32_16x16x32_bf16((a), (b), (c), 0, 0, 0)
; __device__ __forceinline__ void pv_at(const LAS unsigned char* const (&vp)[4], int off, const f32x4& P0, const f32x4& P1, f32x4 (&O)[4]) {
;     v4u pw; pw.x = pk2(P0[0], P0[1]); pw.y = pk2(P0[2], P0[3]); pw.z = pk2(P1[0], P1[1]); pw.w = pk2(P1[2], P1[3]);
;     const bf16x8 pb = __builtin_bit_cast(bf16x8, pw);
; #pragma unroll
;     for (int db = 0; db < 4; ++db) {
;         const s16x4 lo = vtr(vp[db] + off), hi = vtr(vp[db] + off + 2048);
;         const bf16x8 vt = (bf16x8){lo[0], lo[1], lo[2], lo[3], hi[0], hi[1], hi[2], hi[3]};
;         O[db] = MFMA16(vt, pb, O[db]);
;     }
; }
; __device__ __forceinline__ void attn_b_unit(LAS unsigned char* lds, const bf16* Z, bf16* Y, int unit) {
;     ...
;     for (int st = 0; st < 4; ++st) {
;         const int offA = st * 8192, offB = offA + 4 * 8192;
;         f32x4 SA0, SA1, SB0, SB1;
;         qk_at(kp0, kp1, offA, qf0, qf1, SA0, SA1);
;         qk_at(kp0, kp1, offB, qf0, qf1, SB0, SB1);
; #pragma unroll
;         for (int r = 0; r < 4; ++r) {
;             SA0[r] += tpa[r][st * 32]; SA1[r] += tpb[r][st * 32]; SB0[r] += tpa[r][st * 32 + 128]; SB1[r] += tpb[r][st * 32 + 128];
;         }
	ds_read_b32 v172, v92 offset:512
	ds_read_b32 v173, v93 offset:512
	ds_read_b32 v174, v94 offset:512
	ds_read_b32 v175, v95 offset:512
	v_add_u32_e32 v100, s80, v86
	v_add_u32_e32 v101, s80, v87
	ds_read_b128 v[224:227], v100
	ds_read_b128 v[228:231], v100 offset:2048
	ds_read_b128 v[232:235], v101
	ds_read_b128 v[236:239], v101 offset:2048
	v_cndmask_b32_e64 v160, v196, v200, s[6:7]
	v_cndmask_b32_e64 v161, v197, v201, s[10:11]
	v_cndmask_b32_e64 v162, v198, v202, s[14:15]
	v_cndmask_b32_e64 v163, v199, v203, s[18:19]
	s_waitcnt lgkmcnt(11)
	v_mfma_f32_16x16x32_bf16 v[196:199], v[204:207], v[82:85], v[168:171]
	s_waitcnt lgkmcnt(10)
	v_mfma_f32_16x16x32_bf16 v[200:203], v[208:211], v[82:85], v[168:171]
	s_waitcnt lgkmcnt(9)
	v_mfma_f32_16x16x32_bf16 v[196:199], v[212:215], v[78:81], v[196:199]
	s_waitcnt lgkmcnt(8)
	v_mfma_f32_16x16x32_bf16 v[200:203], v[220:223], v[78:81], v[200:203]
	s_waitcnt lgkmcnt(7)
	ds_read_b32 v176, v92 offset:640
	ds_read_b32 v177, v93 offset:640
	ds_read_b32 v178, v94 offset:640
	ds_read_b32 v179, v95 offset:640
	v_add_u32_e32 v100, s81, v86
	v_add_u32_e32 v101, s81, v87
	ds_read_b128 v[240:243], v100
	ds_read_b128 v[144:147], v100 offset:2048
	ds_read_b128 v[148:151], v101
	ds_read_b128 v[152:155], v101 offset:2048
	v_cndmask_b32_e64 v164, v188, v192, s[6:7]
	v_cndmask_b32_e64 v165, v189, v193, s[10:11]
	v_cndmask_b32_e64 v166, v190, v194, s[14:15]
	v_cndmask_b32_e64 v167, v191, v195, s[18:19]
	s_waitcnt lgkmcnt(11)
	v_mfma_f32_16x16x32_bf16 v[188:191], v[224:227], v[82:85], v[172:175]
	s_waitcnt lgkmcnt(10)
	v_mfma_f32_16x16x32_bf16 v[192:195], v[228:231], v[82:85], v[172:175]
	s_waitcnt lgkmcnt(9)
	v_mfma_f32_16x16x32_bf16 v[188:191], v[232:235], v[78:81], v[188:191]
	s_waitcnt lgkmcnt(8)
	v_mfma_f32_16x16x32_bf16 v[192:195], v[236:239], v[78:81], v[192:195]
	s_waitcnt lgkmcnt(7)
	ds_read_b32 v180, v92 offset:768
	ds_read_b32 v181, v93 offset:768
	ds_read_b32 v182, v94 offset:768
	ds_read_b32 v183, v95 offset:768
	v_add_u32_e32 v100, s82, v86
	v_add_u32_e32 v101, s82, v87
	ds_read_b128 v[204:207], v100
	ds_read_b128 v[208:211], v100 offset:2048
	ds_read_b128 v[212:215], v101
	ds_read_b128 v[220:223], v101 offset:2048
	v_cndmask_b32_e64 v168, v196, v200, s[6:7]
	v_cndmask_b32_e64 v169, v197, v201, s[10:11]
	v_cndmask_b32_e64 v170, v198, v202, s[14:15]
	v_cndmask_b32_e64 v171, v199, v203, s[18:19]
	s_waitcnt lgkmcnt(11)
	v_mfma_f32_16x16x32_bf16 v[196:199], v[240:243], v[82:85], v[176:179]
	s_waitcnt lgkmcnt(10)
	v_mfma_f32_16x16x32_bf16 v[200:203], v[144:147], v[82:85], v[176:179]
	s_waitcnt lgkmcnt(9)
	v_mfma_f32_16x16x32_bf16 v[196:199], v[148:151], v[78:81], v[196:199]
	s_waitcnt lgkmcnt(8)
	v_mfma_f32_16x16x32_bf16 v[200:203], v[152:155], v[78:81], v[200:203]
	s_waitcnt lgkmcnt(7)
	ds_read_b32 v184, v92 offset:896
	ds_read_b32 v185, v93 offset:896
	ds_read_b32 v186, v94 offset:896
	ds_read_b32 v187, v95 offset:896
	v_add_u32_e32 v100, s83, v86
	v_add_u32_e32 v101, s83, v87
	ds_read_b128 v[224:227], v100
	ds_read_b128 v[228:231], v100 offset:2048
	ds_read_b128 v[232:235], v101
	ds_read_b128 v[236:239], v101 offset:2048
	v_cndmask_b32_e64 v172, v188, v192, s[6:7]
	v_cndmask_b32_e64 v173, v189, v193, s[10:11]
	v_cndmask_b32_e64 v174, v190, v194, s[14:15]
	v_cndmask_b32_e64 v175, v191, v195, s[18:19]
	s_waitcnt lgkmcnt(11)
	v_mfma_f32_16x16x32_bf16 v[188:191], v[204:207], v[82:85], v[180:183]
	s_waitcnt lgkmcnt(10)
	v_mfma_f32_16x16x32_bf16 v[192:195], v[208:211], v[82:85], v[180:183]
	s_waitcnt lgkmcnt(9)
	v_mfma_f32_16x16x32_bf16 v[188:191], v[212:215], v[78:81], v[188:191]
	s_waitcnt lgkmcnt(8)
	v_mfma_f32_16x16x32_bf16 v[192:195], v[220:223], v[78:81], v[192:195]
	v_cndmask_b32_e64 v176, v196, v200, s[6:7]
	v_cndmask_b32_e64 v177, v197, v201, s[10:11]
	v_cndmask_b32_e64 v178, v198, v202, s[14:15]
	v_cndmask_b32_e64 v179, v199, v203, s[18:19]
	s_waitcnt lgkmcnt(3)
	v_mfma_f32_16x16x32_bf16 v[196:199], v[224:227], v[82:85], v[184:187]
	s_waitcnt lgkmcnt(2)
	v_mfma_f32_16x16x32_bf16 v[200:203], v[228:231], v[82:85], v[184:187]
	s_waitcnt lgkmcnt(1)
	v_mfma_f32_16x16x32_bf16 v[196:199], v[232:235], v[78:81], v[196:199]
	s_waitcnt lgkmcnt(0)
	v_mfma_f32_16x16x32_bf16 v[200:203], v[236:239], v[78:81], v[200:203]
	v_cndmask_b32_e64 v180, v188, v192, s[6:7]
	v_cndmask_b32_e64 v181, v189, v193, s[10:11]
	v_cndmask_b32_e64 v182, v190, v194, s[14:15]
	v_cndmask_b32_e64 v183, v191, v195, s[18:19]
	v_add_u32_e32 v219, s76, v88
	v_add_u32_e32 v86, s76, v89
	v_add_u32_e32 v87, s76, v90
	v_add_u32_e32 v92, s76, v91
	ds_read_b64_tr_b16 v[212:213], v219
	ds_read_b64_tr_b16 v[214:215], v219 offset:2048
	ds_read_b64_tr_b16 v[220:221], v86
	ds_read_b64_tr_b16 v[222:223], v86 offset:2048
	ds_read_b64_tr_b16 v[224:225], v87
	ds_read_b64_tr_b16 v[226:227], v87 offset:2048
	ds_read_b64_tr_b16 v[228:229], v92
	ds_read_b64_tr_b16 v[230:231], v92 offset:2048
	v_mov_b32_e32 v100, 0xffff
	v_mov_b32_e32 v101, 0xffff0000
	v_cndmask_b32_e64 v96, v100, 0, s[6:7]
	v_cndmask_b32_e64 v216, v101, 0, s[10:11]
	v_cndmask_b32_e64 v97, v100, 0, s[14:15]
	v_cndmask_b32_e64 v217, v101, 0, s[18:19]
	v_cndmask_b32_e64 v184, v196, v200, s[6:7]
	v_cndmask_b32_e64 v185, v197, v201, s[10:11]
	v_cndmask_b32_e64 v186, v198, v202, s[14:15]
	v_cndmask_b32_e64 v187, v199, v203, s[18:19]
	v_or_b32_e32 v96, v96, v216
	v_or_b32_e32 v97, v97, v217
	v_not_b32_e32 v98, v96
	v_not_b32_e32 v99, v97
	s_waitcnt lgkmcnt(7)
; #define LAS __attribute__((address_space(3)))
; __device__ __forceinline__ unsigned pk2(float lo, float hi) { return pg8::cvt_pk_bf16(lo, hi); }
; __device__ __forceinline__ s16x4 vtr(const LAS unsigned char* p) { return __builtin_bit_cast(s16x4, __builtin_amdgcn_ds_read_tr16_b64_v4i16((LAS s16x4*)p)); }
; #define MFMA16(a, b, c) __builtin_amdgcn_mfma_f32_16x16x32_bf16((a), (b), (c), 0, 0, 0)
; __device__ __forceinline__ void pv_at(const LAS unsigned char* const (&vp)[4], int off, const f32x4& P0, const f32x4& P1, f32x4 (&O)[4]) {
;     v4u pw; pw.x = pk2(P0[0], P0[1]); pw.y = pk2(P0[2], P0[3]); pw.z = pk2(P1[0], P1[1]); pw.w = pk2(P1[2], P1[3]);
;     const bf16x8 pb = __builtin_bit_cast(bf16x8, pw);
; #pragma unroll
;     for (int db = 0; db < 4; ++db) {
;         const s16x4 lo = vtr(vp[db] + off), hi = vtr(vp[db] + off + 2048);
;         const bf16x8 vt = (bf16x8){lo[0], lo[1], lo[2], lo[3], hi[0], hi[1], hi[2], hi[3]};
;         O[db] = MFMA16(vt, pb, O[db]);
;     }
; }
; __device__ __forceinline__ void softmax_step(f32x4& s0, f32x4& s1, float& m, float& l, f32x4 (&O)[4]) {
;     float t = fmaxf(fmaxf(fmaxf(s0[0], s0[1]), fmaxf(s0[2], s0[3])), fmaxf(fmaxf(s1[0], s1[1]), fmaxf(s1[2], s1[3])));
;     t = xrow16_max(t);
;     const float mn = fmaxf(m, t), alpha = __builtin_amdgcn_exp2f(m - mn);
;     m = mn;
; #pragma unroll
;     for (int k = 0; k < 4; ++k) { s0[k] = __builtin_amdgcn_exp2f(s0[k] - mn); s1[k] = __builtin_amdgcn_exp2f(s1[k] - mn); }
;     l = l * alpha + ((s0[0] + s0[1]) + (s0[2] + s0[3])) + ((s1[0] + s1[1]) + (s1[2] + s1[3]));
; #pragma unroll
;     for (int db = 0; db < 4; ++db) O[db] *= alpha;
; }
	v_add_u32_e32 v219, s77, v88
	v_add_u32_e32 v86, s77, v89
	v_add_u32_e32 v87, s77, v90
	v_add_u32_e32 v92, s77, v91
	ds_read_b64_tr_b16 v[232:233], v219
	ds_read_b64_tr_b16 v[234:235], v219 offset:2048
	ds_read_b64_tr_b16 v[236:237], v86
	ds_read_b64_tr_b16 v[238:239], v86 offset:2048
	ds_read_b64_tr_b16 v[240:241], v87
	ds_read_b64_tr_b16 v[242:243], v87 offset:2048
	ds_read_b64_tr_b16 v[144:145], v92
	ds_read_b64_tr_b16 v[146:147], v92 offset:2048
	v_max3_f32 v142, v156, v157, v158
	v_max3_f32 v143, v164, v165, v166
	v_max3_f32 v216, v172, v173, v174
	v_max3_f32 v217, v180, v181, v182
	v_max3_f32 v142, v142, v159, v160
	v_max3_f32 v143, v143, v167, v168
	v_max3_f32 v216, v216, v175, v176
	v_max3_f32 v217, v217, v183, v184
	v_max3_f32 v142, v142, v161, v162
	v_max3_f32 v143, v143, v169, v170
	v_max3_f32 v216, v216, v177, v178
	v_max3_f32 v217, v217, v185, v186
	v_max_f32_e32 v142, v142, v163
	v_max_f32_e32 v143, v143, v171
	v_max_f32_e32 v216, v216, v179
	v_max_f32_e32 v217, v217, v187
	v_max3_f32 v244, v142, v143, v216
	v_max_f32_e32 v244, v244, v217
	v_mov_b32_e32 v100, v244
	s_nop 1
	v_permlane16_swap_b32_e32 v244, v100
	v_max_f32_e32 v244, v244, v100
	v_mov_b32_e32 v100, v244
	s_nop 1
	v_permlane32_swap_b32_e32 v244, v100
	v_max3_f32 v244, v244, v100, s54
	v_pk_add_f32 v[156:157], v[156:157], v[244:245] op_sel_hi:[1,0] neg_lo:[0,1] neg_hi:[0,1]
	v_pk_add_f32 v[158:159], v[158:159], v[244:245] op_sel_hi:[1,0] neg_lo:[0,1] neg_hi:[0,1]
	v_pk_add_f32 v[160:161], v[160:161], v[244:245] op_sel_hi:[1,0] neg_lo:[0,1] neg_hi:[0,1]
	v_pk_add_f32 v[162:163], v[162:163], v[244:245] op_sel_hi:[1,0] neg_lo:[0,1] neg_hi:[0,1]
	v_pk_add_f32 v[164:165], v[164:165], v[244:245] op_sel_hi:[1,0] neg_lo:[0,1] neg_hi:[0,1]
	v_pk_add_f32 v[166:167], v[166:167], v[244:245] op_sel_hi:[1,0] neg_lo:[0,1] neg_hi:[0,1]
	v_pk_add_f32 v[168:169], v[168:169], v[244:245] op_sel_hi:[1,0] neg_lo:[0,1] neg_hi:[0,1]
	v_pk_add_f32 v[170:171], v[170:171], v[244:245] op_sel_hi:[1,0] neg_lo:[0,1] neg_hi:[0,1]
	v_pk_add_f32 v[172:173], v[172:173], v[244:245] op_sel_hi:[1,0] neg_lo:[0,1] neg_hi:[0,1]
	v_pk_add_f32 v[174:175], v[174:175], v[244:245] op_sel_hi:[1,0] neg_lo:[0,1] neg_hi:[0,1]
	v_pk_add_f32 v[176:177], v[176:177], v[244:245] op_sel_hi:[1,0] neg_lo:[0,1] neg_hi:[0,1]
	v_pk_add_f32 v[178:179], v[178:179], v[244:245] op_sel_hi:[1,0] neg_lo:[0,1] neg_hi:[0,1]
	v_pk_add_f32 v[180:181], v[180:181], v[244:245] op_sel_hi:[1,0] neg_lo:[0,1] neg_hi:[0,1]
	v_pk_add_f32 v[182:183], v[182:183], v[244:245] op_sel_hi:[1,0] neg_lo:[0,1] neg_hi:[0,1]
	v_pk_add_f32 v[184:185], v[184:185], v[244:245] op_sel_hi:[1,0] neg_lo:[0,1] neg_hi:[0,1]
	v_pk_add_f32 v[186:187], v[186:187], v[244:245] op_sel_hi:[1,0] neg_lo:[0,1] neg_hi:[0,1]
	v_exp_f32_e32 v156, v156
	v_exp_f32_e32 v157, v157
	v_exp_f32_e32 v158, v158
	v_exp_f32_e32 v159, v159
	v_exp_f32_e32 v160, v160
	v_exp_f32_e32 v161, v161
	v_exp_f32_e32 v162, v162
	v_exp_f32_e32 v163, v163
	v_exp_f32_e32 v164, v164
	v_exp_f32_e32 v165, v165
	v_exp_f32_e32 v166, v166
	v_exp_f32_e32 v167, v167
	v_exp_f32_e32 v168, v168
	v_exp_f32_e32 v169, v169
	v_exp_f32_e32 v170, v170
	v_exp_f32_e32 v171, v171
	v_exp_f32_e32 v172, v172
	v_exp_f32_e32 v173, v173
	v_exp_f32_e32 v174, v174
	v_exp_f32_e32 v175, v175
	v_exp_f32_e32 v176, v176
	v_exp_f32_e32 v177, v177
	v_exp_f32_e32 v178, v178
	v_exp_f32_e32 v179, v179
	v_exp_f32_e32 v180, v180
	v_exp_f32_e32 v181, v181
	v_exp_f32_e32 v182, v182
	v_exp_f32_e32 v183, v183
	v_exp_f32_e32 v184, v184
	v_exp_f32_e32 v185, v185
	v_exp_f32_e32 v186, v186
	v_exp_f32_e32 v187, v187
	v_pk_add_f32 v[148:149], v[156:157], v[158:159]
	v_pk_add_f32 v[150:151], v[164:165], v[166:167]
	v_pk_add_f32 v[152:153], v[172:173], v[174:175]
	v_pk_add_f32 v[154:155], v[180:181], v[182:183]
	v_pk_add_f32 v[148:149], v[148:149], v[160:161]
	v_pk_add_f32 v[150:151], v[150:151], v[168:169]
	v_pk_add_f32 v[152:153], v[152:153], v[176:177]
	v_pk_add_f32 v[154:155], v[154:155], v[184:185]
	v_pk_add_f32 v[148:149], v[148:149], v[162:163]
	v_pk_add_f32 v[150:151], v[150:151], v[170:171]
	v_pk_add_f32 v[152:153], v[152:153], v[178:179]
	v_pk_add_f32 v[154:155], v[154:155], v[186:187]
	v_pk_add_f32 v[148:149], v[148:149], v[150:151]
	v_pk_add_f32 v[152:153], v[152:153], v[154:155]
	v_pk_add_f32 v[148:149], v[148:149], v[152:153]
	v_add_f32_e32 v245, v148, v149
	v_cvt_pk_bf16_f32 v100, v156, v157
	v_cvt_pk_bf16_f32 v101, v158, v159
	v_and_b32_e32 v188, v100, v96
	v_and_b32_e32 v189, v101, v97
	v_and_b32_e32 v190, v100, v98
	v_and_b32_e32 v191, v101, v99
	s_nop 1
	s_waitcnt lgkmcnt(14)
	v_mfma_f32_16x16x32_bf16 v[196:199], v[212:215], v[188:191], 0
	s_waitcnt lgkmcnt(12)
	v_mfma_f32_16x16x32_bf16 v[200:203], v[220:223], v[188:191], 0
	s_waitcnt lgkmcnt(10)
	v_mfma_f32_16x16x32_bf16 v[204:207], v[224:227], v[188:191], 0
	s_waitcnt lgkmcnt(8)
	v_mfma_f32_16x16x32_bf16 v[208:211], v[228:231], v[188:191], 0
	v_cvt_pk_bf16_f32 v100, v160, v161
	v_cvt_pk_bf16_f32 v101, v162, v163
	v_and_b32_e32 v192, v100, v96
	v_and_b32_e32 v193, v101, v97
	v_and_b32_e32 v194, v100, v98
	v_and_b32_e32 v195, v101, v99
	s_waitcnt lgkmcnt(7)
	v_add_u32_e32 v219, s78, v88
	v_add_u32_e32 v86, s78, v89
	v_add_u32_e32 v87, s78, v90
	v_add_u32_e32 v92, s78, v91
	ds_read_b64_tr_b16 v[212:213], v219
	ds_read_b64_tr_b16 v[214:215], v219 offset:2048
	ds_read_b64_tr_b16 v[220:221], v86
	ds_read_b64_tr_b16 v[222:223], v86 offset:2048
	ds_read_b64_tr_b16 v[224:225], v87
	ds_read_b64_tr_b16 v[226:227], v87 offset:2048
	ds_read_b64_tr_b16 v[228:229], v92
	ds_read_b64_tr_b16 v[230:231], v92 offset:2048
	s_waitcnt lgkmcnt(14)
	v_mfma_f32_16x16x32_bf16 v[196:199], v[232:235], v[192:195], v[196:199]
	s_waitcnt lgkmcnt(12)
; #define LAS __attribute__((address_space(3)))
; __device__ __forceinline__ unsigned pk2(float lo, float hi) { return pg8::cvt_pk_bf16(lo, hi); }
; __device__ __forceinline__ s16x4 vtr(const LAS unsigned char* p) { return __builtin_bit_cast(s16x4, __builtin_amdgcn_ds_read_tr16_b64_v4i16((LAS s16x4*)p)); }
; #define MFMA16(a, b, c) __builtin_amdgcn_mfma_f32_16x16x32_bf16((a), (b), (c), 0, 0, 0)
; __device__ __forceinline__ void pv_at(const LAS unsigned char* const (&vp)[4], int off, const f32x4& P0, const f32x4& P1, f32x4 (&O)[4]) {
;     v4u pw; pw.x = pk2(P0[0], P0[1]); pw.y = pk2(P0[2], P0[3]); pw.z = pk2(P1[0], P1[1]); pw.w = pk2(P1[2], P1[3]);
;     const bf16x8 pb = __builtin_bit_cast(bf16x8, pw);
; #pragma unroll
;     for (int db = 0; db < 4; ++db) {
;         const s16x4 lo = vtr(vp[db] + off), hi = vtr(vp[db] + off + 2048);
;         const bf16x8 vt = (bf16x8){lo[0], lo[1], lo[2], lo[3], hi[0], hi[1], hi[2], hi[3]};
;         O[db] = MFMA16(vt, pb, O[db]);
;     }
; }
	v_mfma_f32_16x16x32_bf16 v[200:203], v[236:239], v[192:195], v[200:203]
	s_waitcnt lgkmcnt(10)
	v_mfma_f32_16x16x32_bf16 v[204:207], v[240:243], v[192:195], v[204:207]
	s_waitcnt lgkmcnt(8)
	v_mfma_f32_16x16x32_bf16 v[208:211], v[144:147], v[192:195], v[208:211]
	v_cvt_pk_bf16_f32 v100, v164, v165
	v_cvt_pk_bf16_f32 v101, v166, v167
	v_and_b32_e32 v188, v100, v96
	v_and_b32_e32 v189, v101, v97
	v_and_b32_e32 v190, v100, v98
	v_and_b32_e32 v191, v101, v99
	s_waitcnt lgkmcnt(7)
	v_add_u32_e32 v219, s79, v88
	v_add_u32_e32 v86, s79, v89
	v_add_u32_e32 v87, s79, v90
	v_add_u32_e32 v92, s79, v91
	ds_read_b64_tr_b16 v[232:233], v219
	ds_read_b64_tr_b16 v[234:235], v219 offset:2048
	ds_read_b64_tr_b16 v[236:237], v86
	ds_read_b64_tr_b16 v[238:239], v86 offset:2048
	ds_read_b64_tr_b16 v[240:241], v87
	ds_read_b64_tr_b16 v[242:243], v87 offset:2048
	ds_read_b64_tr_b16 v[144:145], v92
	ds_read_b64_tr_b16 v[146:147], v92 offset:2048
	s_waitcnt lgkmcnt(14)
	v_mfma_f32_16x16x32_bf16 v[196:199], v[212:215], v[188:191], v[196:199]
	s_waitcnt lgkmcnt(12)
	v_mfma_f32_16x16x32_bf16 v[200:203], v[220:223], v[188:191], v[200:203]
	s_waitcnt lgkmcnt(10)
	v_mfma_f32_16x16x32_bf16 v[204:207], v[224:227], v[188:191], v[204:207]
	s_waitcnt lgkmcnt(8)
	v_mfma_f32_16x16x32_bf16 v[208:211], v[228:231], v[188:191], v[208:211]
	v_cvt_pk_bf16_f32 v100, v168, v169
	v_cvt_pk_bf16_f32 v101, v170, v171
	v_and_b32_e32 v192, v100, v96
	v_and_b32_e32 v193, v101, v97
	v_and_b32_e32 v194, v100, v98
	v_and_b32_e32 v195, v101, v99
	s_waitcnt lgkmcnt(7)
	v_add_u32_e32 v219, s80, v88
	v_add_u32_e32 v86, s80, v89
	v_add_u32_e32 v87, s80, v90
	v_add_u32_e32 v92, s80, v91
	ds_read_b64_tr_b16 v[212:213], v219
	ds_read_b64_tr_b16 v[214:215], v219 offset:2048
	ds_read_b64_tr_b16 v[220:221], v86
	ds_read_b64_tr_b16 v[222:223], v86 offset:2048
	ds_read_b64_tr_b16 v[224:225], v87
	ds_read_b64_tr_b16 v[226:227], v87 offset:2048
	ds_read_b64_tr_b16 v[228:229], v92
	ds_read_b64_tr_b16 v[230:231], v92 offset:2048
	s_waitcnt lgkmcnt(14)
	v_mfma_f32_16x16x32_bf16 v[196:199], v[232:235], v[192:195], v[196:199]
	s_waitcnt lgkmcnt(12)
	v_mfma_f32_16x16x32_bf16 v[200:203], v[236:239], v[192:195], v[200:203]
	s_waitcnt lgkmcnt(10)
	v_mfma_f32_16x16x32_bf16 v[204:207], v[240:243], v[192:195], v[204:207]
	s_waitcnt lgkmcnt(8)
	v_mfma_f32_16x16x32_bf16 v[208:211], v[144:147], v[192:195], v[208:211]
	v_cvt_pk_bf16_f32 v100, v172, v173
	v_cvt_pk_bf16_f32 v101, v174, v175
	v_and_b32_e32 v188, v100, v96
	v_and_b32_e32 v189, v101, v97
	v_and_b32_e32 v190, v100, v98
	v_and_b32_e32 v191, v101, v99
	s_waitcnt lgkmcnt(7)
	v_add_u32_e32 v219, s81, v88
	v_add_u32_e32 v86, s81, v89
	v_add_u32_e32 v87, s81, v90
	v_add_u32_e32 v92, s81, v91
	ds_read_b64_tr_b16 v[232:233], v219
	ds_read_b64_tr_b16 v[234:235], v219 offset:2048
	ds_read_b64_tr_b16 v[236:237], v86
	ds_read_b64_tr_b16 v[238:239], v86 offset:2048
	ds_read_b64_tr_b16 v[240:241], v87
	ds_read_b64_tr_b16 v[242:243], v87 offset:2048
	ds_read_b64_tr_b16 v[144:145], v92
	ds_read_b64_tr_b16 v[146:147], v92 offset:2048
	s_waitcnt lgkmcnt(14)
	v_mfma_f32_16x16x32_bf16 v[196:199], v[212:215], v[188:191], v[196:199]
	s_waitcnt lgkmcnt(12)
	v_mfma_f32_16x16x32_bf16 v[200:203], v[220:223], v[188:191], v[200:203]
	s_waitcnt lgkmcnt(10)
	v_mfma_f32_16x16x32_bf16 v[204:207], v[224:227], v[188:191], v[204:207]
	s_waitcnt lgkmcnt(8)
	v_mfma_f32_16x16x32_bf16 v[208:211], v[228:231], v[188:191], v[208:211]
	v_cvt_pk_bf16_f32 v100, v176, v177
	v_cvt_pk_bf16_f32 v101, v178, v179
	v_and_b32_e32 v192, v100, v96
	v_and_b32_e32 v193, v101, v97
	v_and_b32_e32 v194, v100, v98
	v_and_b32_e32 v195, v101, v99
	s_waitcnt lgkmcnt(7)
	v_add_u32_e32 v219, s82, v88
	v_add_u32_e32 v86, s82, v89
	v_add_u32_e32 v87, s82, v90
	v_add_u32_e32 v92, s82, v91
	ds_read_b64_tr_b16 v[212:213], v219
	ds_read_b64_tr_b16 v[214:215], v219 offset:2048
	ds_read_b64_tr_b16 v[220:221], v86
	ds_read_b64_tr_b16 v[222:223], v86 offset:2048
	ds_read_b64_tr_b16 v[224:225], v87
	ds_read_b64_tr_b16 v[226:227], v87 offset:2048
	ds_read_b64_tr_b16 v[228:229], v92
	ds_read_b64_tr_b16 v[230:231], v92 offset:2048
	s_waitcnt lgkmcnt(14)
; #define LAS __attribute__((address_space(3)))
; __device__ __forceinline__ unsigned pk2(float lo, float hi) { return pg8::cvt_pk_bf16(lo, hi); }
; __device__ __forceinline__ s16x4 vtr(const LAS unsigned char* p) { return __builtin_bit_cast(s16x4, __builtin_amdgcn_ds_read_tr16_b64_v4i16((LAS s16x4*)p)); }
; #define MFMA16(a, b, c) __builtin_amdgcn_mfma_f32_16x16x32_bf16((a), (b), (c), 0, 0, 0)
; __device__ __forceinline__ void pv_at(const LAS unsigned char* const (&vp)[4], int off, const f32x4& P0, const f32x4& P1, f32x4 (&O)[4]) {
;     v4u pw; pw.x = pk2(P0[0], P0[1]); pw.y = pk2(P0[2], P0[3]); pw.z = pk2(P1[0], P1[1]); pw.w = pk2(P1[2], P1[3]);
;     const bf16x8 pb = __builtin_bit_cast(bf16x8, pw);
; #pragma unroll
;     for (int db = 0; db < 4; ++db) {
;         const s16x4 lo = vtr(vp[db] + off), hi = vtr(vp[db] + off + 2048);
;         const bf16x8 vt = (bf16x8){lo[0], lo[1], lo[2], lo[3], hi[0], hi[1], hi[2], hi[3]};
;         O[db] = MFMA16(vt, pb, O[db]);
;     }
; }
; __device__ __forceinline__ void store_o(bf16* yrow, int g, float l, const f32x4 (&O)[4]) {
;     const float inv = 1.0f / xrow16_sum(l);
;     unsigned wx[4], wy[4];
; #pragma unroll
;     for (int db = 0; db < 4; ++db) { wx[db] = pk2(O[db][0] * inv, O[db][1] * inv); wy[db] = pk2(O[db][2] * inv, O[db][3] * inv); }
; #pragma unroll
;     for (int p = 0; p < 2; ++p) {
;         auto rx = __builtin_amdgcn_permlane16_swap(wx[2 * p], wx[2 * p + 1], false, false); wx[2 * p] = rx[0]; wx[2 * p + 1] = rx[1];
;         auto ry = __builtin_amdgcn_permlane16_swap(wy[2 * p], wy[2 * p + 1], false, false); wy[2 * p] = ry[0]; wy[2 * p + 1] = ry[1]; }
; #pragma unroll
;     for (int p = 0; p < 2; ++p) {
;         auto rx = __builtin_amdgcn_permlane32_swap(wx[p], wx[p + 2], false, false); wx[p] = rx[0]; wx[p + 2] = rx[1];
;         auto ry = __builtin_amdgcn_permlane32_swap(wy[p], wy[p + 2], false, false); wy[p] = ry[0]; wy[p + 2] = ry[1]; }
;     v4u lo = {wx[0], wy[0], wx[1], wy[1]}, hi = {wx[2], wy[2], wx[3], wy[3]};
;     *(v4u*)(yrow + 16 * g) = lo; *(v4u*)(yrow + 16 * g + 8) = hi;
; }
	v_mfma_f32_16x16x32_bf16 v[196:199], v[232:235], v[192:195], v[196:199]
	s_waitcnt lgkmcnt(12)
	v_mfma_f32_16x16x32_bf16 v[200:203], v[236:239], v[192:195], v[200:203]
	s_waitcnt lgkmcnt(10)
	v_mfma_f32_16x16x32_bf16 v[204:207], v[240:243], v[192:195], v[204:207]
	s_waitcnt lgkmcnt(8)
	v_mfma_f32_16x16x32_bf16 v[208:211], v[144:147], v[192:195], v[208:211]
	v_cvt_pk_bf16_f32 v100, v180, v181
	v_cvt_pk_bf16_f32 v101, v182, v183
	v_and_b32_e32 v188, v100, v96
	v_and_b32_e32 v189, v101, v97
	v_and_b32_e32 v190, v100, v98
	v_and_b32_e32 v191, v101, v99
	s_waitcnt lgkmcnt(7)
	v_add_u32_e32 v219, s83, v88
	v_add_u32_e32 v86, s83, v89
	v_add_u32_e32 v87, s83, v90
	v_add_u32_e32 v92, s83, v91
	ds_read_b64_tr_b16 v[232:233], v219
	ds_read_b64_tr_b16 v[234:235], v219 offset:2048
	ds_read_b64_tr_b16 v[236:237], v86
	ds_read_b64_tr_b16 v[238:239], v86 offset:2048
	ds_read_b64_tr_b16 v[240:241], v87
	ds_read_b64_tr_b16 v[242:243], v87 offset:2048
	ds_read_b64_tr_b16 v[144:145], v92
	ds_read_b64_tr_b16 v[146:147], v92 offset:2048
	s_waitcnt lgkmcnt(14)
	v_mfma_f32_16x16x32_bf16 v[196:199], v[212:215], v[188:191], v[196:199]
	s_waitcnt lgkmcnt(12)
	v_mfma_f32_16x16x32_bf16 v[200:203], v[220:223], v[188:191], v[200:203]
	s_waitcnt lgkmcnt(10)
	v_mfma_f32_16x16x32_bf16 v[204:207], v[224:227], v[188:191], v[204:207]
	s_waitcnt lgkmcnt(8)
	v_mfma_f32_16x16x32_bf16 v[208:211], v[228:231], v[188:191], v[208:211]
	v_cvt_pk_bf16_f32 v100, v184, v185
	v_cvt_pk_bf16_f32 v101, v186, v187
	v_and_b32_e32 v192, v100, v96
	v_and_b32_e32 v193, v101, v97
	v_and_b32_e32 v194, v100, v98
	v_and_b32_e32 v195, v101, v99
	s_nop 1
	s_waitcnt lgkmcnt(6)
	v_mfma_f32_16x16x32_bf16 v[196:199], v[232:235], v[192:195], v[196:199]
	s_waitcnt lgkmcnt(4)
	v_mfma_f32_16x16x32_bf16 v[200:203], v[236:239], v[192:195], v[200:203]
	s_waitcnt lgkmcnt(2)
	v_mfma_f32_16x16x32_bf16 v[204:207], v[240:243], v[192:195], v[204:207]
	s_waitcnt lgkmcnt(0)
	v_mfma_f32_16x16x32_bf16 v[208:211], v[144:147], v[192:195], v[208:211]
	v_mov_b32_e32 v100, v245
	s_nop 1
	v_permlane16_swap_b32_e32 v245, v100
	v_add_f32_e32 v245, v245, v100
	v_mov_b32_e32 v100, v245
	s_nop 1
	v_permlane32_swap_b32_e32 v245, v100
	v_add_f32_e32 v245, v245, v100
	v_div_scale_f32 v142, s[50:51], v245, v245, 1.0
	v_div_scale_f32 v216, vcc, 1.0, v245, 1.0
	v_rcp_f32_e32 v143, v142
	s_nop 0
	v_fma_f32 v217, -v142, v143, 1.0
	v_fmac_f32_e32 v143, v217, v143
	v_mul_f32_e32 v148, v216, v143
	v_fma_f32 v149, -v142, v148, v216
	v_fmac_f32_e32 v148, v149, v143
	v_fma_f32 v216, -v142, v148, v216
	v_div_fmas_f32 v216, v216, v143, v148
	v_div_fixup_f32 v216, v216, v245, 1.0
	v_mul_f32_e32 v100, v196, v216
	v_mul_f32_e32 v101, v197, v216
	v_mul_f32_e32 v142, v198, v216
	v_mul_f32_e32 v143, v199, v216
	v_cvt_pk_bf16_f32 v78, v100, v101
	v_cvt_pk_bf16_f32 v79, v142, v143
	v_mul_f32_e32 v100, v200, v216
	v_mul_f32_e32 v101, v201, v216
	v_mul_f32_e32 v142, v202, v216
	v_mul_f32_e32 v143, v203, v216
	v_cvt_pk_bf16_f32 v80, v100, v101
	v_cvt_pk_bf16_f32 v81, v142, v143
	v_mul_f32_e32 v100, v204, v216
	v_mul_f32_e32 v101, v205, v216
	v_mul_f32_e32 v142, v206, v216
	v_mul_f32_e32 v143, v207, v216
	v_cvt_pk_bf16_f32 v82, v100, v101
	v_cvt_pk_bf16_f32 v83, v142, v143
	v_mul_f32_e32 v100, v208, v216
	v_mul_f32_e32 v101, v209, v216
	v_mul_f32_e32 v142, v210, v216
	v_mul_f32_e32 v143, v211, v216
	v_cvt_pk_bf16_f32 v84, v100, v101
	v_cvt_pk_bf16_f32 v85, v142, v143
	s_nop 1
	v_permlane16_swap_b32_e32 v78, v80
	v_permlane16_swap_b32_e32 v79, v81
	v_permlane16_swap_b32_e32 v82, v84
	v_permlane16_swap_b32_e32 v83, v85
	s_nop 0
	v_permlane32_swap_b32_e32 v78, v82
	v_permlane32_swap_b32_e32 v79, v83
	v_permlane32_swap_b32_e32 v80, v84
	v_permlane32_swap_b32_e32 v81, v85
	s_andn2_b64 vcc, exec, s[44:45]
	global_store_dwordx4 v[60:61], v[78:81], off sc1
	global_store_dwordx4 v[60:61], v[82:85], off offset:16 sc1
	s_barrier
	s_cbranch_vccz .LBB0_294

; __device__ __forceinline__ size_t tm_block(int pm, int ct, int nct) { return ((size_t)pm * nct + ct) * 32768; }
; #define UNPK0(q_) ((f32x4){bf_lo((q_).x), bf_hi((q_).x), bf_lo((q_).y), bf_hi((q_).y)})
; #define UNPK1(q_) ((f32x4){bf_lo((q_).z), bf_hi((q_).z), bf_lo((q_).w), bf_hi((q_).w)})
;     __device__ __forceinline__ void mid(f32x4 (&acc)[2][2][4][2], const Unit& u, int wr, int wc, int fr, int fq) const {
;         int pm = u.pm, cb = u.pn * 4 + wc;
;         asm volatile("" : "+v"(pm), "+v"(cb));
;         const PieceIn pa(scr, Z, tm_block(pm, ga_ct + cb, znct), wr, wc, fr, fq), pb(scr, Z, tm_block(pm, gb_ct + cb, znct), wr, wc, fr, fq);
;         const int col0 = cb * 64 + 8 * fq;
;         f32x4 ba[2][2], bb[2][2];
; #pragma unroll
;         for (int bj = 0; bj < 2; ++bj) { ba[bj][0] = *(const f32x4*)(bg + col0 + bj * 32); ba[bj][1] = *(const f32x4*)(bg + col0 + bj * 32 + 4); bb[bj][0] = *(const f32x4*)(bg + 1024 + col0 + bj * 32); bb[bj][1] = *(const f32x4*)(bg + 1024 + col0 + bj * 32 + 4); }
; #pragma unroll
;         for (int am = 0; am < 4; ++am) { const int ai = am >> 1;
;             u32x4 ra[4][2], rb[4][2];
; #pragma unroll
;             for (int m = 2 * (am & 1); m < 2 * (am & 1) + 2; ++m) { pa.fetch(ai, m, ra[m][0], ra[m][1]); pb.fetch(ai, m, rb[m][0], rb[m][1]); }
;             asm volatile("" ::: "memory");
; #pragma unroll
;             for (int m = 2 * (am & 1); m < 2 * (am & 1) + 2; ++m) {
;                 pa.stage(ra[m][0], ra[m][1]); const u32x4 ga0 = pa.get(0), ga1 = pa.get(1);
;                 asm volatile("" ::: "memory");
;                 pb.stage(rb[m][0], rb[m][1]); const u32x4 gb0 = pb.get(0), gb1 = pb.get(1);
;                 asm volatile("" ::: "memory");
; #pragma unroll
;                 for (int bj = 0; bj < 2; ++bj) { const u32x4 ga = bj ? ga1 : ga0, gb = bj ? gb1 : gb0;
;                     const f32x4 a0 = UNPK0(ga) + ba[bj][0], a1 = UNPK1(ga) + ba[bj][1], b0 = UNPK0(gb) + bb[bj][0], b1 = UNPK1(gb) + bb[bj][1];
; #pragma unroll
;                     for (int k = 0; k < 4; ++k) { acc[ai][bj][m][0][k] *= (1.0f + eneg(b0[k])) * __builtin_amdgcn_rcpf(1.0f + eneg(a0[k]));
;                                                   acc[ai][bj][m][1][k] *= (1.0f + eneg(b1[k])) * __builtin_amdgcn_rcpf(1.0f + eneg(a1[k])); } } }
;         }
.LBB0_385:
	s_ashr_i32 s27, s26, 31
	s_lshl_b64 s[0:1], s[26:27], 19
	s_add_u32 s19, s3, s0
	s_addc_u32 s21, s76, s1
	s_add_i32 s0, s44, 52
	s_mul_hi_i32 s1, s26, 0x44
	s_mulk_i32 s26, 0x44
	s_ashr_i32 s27, s0, 31
	s_add_u32 s0, s26, s0
	s_addc_u32 s1, s1, s27
	s_lshl_b64 s[0:1], s[0:1], 15
	v_lshl_add_u64 v[4:5], v[208:209], 0, s[0:1]
	global_load_dwordx4 v[228:231], v[4:5], off
	global_load_dwordx4 v[232:235], v[4:5], off offset:1024
	v_lshl_or_b32 v134, s44, 6, v219
	v_ashrrev_i32_e32 v135, 31, v134
	v_lshlrev_b64 v[134:135], 2, v[134:135]
	v_lshl_add_u64 v[136:137], s[16:17], 0, v[134:135]
	v_lshl_add_u64 v[134:135], s[42:43], 0, v[134:135]
	v_add_co_u32_e32 v134, vcc, s84, v134
	global_load_dwordx4 v[146:149], v[136:137], off
	s_nop 0
	v_addc_co_u32_e32 v135, vcc, 0, v135, vcc
	global_load_dwordx4 v[142:145], v[134:135], off offset:16
	global_load_dwordx4 v[138:141], v[136:137], off offset:128
	s_nop 0
	global_load_dwordx4 v[134:137], v[134:135], off offset:144
	s_nop 0
	global_load_dwordx4 v[236:239], v[4:5], off offset:2048
	global_load_dwordx4 v[240:243], v[4:5], off offset:3072
	v_add_co_u32_e32 v150, vcc, s84, v4
	v_add_u32_e32 v3, v224, v222
	s_nop 0
	v_addc_co_u32_e32 v151, vcc, 0, v5, vcc
	v_add_co_u32_e32 v152, vcc, s79, v4
	v_add_u32_e32 v227, v223, v220
	s_nop 0
	v_addc_co_u32_e32 v153, vcc, 0, v5, vcc
	v_add_co_u32_e32 v4, vcc, s86, v4
	s_ashr_i32 s45, s44, 31
	s_nop 0
	v_addc_co_u32_e32 v5, vcc, 0, v5, vcc
	global_load_dwordx4 v[190:193], v[150:151], off
	global_load_dwordx4 v[194:197], v[150:151], off offset:1024
	global_load_dwordx4 v[182:185], v[150:151], off offset:2048
	global_load_dwordx4 v[186:189], v[150:151], off offset:3072
	global_load_dwordx4 v[174:177], v[152:153], off offset:1024
	global_load_dwordx4 v[166:169], v[152:153], off offset:2048
	global_load_dwordx4 v[178:181], v[4:5], off offset:-4096
	global_load_dwordx4 v[170:173], v[152:153], off offset:3072
	global_load_dwordx4 v[158:161], v[4:5], off
	global_load_dwordx4 v[162:165], v[4:5], off offset:1024
	s_nop 0
	global_load_dwordx4 v[150:153], v[4:5], off offset:2048
	global_load_dwordx4 v[154:157], v[4:5], off offset:3072
	s_lshl_b64 s[0:1], s[44:45], 15
	s_add_u32 s0, s19, s0
	s_addc_u32 s1, s21, s1
	s_add_u32 s0, s0, s12
	s_addc_u32 s1, s1, s13
	s_waitcnt vmcnt(0)
	ds_write_b128 v3, v[228:231]
	ds_write_b128 v3, v[232:235] offset:1152
	ds_read_b128 v[228:231], v227
	ds_read_b128 v[232:235], v227 offset:64
	s_waitcnt lgkmcnt(1)
	v_lshlrev_b32_e32 v4, 16, v228
	v_lshlrev_b32_e32 v244, 16, v230
	v_add_f32_e32 v4, v146, v4
	v_med3_f32 v4, v4, s85, v226
	v_mul_f32_e32 v4, 0xbfb8aa3b, v4
	v_add_f32_e32 v244, v142, v244
	v_med3_f32 v244, v244, s85, v226
	v_mul_f32_e32 v244, 0xbfb8aa3b, v244
	v_exp_f32_e32 v4, v4
	v_exp_f32_e32 v244, v244
	v_and_b32_e32 v5, 0xffff0000, v228
	v_lshlrev_b32_e32 v228, 16, v229
	v_add_f32_e32 v228, v148, v228
	v_and_b32_e32 v230, 0xffff0000, v230
	v_med3_f32 v228, v228, s85, v226
	v_add_f32_e32 v5, v147, v5
	v_add_f32_e32 v230, v143, v230
	v_mul_f32_e32 v228, 0xbfb8aa3b, v228
	v_add_f32_e32 v4, 1.0, v4
	v_add_f32_e32 v244, 1.0, v244
	v_med3_f32 v5, v5, s85, v226
	v_med3_f32 v230, v230, s85, v226
	v_exp_f32_e32 v228, v228
	v_rcp_f32_e32 v4, v4
	v_rcp_f32_e32 v244, v244
	v_mul_f32_e32 v5, 0xbfb8aa3b, v5
	v_mul_f32_e32 v230, 0xbfb8aa3b, v230
	v_exp_f32_e32 v5, v5
	v_exp_f32_e32 v230, v230
	v_and_b32_e32 v229, 0xffff0000, v229
	v_lshlrev_b32_e32 v245, 16, v231
	v_and_b32_e32 v231, 0xffff0000, v231
	v_add_f32_e32 v245, v144, v245
	v_mul_f32_e32 v4, v130, v4
	v_mul_f32_e32 v130, v126, v244
	v_add_f32_e32 v126, 1.0, v228
	v_add_f32_e32 v228, v149, v229
	v_med3_f32 v245, v245, s85, v226
	v_med3_f32 v228, v228, s85, v226
	v_add_f32_e32 v229, v145, v231
	v_mul_f32_e32 v245, 0xbfb8aa3b, v245
	v_add_f32_e32 v5, 1.0, v5
	v_add_f32_e32 v230, 1.0, v230
	v_mul_f32_e32 v228, 0xbfb8aa3b, v228
	v_med3_f32 v229, v229, s85, v226
	v_exp_f32_e32 v245, v245
	v_rcp_f32_e32 v5, v5
	v_rcp_f32_e32 v230, v230
	v_exp_f32_e32 v228, v228
	v_mul_f32_e32 v229, 0xbfb8aa3b, v229
	v_exp_f32_e32 v229, v229
	v_mul_f32_e32 v5, v131, v5
	v_mul_f32_e32 v131, v127, v230
	v_add_f32_e32 v127, 1.0, v245
	v_add_f32_e32 v228, 1.0, v228
	v_rcp_f32_e32 v126, v126
	v_rcp_f32_e32 v127, v127
	v_rcp_f32_e32 v228, v228
	v_add_f32_e32 v229, 1.0, v229
	v_rcp_f32_e32 v229, v229
	v_mul_f32_e32 v132, v132, v126
	v_mul_f32_e32 v230, v128, v127
	v_mul_f32_e32 v127, v133, v228
	v_cvt_pk_bf16_f32 v126, v4, v5
	s_waitcnt lgkmcnt(0)
; __device__ __forceinline__ u32x4 pack8(const f32x4& v0, const f32x4& v1) { u32x4 w; w.x = cvt_pk_bf16(v0[0], v0[1]); w.y = cvt_pk_bf16(v0[2], v0[3]); w.z = cvt_pk_bf16(v1[0], v1[1]); w.w = cvt_pk_bf16(v1[2], v1[3]); return w; }
; #define UNPK0(q_) ((f32x4){bf_lo((q_).x), bf_hi((q_).x), bf_lo((q_).y), bf_hi((q_).y)})
; #define UNPK1(q_) ((f32x4){bf_lo((q_).z), bf_hi((q_).z), bf_lo((q_).w), bf_hi((q_).w)})
;     static __device__ __forceinline__ float eneg(float g) { return __builtin_amdgcn_exp2f(-1.4426950408889634f * fminf(fmaxf(g, -30.f), 30.f)); }
;     __device__ __forceinline__ void operator()(const f32x4 (&acc)[2][2][4][2], const Unit& u, int wr, int wc, int fr, int fq) const {
;     ...
;         for (int ai = 0; ai < 2; ++ai)
; #pragma unroll
;             for (int m = 0; m < 4; ++m) {
;                 pb.stage(rb[ai][m][0], rb[ai][m][1]); const u32x4 gb0 = pb.get(0), gb1 = pb.get(1);
;                 asm volatile("" ::: "memory");
; #pragma unroll
;                 for (int bj = 0; bj < 2; ++bj) { const u32x4 gb = bj ? gb1 : gb0;
;                     const f32x4 b0 = UNPK0(gb) + bb[bj][0], b1 = UNPK1(gb) + bb[bj][1];
;                     f32x4 v0 = acc[ai][bj][m][0], v1 = acc[ai][bj][m][1];
; #pragma unroll
;                     for (int k = 0; k < 4; ++k) { v0[k] *= __builtin_amdgcn_rcpf(1.0f + eneg(b0[k])); v1[k] *= __builtin_amdgcn_rcpf(1.0f + eneg(b1[k])); }
;                     po.put(bj, pack8(v0, v1)); }
;                 po.flush<false>(ai, m);
;                 asm volatile("" ::: "memory"); }
	v_and_b32_e32 v5, 0xffff0000, v232
	v_mul_f32_e32 v129, v129, v229
	v_cvt_pk_bf16_f32 v127, v132, v127
	v_cvt_pk_bf16_f32 v128, v130, v131
	v_add_f32_e32 v5, v139, v5
	v_cvt_pk_bf16_f32 v129, v230, v129
	ds_write_b128 v227, v[126:129]
	v_lshlrev_b32_e32 v4, 16, v232
	v_lshlrev_b32_e32 v128, 16, v234
	v_med3_f32 v5, v5, s85, v226
	v_add_f32_e32 v4, v138, v4
	v_add_f32_e32 v128, v134, v128
	v_mul_f32_e32 v5, 0xbfb8aa3b, v5
	v_med3_f32 v4, v4, s85, v226
	v_med3_f32 v128, v128, s85, v226
	v_exp_f32_e32 v5, v5
	v_mul_f32_e32 v4, 0xbfb8aa3b, v4
	v_mul_f32_e32 v128, 0xbfb8aa3b, v128
	v_exp_f32_e32 v4, v4
	v_exp_f32_e32 v128, v128
	v_and_b32_e32 v129, 0xffff0000, v234
	v_add_f32_e32 v5, 1.0, v5
	v_add_f32_e32 v129, v135, v129
	v_rcp_f32_e32 v5, v5
	v_med3_f32 v129, v129, s85, v226
	v_add_f32_e32 v4, 1.0, v4
	v_add_f32_e32 v128, 1.0, v128
	v_mul_f32_e32 v129, 0xbfb8aa3b, v129
	v_rcp_f32_e32 v4, v4
	v_rcp_f32_e32 v128, v128
	v_exp_f32_e32 v129, v129
	v_lshlrev_b32_e32 v126, 16, v233
	v_lshlrev_b32_e32 v130, 16, v235
	v_mul_f32_e32 v5, v123, v5
	v_add_f32_e32 v123, v140, v126
	v_add_f32_e32 v126, v136, v130
	v_med3_f32 v123, v123, s85, v226
	v_med3_f32 v126, v126, s85, v226
	v_mul_f32_e32 v4, v122, v4
	v_mul_f32_e32 v122, v118, v128
	v_add_f32_e32 v118, 1.0, v129
	v_mul_f32_e32 v123, 0xbfb8aa3b, v123
	v_mul_f32_e32 v126, 0xbfb8aa3b, v126
	v_rcp_f32_e32 v118, v118
	v_exp_f32_e32 v123, v123
	v_exp_f32_e32 v126, v126
	v_and_b32_e32 v127, 0xffff0000, v233
	v_and_b32_e32 v131, 0xffff0000, v235
	v_mul_f32_e32 v128, v119, v118
	v_add_f32_e32 v118, 1.0, v123
	v_add_f32_e32 v119, 1.0, v126
	v_add_f32_e32 v123, v141, v127
	v_add_f32_e32 v126, v137, v131
	v_med3_f32 v123, v123, s85, v226
	v_med3_f32 v126, v126, s85, v226
	v_mul_f32_e32 v123, 0xbfb8aa3b, v123
	v_mul_f32_e32 v126, 0xbfb8aa3b, v126
	v_exp_f32_e32 v123, v123
	v_exp_f32_e32 v126, v126
	v_rcp_f32_e32 v119, v119
	v_rcp_f32_e32 v118, v118
	v_add_f32_e32 v123, 1.0, v123
	v_add_f32_e32 v126, 1.0, v126
	v_rcp_f32_e32 v123, v123
	v_rcp_f32_e32 v126, v126
	v_mul_f32_e32 v127, v120, v119
	v_mul_f32_e32 v124, v124, v118
	v_mul_f32_e32 v119, v125, v123
	v_mul_f32_e32 v121, v121, v126
	v_cvt_pk_bf16_f32 v118, v4, v5
	v_cvt_pk_bf16_f32 v119, v124, v119
	v_cvt_pk_bf16_f32 v120, v122, v128
	v_cvt_pk_bf16_f32 v121, v127, v121
	ds_write_b128 v227, v[118:121] offset:64
	ds_read_b128 v[118:121], v3
	ds_read_b128 v[122:125], v3 offset:1152
	v_lshl_add_u64 v[4:5], s[0:1], 0, v[206:207]
	s_waitcnt lgkmcnt(1)
	global_store_dwordx4 v[4:5], v[118:121], off sc1
	s_waitcnt lgkmcnt(0)
	global_store_dwordx4 v[4:5], v[122:125], off offset:1024 sc1
	ds_write_b128 v3, v[236:239]
	ds_write_b128 v3, v[240:243] offset:1152
	ds_read_b128 v[118:121], v227
	ds_read_b128 v[122:125], v227 offset:64
	s_waitcnt lgkmcnt(1)
	v_lshlrev_b32_e32 v126, 16, v118
	v_and_b32_e32 v118, 0xffff0000, v118
	v_lshlrev_b32_e32 v128, 16, v120
	v_add_f32_e32 v126, v146, v126
	v_add_f32_e32 v128, v142, v128
	v_add_f32_e32 v118, v147, v118
	v_med3_f32 v126, v126, s85, v226
	v_med3_f32 v128, v128, s85, v226
	v_med3_f32 v118, v118, s85, v226
	v_mul_f32_e32 v126, 0xbfb8aa3b, v126
	v_mul_f32_e32 v128, 0xbfb8aa3b, v128
	v_mul_f32_e32 v118, 0xbfb8aa3b, v118
	v_exp_f32_e32 v126, v126
	v_exp_f32_e32 v128, v128
	v_exp_f32_e32 v118, v118
	v_and_b32_e32 v120, 0xffff0000, v120
	v_add_f32_e32 v120, v143, v120
	v_med3_f32 v120, v120, s85, v226
	v_add_f32_e32 v126, 1.0, v126
	v_add_f32_e32 v128, 1.0, v128
	v_add_f32_e32 v118, 1.0, v118
	v_mul_f32_e32 v120, 0xbfb8aa3b, v120
	v_rcp_f32_e32 v126, v126
	v_rcp_f32_e32 v128, v128
	v_rcp_f32_e32 v118, v118
	v_exp_f32_e32 v120, v120
	v_lshlrev_b32_e32 v127, 16, v119
	v_lshlrev_b32_e32 v129, 16, v121
	v_mul_f32_e32 v114, v114, v126
	v_mul_f32_e32 v126, v110, v128
	v_mul_f32_e32 v110, v115, v118
	v_add_f32_e32 v115, 1.0, v120
	v_add_f32_e32 v118, v148, v127
	v_add_f32_e32 v120, v144, v129
	v_med3_f32 v118, v118, s85, v226
	v_med3_f32 v120, v120, s85, v226
	v_mul_f32_e32 v118, 0xbfb8aa3b, v118
	v_mul_f32_e32 v120, 0xbfb8aa3b, v120
	v_rcp_f32_e32 v115, v115
	v_exp_f32_e32 v118, v118
	v_exp_f32_e32 v120, v120
	v_and_b32_e32 v119, 0xffff0000, v119
	v_and_b32_e32 v121, 0xffff0000, v121
	v_mul_f32_e32 v115, v111, v115
	v_add_f32_e32 v111, 1.0, v118
	v_add_f32_e32 v118, 1.0, v120
	v_add_f32_e32 v119, v149, v119
	v_add_f32_e32 v120, v145, v121
	v_med3_f32 v119, v119, s85, v226
	v_med3_f32 v120, v120, s85, v226
	v_mul_f32_e32 v119, 0xbfb8aa3b, v119
	v_mul_f32_e32 v120, 0xbfb8aa3b, v120
	v_exp_f32_e32 v119, v119
	v_exp_f32_e32 v120, v120
	v_rcp_f32_e32 v111, v111
	v_rcp_f32_e32 v118, v118
	v_add_f32_e32 v119, 1.0, v119
	v_add_f32_e32 v120, 1.0, v120
	v_rcp_f32_e32 v119, v119
	v_rcp_f32_e32 v120, v120
	v_mul_f32_e32 v111, v116, v111
	v_mul_f32_e32 v116, v112, v118
	v_mul_f32_e32 v112, v117, v119
	v_mul_f32_e32 v113, v113, v120
	v_cvt_pk_bf16_f32 v110, v114, v110
	v_cvt_pk_bf16_f32 v111, v111, v112
	v_cvt_pk_bf16_f32 v112, v126, v115
	v_cvt_pk_bf16_f32 v113, v116, v113
	ds_write_b128 v227, v[110:113]
	s_waitcnt lgkmcnt(1)
; __device__ __forceinline__ u32x4 pack8(const f32x4& v0, const f32x4& v1) { u32x4 w; w.x = cvt_pk_bf16(v0[0], v0[1]); w.y = cvt_pk_bf16(v0[2], v0[3]); w.z = cvt_pk_bf16(v1[0], v1[1]); w.w = cvt_pk_bf16(v1[2], v1[3]); return w; }
; #define UNPK0(q_) ((f32x4){bf_lo((q_).x), bf_hi((q_).x), bf_lo((q_).y), bf_hi((q_).y)})
; #define UNPK1(q_) ((f32x4){bf_lo((q_).z), bf_hi((q_).z), bf_lo((q_).w), bf_hi((q_).w)})
;     static __device__ __forceinline__ float eneg(float g) { return __builtin_amdgcn_exp2f(-1.4426950408889634f * fminf(fmaxf(g, -30.f), 30.f)); }
;     __device__ __forceinline__ void operator()(const f32x4 (&acc)[2][2][4][2], const Unit& u, int wr, int wc, int fr, int fq) const {
;     ...
;         for (int ai = 0; ai < 2; ++ai)
; #pragma unroll
;             for (int m = 0; m < 4; ++m) {
;                 pb.stage(rb[ai][m][0], rb[ai][m][1]); const u32x4 gb0 = pb.get(0), gb1 = pb.get(1);
;                 asm volatile("" ::: "memory");
; #pragma unroll
;                 for (int bj = 0; bj < 2; ++bj) { const u32x4 gb = bj ? gb1 : gb0;
;                     const f32x4 b0 = UNPK0(gb) + bb[bj][0], b1 = UNPK1(gb) + bb[bj][1];
;                     f32x4 v0 = acc[ai][bj][m][0], v1 = acc[ai][bj][m][1];
; #pragma unroll
;                     for (int k = 0; k < 4; ++k) { v0[k] *= __builtin_amdgcn_rcpf(1.0f + eneg(b0[k])); v1[k] *= __builtin_amdgcn_rcpf(1.0f + eneg(b1[k])); }
;                     po.put(bj, pack8(v0, v1)); }
;                 po.flush<false>(ai, m);
;                 asm volatile("" ::: "memory"); }
	v_lshlrev_b32_e32 v110, 16, v122
	v_and_b32_e32 v111, 0xffff0000, v122
	v_lshlrev_b32_e32 v114, 16, v124
	v_add_f32_e32 v110, v138, v110
	v_add_f32_e32 v114, v134, v114
	v_add_f32_e32 v111, v139, v111
	v_med3_f32 v110, v110, s85, v226
	v_med3_f32 v114, v114, s85, v226
	v_med3_f32 v111, v111, s85, v226
	v_mul_f32_e32 v110, 0xbfb8aa3b, v110
	v_mul_f32_e32 v114, 0xbfb8aa3b, v114
	v_mul_f32_e32 v111, 0xbfb8aa3b, v111
	v_exp_f32_e32 v110, v110
	v_exp_f32_e32 v114, v114
	v_exp_f32_e32 v111, v111
	v_and_b32_e32 v115, 0xffff0000, v124
	v_add_f32_e32 v110, 1.0, v110
	v_add_f32_e32 v114, 1.0, v114
	v_add_f32_e32 v111, 1.0, v111
	v_add_f32_e32 v115, v135, v115
	v_rcp_f32_e32 v110, v110
	v_rcp_f32_e32 v114, v114
	v_rcp_f32_e32 v111, v111
	v_med3_f32 v115, v115, s85, v226
	v_mul_f32_e32 v115, 0xbfb8aa3b, v115
	v_exp_f32_e32 v115, v115
	v_lshlrev_b32_e32 v112, 16, v123
	v_lshlrev_b32_e32 v116, 16, v125
	v_mul_f32_e32 v106, v106, v110
	v_mul_f32_e32 v110, v102, v114
	v_mul_f32_e32 v102, v107, v111
	v_add_f32_e32 v111, v140, v112
	v_add_f32_e32 v112, v136, v116
	v_med3_f32 v111, v111, s85, v226
	v_med3_f32 v112, v112, s85, v226
	v_add_f32_e32 v107, 1.0, v115
	v_mul_f32_e32 v111, 0xbfb8aa3b, v111
	v_mul_f32_e32 v112, 0xbfb8aa3b, v112
	v_rcp_f32_e32 v107, v107
	v_exp_f32_e32 v111, v111
	v_exp_f32_e32 v112, v112
	v_and_b32_e32 v113, 0xffff0000, v123
	v_and_b32_e32 v117, 0xffff0000, v125
	v_mul_f32_e32 v107, v103, v107
	v_add_f32_e32 v103, 1.0, v111
	v_add_f32_e32 v111, 1.0, v112
	v_add_f32_e32 v112, v141, v113
	v_add_f32_e32 v113, v137, v117
	v_med3_f32 v112, v112, s85, v226
	v_med3_f32 v113, v113, s85, v226
	v_mul_f32_e32 v112, 0xbfb8aa3b, v112
	v_mul_f32_e32 v113, 0xbfb8aa3b, v113
	v_exp_f32_e32 v112, v112
	v_exp_f32_e32 v113, v113
	v_rcp_f32_e32 v103, v103
	v_rcp_f32_e32 v111, v111
	v_add_f32_e32 v112, 1.0, v112
	v_add_f32_e32 v113, 1.0, v113
	v_rcp_f32_e32 v112, v112
	v_rcp_f32_e32 v113, v113
	v_mul_f32_e32 v103, v108, v103
	v_mul_f32_e32 v108, v104, v111
	v_mul_f32_e32 v104, v109, v112
	v_mul_f32_e32 v105, v105, v113
	v_cvt_pk_bf16_f32 v102, v106, v102
	v_cvt_pk_bf16_f32 v103, v103, v104
	v_cvt_pk_bf16_f32 v104, v110, v107
	v_cvt_pk_bf16_f32 v105, v108, v105
	ds_write_b128 v227, v[102:105] offset:64
	ds_read_b128 v[102:105], v3
	ds_read_b128 v[106:109], v3 offset:1152
	s_waitcnt lgkmcnt(1)
	global_store_dwordx4 v[4:5], v[102:105], off offset:2048 sc1
	s_waitcnt lgkmcnt(0)
	global_store_dwordx4 v[4:5], v[106:109], off offset:3072 sc1
	ds_write_b128 v3, v[190:193]
	ds_write_b128 v3, v[194:197] offset:1152
	ds_read_b128 v[102:105], v227
	ds_read_b128 v[106:109], v227 offset:64
	s_waitcnt lgkmcnt(1)
	v_lshlrev_b32_e32 v110, 16, v102
	v_and_b32_e32 v102, 0xffff0000, v102
	v_lshlrev_b32_e32 v112, 16, v104
	v_add_f32_e32 v110, v146, v110
	v_add_f32_e32 v112, v142, v112
	v_add_f32_e32 v102, v147, v102
	v_med3_f32 v110, v110, s85, v226
	v_med3_f32 v112, v112, s85, v226
	v_med3_f32 v102, v102, s85, v226
	v_mul_f32_e32 v110, 0xbfb8aa3b, v110
	v_mul_f32_e32 v112, 0xbfb8aa3b, v112
	v_mul_f32_e32 v102, 0xbfb8aa3b, v102
	v_exp_f32_e32 v110, v110
	v_exp_f32_e32 v112, v112
	v_exp_f32_e32 v102, v102
	v_and_b32_e32 v104, 0xffff0000, v104
	v_add_f32_e32 v104, v143, v104
	v_med3_f32 v104, v104, s85, v226
	v_add_f32_e32 v110, 1.0, v110
	v_add_f32_e32 v112, 1.0, v112
	v_add_f32_e32 v102, 1.0, v102
	v_mul_f32_e32 v104, 0xbfb8aa3b, v104
	v_rcp_f32_e32 v110, v110
	v_rcp_f32_e32 v112, v112
	v_rcp_f32_e32 v102, v102
	v_exp_f32_e32 v104, v104
	v_lshlrev_b32_e32 v111, 16, v103
	v_lshlrev_b32_e32 v113, 16, v105
	v_mul_f32_e32 v98, v98, v110
	v_mul_f32_e32 v110, v94, v112
	v_mul_f32_e32 v94, v99, v102
	v_add_f32_e32 v99, 1.0, v104
	v_add_f32_e32 v102, v148, v111
	v_add_f32_e32 v104, v144, v113
	v_med3_f32 v102, v102, s85, v226
	v_med3_f32 v104, v104, s85, v226
	v_mul_f32_e32 v102, 0xbfb8aa3b, v102
	v_mul_f32_e32 v104, 0xbfb8aa3b, v104
	v_rcp_f32_e32 v99, v99
	v_exp_f32_e32 v102, v102
	v_exp_f32_e32 v104, v104
	v_and_b32_e32 v103, 0xffff0000, v103
	v_and_b32_e32 v105, 0xffff0000, v105
	v_mul_f32_e32 v99, v95, v99
	v_add_f32_e32 v95, 1.0, v102
	v_add_f32_e32 v102, 1.0, v104
	v_add_f32_e32 v103, v149, v103
	v_add_f32_e32 v104, v145, v105
	v_med3_f32 v103, v103, s85, v226
	v_med3_f32 v104, v104, s85, v226
	v_mul_f32_e32 v103, 0xbfb8aa3b, v103
	v_mul_f32_e32 v104, 0xbfb8aa3b, v104
	v_exp_f32_e32 v103, v103
	v_exp_f32_e32 v104, v104
	v_rcp_f32_e32 v95, v95
	v_rcp_f32_e32 v102, v102
	v_add_f32_e32 v103, 1.0, v103
	v_add_f32_e32 v104, 1.0, v104
	v_rcp_f32_e32 v103, v103
	v_rcp_f32_e32 v104, v104
	v_mul_f32_e32 v95, v100, v95
	v_mul_f32_e32 v100, v96, v102
	v_mul_f32_e32 v96, v101, v103
	v_mul_f32_e32 v97, v97, v104
	v_cvt_pk_bf16_f32 v94, v98, v94
	v_cvt_pk_bf16_f32 v95, v95, v96
	v_cvt_pk_bf16_f32 v96, v110, v99
	v_cvt_pk_bf16_f32 v97, v100, v97
	ds_write_b128 v227, v[94:97]
	s_waitcnt lgkmcnt(1)
; __device__ __forceinline__ u32x4 pack8(const f32x4& v0, const f32x4& v1) { u32x4 w; w.x = cvt_pk_bf16(v0[0], v0[1]); w.y = cvt_pk_bf16(v0[2], v0[3]); w.z = cvt_pk_bf16(v1[0], v1[1]); w.w = cvt_pk_bf16(v1[2], v1[3]); return w; }
; #define UNPK0(q_) ((f32x4){bf_lo((q_).x), bf_hi((q_).x), bf_lo((q_).y), bf_hi((q_).y)})
; #define UNPK1(q_) ((f32x4){bf_lo((q_).z), bf_hi((q_).z), bf_lo((q_).w), bf_hi((q_).w)})
;     static __device__ __forceinline__ float eneg(float g) { return __builtin_amdgcn_exp2f(-1.4426950408889634f * fminf(fmaxf(g, -30.f), 30.f)); }
;     __device__ __forceinline__ void operator()(const f32x4 (&acc)[2][2][4][2], const Unit& u, int wr, int wc, int fr, int fq) const {
;     ...
;         for (int ai = 0; ai < 2; ++ai)
; #pragma unroll
;             for (int m = 0; m < 4; ++m) {
;                 pb.stage(rb[ai][m][0], rb[ai][m][1]); const u32x4 gb0 = pb.get(0), gb1 = pb.get(1);
;                 asm volatile("" ::: "memory");
; #pragma unroll
;                 for (int bj = 0; bj < 2; ++bj) { const u32x4 gb = bj ? gb1 : gb0;
;                     const f32x4 b0 = UNPK0(gb) + bb[bj][0], b1 = UNPK1(gb) + bb[bj][1];
;                     f32x4 v0 = acc[ai][bj][m][0], v1 = acc[ai][bj][m][1];
; #pragma unroll
;                     for (int k = 0; k < 4; ++k) { v0[k] *= __builtin_amdgcn_rcpf(1.0f + eneg(b0[k])); v1[k] *= __builtin_amdgcn_rcpf(1.0f + eneg(b1[k])); }
;                     po.put(bj, pack8(v0, v1)); }
;                 po.flush<false>(ai, m);
;                 asm volatile("" ::: "memory"); }
	v_lshlrev_b32_e32 v94, 16, v106
	v_and_b32_e32 v95, 0xffff0000, v106
	v_lshlrev_b32_e32 v98, 16, v108
	v_add_f32_e32 v94, v138, v94
	v_add_f32_e32 v98, v134, v98
	v_add_f32_e32 v95, v139, v95
	v_med3_f32 v94, v94, s85, v226
	v_med3_f32 v98, v98, s85, v226
	v_med3_f32 v95, v95, s85, v226
	v_mul_f32_e32 v94, 0xbfb8aa3b, v94
	v_mul_f32_e32 v98, 0xbfb8aa3b, v98
	v_mul_f32_e32 v95, 0xbfb8aa3b, v95
	v_exp_f32_e32 v94, v94
	v_exp_f32_e32 v98, v98
	v_exp_f32_e32 v95, v95
	v_and_b32_e32 v99, 0xffff0000, v108
	v_add_f32_e32 v94, 1.0, v94
	v_add_f32_e32 v98, 1.0, v98
	v_add_f32_e32 v95, 1.0, v95
	v_add_f32_e32 v99, v135, v99
	v_rcp_f32_e32 v94, v94
	v_rcp_f32_e32 v98, v98
	v_rcp_f32_e32 v95, v95
	v_med3_f32 v99, v99, s85, v226
	v_mul_f32_e32 v99, 0xbfb8aa3b, v99
	v_exp_f32_e32 v99, v99
	v_lshlrev_b32_e32 v96, 16, v107
	v_lshlrev_b32_e32 v100, 16, v109
	v_mul_f32_e32 v90, v90, v94
	v_mul_f32_e32 v94, v86, v98
	v_mul_f32_e32 v86, v91, v95
	v_add_f32_e32 v95, v140, v96
	v_add_f32_e32 v96, v136, v100
	v_med3_f32 v95, v95, s85, v226
	v_med3_f32 v96, v96, s85, v226
	v_add_f32_e32 v91, 1.0, v99
	v_mul_f32_e32 v95, 0xbfb8aa3b, v95
	v_mul_f32_e32 v96, 0xbfb8aa3b, v96
	v_rcp_f32_e32 v91, v91
	v_exp_f32_e32 v95, v95
	v_exp_f32_e32 v96, v96
	v_and_b32_e32 v97, 0xffff0000, v107
	v_and_b32_e32 v101, 0xffff0000, v109
	v_mul_f32_e32 v91, v87, v91
	v_add_f32_e32 v87, 1.0, v95
	v_add_f32_e32 v95, 1.0, v96
	v_add_f32_e32 v96, v141, v97
	v_add_f32_e32 v97, v137, v101
	v_med3_f32 v96, v96, s85, v226
	v_med3_f32 v97, v97, s85, v226
	v_mul_f32_e32 v96, 0xbfb8aa3b, v96
	v_mul_f32_e32 v97, 0xbfb8aa3b, v97
	v_exp_f32_e32 v96, v96
	v_exp_f32_e32 v97, v97
	v_rcp_f32_e32 v87, v87
	v_rcp_f32_e32 v95, v95
	v_add_f32_e32 v96, 1.0, v96
	v_add_f32_e32 v97, 1.0, v97
	v_rcp_f32_e32 v96, v96
	v_rcp_f32_e32 v97, v97
	v_mul_f32_e32 v87, v92, v87
	v_mul_f32_e32 v92, v88, v95
	v_mul_f32_e32 v88, v93, v96
	v_mul_f32_e32 v89, v89, v97
	v_cvt_pk_bf16_f32 v86, v90, v86
	v_cvt_pk_bf16_f32 v87, v87, v88
	v_cvt_pk_bf16_f32 v88, v94, v91
	v_cvt_pk_bf16_f32 v89, v92, v89
	ds_write_b128 v227, v[86:89] offset:64
	ds_read_b128 v[86:89], v3
	ds_read_b128 v[90:93], v3 offset:1152
	v_add_co_u32_e32 v94, vcc, s84, v4
	s_nop 1
	v_addc_co_u32_e32 v95, vcc, 0, v5, vcc
	s_waitcnt lgkmcnt(1)
	global_store_dwordx4 v[94:95], v[86:89], off sc1
	s_waitcnt lgkmcnt(0)
	global_store_dwordx4 v[94:95], v[90:93], off offset:1024 sc1
	ds_write_b128 v3, v[182:185]
	ds_write_b128 v3, v[186:189] offset:1152
	ds_read_b128 v[86:89], v227
	ds_read_b128 v[90:93], v227 offset:64
	s_waitcnt lgkmcnt(1)
	v_lshlrev_b32_e32 v96, 16, v86
	v_and_b32_e32 v86, 0xffff0000, v86
	v_lshlrev_b32_e32 v98, 16, v88
	v_add_f32_e32 v96, v146, v96
	v_add_f32_e32 v98, v142, v98
	v_add_f32_e32 v86, v147, v86
	v_med3_f32 v96, v96, s85, v226
	v_med3_f32 v98, v98, s85, v226
	v_med3_f32 v86, v86, s85, v226
	v_mul_f32_e32 v96, 0xbfb8aa3b, v96
	v_mul_f32_e32 v98, 0xbfb8aa3b, v98
	v_mul_f32_e32 v86, 0xbfb8aa3b, v86
	v_exp_f32_e32 v96, v96
	v_exp_f32_e32 v98, v98
	v_exp_f32_e32 v86, v86
	v_and_b32_e32 v88, 0xffff0000, v88
	v_add_f32_e32 v88, v143, v88
	v_med3_f32 v88, v88, s85, v226
	v_add_f32_e32 v96, 1.0, v96
	v_add_f32_e32 v98, 1.0, v98
	v_add_f32_e32 v86, 1.0, v86
	v_mul_f32_e32 v88, 0xbfb8aa3b, v88
	v_rcp_f32_e32 v96, v96
	v_rcp_f32_e32 v98, v98
	v_rcp_f32_e32 v86, v86
	v_exp_f32_e32 v88, v88
	v_lshlrev_b32_e32 v97, 16, v87
	v_lshlrev_b32_e32 v99, 16, v89
	v_mul_f32_e32 v82, v82, v96
	v_mul_f32_e32 v96, v78, v98
	v_mul_f32_e32 v78, v83, v86
	v_add_f32_e32 v83, 1.0, v88
	v_add_f32_e32 v86, v148, v97
	v_add_f32_e32 v88, v144, v99
	v_med3_f32 v86, v86, s85, v226
	v_med3_f32 v88, v88, s85, v226
	v_mul_f32_e32 v86, 0xbfb8aa3b, v86
	v_mul_f32_e32 v88, 0xbfb8aa3b, v88
	v_rcp_f32_e32 v83, v83
	v_exp_f32_e32 v86, v86
	v_exp_f32_e32 v88, v88
	v_and_b32_e32 v87, 0xffff0000, v87
	v_and_b32_e32 v89, 0xffff0000, v89
	v_mul_f32_e32 v83, v79, v83
	v_add_f32_e32 v79, 1.0, v86
	v_add_f32_e32 v86, 1.0, v88
	v_add_f32_e32 v87, v149, v87
	v_add_f32_e32 v88, v145, v89
	v_med3_f32 v87, v87, s85, v226
	v_med3_f32 v88, v88, s85, v226
	v_mul_f32_e32 v87, 0xbfb8aa3b, v87
	v_mul_f32_e32 v88, 0xbfb8aa3b, v88
	v_exp_f32_e32 v87, v87
	v_exp_f32_e32 v88, v88
	v_rcp_f32_e32 v79, v79
	v_rcp_f32_e32 v86, v86
	v_add_f32_e32 v87, 1.0, v87
	v_add_f32_e32 v88, 1.0, v88
	v_rcp_f32_e32 v87, v87
	v_rcp_f32_e32 v88, v88
	v_mul_f32_e32 v79, v84, v79
	v_mul_f32_e32 v84, v80, v86
	v_mul_f32_e32 v80, v85, v87
	v_mul_f32_e32 v81, v81, v88
	v_cvt_pk_bf16_f32 v78, v82, v78
	v_cvt_pk_bf16_f32 v79, v79, v80
	v_cvt_pk_bf16_f32 v80, v96, v83
	v_cvt_pk_bf16_f32 v81, v84, v81
	ds_write_b128 v227, v[78:81]
	s_waitcnt lgkmcnt(1)
; __device__ __forceinline__ u32x4 pack8(const f32x4& v0, const f32x4& v1) { u32x4 w; w.x = cvt_pk_bf16(v0[0], v0[1]); w.y = cvt_pk_bf16(v0[2], v0[3]); w.z = cvt_pk_bf16(v1[0], v1[1]); w.w = cvt_pk_bf16(v1[2], v1[3]); return w; }
; #define UNPK0(q_) ((f32x4){bf_lo((q_).x), bf_hi((q_).x), bf_lo((q_).y), bf_hi((q_).y)})
; #define UNPK1(q_) ((f32x4){bf_lo((q_).z), bf_hi((q_).z), bf_lo((q_).w), bf_hi((q_).w)})
;     static __device__ __forceinline__ float eneg(float g) { return __builtin_amdgcn_exp2f(-1.4426950408889634f * fminf(fmaxf(g, -30.f), 30.f)); }
;     __device__ __forceinline__ void operator()(const f32x4 (&acc)[2][2][4][2], const Unit& u, int wr, int wc, int fr, int fq) const {
;     ...
;         for (int ai = 0; ai < 2; ++ai)
; #pragma unroll
;             for (int m = 0; m < 4; ++m) {
;                 pb.stage(rb[ai][m][0], rb[ai][m][1]); const u32x4 gb0 = pb.get(0), gb1 = pb.get(1);
;                 asm volatile("" ::: "memory");
; #pragma unroll
;                 for (int bj = 0; bj < 2; ++bj) { const u32x4 gb = bj ? gb1 : gb0;
;                     const f32x4 b0 = UNPK0(gb) + bb[bj][0], b1 = UNPK1(gb) + bb[bj][1];
;                     f32x4 v0 = acc[ai][bj][m][0], v1 = acc[ai][bj][m][1];
; #pragma unroll
;                     for (int k = 0; k < 4; ++k) { v0[k] *= __builtin_amdgcn_rcpf(1.0f + eneg(b0[k])); v1[k] *= __builtin_amdgcn_rcpf(1.0f + eneg(b1[k])); }
;                     po.put(bj, pack8(v0, v1)); }
;                 po.flush<false>(ai, m);
;                 asm volatile("" ::: "memory"); }
	v_lshlrev_b32_e32 v78, 16, v90
	v_and_b32_e32 v79, 0xffff0000, v90
	v_lshlrev_b32_e32 v82, 16, v92
	v_add_f32_e32 v78, v138, v78
	v_add_f32_e32 v82, v134, v82
	v_add_f32_e32 v79, v139, v79
	v_med3_f32 v78, v78, s85, v226
	v_med3_f32 v82, v82, s85, v226
	v_med3_f32 v79, v79, s85, v226
	v_mul_f32_e32 v78, 0xbfb8aa3b, v78
	v_mul_f32_e32 v82, 0xbfb8aa3b, v82
	v_mul_f32_e32 v79, 0xbfb8aa3b, v79
	v_exp_f32_e32 v78, v78
	v_exp_f32_e32 v82, v82
	v_exp_f32_e32 v79, v79
	v_and_b32_e32 v83, 0xffff0000, v92
	v_add_f32_e32 v78, 1.0, v78
	v_add_f32_e32 v82, 1.0, v82
	v_add_f32_e32 v79, 1.0, v79
	v_add_f32_e32 v83, v135, v83
	v_rcp_f32_e32 v78, v78
	v_rcp_f32_e32 v82, v82
	v_rcp_f32_e32 v79, v79
	v_med3_f32 v83, v83, s85, v226
	v_mul_f32_e32 v83, 0xbfb8aa3b, v83
	v_exp_f32_e32 v83, v83
	v_lshlrev_b32_e32 v80, 16, v91
	v_lshlrev_b32_e32 v84, 16, v93
	v_mul_f32_e32 v74, v74, v78
	v_mul_f32_e32 v78, v70, v82
	v_mul_f32_e32 v70, v75, v79
	v_add_f32_e32 v79, v140, v80
	v_add_f32_e32 v80, v136, v84
	v_med3_f32 v79, v79, s85, v226
	v_med3_f32 v80, v80, s85, v226
	v_add_f32_e32 v75, 1.0, v83
	v_mul_f32_e32 v79, 0xbfb8aa3b, v79
	v_mul_f32_e32 v80, 0xbfb8aa3b, v80
	v_rcp_f32_e32 v75, v75
	v_exp_f32_e32 v79, v79
	v_exp_f32_e32 v80, v80
	v_and_b32_e32 v81, 0xffff0000, v91
	v_and_b32_e32 v85, 0xffff0000, v93
	v_mul_f32_e32 v75, v71, v75
	v_add_f32_e32 v71, 1.0, v79
	v_add_f32_e32 v79, 1.0, v80
	v_add_f32_e32 v80, v141, v81
	v_add_f32_e32 v81, v137, v85
	v_med3_f32 v80, v80, s85, v226
	v_med3_f32 v81, v81, s85, v226
	v_mul_f32_e32 v80, 0xbfb8aa3b, v80
	v_mul_f32_e32 v81, 0xbfb8aa3b, v81
	v_exp_f32_e32 v80, v80
	v_exp_f32_e32 v81, v81
	v_rcp_f32_e32 v71, v71
	v_rcp_f32_e32 v79, v79
	v_add_f32_e32 v80, 1.0, v80
	v_add_f32_e32 v81, 1.0, v81
	v_rcp_f32_e32 v80, v80
	v_rcp_f32_e32 v81, v81
	v_mul_f32_e32 v71, v76, v71
	v_mul_f32_e32 v76, v72, v79
	v_mul_f32_e32 v72, v77, v80
	v_mul_f32_e32 v73, v73, v81
	v_cvt_pk_bf16_f32 v70, v74, v70
	v_cvt_pk_bf16_f32 v71, v71, v72
	v_cvt_pk_bf16_f32 v72, v78, v75
	v_cvt_pk_bf16_f32 v73, v76, v73
	ds_write_b128 v227, v[70:73] offset:64
	ds_read_b128 v[70:73], v3
	ds_read_b128 v[74:77], v3 offset:1152
	s_waitcnt lgkmcnt(1)
	global_store_dwordx4 v[94:95], v[70:73], off offset:2048 sc1
	s_waitcnt lgkmcnt(0)
	global_store_dwordx4 v[94:95], v[74:77], off offset:3072 sc1
	ds_write_b128 v3, v[178:181]
	ds_write_b128 v3, v[174:177] offset:1152
	ds_read_b128 v[70:73], v227
	ds_read_b128 v[74:77], v227 offset:64
	s_waitcnt lgkmcnt(1)
	v_lshlrev_b32_e32 v78, 16, v70
	v_and_b32_e32 v70, 0xffff0000, v70
	v_lshlrev_b32_e32 v80, 16, v72
	v_add_f32_e32 v78, v146, v78
	v_add_f32_e32 v80, v142, v80
	v_add_f32_e32 v70, v147, v70
	v_med3_f32 v78, v78, s85, v226
	v_med3_f32 v80, v80, s85, v226
	v_med3_f32 v70, v70, s85, v226
	v_mul_f32_e32 v78, 0xbfb8aa3b, v78
	v_mul_f32_e32 v80, 0xbfb8aa3b, v80
	v_mul_f32_e32 v70, 0xbfb8aa3b, v70
	v_exp_f32_e32 v78, v78
	v_exp_f32_e32 v80, v80
	v_exp_f32_e32 v70, v70
	v_and_b32_e32 v72, 0xffff0000, v72
	v_add_f32_e32 v72, v143, v72
	v_med3_f32 v72, v72, s85, v226
	v_add_f32_e32 v78, 1.0, v78
	v_add_f32_e32 v80, 1.0, v80
	v_add_f32_e32 v70, 1.0, v70
	v_mul_f32_e32 v72, 0xbfb8aa3b, v72
	v_rcp_f32_e32 v78, v78
	v_rcp_f32_e32 v80, v80
	v_rcp_f32_e32 v70, v70
	v_exp_f32_e32 v72, v72
	v_lshlrev_b32_e32 v79, 16, v71
	v_lshlrev_b32_e32 v81, 16, v73
	v_mul_f32_e32 v66, v66, v78
	v_mul_f32_e32 v78, v62, v80
	v_mul_f32_e32 v62, v67, v70
	v_add_f32_e32 v67, 1.0, v72
	v_add_f32_e32 v70, v148, v79
	v_add_f32_e32 v72, v144, v81
	v_med3_f32 v70, v70, s85, v226
	v_med3_f32 v72, v72, s85, v226
	v_mul_f32_e32 v70, 0xbfb8aa3b, v70
	v_mul_f32_e32 v72, 0xbfb8aa3b, v72
	v_rcp_f32_e32 v67, v67
	v_exp_f32_e32 v70, v70
	v_exp_f32_e32 v72, v72
	v_and_b32_e32 v71, 0xffff0000, v71
	v_and_b32_e32 v73, 0xffff0000, v73
	v_mul_f32_e32 v67, v63, v67
	v_add_f32_e32 v63, 1.0, v70
	v_add_f32_e32 v70, 1.0, v72
	v_add_f32_e32 v71, v149, v71
	v_add_f32_e32 v72, v145, v73
	v_med3_f32 v71, v71, s85, v226
	v_med3_f32 v72, v72, s85, v226
	v_mul_f32_e32 v71, 0xbfb8aa3b, v71
	v_mul_f32_e32 v72, 0xbfb8aa3b, v72
	v_exp_f32_e32 v71, v71
	v_exp_f32_e32 v72, v72
	v_rcp_f32_e32 v63, v63
	v_rcp_f32_e32 v70, v70
	v_add_f32_e32 v71, 1.0, v71
	v_add_f32_e32 v72, 1.0, v72
	v_rcp_f32_e32 v71, v71
	v_rcp_f32_e32 v72, v72
	v_mul_f32_e32 v63, v68, v63
	v_mul_f32_e32 v68, v64, v70
	v_mul_f32_e32 v64, v69, v71
	v_mul_f32_e32 v65, v65, v72
	v_cvt_pk_bf16_f32 v62, v66, v62
	v_cvt_pk_bf16_f32 v63, v63, v64
	v_cvt_pk_bf16_f32 v64, v78, v67
	v_cvt_pk_bf16_f32 v65, v68, v65
	ds_write_b128 v227, v[62:65]
	s_waitcnt lgkmcnt(1)
; __device__ __forceinline__ u32x4 pack8(const f32x4& v0, const f32x4& v1) { u32x4 w; w.x = cvt_pk_bf16(v0[0], v0[1]); w.y = cvt_pk_bf16(v0[2], v0[3]); w.z = cvt_pk_bf16(v1[0], v1[1]); w.w = cvt_pk_bf16(v1[2], v1[3]); return w; }
; #define UNPK0(q_) ((f32x4){bf_lo((q_).x), bf_hi((q_).x), bf_lo((q_).y), bf_hi((q_).y)})
; #define UNPK1(q_) ((f32x4){bf_lo((q_).z), bf_hi((q_).z), bf_lo((q_).w), bf_hi((q_).w)})
;     static __device__ __forceinline__ float eneg(float g) { return __builtin_amdgcn_exp2f(-1.4426950408889634f * fminf(fmaxf(g, -30.f), 30.f)); }
;     __device__ __forceinline__ void operator()(const f32x4 (&acc)[2][2][4][2], const Unit& u, int wr, int wc, int fr, int fq) const {
;     ...
;         for (int ai = 0; ai < 2; ++ai)
; #pragma unroll
;             for (int m = 0; m < 4; ++m) {
;                 pb.stage(rb[ai][m][0], rb[ai][m][1]); const u32x4 gb0 = pb.get(0), gb1 = pb.get(1);
;                 asm volatile("" ::: "memory");
; #pragma unroll
;                 for (int bj = 0; bj < 2; ++bj) { const u32x4 gb = bj ? gb1 : gb0;
;                     const f32x4 b0 = UNPK0(gb) + bb[bj][0], b1 = UNPK1(gb) + bb[bj][1];
;                     f32x4 v0 = acc[ai][bj][m][0], v1 = acc[ai][bj][m][1];
; #pragma unroll
;                     for (int k = 0; k < 4; ++k) { v0[k] *= __builtin_amdgcn_rcpf(1.0f + eneg(b0[k])); v1[k] *= __builtin_amdgcn_rcpf(1.0f + eneg(b1[k])); }
;                     po.put(bj, pack8(v0, v1)); }
;                 po.flush<false>(ai, m);
;                 asm volatile("" ::: "memory"); }
	v_lshlrev_b32_e32 v62, 16, v74
	v_and_b32_e32 v63, 0xffff0000, v74
	v_lshlrev_b32_e32 v66, 16, v76
	v_add_f32_e32 v62, v138, v62
	v_add_f32_e32 v66, v134, v66
	v_add_f32_e32 v63, v139, v63
	v_med3_f32 v62, v62, s85, v226
	v_med3_f32 v66, v66, s85, v226
	v_med3_f32 v63, v63, s85, v226
	v_mul_f32_e32 v62, 0xbfb8aa3b, v62
	v_mul_f32_e32 v66, 0xbfb8aa3b, v66
	v_mul_f32_e32 v63, 0xbfb8aa3b, v63
	v_exp_f32_e32 v62, v62
	v_exp_f32_e32 v66, v66
	v_exp_f32_e32 v63, v63
	v_and_b32_e32 v67, 0xffff0000, v76
	v_add_f32_e32 v62, 1.0, v62
	v_add_f32_e32 v66, 1.0, v66
	v_add_f32_e32 v63, 1.0, v63
	v_add_f32_e32 v67, v135, v67
	v_rcp_f32_e32 v62, v62
	v_rcp_f32_e32 v66, v66
	v_rcp_f32_e32 v63, v63
	v_med3_f32 v67, v67, s85, v226
	v_mul_f32_e32 v67, 0xbfb8aa3b, v67
	v_exp_f32_e32 v67, v67
	v_lshlrev_b32_e32 v64, 16, v75
	v_lshlrev_b32_e32 v68, 16, v77
	v_mul_f32_e32 v58, v58, v62
	v_mul_f32_e32 v62, v54, v66
	v_mul_f32_e32 v54, v59, v63
	v_add_f32_e32 v63, v140, v64
	v_add_f32_e32 v64, v136, v68
	v_med3_f32 v63, v63, s85, v226
	v_med3_f32 v64, v64, s85, v226
	v_add_f32_e32 v59, 1.0, v67
	v_mul_f32_e32 v63, 0xbfb8aa3b, v63
	v_mul_f32_e32 v64, 0xbfb8aa3b, v64
	v_rcp_f32_e32 v59, v59
	v_exp_f32_e32 v63, v63
	v_exp_f32_e32 v64, v64
	v_and_b32_e32 v65, 0xffff0000, v75
	v_and_b32_e32 v69, 0xffff0000, v77
	v_mul_f32_e32 v59, v55, v59
	v_add_f32_e32 v55, 1.0, v63
	v_add_f32_e32 v63, 1.0, v64
	v_add_f32_e32 v64, v141, v65
	v_add_f32_e32 v65, v137, v69
	v_med3_f32 v64, v64, s85, v226
	v_med3_f32 v65, v65, s85, v226
	v_mul_f32_e32 v64, 0xbfb8aa3b, v64
	v_mul_f32_e32 v65, 0xbfb8aa3b, v65
	v_exp_f32_e32 v64, v64
	v_exp_f32_e32 v65, v65
	v_rcp_f32_e32 v55, v55
	v_rcp_f32_e32 v63, v63
	v_add_f32_e32 v64, 1.0, v64
	v_add_f32_e32 v65, 1.0, v65
	v_rcp_f32_e32 v64, v64
	v_rcp_f32_e32 v65, v65
	v_mul_f32_e32 v55, v60, v55
	v_mul_f32_e32 v60, v56, v63
	v_mul_f32_e32 v56, v61, v64
	v_mul_f32_e32 v57, v57, v65
	v_cvt_pk_bf16_f32 v54, v58, v54
	v_cvt_pk_bf16_f32 v55, v55, v56
	v_cvt_pk_bf16_f32 v56, v62, v59
	v_cvt_pk_bf16_f32 v57, v60, v57
	ds_write_b128 v227, v[54:57] offset:64
	ds_read_b128 v[54:57], v3
	ds_read_b128 v[58:61], v3 offset:1152
	v_add_co_u32_e32 v62, vcc, s79, v4
	s_nop 1
	v_addc_co_u32_e32 v63, vcc, 0, v5, vcc
	v_add_co_u32_e32 v4, vcc, s86, v4
	s_nop 1
	v_addc_co_u32_e32 v5, vcc, 0, v5, vcc
	s_waitcnt lgkmcnt(1)
	global_store_dwordx4 v[4:5], v[54:57], off offset:-4096 sc1
	s_waitcnt lgkmcnt(0)
	global_store_dwordx4 v[62:63], v[58:61], off offset:1024 sc1
	ds_write_b128 v3, v[166:169]
	ds_write_b128 v3, v[170:173] offset:1152
	ds_read_b128 v[54:57], v227
	ds_read_b128 v[58:61], v227 offset:64
	s_andn2_b64 vcc, exec, s[4:5]
	s_mov_b64 s[4:5], -1
	s_waitcnt lgkmcnt(1)
	v_lshlrev_b32_e32 v64, 16, v54
	v_and_b32_e32 v54, 0xffff0000, v54
	v_lshlrev_b32_e32 v66, 16, v56
	v_add_f32_e32 v64, v146, v64
	v_add_f32_e32 v66, v142, v66
	v_add_f32_e32 v54, v147, v54
	v_med3_f32 v64, v64, s85, v226
	v_med3_f32 v66, v66, s85, v226
	v_med3_f32 v54, v54, s85, v226
	v_mul_f32_e32 v64, 0xbfb8aa3b, v64
	v_mul_f32_e32 v66, 0xbfb8aa3b, v66
	v_mul_f32_e32 v54, 0xbfb8aa3b, v54
	v_exp_f32_e32 v64, v64
	v_exp_f32_e32 v66, v66
	v_exp_f32_e32 v54, v54
	v_and_b32_e32 v56, 0xffff0000, v56
	v_add_f32_e32 v56, v143, v56
	v_med3_f32 v56, v56, s85, v226
	v_add_f32_e32 v64, 1.0, v64
	v_add_f32_e32 v66, 1.0, v66
	v_add_f32_e32 v54, 1.0, v54
	v_mul_f32_e32 v56, 0xbfb8aa3b, v56
	v_rcp_f32_e32 v64, v64
	v_rcp_f32_e32 v66, v66
	v_rcp_f32_e32 v54, v54
	v_exp_f32_e32 v56, v56
	v_lshlrev_b32_e32 v65, 16, v55
	v_lshlrev_b32_e32 v67, 16, v57
	v_mul_f32_e32 v50, v50, v64
	v_mul_f32_e32 v64, v46, v66
	v_mul_f32_e32 v46, v51, v54
	v_add_f32_e32 v51, 1.0, v56
	v_add_f32_e32 v54, v148, v65
	v_add_f32_e32 v56, v144, v67
	v_med3_f32 v54, v54, s85, v226
	v_med3_f32 v56, v56, s85, v226
	v_mul_f32_e32 v54, 0xbfb8aa3b, v54
	v_mul_f32_e32 v56, 0xbfb8aa3b, v56
	v_rcp_f32_e32 v51, v51
	v_exp_f32_e32 v54, v54
	v_exp_f32_e32 v56, v56
	v_and_b32_e32 v55, 0xffff0000, v55
	v_and_b32_e32 v57, 0xffff0000, v57
	v_mul_f32_e32 v51, v47, v51
	v_add_f32_e32 v47, 1.0, v54
	v_add_f32_e32 v54, 1.0, v56
	v_add_f32_e32 v55, v149, v55
	v_add_f32_e32 v56, v145, v57
	v_med3_f32 v55, v55, s85, v226
	v_med3_f32 v56, v56, s85, v226
	v_mul_f32_e32 v55, 0xbfb8aa3b, v55
	v_mul_f32_e32 v56, 0xbfb8aa3b, v56
	v_exp_f32_e32 v55, v55
	v_exp_f32_e32 v56, v56
	v_rcp_f32_e32 v47, v47
	v_rcp_f32_e32 v54, v54
	v_add_f32_e32 v55, 1.0, v55
	v_add_f32_e32 v56, 1.0, v56
	v_rcp_f32_e32 v55, v55
	v_rcp_f32_e32 v56, v56
	v_mul_f32_e32 v47, v52, v47
	v_mul_f32_e32 v52, v48, v54
	v_mul_f32_e32 v48, v53, v55
	v_mul_f32_e32 v49, v49, v56
	v_cvt_pk_bf16_f32 v46, v50, v46
	v_cvt_pk_bf16_f32 v47, v47, v48
	v_cvt_pk_bf16_f32 v48, v64, v51
	v_cvt_pk_bf16_f32 v49, v52, v49
	ds_write_b128 v227, v[46:49]
	s_waitcnt lgkmcnt(1)
; __device__ __forceinline__ u32x4 pack8(const f32x4& v0, const f32x4& v1) { u32x4 w; w.x = cvt_pk_bf16(v0[0], v0[1]); w.y = cvt_pk_bf16(v0[2], v0[3]); w.z = cvt_pk_bf16(v1[0], v1[1]); w.w = cvt_pk_bf16(v1[2], v1[3]); return w; }
; #define UNPK0(q_) ((f32x4){bf_lo((q_).x), bf_hi((q_).x), bf_lo((q_).y), bf_hi((q_).y)})
; #define UNPK1(q_) ((f32x4){bf_lo((q_).z), bf_hi((q_).z), bf_lo((q_).w), bf_hi((q_).w)})
;     static __device__ __forceinline__ float eneg(float g) { return __builtin_amdgcn_exp2f(-1.4426950408889634f * fminf(fmaxf(g, -30.f), 30.f)); }
;     __device__ __forceinline__ void operator()(const f32x4 (&acc)[2][2][4][2], const Unit& u, int wr, int wc, int fr, int fq) const {
;     ...
;         for (int ai = 0; ai < 2; ++ai)
; #pragma unroll
;             for (int m = 0; m < 4; ++m) {
;                 pb.stage(rb[ai][m][0], rb[ai][m][1]); const u32x4 gb0 = pb.get(0), gb1 = pb.get(1);
;                 asm volatile("" ::: "memory");
; #pragma unroll
;                 for (int bj = 0; bj < 2; ++bj) { const u32x4 gb = bj ? gb1 : gb0;
;                     const f32x4 b0 = UNPK0(gb) + bb[bj][0], b1 = UNPK1(gb) + bb[bj][1];
;                     f32x4 v0 = acc[ai][bj][m][0], v1 = acc[ai][bj][m][1];
; #pragma unroll
;                     for (int k = 0; k < 4; ++k) { v0[k] *= __builtin_amdgcn_rcpf(1.0f + eneg(b0[k])); v1[k] *= __builtin_amdgcn_rcpf(1.0f + eneg(b1[k])); }
;                     po.put(bj, pack8(v0, v1)); }
;                 po.flush<false>(ai, m);
;                 asm volatile("" ::: "memory"); }
	v_lshlrev_b32_e32 v46, 16, v58
	v_and_b32_e32 v47, 0xffff0000, v58
	v_lshlrev_b32_e32 v50, 16, v60
	v_add_f32_e32 v46, v138, v46
	v_add_f32_e32 v50, v134, v50
	v_add_f32_e32 v47, v139, v47
	v_med3_f32 v46, v46, s85, v226
	v_med3_f32 v50, v50, s85, v226
	v_med3_f32 v47, v47, s85, v226
	v_mul_f32_e32 v46, 0xbfb8aa3b, v46
	v_mul_f32_e32 v50, 0xbfb8aa3b, v50
	v_mul_f32_e32 v47, 0xbfb8aa3b, v47
	v_exp_f32_e32 v46, v46
	v_exp_f32_e32 v50, v50
	v_exp_f32_e32 v47, v47
	v_and_b32_e32 v51, 0xffff0000, v60
	v_add_f32_e32 v46, 1.0, v46
	v_add_f32_e32 v50, 1.0, v50
	v_add_f32_e32 v47, 1.0, v47
	v_add_f32_e32 v51, v135, v51
	v_rcp_f32_e32 v46, v46
	v_rcp_f32_e32 v50, v50
	v_rcp_f32_e32 v47, v47
	v_med3_f32 v51, v51, s85, v226
	v_mul_f32_e32 v51, 0xbfb8aa3b, v51
	v_exp_f32_e32 v51, v51
	v_lshlrev_b32_e32 v48, 16, v59
	v_lshlrev_b32_e32 v52, 16, v61
	v_mul_f32_e32 v42, v42, v46
	v_mul_f32_e32 v46, v38, v50
	v_mul_f32_e32 v38, v43, v47
	v_add_f32_e32 v47, v140, v48
	v_add_f32_e32 v48, v136, v52
	v_med3_f32 v47, v47, s85, v226
	v_med3_f32 v48, v48, s85, v226
	v_add_f32_e32 v43, 1.0, v51
	v_mul_f32_e32 v47, 0xbfb8aa3b, v47
	v_mul_f32_e32 v48, 0xbfb8aa3b, v48
	v_rcp_f32_e32 v43, v43
	v_exp_f32_e32 v47, v47
	v_exp_f32_e32 v48, v48
	v_and_b32_e32 v49, 0xffff0000, v59
	v_and_b32_e32 v53, 0xffff0000, v61
	v_mul_f32_e32 v43, v39, v43
	v_add_f32_e32 v39, 1.0, v47
	v_add_f32_e32 v47, 1.0, v48
	v_add_f32_e32 v48, v141, v49
	v_add_f32_e32 v49, v137, v53
	v_med3_f32 v48, v48, s85, v226
	v_med3_f32 v49, v49, s85, v226
	v_mul_f32_e32 v48, 0xbfb8aa3b, v48
	v_mul_f32_e32 v49, 0xbfb8aa3b, v49
	v_exp_f32_e32 v48, v48
	v_exp_f32_e32 v49, v49
	v_rcp_f32_e32 v39, v39
	v_rcp_f32_e32 v47, v47
	v_add_f32_e32 v48, 1.0, v48
	v_add_f32_e32 v49, 1.0, v49
	v_rcp_f32_e32 v48, v48
	v_rcp_f32_e32 v49, v49
	v_mul_f32_e32 v39, v44, v39
	v_mul_f32_e32 v44, v40, v47
	v_mul_f32_e32 v40, v45, v48
	v_mul_f32_e32 v41, v41, v49
	v_cvt_pk_bf16_f32 v38, v42, v38
	v_cvt_pk_bf16_f32 v39, v39, v40
	v_cvt_pk_bf16_f32 v40, v46, v43
	v_cvt_pk_bf16_f32 v41, v44, v41
	ds_write_b128 v227, v[38:41] offset:64
	ds_read_b128 v[38:41], v3
	ds_read_b128 v[42:45], v3 offset:1152
	s_waitcnt lgkmcnt(1)
	global_store_dwordx4 v[62:63], v[38:41], off offset:2048 sc1
	s_waitcnt lgkmcnt(0)
	global_store_dwordx4 v[62:63], v[42:45], off offset:3072 sc1
	ds_write_b128 v3, v[158:161]
	ds_write_b128 v3, v[162:165] offset:1152
	ds_read_b128 v[38:41], v227
	ds_read_b128 v[42:45], v227 offset:64
	s_waitcnt lgkmcnt(1)
	v_lshlrev_b32_e32 v46, 16, v38
	v_and_b32_e32 v38, 0xffff0000, v38
	v_lshlrev_b32_e32 v48, 16, v40
	v_add_f32_e32 v46, v146, v46
	v_add_f32_e32 v48, v142, v48
	v_add_f32_e32 v38, v147, v38
	v_med3_f32 v46, v46, s85, v226
	v_med3_f32 v48, v48, s85, v226
	v_med3_f32 v38, v38, s85, v226
	v_mul_f32_e32 v46, 0xbfb8aa3b, v46
	v_mul_f32_e32 v48, 0xbfb8aa3b, v48
	v_mul_f32_e32 v38, 0xbfb8aa3b, v38
	v_exp_f32_e32 v46, v46
	v_exp_f32_e32 v48, v48
	v_exp_f32_e32 v38, v38
	v_and_b32_e32 v40, 0xffff0000, v40
	v_add_f32_e32 v40, v143, v40
	v_med3_f32 v40, v40, s85, v226
	v_add_f32_e32 v46, 1.0, v46
	v_add_f32_e32 v48, 1.0, v48
	v_add_f32_e32 v38, 1.0, v38
	v_mul_f32_e32 v40, 0xbfb8aa3b, v40
	v_rcp_f32_e32 v46, v46
	v_rcp_f32_e32 v48, v48
	v_rcp_f32_e32 v38, v38
	v_exp_f32_e32 v40, v40
	v_lshlrev_b32_e32 v47, 16, v39
	v_lshlrev_b32_e32 v49, 16, v41
	v_mul_f32_e32 v34, v34, v46
	v_mul_f32_e32 v46, v30, v48
	v_mul_f32_e32 v30, v35, v38
	v_add_f32_e32 v35, 1.0, v40
	v_add_f32_e32 v38, v148, v47
	v_add_f32_e32 v40, v144, v49
	v_med3_f32 v38, v38, s85, v226
	v_med3_f32 v40, v40, s85, v226
	v_mul_f32_e32 v38, 0xbfb8aa3b, v38
	v_mul_f32_e32 v40, 0xbfb8aa3b, v40
	v_rcp_f32_e32 v35, v35
	v_exp_f32_e32 v38, v38
	v_exp_f32_e32 v40, v40
	v_and_b32_e32 v39, 0xffff0000, v39
	v_and_b32_e32 v41, 0xffff0000, v41
	v_mul_f32_e32 v35, v31, v35
	v_add_f32_e32 v31, 1.0, v38
	v_add_f32_e32 v38, 1.0, v40
	v_add_f32_e32 v39, v149, v39
	v_add_f32_e32 v40, v145, v41
	v_med3_f32 v39, v39, s85, v226
	v_med3_f32 v40, v40, s85, v226
	v_mul_f32_e32 v39, 0xbfb8aa3b, v39
	v_mul_f32_e32 v40, 0xbfb8aa3b, v40
	v_exp_f32_e32 v39, v39
	v_exp_f32_e32 v40, v40
	v_rcp_f32_e32 v31, v31
	v_rcp_f32_e32 v38, v38
	v_add_f32_e32 v39, 1.0, v39
	v_add_f32_e32 v40, 1.0, v40
	v_rcp_f32_e32 v39, v39
	v_rcp_f32_e32 v40, v40
	v_mul_f32_e32 v31, v36, v31
	v_mul_f32_e32 v36, v32, v38
	v_mul_f32_e32 v32, v37, v39
	v_mul_f32_e32 v33, v33, v40
	v_cvt_pk_bf16_f32 v30, v34, v30
	v_cvt_pk_bf16_f32 v31, v31, v32
	v_cvt_pk_bf16_f32 v32, v46, v35
	v_cvt_pk_bf16_f32 v33, v36, v33
	ds_write_b128 v227, v[30:33]
	s_waitcnt lgkmcnt(1)
; __device__ __forceinline__ u32x4 pack8(const f32x4& v0, const f32x4& v1) { u32x4 w; w.x = cvt_pk_bf16(v0[0], v0[1]); w.y = cvt_pk_bf16(v0[2], v0[3]); w.z = cvt_pk_bf16(v1[0], v1[1]); w.w = cvt_pk_bf16(v1[2], v1[3]); return w; }
; #define UNPK0(q_) ((f32x4){bf_lo((q_).x), bf_hi((q_).x), bf_lo((q_).y), bf_hi((q_).y)})
; #define UNPK1(q_) ((f32x4){bf_lo((q_).z), bf_hi((q_).z), bf_lo((q_).w), bf_hi((q_).w)})
;     static __device__ __forceinline__ float eneg(float g) { return __builtin_amdgcn_exp2f(-1.4426950408889634f * fminf(fmaxf(g, -30.f), 30.f)); }
;     __device__ __forceinline__ void operator()(const f32x4 (&acc)[2][2][4][2], const Unit& u, int wr, int wc, int fr, int fq) const {
;     ...
;         for (int ai = 0; ai < 2; ++ai)
; #pragma unroll
;             for (int m = 0; m < 4; ++m) {
;                 pb.stage(rb[ai][m][0], rb[ai][m][1]); const u32x4 gb0 = pb.get(0), gb1 = pb.get(1);
;                 asm volatile("" ::: "memory");
; #pragma unroll
;                 for (int bj = 0; bj < 2; ++bj) { const u32x4 gb = bj ? gb1 : gb0;
;                     const f32x4 b0 = UNPK0(gb) + bb[bj][0], b1 = UNPK1(gb) + bb[bj][1];
;                     f32x4 v0 = acc[ai][bj][m][0], v1 = acc[ai][bj][m][1];
; #pragma unroll
;                     for (int k = 0; k < 4; ++k) { v0[k] *= __builtin_amdgcn_rcpf(1.0f + eneg(b0[k])); v1[k] *= __builtin_amdgcn_rcpf(1.0f + eneg(b1[k])); }
;                     po.put(bj, pack8(v0, v1)); }
;                 po.flush<false>(ai, m);
;                 asm volatile("" ::: "memory"); }
	v_lshlrev_b32_e32 v30, 16, v42
	v_and_b32_e32 v31, 0xffff0000, v42
	v_lshlrev_b32_e32 v34, 16, v44
	v_add_f32_e32 v30, v138, v30
	v_add_f32_e32 v34, v134, v34
	v_add_f32_e32 v31, v139, v31
	v_med3_f32 v30, v30, s85, v226
	v_med3_f32 v34, v34, s85, v226
	v_med3_f32 v31, v31, s85, v226
	v_mul_f32_e32 v30, 0xbfb8aa3b, v30
	v_mul_f32_e32 v34, 0xbfb8aa3b, v34
	v_mul_f32_e32 v31, 0xbfb8aa3b, v31
	v_exp_f32_e32 v30, v30
	v_exp_f32_e32 v34, v34
	v_exp_f32_e32 v31, v31
	v_and_b32_e32 v35, 0xffff0000, v44
	v_add_f32_e32 v30, 1.0, v30
	v_add_f32_e32 v34, 1.0, v34
	v_add_f32_e32 v31, 1.0, v31
	v_add_f32_e32 v35, v135, v35
	v_rcp_f32_e32 v30, v30
	v_rcp_f32_e32 v34, v34
	v_rcp_f32_e32 v31, v31
	v_med3_f32 v35, v35, s85, v226
	v_mul_f32_e32 v35, 0xbfb8aa3b, v35
	v_exp_f32_e32 v35, v35
	v_lshlrev_b32_e32 v32, 16, v43
	v_lshlrev_b32_e32 v36, 16, v45
	v_mul_f32_e32 v26, v26, v30
	v_mul_f32_e32 v30, v22, v34
	v_mul_f32_e32 v22, v27, v31
	v_add_f32_e32 v31, v140, v32
	v_add_f32_e32 v32, v136, v36
	v_med3_f32 v31, v31, s85, v226
	v_med3_f32 v32, v32, s85, v226
	v_add_f32_e32 v27, 1.0, v35
	v_mul_f32_e32 v31, 0xbfb8aa3b, v31
	v_mul_f32_e32 v32, 0xbfb8aa3b, v32
	v_rcp_f32_e32 v27, v27
	v_exp_f32_e32 v31, v31
	v_exp_f32_e32 v32, v32
	v_and_b32_e32 v33, 0xffff0000, v43
	v_and_b32_e32 v37, 0xffff0000, v45
	v_mul_f32_e32 v27, v23, v27
	v_add_f32_e32 v23, 1.0, v31
	v_add_f32_e32 v31, 1.0, v32
	v_add_f32_e32 v32, v141, v33
	v_add_f32_e32 v33, v137, v37
	v_med3_f32 v32, v32, s85, v226
	v_med3_f32 v33, v33, s85, v226
	v_mul_f32_e32 v32, 0xbfb8aa3b, v32
	v_mul_f32_e32 v33, 0xbfb8aa3b, v33
	v_exp_f32_e32 v32, v32
	v_exp_f32_e32 v33, v33
	v_rcp_f32_e32 v23, v23
	v_rcp_f32_e32 v31, v31
	v_add_f32_e32 v32, 1.0, v32
	v_add_f32_e32 v33, 1.0, v33
	v_rcp_f32_e32 v32, v32
	v_rcp_f32_e32 v33, v33
	v_mul_f32_e32 v23, v28, v23
	v_mul_f32_e32 v28, v24, v31
	v_mul_f32_e32 v24, v29, v32
	v_mul_f32_e32 v25, v25, v33
	v_cvt_pk_bf16_f32 v22, v26, v22
	v_cvt_pk_bf16_f32 v23, v23, v24
	v_cvt_pk_bf16_f32 v24, v30, v27
	v_cvt_pk_bf16_f32 v25, v28, v25
	ds_write_b128 v227, v[22:25] offset:64
	ds_read_b128 v[22:25], v3
	ds_read_b128 v[26:29], v3 offset:1152
	s_waitcnt lgkmcnt(1)
	global_store_dwordx4 v[4:5], v[22:25], off sc1
	s_waitcnt lgkmcnt(0)
	global_store_dwordx4 v[4:5], v[26:29], off offset:1024 sc1
	ds_write_b128 v3, v[150:153]
	ds_write_b128 v3, v[154:157] offset:1152
	ds_read_b128 v[22:25], v227
	ds_read_b128 v[26:29], v227 offset:64
	s_waitcnt lgkmcnt(1)
	v_lshlrev_b32_e32 v30, 16, v22
	v_and_b32_e32 v22, 0xffff0000, v22
	v_lshlrev_b32_e32 v32, 16, v24
	v_add_f32_e32 v30, v146, v30
	v_add_f32_e32 v32, v142, v32
	v_add_f32_e32 v22, v147, v22
	v_med3_f32 v30, v30, s85, v226
	v_med3_f32 v32, v32, s85, v226
	v_med3_f32 v22, v22, s85, v226
	v_mul_f32_e32 v30, 0xbfb8aa3b, v30
	v_mul_f32_e32 v32, 0xbfb8aa3b, v32
	v_mul_f32_e32 v22, 0xbfb8aa3b, v22
	v_exp_f32_e32 v30, v30
	v_exp_f32_e32 v32, v32
	v_exp_f32_e32 v22, v22
	v_and_b32_e32 v24, 0xffff0000, v24
	v_add_f32_e32 v24, v143, v24
	v_med3_f32 v24, v24, s85, v226
	v_add_f32_e32 v30, 1.0, v30
	v_add_f32_e32 v32, 1.0, v32
	v_add_f32_e32 v22, 1.0, v22
	v_mul_f32_e32 v24, 0xbfb8aa3b, v24
	v_rcp_f32_e32 v30, v30
	v_rcp_f32_e32 v32, v32
	v_rcp_f32_e32 v22, v22
	v_exp_f32_e32 v24, v24
	v_lshlrev_b32_e32 v31, 16, v23
	v_lshlrev_b32_e32 v33, 16, v25
	v_mul_f32_e32 v18, v18, v30
	v_mul_f32_e32 v30, v14, v32
	v_mul_f32_e32 v14, v19, v22
	v_add_f32_e32 v19, 1.0, v24
	v_add_f32_e32 v22, v148, v31
	v_add_f32_e32 v24, v144, v33
	v_med3_f32 v22, v22, s85, v226
	v_med3_f32 v24, v24, s85, v226
	v_mul_f32_e32 v22, 0xbfb8aa3b, v22
	v_mul_f32_e32 v24, 0xbfb8aa3b, v24
	v_rcp_f32_e32 v19, v19
	v_exp_f32_e32 v22, v22
	v_exp_f32_e32 v24, v24
	v_and_b32_e32 v23, 0xffff0000, v23
	v_and_b32_e32 v25, 0xffff0000, v25
	v_mul_f32_e32 v19, v15, v19
	v_add_f32_e32 v15, 1.0, v22
	v_add_f32_e32 v22, 1.0, v24
	v_add_f32_e32 v23, v149, v23
	v_add_f32_e32 v24, v145, v25
	v_med3_f32 v23, v23, s85, v226
	v_med3_f32 v24, v24, s85, v226
	v_mul_f32_e32 v23, 0xbfb8aa3b, v23
	v_mul_f32_e32 v24, 0xbfb8aa3b, v24
	v_exp_f32_e32 v23, v23
	v_exp_f32_e32 v24, v24
	v_rcp_f32_e32 v15, v15
	v_rcp_f32_e32 v22, v22
	v_add_f32_e32 v23, 1.0, v23
	v_add_f32_e32 v24, 1.0, v24
	v_rcp_f32_e32 v23, v23
	v_rcp_f32_e32 v24, v24
	v_mul_f32_e32 v15, v20, v15
	v_mul_f32_e32 v20, v16, v22
	v_mul_f32_e32 v16, v21, v23
	v_mul_f32_e32 v17, v17, v24
	v_cvt_pk_bf16_f32 v14, v18, v14
	v_cvt_pk_bf16_f32 v15, v15, v16
	v_cvt_pk_bf16_f32 v16, v30, v19
	v_cvt_pk_bf16_f32 v17, v20, v17
	ds_write_b128 v227, v[14:17]
	s_waitcnt lgkmcnt(1)
	v_lshlrev_b32_e32 v14, 16, v26
	v_and_b32_e32 v15, 0xffff0000, v26
	v_lshlrev_b32_e32 v18, 16, v28
	v_add_f32_e32 v14, v138, v14
	v_add_f32_e32 v18, v134, v18
	v_add_f32_e32 v15, v139, v15
	v_med3_f32 v14, v14, s85, v226
	v_med3_f32 v18, v18, s85, v226
	v_med3_f32 v15, v15, s85, v226
	v_mul_f32_e32 v14, 0xbfb8aa3b, v14
	v_mul_f32_e32 v18, 0xbfb8aa3b, v18
	v_mul_f32_e32 v15, 0xbfb8aa3b, v15
	v_exp_f32_e32 v14, v14
	v_exp_f32_e32 v18, v18
	v_exp_f32_e32 v15, v15
	v_and_b32_e32 v19, 0xffff0000, v28
	v_add_f32_e32 v14, 1.0, v14
	v_add_f32_e32 v18, 1.0, v18
	v_add_f32_e32 v15, 1.0, v15
	v_add_f32_e32 v19, v135, v19
	v_rcp_f32_e32 v14, v14
	v_rcp_f32_e32 v18, v18
	v_rcp_f32_e32 v15, v15
	v_med3_f32 v19, v19, s85, v226
	v_mul_f32_e32 v19, 0xbfb8aa3b, v19
	v_exp_f32_e32 v19, v19
	v_lshlrev_b32_e32 v16, 16, v27
	v_lshlrev_b32_e32 v20, 16, v29
	v_mul_f32_e32 v10, v10, v14
	v_mul_f32_e32 v14, v6, v18
	v_mul_f32_e32 v6, v11, v15
	v_add_f32_e32 v15, v140, v16
	v_add_f32_e32 v16, v136, v20
	v_med3_f32 v15, v15, s85, v226
	v_med3_f32 v16, v16, s85, v226
	v_add_f32_e32 v11, 1.0, v19
	v_mul_f32_e32 v15, 0xbfb8aa3b, v15
	v_mul_f32_e32 v16, 0xbfb8aa3b, v16
	v_rcp_f32_e32 v11, v11
	v_exp_f32_e32 v15, v15
	v_exp_f32_e32 v16, v16
	v_and_b32_e32 v17, 0xffff0000, v27
	v_and_b32_e32 v21, 0xffff0000, v29
	v_mul_f32_e32 v11, v7, v11
	v_add_f32_e32 v7, 1.0, v15
	v_add_f32_e32 v15, 1.0, v16
	v_add_f32_e32 v16, v141, v17
	v_add_f32_e32 v17, v137, v21
	v_med3_f32 v16, v16, s85, v226
	v_med3_f32 v17, v17, s85, v226
	v_mul_f32_e32 v16, 0xbfb8aa3b, v16
	v_mul_f32_e32 v17, 0xbfb8aa3b, v17
	v_exp_f32_e32 v16, v16
	v_exp_f32_e32 v17, v17
	v_rcp_f32_e32 v7, v7
	v_rcp_f32_e32 v15, v15
	v_add_f32_e32 v16, 1.0, v16
	v_add_f32_e32 v17, 1.0, v17
	v_rcp_f32_e32 v16, v16
	v_rcp_f32_e32 v17, v17
	v_mul_f32_e32 v7, v12, v7
	v_mul_f32_e32 v12, v8, v15
	v_mul_f32_e32 v8, v13, v16
	v_mul_f32_e32 v9, v9, v17
	v_cvt_pk_bf16_f32 v6, v10, v6
	v_cvt_pk_bf16_f32 v7, v7, v8
	v_cvt_pk_bf16_f32 v8, v14, v11
	v_cvt_pk_bf16_f32 v9, v12, v9
	ds_write_b128 v227, v[6:9] offset:64
	ds_read_b128 v[6:9], v3
	ds_read_b128 v[10:13], v3 offset:1152
	s_waitcnt lgkmcnt(1)
	global_store_dwordx4 v[4:5], v[6:9], off offset:2048 sc1
	s_waitcnt lgkmcnt(0)
	global_store_dwordx4 v[4:5], v[10:13], off offset:3072 sc1
	s_cbranch_vccnz .LBB0_372
	s_andn2_b64 vcc, exec, s[10:11]
	s_cbranch_vccnz .LBB0_371
	s_barrier
	s_branch .LBB0_371

; __device__ __forceinline__ u32x4 pack8(const f32x4& v0, const f32x4& v1) { u32x4 w; w.x = cvt_pk_bf16(v0[0], v0[1]); w.y = cvt_pk_bf16(v0[2], v0[3]); w.z = cvt_pk_bf16(v1[0], v1[1]); w.w = cvt_pk_bf16(v1[2], v1[3]); return w; }
;     __device__ __forceinline__ void operator()(const f32x4 (&acc)[2][2][4][2], const Unit& u, int wr, int wc, int fr, int fq) const {
;     ...
;             for (int m = 0; m < 4; ++m) { const float* xp = x + (size_t)(row0 + ai * HALF + m * 16) * 1024 + col0;
; #pragma unroll
;                 for (int bj = 0; bj < 2; ++bj) { xv[m][bj][0] = *(const f32x4*)(xp + bj * 32); xv[m][bj][1] = *(const f32x4*)(xp + bj * 32 + 4); } }
;             asm volatile("" ::: "memory");
; #pragma unroll
;             for (int m = 0; m < 4; ++m) { const int row = row0 + ai * HALF + m * 16; float sq = 0.f;
; #pragma unroll
;                 for (int bj = 0; bj < 2; ++bj) { const f32x4 o0 = xv[m][bj][0] + acc[ai][bj][m][0], o1 = xv[m][bj][1] + acc[ai][bj][m][1];
;                     sq += ((o0[0] * o0[0] + o0[1] * o0[1]) + (o0[2] * o0[2] + o0[3] * o0[3])) + ((o1[0] * o1[0] + o1[1] * o1[1]) + (o1[2] * o1[2] + o1[3] * o1[3]));
;                     po.put(bj, pack8(o0, o1)); }
;                 po.flush<false>(ai, m);
;                 sq += __shfl_xor(sq, 16); sq += __shfl_xor(sq, 32);
;                 if (fq == 0) atomicAdd(ss + row, sq); }
.LBB0_480:
	v_lshl_add_u32 v216, s46, 8, v198
	v_lshl_or_b32 v130, s48, 8, v200
	v_ashrrev_i32_e32 v131, 31, v130
	v_ashrrev_i32_e32 v217, 31, v216
	v_lshl_add_u64 v[130:131], v[130:131], 2, s[36:37]
	v_lshlrev_b64 v[132:133], 12, v[216:217]
	v_lshl_add_u64 v[196:197], v[130:131], 0, v[132:133]
	global_load_dwordx4 v[208:211], v[196:197], off
	global_load_dwordx4 v[212:215], v[196:197], off offset:16
	global_load_dwordx4 v[220:223], v[196:197], off offset:128
	global_load_dwordx4 v[224:227], v[196:197], off offset:144
	v_or_b32_e32 v132, 16, v216
	v_or_b32_e32 v134, 32, v216
	v_or_b32_e32 v136, 48, v216
	v_ashrrev_i32_e32 v133, 31, v132
	v_ashrrev_i32_e32 v135, 31, v134
	v_ashrrev_i32_e32 v137, 31, v136
	v_lshlrev_b64 v[132:133], 12, v[132:133]
	v_lshlrev_b64 v[134:135], 12, v[134:135]
	v_lshlrev_b64 v[136:137], 12, v[136:137]
	v_lshl_add_u64 v[132:133], v[130:131], 0, v[132:133]
	v_lshl_add_u64 v[134:135], v[130:131], 0, v[134:135]
	v_lshl_add_u64 v[136:137], v[130:131], 0, v[136:137]
	global_load_dwordx4 v[170:173], v[132:133], off offset:16
	global_load_dwordx4 v[174:177], v[132:133], off
	global_load_dwordx4 v[162:165], v[132:133], off offset:144
	global_load_dwordx4 v[166:169], v[132:133], off offset:128
	global_load_dwordx4 v[154:157], v[134:135], off offset:16
	global_load_dwordx4 v[158:161], v[134:135], off
	global_load_dwordx4 v[146:149], v[134:135], off offset:144
	global_load_dwordx4 v[150:153], v[134:135], off offset:128
	global_load_dwordx4 v[138:141], v[136:137], off offset:16
	global_load_dwordx4 v[142:145], v[136:137], off
	global_load_dwordx4 v[130:133], v[136:137], off offset:144
	s_nop 0
	global_load_dwordx4 v[134:137], v[136:137], off offset:128
	v_and_b32_e32 v219, 64, v204
	v_xor_b32_e32 v207, 16, v204
	v_add_u32_e32 v219, 64, v219
	v_cmp_lt_i32_e32 vcc, v207, v219
	s_lshl_b32 s27, s48, 2
	s_or_b32 s50, s27, s58
	s_ashr_i32 s47, s46, 31
	s_ashr_i32 s51, s50, 31
	s_lshl_b64 s[46:47], s[46:47], 19
	s_lshl_b64 s[50:51], s[50:51], 15
	s_add_u32 s27, s62, s46
	s_addc_u32 s29, s63, s47
	s_add_u32 s27, s27, s50
	s_addc_u32 s29, s29, s51
	s_add_u32 s46, s27, s16
	s_addc_u32 s47, s29, s17
	s_waitcnt vmcnt(0)
	v_pk_add_f32 v[128:129], v[128:129], v[210:211]
	v_pk_add_f32 v[126:127], v[126:127], v[208:209]
	v_pk_add_f32 v[124:125], v[124:125], v[214:215]
	v_pk_add_f32 v[122:123], v[122:123], v[212:213]
	v_pk_add_f32 v[120:121], v[120:121], v[222:223]
	v_pk_add_f32 v[118:119], v[118:119], v[220:221]
	v_pk_add_f32 v[208:209], v[116:117], v[226:227]
	v_pk_add_f32 v[210:211], v[114:115], v[224:225]
	v_mul_f32_e32 v212, v127, v127
	v_mul_f32_e32 v213, v129, v129
	v_mul_f32_e32 v214, v123, v123
	v_mul_f32_e32 v215, v125, v125
	v_cvt_pk_bf16_f32 v114, v126, v127
	v_cvt_pk_bf16_f32 v115, v128, v129
	v_cvt_pk_bf16_f32 v116, v122, v123
	v_cvt_pk_bf16_f32 v117, v124, v125
	v_mul_f32_e32 v123, v119, v119
	v_mul_f32_e32 v125, v121, v121
	v_mul_f32_e32 v127, v211, v211
	v_mul_f32_e32 v129, v209, v209
	v_fmac_f32_e32 v212, v126, v126
	v_fmac_f32_e32 v213, v128, v128
	v_fmac_f32_e32 v214, v122, v122
	v_fmac_f32_e32 v215, v124, v124
	v_fmac_f32_e32 v123, v118, v118
	v_fmac_f32_e32 v125, v120, v120
	v_fmac_f32_e32 v127, v210, v210
	v_fmac_f32_e32 v129, v208, v208
	ds_write_b128 v205, v[114:117]
	v_cvt_pk_bf16_f32 v114, v118, v119
	v_cvt_pk_bf16_f32 v115, v120, v121
	v_add_f32_e32 v117, v212, v213
	v_add_f32_e32 v118, v214, v215
	v_add_f32_e32 v119, v123, v125
	v_add_f32_e32 v120, v127, v129
	v_add_f32_e32 v117, v117, v118
	v_add_f32_e32 v118, v119, v120
	v_add_f32_e32 v119, v117, v118
	v_cndmask_b32_e32 v117, v204, v207, vcc
	v_lshlrev_b32_e32 v118, 2, v117
	ds_bpermute_b32 v120, v118, v119
	v_cvt_pk_bf16_f32 v116, v210, v211
	v_cvt_pk_bf16_f32 v117, v208, v209
	ds_write_b128 v205, v[114:117] offset:64
	v_xor_b32_e32 v114, 32, v204
	v_cmp_lt_i32_e32 vcc, v114, v219
	s_waitcnt lgkmcnt(1)
	v_add_f32_e32 v120, v119, v120
	ds_read_b128 v[122:125], v206
	ds_read_b128 v[126:129], v206 offset:1152
	v_cndmask_b32_e32 v114, v204, v114, vcc
	v_lshlrev_b32_e32 v119, 2, v114
	ds_bpermute_b32 v121, v119, v120
	v_lshl_add_u64 v[116:117], s[46:47], 0, v[186:187]
	v_lshl_add_u64 v[114:115], v[216:217], 2, s[30:31]
	s_waitcnt lgkmcnt(2)
	global_store_dwordx4 v[116:117], v[122:125], off sc1
	s_waitcnt lgkmcnt(1)
	global_store_dwordx4 v[116:117], v[126:129], off offset:1024 sc1
	s_and_saveexec_b64 s[46:47], s[6:7]
	s_cbranch_execz .LBB0_482
	s_waitcnt lgkmcnt(0)
	v_add_f32_e32 v120, v120, v121
	global_atomic_add_f32 v[114:115], v120, off
.LBB0_482:
	s_or_b64 exec, exec, s[46:47]
	v_pk_add_f32 v[112:113], v[112:113], v[176:177]
	v_pk_add_f32 v[110:111], v[110:111], v[174:175]
	s_waitcnt lgkmcnt(0)
	v_pk_add_f32 v[120:121], v[108:109], v[172:173]
	v_pk_add_f32 v[108:109], v[106:107], v[170:171]
	v_mul_f32_e32 v106, v111, v111
	v_mul_f32_e32 v107, v113, v113
	v_fmac_f32_e32 v106, v110, v110
	v_fmac_f32_e32 v107, v112, v112
	v_add_f32_e32 v106, v106, v107
	v_mul_f32_e32 v107, v109, v109
	v_mul_f32_e32 v122, v121, v121
	v_fmac_f32_e32 v107, v108, v108
	v_fmac_f32_e32 v122, v120, v120
	v_add_f32_e32 v107, v107, v122
	v_add_f32_e32 v122, v106, v107
	v_cvt_pk_bf16_f32 v106, v110, v111
	v_cvt_pk_bf16_f32 v107, v112, v113
	v_pk_add_f32 v[104:105], v[104:105], v[168:169]
	v_pk_add_f32 v[102:103], v[102:103], v[166:167]
	v_cvt_pk_bf16_f32 v108, v108, v109
	v_cvt_pk_bf16_f32 v109, v120, v121
	ds_write_b128 v205, v[106:109]
	v_pk_add_f32 v[106:107], v[100:101], v[164:165]
	v_pk_add_f32 v[100:101], v[98:99], v[162:163]
	v_mul_f32_e32 v98, v103, v103
	v_mul_f32_e32 v99, v105, v105
	v_fmac_f32_e32 v98, v102, v102
	v_fmac_f32_e32 v99, v104, v104
	v_add_f32_e32 v98, v98, v99
	v_mul_f32_e32 v99, v101, v101
	v_mul_f32_e32 v108, v107, v107
	v_fmac_f32_e32 v99, v100, v100
	v_fmac_f32_e32 v108, v106, v106
	v_add_f32_e32 v99, v99, v108
	v_add_f32_e32 v98, v98, v99
	v_add_f32_e32 v108, v122, v98
	ds_bpermute_b32 v109, v118, v108
	v_cvt_pk_bf16_f32 v98, v102, v103
	v_cvt_pk_bf16_f32 v99, v104, v105
	v_cvt_pk_bf16_f32 v100, v100, v101
	v_cvt_pk_bf16_f32 v101, v106, v107
	ds_write_b128 v205, v[98:101] offset:64
	s_waitcnt lgkmcnt(1)
	v_add_f32_e32 v98, v108, v109
	ds_read_b128 v[100:103], v206
	ds_read_b128 v[104:107], v206 offset:1152
	ds_bpermute_b32 v99, v119, v98
	s_waitcnt lgkmcnt(2)
	global_store_dwordx4 v[116:117], v[100:103], off offset:2048 sc1
	s_waitcnt lgkmcnt(1)
	global_store_dwordx4 v[116:117], v[104:107], off offset:3072 sc1
	s_and_saveexec_b64 s[46:47], s[6:7]
	s_cbranch_execz .LBB0_484
	s_waitcnt lgkmcnt(0)
	v_add_f32_e32 v98, v98, v99
	global_atomic_add_f32 v[114:115], v98, off offset:64
; __device__ __forceinline__ u32x4 pack8(const f32x4& v0, const f32x4& v1) { u32x4 w; w.x = cvt_pk_bf16(v0[0], v0[1]); w.y = cvt_pk_bf16(v0[2], v0[3]); w.z = cvt_pk_bf16(v1[0], v1[1]); w.w = cvt_pk_bf16(v1[2], v1[3]); return w; }
;     __device__ __forceinline__ void operator()(const f32x4 (&acc)[2][2][4][2], const Unit& u, int wr, int wc, int fr, int fq) const {
;     ...
;             for (int m = 0; m < 4; ++m) { const float* xp = x + (size_t)(row0 + ai * HALF + m * 16) * 1024 + col0;
; #pragma unroll
;                 for (int bj = 0; bj < 2; ++bj) { xv[m][bj][0] = *(const f32x4*)(xp + bj * 32); xv[m][bj][1] = *(const f32x4*)(xp + bj * 32 + 4); } }
;             asm volatile("" ::: "memory");
; #pragma unroll
;             for (int m = 0; m < 4; ++m) { const int row = row0 + ai * HALF + m * 16; float sq = 0.f;
; #pragma unroll
;                 for (int bj = 0; bj < 2; ++bj) { const f32x4 o0 = xv[m][bj][0] + acc[ai][bj][m][0], o1 = xv[m][bj][1] + acc[ai][bj][m][1];
;                     sq += ((o0[0] * o0[0] + o0[1] * o0[1]) + (o0[2] * o0[2] + o0[3] * o0[3])) + ((o1[0] * o1[0] + o1[1] * o1[1]) + (o1[2] * o1[2] + o1[3] * o1[3]));
;                     po.put(bj, pack8(o0, o1)); }
;                 po.flush<false>(ai, m);
;                 sq += __shfl_xor(sq, 16); sq += __shfl_xor(sq, 32);
;                 if (fq == 0) atomicAdd(ss + row, sq); }
.LBB0_484:
	s_or_b64 exec, exec, s[46:47]
	v_pk_add_f32 v[96:97], v[96:97], v[160:161]
	v_pk_add_f32 v[94:95], v[94:95], v[158:159]
	s_waitcnt lgkmcnt(0)
	v_pk_add_f32 v[98:99], v[92:93], v[156:157]
	v_pk_add_f32 v[92:93], v[90:91], v[154:155]
	v_mul_f32_e32 v90, v95, v95
	v_mul_f32_e32 v91, v97, v97
	v_fmac_f32_e32 v90, v94, v94
	v_fmac_f32_e32 v91, v96, v96
	v_add_f32_e32 v90, v90, v91
	v_mul_f32_e32 v91, v93, v93
	v_mul_f32_e32 v100, v99, v99
	v_fmac_f32_e32 v91, v92, v92
	v_fmac_f32_e32 v100, v98, v98
	v_add_f32_e32 v91, v91, v100
	v_add_f32_e32 v100, v90, v91
	v_cvt_pk_bf16_f32 v90, v94, v95
	v_cvt_pk_bf16_f32 v91, v96, v97
	v_pk_add_f32 v[88:89], v[88:89], v[152:153]
	v_pk_add_f32 v[86:87], v[86:87], v[150:151]
	v_cvt_pk_bf16_f32 v92, v92, v93
	v_cvt_pk_bf16_f32 v93, v98, v99
	ds_write_b128 v205, v[90:93]
	v_pk_add_f32 v[90:91], v[84:85], v[148:149]
	v_pk_add_f32 v[84:85], v[82:83], v[146:147]
	v_mul_f32_e32 v82, v87, v87
	v_mul_f32_e32 v83, v89, v89
	v_fmac_f32_e32 v82, v86, v86
	v_fmac_f32_e32 v83, v88, v88
	v_add_f32_e32 v82, v82, v83
	v_mul_f32_e32 v83, v85, v85
	v_mul_f32_e32 v92, v91, v91
	v_fmac_f32_e32 v83, v84, v84
	v_fmac_f32_e32 v92, v90, v90
	v_add_f32_e32 v83, v83, v92
	v_add_f32_e32 v82, v82, v83
	v_add_f32_e32 v93, v100, v82
	v_cvt_pk_bf16_f32 v82, v86, v87
	v_cvt_pk_bf16_f32 v83, v88, v89
	v_cvt_pk_bf16_f32 v84, v84, v85
	v_cvt_pk_bf16_f32 v85, v90, v91
	ds_write_b128 v205, v[82:85] offset:64
	ds_bpermute_b32 v82, v118, v93
	ds_read_b128 v[84:87], v206
	ds_read_b128 v[88:91], v206 offset:1152
	v_add_co_u32_e32 v92, vcc, 0x1000, v116
	s_waitcnt lgkmcnt(2)
	v_add_f32_e32 v82, v93, v82
	ds_bpermute_b32 v83, v119, v82
	v_addc_co_u32_e32 v93, vcc, 0, v117, vcc
	s_waitcnt lgkmcnt(2)
	global_store_dwordx4 v[92:93], v[84:87], off sc1
	s_waitcnt lgkmcnt(1)
	global_store_dwordx4 v[92:93], v[88:91], off offset:1024 sc1
	s_and_saveexec_b64 s[46:47], s[6:7]
	s_cbranch_execz .LBB0_486
	s_waitcnt lgkmcnt(0)
	v_add_f32_e32 v82, v82, v83
	global_atomic_add_f32 v[114:115], v82, off offset:128
.LBB0_486:
	s_or_b64 exec, exec, s[46:47]
	v_pk_add_f32 v[80:81], v[80:81], v[144:145]
	v_pk_add_f32 v[78:79], v[78:79], v[142:143]
	s_waitcnt lgkmcnt(0)
	v_pk_add_f32 v[82:83], v[76:77], v[140:141]
	v_pk_add_f32 v[76:77], v[74:75], v[138:139]
	v_mul_f32_e32 v74, v79, v79
	v_mul_f32_e32 v75, v81, v81
	v_fmac_f32_e32 v74, v78, v78
	v_fmac_f32_e32 v75, v80, v80
	v_add_f32_e32 v74, v74, v75
	v_mul_f32_e32 v75, v77, v77
	v_mul_f32_e32 v84, v83, v83
	v_fmac_f32_e32 v75, v76, v76
	v_fmac_f32_e32 v84, v82, v82
	v_add_f32_e32 v75, v75, v84
	v_add_f32_e32 v84, v74, v75
	v_cvt_pk_bf16_f32 v74, v78, v79
	v_cvt_pk_bf16_f32 v75, v80, v81
	v_pk_add_f32 v[72:73], v[72:73], v[136:137]
	v_pk_add_f32 v[70:71], v[70:71], v[134:135]
	v_cvt_pk_bf16_f32 v76, v76, v77
	v_cvt_pk_bf16_f32 v77, v82, v83
	ds_write_b128 v205, v[74:77]
	v_pk_add_f32 v[74:75], v[68:69], v[132:133]
	v_pk_add_f32 v[68:69], v[66:67], v[130:131]
	v_mul_f32_e32 v66, v71, v71
	v_mul_f32_e32 v67, v73, v73
	v_fmac_f32_e32 v66, v70, v70
	v_fmac_f32_e32 v67, v72, v72
	v_add_f32_e32 v66, v66, v67
	v_mul_f32_e32 v67, v69, v69
	v_mul_f32_e32 v76, v75, v75
	v_fmac_f32_e32 v67, v68, v68
	v_fmac_f32_e32 v76, v74, v74
	v_add_f32_e32 v67, v67, v76
	v_add_f32_e32 v66, v66, v67
	v_add_f32_e32 v77, v84, v66
	v_cvt_pk_bf16_f32 v66, v70, v71
	v_cvt_pk_bf16_f32 v67, v72, v73
	v_cvt_pk_bf16_f32 v68, v68, v69
	v_cvt_pk_bf16_f32 v69, v74, v75
	ds_write_b128 v205, v[66:69] offset:64
	ds_bpermute_b32 v66, v118, v77
	ds_read_b128 v[68:71], v206
	ds_read_b128 v[72:75], v206 offset:1152
	v_add_co_u32_e32 v76, vcc, 0x1000, v116
	s_waitcnt lgkmcnt(2)
	v_add_f32_e32 v66, v77, v66
	ds_bpermute_b32 v67, v119, v66
	v_addc_co_u32_e32 v77, vcc, 0, v117, vcc
	s_waitcnt lgkmcnt(2)
	global_store_dwordx4 v[76:77], v[68:71], off offset:2048 sc1
	s_waitcnt lgkmcnt(1)
	global_store_dwordx4 v[76:77], v[72:75], off offset:3072 sc1
	s_and_saveexec_b64 s[46:47], s[6:7]
	s_cbranch_execz .LBB0_488
	s_waitcnt lgkmcnt(0)
	v_add_f32_e32 v66, v66, v67
	global_atomic_add_f32 v[114:115], v66, off offset:192
.LBB0_488:
	s_or_b64 exec, exec, s[46:47]
	v_add_co_u32_e32 v68, vcc, 0x80000, v196
	s_waitcnt lgkmcnt(0)
	v_lshl_add_u64 v[66:67], v[196:197], 0, s[18:19]
	v_addc_co_u32_e32 v69, vcc, 0, v197, vcc
	global_load_dwordx4 v[120:123], v[66:67], off offset:16
	global_load_dwordx4 v[124:127], v[66:67], off offset:128
	global_load_dwordx4 v[128:131], v[68:69], off
	global_load_dwordx4 v[132:135], v[66:67], off offset:144
	v_add_co_u32_e32 v78, vcc, 0x90000, v196
	v_lshl_add_u64 v[70:71], v[196:197], 0, s[20:21]
	s_nop 0
	v_addc_co_u32_e32 v79, vcc, 0, v197, vcc
	v_lshl_add_u64 v[72:73], v[196:197], 0, s[22:23]
	v_lshl_add_u64 v[136:137], v[196:197], 0, s[24:25]
	global_load_dwordx4 v[106:109], v[70:71], off offset:16
	global_load_dwordx4 v[98:101], v[70:71], off offset:128
	global_load_dwordx4 v[90:93], v[72:73], off offset:16
	global_load_dwordx4 v[82:85], v[72:73], off offset:128
	global_load_dwordx4 v[74:77], v[136:137], off offset:16
	global_load_dwordx4 v[66:69], v[136:137], off offset:128
	v_add_co_u32_e32 v80, vcc, 0xa0000, v196
	global_load_dwordx4 v[110:113], v[78:79], off
	global_load_dwordx4 v[102:105], v[70:71], off offset:144
	v_addc_co_u32_e32 v81, vcc, 0, v197, vcc
	v_add_co_u32_e32 v70, vcc, 0xb0000, v196
	global_load_dwordx4 v[94:97], v[80:81], off
	global_load_dwordx4 v[86:89], v[72:73], off offset:144
	v_addc_co_u32_e32 v71, vcc, 0, v197, vcc
	global_load_dwordx4 v[78:81], v[70:71], off
	s_nop 0
	global_load_dwordx4 v[70:73], v[136:137], off offset:144
	v_add_co_u32_e32 v136, vcc, 0x4000, v116
	s_waitcnt vmcnt(15)
; __device__ __forceinline__ u32x4 pack8(const f32x4& v0, const f32x4& v1) { u32x4 w; w.x = cvt_pk_bf16(v0[0], v0[1]); w.y = cvt_pk_bf16(v0[2], v0[3]); w.z = cvt_pk_bf16(v1[0], v1[1]); w.w = cvt_pk_bf16(v1[2], v1[3]); return w; }
;     __device__ __forceinline__ void operator()(const f32x4 (&acc)[2][2][4][2], const Unit& u, int wr, int wc, int fr, int fq) const {
;     ...
;             for (int m = 0; m < 4; ++m) { const float* xp = x + (size_t)(row0 + ai * HALF + m * 16) * 1024 + col0;
; #pragma unroll
;                 for (int bj = 0; bj < 2; ++bj) { xv[m][bj][0] = *(const f32x4*)(xp + bj * 32); xv[m][bj][1] = *(const f32x4*)(xp + bj * 32 + 4); } }
;             asm volatile("" ::: "memory");
; #pragma unroll
;             for (int m = 0; m < 4; ++m) { const int row = row0 + ai * HALF + m * 16; float sq = 0.f;
; #pragma unroll
;                 for (int bj = 0; bj < 2; ++bj) { const f32x4 o0 = xv[m][bj][0] + acc[ai][bj][m][0], o1 = xv[m][bj][1] + acc[ai][bj][m][1];
;                     sq += ((o0[0] * o0[0] + o0[1] * o0[1]) + (o0[2] * o0[2] + o0[3] * o0[3])) + ((o1[0] * o1[0] + o1[1] * o1[1]) + (o1[2] * o1[2] + o1[3] * o1[3]));
;                     po.put(bj, pack8(o0, o1)); }
;                 po.flush<false>(ai, m);
;                 sq += __shfl_xor(sq, 16); sq += __shfl_xor(sq, 32);
;                 if (fq == 0) atomicAdd(ss + row, sq); }
	v_pk_add_f32 v[58:59], v[58:59], v[120:121]
	v_pk_add_f32 v[60:61], v[60:61], v[122:123]
	s_waitcnt vmcnt(14)
	v_pk_add_f32 v[56:57], v[56:57], v[126:127]
	v_pk_add_f32 v[54:55], v[54:55], v[124:125]
	s_waitcnt vmcnt(13)
	v_pk_add_f32 v[64:65], v[64:65], v[130:131]
	v_pk_add_f32 v[62:63], v[62:63], v[128:129]
	v_mul_f32_e32 v124, v59, v59
	s_waitcnt vmcnt(12)
	v_pk_add_f32 v[120:121], v[52:53], v[134:135]
	v_pk_add_f32 v[122:123], v[50:51], v[132:133]
	v_mul_f32_e32 v125, v61, v61
	v_mul_f32_e32 v126, v55, v55
	v_mul_f32_e32 v127, v57, v57
	v_mul_f32_e32 v128, v63, v63
	v_mul_f32_e32 v129, v65, v65
	v_fmac_f32_e32 v124, v58, v58
	v_cvt_pk_bf16_f32 v50, v62, v63
	v_cvt_pk_bf16_f32 v51, v64, v65
	v_cvt_pk_bf16_f32 v52, v58, v59
	v_mul_f32_e32 v58, v123, v123
	v_mul_f32_e32 v59, v121, v121
	v_fmac_f32_e32 v125, v60, v60
	v_cvt_pk_bf16_f32 v53, v60, v61
	v_fmac_f32_e32 v126, v54, v54
	v_fmac_f32_e32 v127, v56, v56
	v_fmac_f32_e32 v128, v62, v62
	v_fmac_f32_e32 v129, v64, v64
	v_fmac_f32_e32 v58, v122, v122
	v_fmac_f32_e32 v59, v120, v120
	v_add_f32_e32 v60, v124, v125
	ds_write_b128 v205, v[50:53]
	v_add_f32_e32 v53, v126, v127
	v_cvt_pk_bf16_f32 v50, v54, v55
	v_add_f32_e32 v54, v128, v129
	v_add_f32_e32 v55, v58, v59
	v_add_f32_e32 v54, v54, v60
	v_add_f32_e32 v53, v53, v55
	v_add_f32_e32 v60, v54, v53
	ds_bpermute_b32 v61, v118, v60
	v_cvt_pk_bf16_f32 v51, v56, v57
	v_cvt_pk_bf16_f32 v52, v122, v123
	v_cvt_pk_bf16_f32 v53, v120, v121
	ds_write_b128 v205, v[50:53] offset:64
	s_waitcnt lgkmcnt(1)
	v_add_f32_e32 v50, v60, v61
	ds_read_b128 v[52:55], v206
	ds_read_b128 v[56:59], v206 offset:1152
	ds_bpermute_b32 v51, v119, v50
	v_addc_co_u32_e32 v137, vcc, 0, v117, vcc
	s_waitcnt lgkmcnt(2)
	global_store_dwordx4 v[136:137], v[52:55], off sc1
	s_waitcnt lgkmcnt(1)
	global_store_dwordx4 v[136:137], v[56:59], off offset:1024 sc1
	s_and_saveexec_b64 s[46:47], s[6:7]
	s_cbranch_execz .LBB0_490
	s_waitcnt lgkmcnt(0)
	v_add_f32_e32 v50, v50, v51
	global_atomic_add_f32 v[114:115], v50, off offset:512
.LBB0_490:
	s_or_b64 exec, exec, s[46:47]
	s_waitcnt vmcnt(7)
	v_pk_add_f32 v[48:49], v[48:49], v[112:113]
	v_pk_add_f32 v[46:47], v[46:47], v[110:111]
	s_waitcnt lgkmcnt(0)
	v_pk_add_f32 v[50:51], v[44:45], v[108:109]
	v_pk_add_f32 v[44:45], v[42:43], v[106:107]
	v_mul_f32_e32 v42, v47, v47
	v_mul_f32_e32 v43, v49, v49
	v_fmac_f32_e32 v42, v46, v46
	v_fmac_f32_e32 v43, v48, v48
	v_add_f32_e32 v42, v42, v43
	v_mul_f32_e32 v43, v45, v45
	v_mul_f32_e32 v52, v51, v51
	v_fmac_f32_e32 v43, v44, v44
	v_fmac_f32_e32 v52, v50, v50
	v_add_f32_e32 v43, v43, v52
	v_add_f32_e32 v52, v42, v43
	v_cvt_pk_bf16_f32 v42, v46, v47
	v_cvt_pk_bf16_f32 v43, v48, v49
	v_pk_add_f32 v[40:41], v[40:41], v[100:101]
	v_pk_add_f32 v[38:39], v[38:39], v[98:99]
	v_cvt_pk_bf16_f32 v44, v44, v45
	v_cvt_pk_bf16_f32 v45, v50, v51
	ds_write_b128 v205, v[42:45]
	s_waitcnt vmcnt(6)
	v_pk_add_f32 v[42:43], v[36:37], v[104:105]
	v_pk_add_f32 v[36:37], v[34:35], v[102:103]
	v_mul_f32_e32 v34, v39, v39
	v_mul_f32_e32 v35, v41, v41
	v_fmac_f32_e32 v34, v38, v38
	v_fmac_f32_e32 v35, v40, v40
	v_add_f32_e32 v34, v34, v35
	v_mul_f32_e32 v35, v37, v37
	v_mul_f32_e32 v44, v43, v43
	v_fmac_f32_e32 v35, v36, v36
	v_fmac_f32_e32 v44, v42, v42
	v_add_f32_e32 v35, v35, v44
	v_add_f32_e32 v34, v34, v35
	v_add_f32_e32 v45, v52, v34
	v_cvt_pk_bf16_f32 v34, v38, v39
	v_cvt_pk_bf16_f32 v35, v40, v41
	v_cvt_pk_bf16_f32 v36, v36, v37
	v_cvt_pk_bf16_f32 v37, v42, v43
	ds_write_b128 v205, v[34:37] offset:64
	ds_bpermute_b32 v34, v118, v45
	ds_read_b128 v[36:39], v206
	ds_read_b128 v[40:43], v206 offset:1152
	v_add_co_u32_e32 v44, vcc, 0x4000, v116
	s_waitcnt lgkmcnt(2)
	v_add_f32_e32 v34, v45, v34
	ds_bpermute_b32 v35, v119, v34
	v_addc_co_u32_e32 v45, vcc, 0, v117, vcc
	s_waitcnt lgkmcnt(2)
	global_store_dwordx4 v[44:45], v[36:39], off offset:2048 sc1
	s_waitcnt lgkmcnt(1)
	global_store_dwordx4 v[44:45], v[40:43], off offset:3072 sc1
	s_and_saveexec_b64 s[46:47], s[6:7]
	s_cbranch_execz .LBB0_492
	s_waitcnt lgkmcnt(0)
	v_add_f32_e32 v34, v34, v35
	global_atomic_add_f32 v[114:115], v34, off offset:576
; __device__ __forceinline__ u32x4 pack8(const f32x4& v0, const f32x4& v1) { u32x4 w; w.x = cvt_pk_bf16(v0[0], v0[1]); w.y = cvt_pk_bf16(v0[2], v0[3]); w.z = cvt_pk_bf16(v1[0], v1[1]); w.w = cvt_pk_bf16(v1[2], v1[3]); return w; }
;     __device__ __forceinline__ void operator()(const f32x4 (&acc)[2][2][4][2], const Unit& u, int wr, int wc, int fr, int fq) const {
;     ...
;             for (int m = 0; m < 4; ++m) { const float* xp = x + (size_t)(row0 + ai * HALF + m * 16) * 1024 + col0;
; #pragma unroll
;                 for (int bj = 0; bj < 2; ++bj) { xv[m][bj][0] = *(const f32x4*)(xp + bj * 32); xv[m][bj][1] = *(const f32x4*)(xp + bj * 32 + 4); } }
;             asm volatile("" ::: "memory");
; #pragma unroll
;             for (int m = 0; m < 4; ++m) { const int row = row0 + ai * HALF + m * 16; float sq = 0.f;
; #pragma unroll
;                 for (int bj = 0; bj < 2; ++bj) { const f32x4 o0 = xv[m][bj][0] + acc[ai][bj][m][0], o1 = xv[m][bj][1] + acc[ai][bj][m][1];
;                     sq += ((o0[0] * o0[0] + o0[1] * o0[1]) + (o0[2] * o0[2] + o0[3] * o0[3])) + ((o1[0] * o1[0] + o1[1] * o1[1]) + (o1[2] * o1[2] + o1[3] * o1[3]));
;                     po.put(bj, pack8(o0, o1)); }
;                 po.flush<false>(ai, m);
;                 sq += __shfl_xor(sq, 16); sq += __shfl_xor(sq, 32);
;                 if (fq == 0) atomicAdd(ss + row, sq); }
.LBB0_492:
	s_or_b64 exec, exec, s[46:47]
	s_waitcnt vmcnt(7)
	v_pk_add_f32 v[32:33], v[32:33], v[96:97]
	v_pk_add_f32 v[30:31], v[30:31], v[94:95]
	s_waitcnt lgkmcnt(0)
	v_pk_add_f32 v[34:35], v[28:29], v[92:93]
	v_pk_add_f32 v[28:29], v[26:27], v[90:91]
	v_mul_f32_e32 v26, v31, v31
	v_mul_f32_e32 v27, v33, v33
	v_fmac_f32_e32 v26, v30, v30
	v_fmac_f32_e32 v27, v32, v32
	v_add_f32_e32 v26, v26, v27
	v_mul_f32_e32 v27, v29, v29
	v_mul_f32_e32 v36, v35, v35
	v_fmac_f32_e32 v27, v28, v28
	v_fmac_f32_e32 v36, v34, v34
	v_add_f32_e32 v27, v27, v36
	v_add_f32_e32 v36, v26, v27
	v_cvt_pk_bf16_f32 v26, v30, v31
	v_cvt_pk_bf16_f32 v27, v32, v33
	v_pk_add_f32 v[24:25], v[24:25], v[84:85]
	v_pk_add_f32 v[22:23], v[22:23], v[82:83]
	v_cvt_pk_bf16_f32 v28, v28, v29
	v_cvt_pk_bf16_f32 v29, v34, v35
	ds_write_b128 v205, v[26:29]
	s_waitcnt vmcnt(6)
	v_pk_add_f32 v[26:27], v[20:21], v[88:89]
	v_pk_add_f32 v[20:21], v[18:19], v[86:87]
	v_mul_f32_e32 v18, v23, v23
	v_mul_f32_e32 v19, v25, v25
	v_fmac_f32_e32 v18, v22, v22
	v_fmac_f32_e32 v19, v24, v24
	v_add_f32_e32 v18, v18, v19
	v_mul_f32_e32 v19, v21, v21
	v_mul_f32_e32 v28, v27, v27
	v_fmac_f32_e32 v19, v20, v20
	v_fmac_f32_e32 v28, v26, v26
	v_add_f32_e32 v19, v19, v28
	v_add_f32_e32 v18, v18, v19
	v_add_f32_e32 v29, v36, v18
	v_cvt_pk_bf16_f32 v18, v22, v23
	v_cvt_pk_bf16_f32 v19, v24, v25
	v_cvt_pk_bf16_f32 v20, v20, v21
	v_cvt_pk_bf16_f32 v21, v26, v27
	ds_write_b128 v205, v[18:21] offset:64
	ds_bpermute_b32 v18, v118, v29
	ds_read_b128 v[20:23], v206
	ds_read_b128 v[24:27], v206 offset:1152
	v_add_co_u32_e32 v28, vcc, 0x5000, v116
	s_waitcnt lgkmcnt(2)
	v_add_f32_e32 v18, v29, v18
	ds_bpermute_b32 v19, v119, v18
	v_addc_co_u32_e32 v29, vcc, 0, v117, vcc
	s_waitcnt lgkmcnt(2)
	global_store_dwordx4 v[28:29], v[20:23], off sc1
	s_waitcnt lgkmcnt(1)
	global_store_dwordx4 v[28:29], v[24:27], off offset:1024 sc1
	s_and_saveexec_b64 s[46:47], s[6:7]
	s_cbranch_execz .LBB0_494
	s_waitcnt lgkmcnt(0)
	v_add_f32_e32 v18, v18, v19
	global_atomic_add_f32 v[114:115], v18, off offset:640
.LBB0_494:
	s_or_b64 exec, exec, s[46:47]
	s_waitcnt vmcnt(7)
	v_pk_add_f32 v[16:17], v[16:17], v[80:81]
	v_pk_add_f32 v[14:15], v[14:15], v[78:79]
	s_waitcnt lgkmcnt(0)
	v_pk_add_f32 v[18:19], v[12:13], v[76:77]
	v_pk_add_f32 v[12:13], v[10:11], v[74:75]
	v_mul_f32_e32 v10, v15, v15
	v_mul_f32_e32 v11, v17, v17
	v_fmac_f32_e32 v10, v14, v14
	v_fmac_f32_e32 v11, v16, v16
	v_add_f32_e32 v10, v10, v11
	v_mul_f32_e32 v11, v13, v13
	v_mul_f32_e32 v20, v19, v19
	v_fmac_f32_e32 v11, v12, v12
	v_fmac_f32_e32 v20, v18, v18
	v_add_f32_e32 v11, v11, v20
	v_add_f32_e32 v20, v10, v11
	v_cvt_pk_bf16_f32 v10, v14, v15
	v_cvt_pk_bf16_f32 v11, v16, v17
	v_pk_add_f32 v[8:9], v[8:9], v[68:69]
	v_pk_add_f32 v[6:7], v[6:7], v[66:67]
	v_cvt_pk_bf16_f32 v12, v12, v13
	v_cvt_pk_bf16_f32 v13, v18, v19
	ds_write_b128 v205, v[10:13]
	s_waitcnt vmcnt(6)
	v_pk_add_f32 v[10:11], v[4:5], v[72:73]
	v_pk_add_f32 v[4:5], v[2:3], v[70:71]
	v_mul_f32_e32 v2, v7, v7
	v_mul_f32_e32 v3, v9, v9
	v_fmac_f32_e32 v2, v6, v6
	v_fmac_f32_e32 v3, v8, v8
	v_add_f32_e32 v2, v2, v3
	v_mul_f32_e32 v3, v5, v5
	v_mul_f32_e32 v12, v11, v11
	v_fmac_f32_e32 v3, v4, v4
	v_fmac_f32_e32 v12, v10, v10
	v_add_f32_e32 v3, v3, v12
	v_add_f32_e32 v2, v2, v3
	v_add_f32_e32 v13, v20, v2
	v_cvt_pk_bf16_f32 v2, v6, v7
	v_cvt_pk_bf16_f32 v3, v8, v9
	v_cvt_pk_bf16_f32 v4, v4, v5
	v_cvt_pk_bf16_f32 v5, v10, v11
	ds_write_b128 v205, v[2:5] offset:64
	ds_bpermute_b32 v2, v118, v13
	ds_read_b128 v[4:7], v206
	ds_read_b128 v[8:11], v206 offset:1152
	v_add_co_u32_e32 v12, vcc, 0x5000, v116
	s_waitcnt lgkmcnt(2)
	v_add_f32_e32 v2, v13, v2
	ds_bpermute_b32 v3, v119, v2
	v_addc_co_u32_e32 v13, vcc, 0, v117, vcc
	s_waitcnt lgkmcnt(2)
	global_store_dwordx4 v[12:13], v[4:7], off offset:2048 sc1
	s_waitcnt lgkmcnt(1)
	global_store_dwordx4 v[12:13], v[8:11], off offset:3072 sc1
	s_and_saveexec_b64 s[46:47], s[6:7]
	s_cbranch_execz .LBB0_496
	s_waitcnt lgkmcnt(0)
	v_add_f32_e32 v2, v2, v3
	global_atomic_add_f32 v[114:115], v2, off offset:704

; __device__ __forceinline__ size_t tm_block(int pm, int ct, int nct) { return ((size_t)pm * nct + ct) * 32768; }
; __device__ __forceinline__ u32x4 pack8(const f32x4& v0, const f32x4& v1) { u32x4 w; w.x = cvt_pk_bf16(v0[0], v0[1]); w.y = cvt_pk_bf16(v0[2], v0[3]); w.z = cvt_pk_bf16(v1[0], v1[1]); w.w = cvt_pk_bf16(v1[2], v1[3]); return w; }
;     __device__ __forceinline__ void post(const f32x4 (&acc)[2][2][4][2], const float (&st)[8], const Unit& u, int wr, int wc, int fr, int fq) const {
;         const PieceOut po(scr, O, tm_block(u.pm, u.pn * 4 + wc, 64), wr, wc, fr, fq);
; #pragma unroll
;         for (int ai = 0; ai < 2; ++ai)
; #pragma unroll
;             for (int m = 0; m < 4; ++m) { const float rs = __builtin_amdgcn_rsqf(st[ai * 4 + m] * (1.0f / 1024.0f) + eps);
; #pragma unroll
;                 for (int bj = 0; bj < 2; ++bj) { f32x4 v0 = acc[ai][bj][m][0] * rs, v1 = acc[ai][bj][m][1] * rs;
; #pragma unroll
;                     for (int k = 0; k < 4; ++k) { const float a = fmaxf(v0[k], 0.f), b = fmaxf(v1[k], 0.f); v0[k] = a * a; v1[k] = b * b; }
;                     po.put(bj, pack8(v0, v1)); }
;                 po.flush<true>(ai, m); }
.LBB0_589:
	s_waitcnt vmcnt(0)
	v_fmamk_f32 v164, v164, 0x3a800000, v156
	v_rsq_f32_e32 v164, v164
	s_lshl_b32 s17, s25, 2
	s_or_b32 s26, s17, s48
	s_ashr_i32 s25, s24, 31
	v_pk_mul_f32 v[122:123], v[164:165], v[122:123] op_sel_hi:[0,1]
	v_pk_mul_f32 v[126:127], v[164:165], v[126:127] op_sel_hi:[0,1]
	v_pk_mul_f32 v[124:125], v[164:165], v[124:125] op_sel_hi:[0,1]
	v_max_f32_e32 v122, 0, v122
	v_pk_mul_f32 v[128:129], v[164:165], v[128:129] op_sel_hi:[0,1]
	v_mul_f32_e32 v165, v122, v122
	v_max_f32_e32 v122, 0, v127
	v_max_f32_e32 v123, 0, v123
	v_max_f32_e32 v124, 0, v124
	v_max_f32_e32 v126, 0, v126
	v_mul_f32_e32 v122, v122, v122
	v_mul_f32_e32 v127, v123, v123
	v_max_f32_e32 v123, 0, v128
	v_mul_f32_e32 v128, v124, v124
	v_max_f32_e32 v124, 0, v129
	v_max_f32_e32 v125, 0, v125
	v_pk_mul_f32 v[114:115], v[164:165], v[114:115] op_sel_hi:[0,1]
	v_mul_f32_e32 v126, v126, v126
	v_mul_f32_e32 v123, v123, v123
	v_mul_f32_e32 v124, v124, v124
	v_mul_f32_e32 v125, v125, v125
	v_cvt_pk_bf16_f32 v122, v126, v122
	v_pk_mul_f32 v[118:119], v[164:165], v[118:119] op_sel_hi:[0,1]
	v_pk_mul_f32 v[116:117], v[164:165], v[116:117] op_sel_hi:[0,1]
	v_max_f32_e32 v114, 0, v114
	v_cvt_pk_bf16_f32 v123, v123, v124
	v_cvt_pk_bf16_f32 v124, v165, v127
	v_cvt_pk_bf16_f32 v125, v128, v125
	ds_write_b128 v157, v[122:125]
	v_pk_mul_f32 v[120:121], v[164:165], v[120:121] op_sel_hi:[0,1]
	v_mul_f32_e32 v122, v114, v114
	v_max_f32_e32 v114, 0, v119
	v_max_f32_e32 v115, 0, v115
	v_max_f32_e32 v116, 0, v116
	s_ashr_i32 s27, s26, 31
	v_max_f32_e32 v118, 0, v118
	v_mul_f32_e32 v114, v114, v114
	v_mul_f32_e32 v119, v115, v115
	v_max_f32_e32 v115, 0, v120
	v_mul_f32_e32 v120, v116, v116
	v_max_f32_e32 v116, 0, v121
	v_max_f32_e32 v117, 0, v117
	s_lshl_b64 s[24:25], s[24:25], 21
	s_lshl_b64 s[26:27], s[26:27], 15
	v_mul_f32_e32 v118, v118, v118
	v_mul_f32_e32 v115, v115, v115
	v_mul_f32_e32 v116, v116, v116
	v_mul_f32_e32 v117, v117, v117
	v_cvt_pk_bf16_f32 v114, v118, v114
	s_add_u32 s17, s38, s24
	v_cvt_pk_bf16_f32 v115, v115, v116
	v_cvt_pk_bf16_f32 v116, v122, v119
	v_cvt_pk_bf16_f32 v117, v120, v117
	ds_write_b128 v157, v[114:117] offset:64
	v_fmamk_f32 v114, v163, 0x3a800000, v156
	s_addc_u32 s19, s39, s25
	v_rsq_f32_e32 v124, v114
	s_add_u32 s17, s17, s26
	ds_read_b128 v[116:119], v158
	ds_read_b128 v[120:123], v158 offset:1152
	s_addc_u32 s19, s19, s27
	s_add_u32 s24, s17, s14
	s_addc_u32 s25, s19, s15
	v_pk_mul_f32 v[106:107], v[124:125], v[106:107] op_sel_hi:[0,1]
	v_lshl_add_u64 v[114:115], s[24:25], 0, v[138:139]
	v_pk_mul_f32 v[110:111], v[124:125], v[110:111] op_sel_hi:[0,1]
	v_pk_mul_f32 v[108:109], v[124:125], v[108:109] op_sel_hi:[0,1]
	v_max_f32_e32 v106, 0, v106
	s_waitcnt lgkmcnt(1)
	global_store_dwordx4 v[114:115], v[116:119], off sc1
	s_waitcnt lgkmcnt(0)
	global_store_dwordx4 v[114:115], v[120:123], off offset:1024 sc1
	v_pk_mul_f32 v[112:113], v[124:125], v[112:113] op_sel_hi:[0,1]
	v_mul_f32_e32 v116, v106, v106
	v_max_f32_e32 v106, 0, v111
	v_max_f32_e32 v107, 0, v107
	v_max_f32_e32 v108, 0, v108
	v_max_f32_e32 v110, 0, v110
	v_mul_f32_e32 v106, v106, v106
	v_mul_f32_e32 v111, v107, v107
	v_max_f32_e32 v107, 0, v112
	v_mul_f32_e32 v112, v108, v108
	v_max_f32_e32 v108, 0, v113
	v_max_f32_e32 v109, 0, v109
	v_pk_mul_f32 v[100:101], v[124:125], v[100:101] op_sel_hi:[0,1]
	v_pk_mul_f32 v[98:99], v[124:125], v[98:99] op_sel_hi:[0,1]
	v_mul_f32_e32 v110, v110, v110
	v_mul_f32_e32 v107, v107, v107
	v_mul_f32_e32 v108, v108, v108
	v_mul_f32_e32 v109, v109, v109
	v_cvt_pk_bf16_f32 v106, v110, v106
	v_pk_mul_f32 v[104:105], v[124:125], v[104:105] op_sel_hi:[0,1]
	v_pk_mul_f32 v[102:103], v[124:125], v[102:103] op_sel_hi:[0,1]
	v_max_f32_e32 v98, 0, v98
	v_max_f32_e32 v99, 0, v99
	v_max_f32_e32 v100, 0, v100
	v_cvt_pk_bf16_f32 v107, v107, v108
	v_cvt_pk_bf16_f32 v108, v116, v111
	v_cvt_pk_bf16_f32 v109, v112, v109
	ds_write_b128 v157, v[106:109]
	v_mul_f32_e32 v106, v98, v98
	v_max_f32_e32 v98, 0, v103
	v_mul_f32_e32 v103, v99, v99
	v_max_f32_e32 v99, 0, v104
	v_mul_f32_e32 v104, v100, v100
	v_max_f32_e32 v100, 0, v105
	v_max_f32_e32 v102, 0, v102
	v_mul_f32_e32 v98, v98, v98
	v_mul_f32_e32 v99, v99, v99
	v_max_f32_e32 v101, 0, v101
	v_mul_f32_e32 v100, v100, v100
	v_mul_f32_e32 v102, v102, v102
	v_mul_f32_e32 v101, v101, v101
	v_cvt_pk_bf16_f32 v98, v102, v98
	v_cvt_pk_bf16_f32 v99, v99, v100
	v_cvt_pk_bf16_f32 v100, v106, v103
	v_fmamk_f32 v106, v162, 0x3a800000, v156
	v_cvt_pk_bf16_f32 v101, v104, v101
	ds_write_b128 v157, v[98:101] offset:64
	v_rsq_f32_e32 v106, v106
	ds_read_b128 v[98:101], v158
	ds_read_b128 v[102:105], v158 offset:1152
	s_waitcnt lgkmcnt(1)
	global_store_dwordx4 v[114:115], v[98:101], off offset:2048 sc1
	s_waitcnt lgkmcnt(0)
; __device__ __forceinline__ size_t tm_block(int pm, int ct, int nct) { return ((size_t)pm * nct + ct) * 32768; }
; __device__ __forceinline__ u32x4 pack8(const f32x4& v0, const f32x4& v1) { u32x4 w; w.x = cvt_pk_bf16(v0[0], v0[1]); w.y = cvt_pk_bf16(v0[2], v0[3]); w.z = cvt_pk_bf16(v1[0], v1[1]); w.w = cvt_pk_bf16(v1[2], v1[3]); return w; }
;     __device__ __forceinline__ void post(const f32x4 (&acc)[2][2][4][2], const float (&st)[8], const Unit& u, int wr, int wc, int fr, int fq) const {
;         const PieceOut po(scr, O, tm_block(u.pm, u.pn * 4 + wc, 64), wr, wc, fr, fq);
; #pragma unroll
;         for (int ai = 0; ai < 2; ++ai)
; #pragma unroll
;             for (int m = 0; m < 4; ++m) { const float rs = __builtin_amdgcn_rsqf(st[ai * 4 + m] * (1.0f / 1024.0f) + eps);
; #pragma unroll
;                 for (int bj = 0; bj < 2; ++bj) { f32x4 v0 = acc[ai][bj][m][0] * rs, v1 = acc[ai][bj][m][1] * rs;
; #pragma unroll
;                     for (int k = 0; k < 4; ++k) { const float a = fmaxf(v0[k], 0.f), b = fmaxf(v1[k], 0.f); v0[k] = a * a; v1[k] = b * b; }
;                     po.put(bj, pack8(v0, v1)); }
;                 po.flush<true>(ai, m); }
	global_store_dwordx4 v[114:115], v[102:105], off offset:3072 sc1
	v_pk_mul_f32 v[90:91], v[106:107], v[90:91] op_sel_hi:[0,1]
	v_pk_mul_f32 v[94:95], v[106:107], v[94:95] op_sel_hi:[0,1]
	v_pk_mul_f32 v[92:93], v[106:107], v[92:93] op_sel_hi:[0,1]
	v_max_f32_e32 v90, 0, v90
	v_pk_mul_f32 v[96:97], v[106:107], v[96:97] op_sel_hi:[0,1]
	v_mul_f32_e32 v98, v90, v90
	v_max_f32_e32 v90, 0, v95
	v_max_f32_e32 v91, 0, v91
	v_max_f32_e32 v92, 0, v92
	v_max_f32_e32 v94, 0, v94
	v_mul_f32_e32 v90, v90, v90
	v_mul_f32_e32 v95, v91, v91
	v_max_f32_e32 v91, 0, v96
	v_mul_f32_e32 v96, v92, v92
	v_max_f32_e32 v92, 0, v97
	v_max_f32_e32 v93, 0, v93
	v_pk_mul_f32 v[84:85], v[106:107], v[84:85] op_sel_hi:[0,1]
	v_pk_mul_f32 v[82:83], v[106:107], v[82:83] op_sel_hi:[0,1]
	v_mul_f32_e32 v94, v94, v94
	v_mul_f32_e32 v91, v91, v91
	v_mul_f32_e32 v92, v92, v92
	v_mul_f32_e32 v93, v93, v93
	v_cvt_pk_bf16_f32 v90, v94, v90
	v_pk_mul_f32 v[88:89], v[106:107], v[88:89] op_sel_hi:[0,1]
	v_pk_mul_f32 v[86:87], v[106:107], v[86:87] op_sel_hi:[0,1]
	v_max_f32_e32 v82, 0, v82
	v_max_f32_e32 v83, 0, v83
	v_max_f32_e32 v84, 0, v84
	v_cvt_pk_bf16_f32 v91, v91, v92
	v_cvt_pk_bf16_f32 v92, v98, v95
	v_cvt_pk_bf16_f32 v93, v96, v93
	ds_write_b128 v157, v[90:93]
	v_mul_f32_e32 v90, v82, v82
	v_max_f32_e32 v82, 0, v87
	v_mul_f32_e32 v87, v83, v83
	v_max_f32_e32 v83, 0, v88
	v_mul_f32_e32 v88, v84, v84
	v_max_f32_e32 v84, 0, v89
	v_max_f32_e32 v86, 0, v86
	v_mul_f32_e32 v82, v82, v82
	v_mul_f32_e32 v83, v83, v83
	v_max_f32_e32 v85, 0, v85
	v_mul_f32_e32 v84, v84, v84
	v_mul_f32_e32 v86, v86, v86
	v_mul_f32_e32 v85, v85, v85
	v_cvt_pk_bf16_f32 v82, v86, v82
	v_cvt_pk_bf16_f32 v83, v83, v84
	v_cvt_pk_bf16_f32 v84, v90, v87
	v_fmamk_f32 v90, v161, 0x3a800000, v156
	v_cvt_pk_bf16_f32 v85, v88, v85
	ds_write_b128 v157, v[82:85] offset:64
	v_rsq_f32_e32 v90, v90
	ds_read_b128 v[82:85], v158
	ds_read_b128 v[86:89], v158 offset:1152
	v_add_co_u32_e32 v92, vcc, s53, v114
	v_pk_mul_f32 v[74:75], v[90:91], v[74:75] op_sel_hi:[0,1]
	s_nop 0
	v_addc_co_u32_e32 v93, vcc, 0, v115, vcc
	v_pk_mul_f32 v[78:79], v[90:91], v[78:79] op_sel_hi:[0,1]
	v_pk_mul_f32 v[76:77], v[90:91], v[76:77] op_sel_hi:[0,1]
	v_max_f32_e32 v74, 0, v74
	s_waitcnt lgkmcnt(1)
	global_store_dwordx4 v[92:93], v[82:85], off sc1
	s_waitcnt lgkmcnt(0)
	global_store_dwordx4 v[92:93], v[86:89], off offset:1024 sc1
	v_pk_mul_f32 v[80:81], v[90:91], v[80:81] op_sel_hi:[0,1]
	v_mul_f32_e32 v82, v74, v74
	v_max_f32_e32 v74, 0, v79
	v_max_f32_e32 v75, 0, v75
	v_max_f32_e32 v76, 0, v76
	v_max_f32_e32 v78, 0, v78
	v_mul_f32_e32 v74, v74, v74
	v_mul_f32_e32 v79, v75, v75
	v_max_f32_e32 v75, 0, v80
	v_mul_f32_e32 v80, v76, v76
	v_max_f32_e32 v76, 0, v81
	v_max_f32_e32 v77, 0, v77
	v_pk_mul_f32 v[68:69], v[90:91], v[68:69] op_sel_hi:[0,1]
	v_pk_mul_f32 v[66:67], v[90:91], v[66:67] op_sel_hi:[0,1]
	v_mul_f32_e32 v78, v78, v78
	v_mul_f32_e32 v75, v75, v75
	v_mul_f32_e32 v76, v76, v76
	v_mul_f32_e32 v77, v77, v77
	v_cvt_pk_bf16_f32 v74, v78, v74
	v_pk_mul_f32 v[72:73], v[90:91], v[72:73] op_sel_hi:[0,1]
	v_pk_mul_f32 v[70:71], v[90:91], v[70:71] op_sel_hi:[0,1]
	v_max_f32_e32 v66, 0, v66
	v_max_f32_e32 v67, 0, v67
	v_max_f32_e32 v68, 0, v68
	v_cvt_pk_bf16_f32 v75, v75, v76
	v_cvt_pk_bf16_f32 v76, v82, v79
	v_cvt_pk_bf16_f32 v77, v80, v77
	ds_write_b128 v157, v[74:77]
	v_mul_f32_e32 v74, v66, v66
	v_max_f32_e32 v66, 0, v71
	v_mul_f32_e32 v71, v67, v67
	v_max_f32_e32 v67, 0, v72
	v_mul_f32_e32 v72, v68, v68
	v_max_f32_e32 v68, 0, v73
	v_max_f32_e32 v70, 0, v70
	v_mul_f32_e32 v66, v66, v66
	v_mul_f32_e32 v67, v67, v67
	v_max_f32_e32 v69, 0, v69
	v_mul_f32_e32 v68, v68, v68
	v_mul_f32_e32 v70, v70, v70
	v_mul_f32_e32 v69, v69, v69
	v_cvt_pk_bf16_f32 v66, v70, v66
	v_cvt_pk_bf16_f32 v67, v67, v68
	v_cvt_pk_bf16_f32 v68, v74, v71
	v_fmamk_f32 v74, v160, 0x3a800000, v156
	v_cvt_pk_bf16_f32 v69, v72, v69
	ds_write_b128 v157, v[66:69] offset:64
	v_rsq_f32_e32 v74, v74
	ds_read_b128 v[66:69], v158
	ds_read_b128 v[70:73], v158 offset:1152
	s_waitcnt lgkmcnt(1)
	global_store_dwordx4 v[92:93], v[66:69], off offset:2048 sc1
	s_waitcnt lgkmcnt(0)
	global_store_dwordx4 v[92:93], v[70:73], off offset:3072 sc1
	v_pk_mul_f32 v[58:59], v[74:75], v[58:59] op_sel_hi:[0,1]
	v_pk_mul_f32 v[62:63], v[74:75], v[62:63] op_sel_hi:[0,1]
	v_pk_mul_f32 v[60:61], v[74:75], v[60:61] op_sel_hi:[0,1]
	v_max_f32_e32 v58, 0, v58
	v_pk_mul_f32 v[64:65], v[74:75], v[64:65] op_sel_hi:[0,1]
	v_mul_f32_e32 v66, v58, v58
	v_max_f32_e32 v58, 0, v63
	v_max_f32_e32 v59, 0, v59
	v_max_f32_e32 v60, 0, v60
	v_max_f32_e32 v62, 0, v62
	v_mul_f32_e32 v58, v58, v58
	v_mul_f32_e32 v63, v59, v59
	v_max_f32_e32 v59, 0, v64
	v_mul_f32_e32 v64, v60, v60
	v_max_f32_e32 v60, 0, v65
	v_max_f32_e32 v61, 0, v61
	v_pk_mul_f32 v[52:53], v[74:75], v[52:53] op_sel_hi:[0,1]
	v_pk_mul_f32 v[50:51], v[74:75], v[50:51] op_sel_hi:[0,1]
	v_mul_f32_e32 v62, v62, v62
	v_mul_f32_e32 v59, v59, v59
	v_mul_f32_e32 v60, v60, v60
	v_mul_f32_e32 v61, v61, v61
	v_cvt_pk_bf16_f32 v58, v62, v58
	v_pk_mul_f32 v[56:57], v[74:75], v[56:57] op_sel_hi:[0,1]
	v_pk_mul_f32 v[54:55], v[74:75], v[54:55] op_sel_hi:[0,1]
	v_max_f32_e32 v50, 0, v50
	v_max_f32_e32 v51, 0, v51
	v_max_f32_e32 v52, 0, v52
	v_cvt_pk_bf16_f32 v59, v59, v60
	v_cvt_pk_bf16_f32 v60, v66, v63
	v_cvt_pk_bf16_f32 v61, v64, v61
	ds_write_b128 v157, v[58:61]
	v_mul_f32_e32 v58, v50, v50
	v_max_f32_e32 v50, 0, v55
	v_mul_f32_e32 v55, v51, v51
	v_max_f32_e32 v51, 0, v56
	v_mul_f32_e32 v56, v52, v52
	v_max_f32_e32 v52, 0, v57
	v_max_f32_e32 v53, 0, v53
	v_max_f32_e32 v54, 0, v54
	v_mul_f32_e32 v50, v50, v50
	v_mul_f32_e32 v51, v51, v51
	v_mul_f32_e32 v52, v52, v52
	v_mul_f32_e32 v53, v53, v53
	v_fmamk_f32 v60, v159, 0x3a800000, v156
	v_mul_f32_e32 v54, v54, v54
	v_cvt_pk_bf16_f32 v50, v54, v50
	v_cvt_pk_bf16_f32 v51, v51, v52
	v_cvt_pk_bf16_f32 v52, v58, v55
	v_cvt_pk_bf16_f32 v53, v56, v53
	ds_write_b128 v157, v[50:53] offset:64
	v_rsq_f32_e32 v60, v60
	ds_read_b128 v[50:53], v158
	ds_read_b128 v[54:57], v158 offset:1152
	v_add_co_u32_e32 v58, vcc, s47, v114
	v_pk_mul_f32 v[42:43], v[60:61], v[42:43] op_sel_hi:[0,1]
	s_nop 0
	v_addc_co_u32_e32 v59, vcc, 0, v115, vcc
	v_add_co_u32_e32 v62, vcc, s54, v114
	v_pk_mul_f32 v[46:47], v[60:61], v[46:47] op_sel_hi:[0,1]
	s_nop 0
	v_addc_co_u32_e32 v63, vcc, 0, v115, vcc
	v_pk_mul_f32 v[44:45], v[60:61], v[44:45] op_sel_hi:[0,1]
	v_max_f32_e32 v42, 0, v42
	s_waitcnt lgkmcnt(1)
; __device__ __forceinline__ size_t tm_block(int pm, int ct, int nct) { return ((size_t)pm * nct + ct) * 32768; }
; __device__ __forceinline__ u32x4 pack8(const f32x4& v0, const f32x4& v1) { u32x4 w; w.x = cvt_pk_bf16(v0[0], v0[1]); w.y = cvt_pk_bf16(v0[2], v0[3]); w.z = cvt_pk_bf16(v1[0], v1[1]); w.w = cvt_pk_bf16(v1[2], v1[3]); return w; }
;     __device__ __forceinline__ void pre(float (&st)[8], const Unit& u, int wr, int wc, int fr, int fq) const {
;         const float* sp = ss + u.pm * BM + wr * 64 + fr;
; #pragma unroll
;         for (int i = 0; i < 8; ++i) st[i] = sp[(i >> 2) * HALF + (i & 3) * 16];
;     }
;     __device__ __forceinline__ void post(const f32x4 (&acc)[2][2][4][2], const float (&st)[8], const Unit& u, int wr, int wc, int fr, int fq) const {
;         const PieceOut po(scr, O, tm_block(u.pm, u.pn * 4 + wc, 64), wr, wc, fr, fq);
; #pragma unroll
;         for (int ai = 0; ai < 2; ++ai)
; #pragma unroll
;             for (int m = 0; m < 4; ++m) { const float rs = __builtin_amdgcn_rsqf(st[ai * 4 + m] * (1.0f / 1024.0f) + eps);
; #pragma unroll
;                 for (int bj = 0; bj < 2; ++bj) { f32x4 v0 = acc[ai][bj][m][0] * rs, v1 = acc[ai][bj][m][1] * rs;
; #pragma unroll
;                     for (int k = 0; k < 4; ++k) { const float a = fmaxf(v0[k], 0.f), b = fmaxf(v1[k], 0.f); v0[k] = a * a; v1[k] = b * b; }
;                     po.put(bj, pack8(v0, v1)); }
;                 po.flush<true>(ai, m); }
	global_store_dwordx4 v[62:63], v[50:53], off offset:-4096 sc1
	s_waitcnt lgkmcnt(0)
	global_store_dwordx4 v[58:59], v[54:57], off offset:1024 sc1
	v_pk_mul_f32 v[48:49], v[60:61], v[48:49] op_sel_hi:[0,1]
	v_mul_f32_e32 v50, v42, v42
	v_max_f32_e32 v42, 0, v47
	v_max_f32_e32 v43, 0, v43
	v_max_f32_e32 v44, 0, v44
	v_max_f32_e32 v46, 0, v46
	v_mul_f32_e32 v42, v42, v42
	v_mul_f32_e32 v47, v43, v43
	v_max_f32_e32 v43, 0, v48
	v_mul_f32_e32 v48, v44, v44
	v_max_f32_e32 v44, 0, v49
	v_max_f32_e32 v45, 0, v45
	v_pk_mul_f32 v[36:37], v[60:61], v[36:37] op_sel_hi:[0,1]
	v_pk_mul_f32 v[34:35], v[60:61], v[34:35] op_sel_hi:[0,1]
	v_mul_f32_e32 v46, v46, v46
	v_mul_f32_e32 v43, v43, v43
	v_mul_f32_e32 v44, v44, v44
	v_mul_f32_e32 v45, v45, v45
	v_cvt_pk_bf16_f32 v42, v46, v42
	v_pk_mul_f32 v[40:41], v[60:61], v[40:41] op_sel_hi:[0,1]
	v_pk_mul_f32 v[38:39], v[60:61], v[38:39] op_sel_hi:[0,1]
	v_max_f32_e32 v34, 0, v34
	v_max_f32_e32 v35, 0, v35
	v_max_f32_e32 v36, 0, v36
	v_cvt_pk_bf16_f32 v43, v43, v44
	v_cvt_pk_bf16_f32 v44, v50, v47
	v_cvt_pk_bf16_f32 v45, v48, v45
	ds_write_b128 v157, v[42:45]
	v_mul_f32_e32 v42, v34, v34
	v_max_f32_e32 v34, 0, v39
	v_mul_f32_e32 v39, v35, v35
	v_max_f32_e32 v35, 0, v40
	v_mul_f32_e32 v40, v36, v36
	v_max_f32_e32 v36, 0, v41
	v_max_f32_e32 v38, 0, v38
	v_mul_f32_e32 v34, v34, v34
	v_mul_f32_e32 v35, v35, v35
	v_max_f32_e32 v37, 0, v37
	v_mul_f32_e32 v36, v36, v36
	v_mul_f32_e32 v38, v38, v38
	v_mul_f32_e32 v37, v37, v37
	v_cvt_pk_bf16_f32 v34, v38, v34
	v_cvt_pk_bf16_f32 v35, v35, v36
	v_cvt_pk_bf16_f32 v36, v42, v39
	v_fmamk_f32 v42, v152, 0x3a800000, v156
	v_cvt_pk_bf16_f32 v37, v40, v37
	ds_write_b128 v157, v[34:37] offset:64
	v_rsq_f32_e32 v42, v42
	ds_read_b128 v[34:37], v158
	ds_read_b128 v[38:41], v158 offset:1152
	s_waitcnt lgkmcnt(1)
	global_store_dwordx4 v[58:59], v[34:37], off offset:2048 sc1
	s_waitcnt lgkmcnt(0)
	global_store_dwordx4 v[58:59], v[38:41], off offset:3072 sc1
	v_pk_mul_f32 v[26:27], v[42:43], v[26:27] op_sel_hi:[0,1]
	v_pk_mul_f32 v[30:31], v[42:43], v[30:31] op_sel_hi:[0,1]
	v_pk_mul_f32 v[28:29], v[42:43], v[28:29] op_sel_hi:[0,1]
	v_max_f32_e32 v26, 0, v26
	v_pk_mul_f32 v[32:33], v[42:43], v[32:33] op_sel_hi:[0,1]
	v_mul_f32_e32 v34, v26, v26
	v_max_f32_e32 v26, 0, v31
	v_max_f32_e32 v27, 0, v27
	v_max_f32_e32 v28, 0, v28
	v_max_f32_e32 v30, 0, v30
	v_mul_f32_e32 v26, v26, v26
	v_mul_f32_e32 v31, v27, v27
	v_max_f32_e32 v27, 0, v32
	v_mul_f32_e32 v32, v28, v28
	v_max_f32_e32 v28, 0, v33
	v_max_f32_e32 v29, 0, v29
	v_pk_mul_f32 v[20:21], v[42:43], v[20:21] op_sel_hi:[0,1]
	v_pk_mul_f32 v[18:19], v[42:43], v[18:19] op_sel_hi:[0,1]
	v_mul_f32_e32 v30, v30, v30
	v_mul_f32_e32 v27, v27, v27
	v_mul_f32_e32 v28, v28, v28
	v_mul_f32_e32 v29, v29, v29
	v_cvt_pk_bf16_f32 v26, v30, v26
	v_pk_mul_f32 v[24:25], v[42:43], v[24:25] op_sel_hi:[0,1]
	v_pk_mul_f32 v[22:23], v[42:43], v[22:23] op_sel_hi:[0,1]
	v_max_f32_e32 v18, 0, v18
	v_max_f32_e32 v19, 0, v19
	v_max_f32_e32 v20, 0, v20
	v_cvt_pk_bf16_f32 v27, v27, v28
	v_cvt_pk_bf16_f32 v28, v34, v31
	v_cvt_pk_bf16_f32 v29, v32, v29
	ds_write_b128 v157, v[26:29]
	v_mul_f32_e32 v26, v18, v18
	v_max_f32_e32 v18, 0, v23
	v_mul_f32_e32 v23, v19, v19
	v_max_f32_e32 v19, 0, v24
	v_mul_f32_e32 v24, v20, v20
	v_max_f32_e32 v20, 0, v25
	v_max_f32_e32 v22, 0, v22
	v_mul_f32_e32 v18, v18, v18
	v_mul_f32_e32 v19, v19, v19
	v_max_f32_e32 v21, 0, v21
	v_mul_f32_e32 v20, v20, v20
	v_mul_f32_e32 v22, v22, v22
	v_mul_f32_e32 v21, v21, v21
	v_cvt_pk_bf16_f32 v18, v22, v18
	v_cvt_pk_bf16_f32 v19, v19, v20
	v_cvt_pk_bf16_f32 v20, v26, v23
	v_fmamk_f32 v26, v150, 0x3a800000, v156
	v_cvt_pk_bf16_f32 v21, v24, v21
	ds_write_b128 v157, v[18:21] offset:64
	v_rsq_f32_e32 v26, v26
	ds_read_b128 v[18:21], v158
	ds_read_b128 v[22:25], v158 offset:1152
	s_waitcnt lgkmcnt(1)
	global_store_dwordx4 v[62:63], v[18:21], off sc1
	s_waitcnt lgkmcnt(0)
	global_store_dwordx4 v[62:63], v[22:25], off offset:1024 sc1
	v_pk_mul_f32 v[10:11], v[26:27], v[10:11] op_sel_hi:[0,1]
	v_pk_mul_f32 v[14:15], v[26:27], v[14:15] op_sel_hi:[0,1]
	v_pk_mul_f32 v[12:13], v[26:27], v[12:13] op_sel_hi:[0,1]
	v_max_f32_e32 v10, 0, v10
	v_pk_mul_f32 v[16:17], v[26:27], v[16:17] op_sel_hi:[0,1]
	v_mul_f32_e32 v18, v10, v10
	v_max_f32_e32 v10, 0, v15
	v_max_f32_e32 v11, 0, v11
	v_max_f32_e32 v12, 0, v12
	v_max_f32_e32 v14, 0, v14
	v_mul_f32_e32 v10, v10, v10
	v_mul_f32_e32 v15, v11, v11
	v_max_f32_e32 v11, 0, v16
	v_mul_f32_e32 v16, v12, v12
	v_max_f32_e32 v12, 0, v17
	v_max_f32_e32 v13, 0, v13
	v_pk_mul_f32 v[4:5], v[26:27], v[4:5] op_sel_hi:[0,1]
	v_pk_mul_f32 v[2:3], v[26:27], v[2:3] op_sel_hi:[0,1]
	v_mul_f32_e32 v14, v14, v14
	v_mul_f32_e32 v11, v11, v11
	v_mul_f32_e32 v12, v12, v12
	v_mul_f32_e32 v13, v13, v13
	v_cvt_pk_bf16_f32 v10, v14, v10
	v_pk_mul_f32 v[8:9], v[26:27], v[8:9] op_sel_hi:[0,1]
	v_pk_mul_f32 v[6:7], v[26:27], v[6:7] op_sel_hi:[0,1]
	v_max_f32_e32 v2, 0, v2
	v_max_f32_e32 v3, 0, v3
	v_max_f32_e32 v4, 0, v4
	v_cvt_pk_bf16_f32 v11, v11, v12
	v_cvt_pk_bf16_f32 v12, v18, v15
	v_cvt_pk_bf16_f32 v13, v16, v13
	ds_write_b128 v157, v[10:13]
	v_mul_f32_e32 v10, v2, v2
	v_max_f32_e32 v2, 0, v7
	v_mul_f32_e32 v7, v3, v3
	v_max_f32_e32 v3, 0, v8
	v_mul_f32_e32 v8, v4, v4
	v_max_f32_e32 v4, 0, v9
	v_max_f32_e32 v5, 0, v5
	v_max_f32_e32 v6, 0, v6
	v_mul_f32_e32 v2, v2, v2
	v_mul_f32_e32 v3, v3, v3
	v_mul_f32_e32 v4, v4, v4
	v_mul_f32_e32 v5, v5, v5
	v_mul_f32_e32 v6, v6, v6
	v_cvt_pk_bf16_f32 v2, v6, v2
	v_cvt_pk_bf16_f32 v3, v3, v4
	v_cvt_pk_bf16_f32 v4, v10, v7
	v_cvt_pk_bf16_f32 v5, v8, v5
	ds_write_b128 v157, v[2:5] offset:64
	ds_read_b128 v[2:5], v158
	ds_read_b128 v[6:9], v158 offset:1152
	s_andn2_b64 vcc, exec, s[4:5]
	s_mov_b64 s[4:5], -1
	s_waitcnt lgkmcnt(1)
	global_store_dwordx4 v[62:63], v[2:5], off offset:2048 sc1
	s_waitcnt lgkmcnt(0)
	global_store_dwordx4 v[62:63], v[6:9], off offset:3072 sc1
	s_cbranch_vccnz .LBB0_578
	s_lshl_b32 s4, s18, 8
	s_ashr_i32 s5, s4, 31
	v_lshl_add_u64 v[2:3], s[4:5], 2, v[140:141]
	global_load_dword v164, v[2:3], off
	global_load_dword v163, v[2:3], off offset:64
	global_load_dword v162, v[2:3], off offset:128
	global_load_dword v161, v[2:3], off offset:192
	global_load_dword v160, v[2:3], off offset:512
	global_load_dword v159, v[2:3], off offset:576
	global_load_dword v152, v[2:3], off offset:640
	global_load_dword v150, v[2:3], off offset:704
	s_andn2_b64 vcc, exec, s[10:11]
	s_cbranch_vccnz .LBB0_577
	s_barrier
	s_branch .LBB0_577
